# mixer-phase rebalance: gMLP units pre-load their rows (L2 warm-up), the ten-chunk workgroups do no conv units, the one-gMLP workgroups take a fourth conv unit
# speedup vs baseline: 1.0004x; 1.0004x over previous
.LBB0_283:
	s_andn2_b64 vcc, exec, s[28:29]
	s_cbranch_vccnz .LBB0_345
	v_readlane_b32 s6, v250, 24
	v_readlane_b32 s7, v250, 25
	s_mov_b64 s[28:29], -1
	s_and_b64 vcc, exec, s[6:7]
	s_cbranch_vccz .LBB0_317
	s_waitcnt vmcnt(0)
	v_mov_b32_e32 v1, v242
	v_readlane_b32 s65, v250, 26
	v_readfirstlane_b32 s5, v1
	s_ashr_i32 s34, s5, 6
	s_lshl_b32 s6, s34, 4
	s_add_i32 s6, s6, s65
	s_mul_i32 s8, s6, 0x1800
	s_mul_hi_i32 s7, s6, 0x1800
	s_add_u32 s28, s80, s8
	s_addc_u32 s29, s81, s7
	s_mov_b64 s[8:9], s[28:29]
	v_and_b32_e32 v200, 63, v242
	v_lshlrev_b32_e32 v200, 4, v200
	s_nop 0
	global_load_dwordx4 v[204:207], v200, s[8:9]
	s_add_u32 s8, s8, 0x1800
	s_addc_u32 s9, s9, 0
	s_nop 0
	global_load_dwordx4 v[204:207], v200, s[8:9]
	s_add_u32 s8, s8, 0x1800
	s_addc_u32 s9, s9, 0
	s_nop 0
	global_load_dwordx4 v[204:207], v200, s[8:9]
	s_add_u32 s8, s8, 0x1800
	s_addc_u32 s9, s9, 0
	s_nop 0
	global_load_dwordx4 v[204:207], v200, s[8:9]
	s_add_u32 s8, s8, 0x1800
	s_addc_u32 s9, s9, 0
	s_nop 0
	global_load_dwordx4 v[204:207], v200, s[8:9]
	s_add_u32 s8, s8, 0x1800
	s_addc_u32 s9, s9, 0
	s_nop 0
	global_load_dwordx4 v[204:207], v200, s[8:9]
	s_add_u32 s8, s8, 0x1800
	s_addc_u32 s9, s9, 0
	s_nop 0
	global_load_dwordx4 v[204:207], v200, s[8:9]
	s_add_u32 s8, s8, 0x1800
	s_addc_u32 s9, s9, 0
	s_nop 0
	global_load_dwordx4 v[204:207], v200, s[8:9]
	s_add_u32 s8, s8, 0x1800
	s_addc_u32 s9, s9, 0
	s_nop 0
	global_load_dwordx4 v[204:207], v200, s[8:9]
	s_add_u32 s8, s8, 0x1800
	s_addc_u32 s9, s9, 0
	s_nop 0
	global_load_dwordx4 v[204:207], v200, s[8:9]
	s_add_u32 s8, s8, 0x1800
	s_addc_u32 s9, s9, 0
	s_nop 0
	global_load_dwordx4 v[204:207], v200, s[8:9]
	s_add_u32 s8, s8, 0x1800
	s_addc_u32 s9, s9, 0
	s_nop 0
	global_load_dwordx4 v[204:207], v200, s[8:9]
	s_add_u32 s8, s8, 0x1800
	s_addc_u32 s9, s9, 0
	s_nop 0
	global_load_dwordx4 v[204:207], v200, s[8:9]
	s_add_u32 s8, s8, 0x1800
	s_addc_u32 s9, s9, 0
	s_nop 0
	global_load_dwordx4 v[204:207], v200, s[8:9]
	s_add_u32 s8, s8, 0x1800
	s_addc_u32 s9, s9, 0
	s_nop 0
	global_load_dwordx4 v[204:207], v200, s[8:9]
	s_add_u32 s8, s8, 0x1800
	s_addc_u32 s9, s9, 0
	s_nop 0
	global_load_dwordx4 v[204:207], v200, s[8:9]
	s_or_b32 s7, s6, 1
	s_mul_hi_i32 s8, s7, 0x1800
	s_mulk_i32 s7, 0x1800
	s_add_u32 s40, s80, s7
	v_and_b32_e32 v66, 63, v1
	s_addc_u32 s41, s81, s8
	v_lshlrev_b32_e32 v38, 1, v66
	global_load_ushort v3, v38, s[40:41] offset:512
	global_load_ushort v14, v38, s[40:41] offset:640
	global_load_ushort v20, v38, s[40:41] offset:768
	global_load_ushort v24, v38, s[40:41] offset:896
	global_load_ushort v2, v38, s[28:29] offset:512
	global_load_ushort v15, v38, s[28:29] offset:640
	global_load_ushort v21, v38, s[28:29] offset:768
	global_load_ushort v25, v38, s[28:29] offset:896
	s_or_b32 s7, s6, 2
	s_mul_hi_i32 s9, s7, 0x1800
	s_mulk_i32 s7, 0x1800
	s_add_u32 s8, s80, s7
	s_addc_u32 s9, s81, s9
	s_or_b32 s7, s6, 3
	s_mul_hi_i32 s11, s7, 0x1800
	s_mulk_i32 s7, 0x1800
	s_add_u32 s10, s80, s7
	s_addc_u32 s11, s81, s11
	global_load_ushort v12, v38, s[10:11] offset:512
	global_load_ushort v13, v38, s[10:11] offset:640
	global_load_ushort v16, v38, s[10:11] offset:768
	global_load_ushort v26, v38, s[10:11] offset:896
	global_load_ushort v17, v38, s[8:9] offset:512
	global_load_ushort v22, v38, s[8:9] offset:640
	global_load_ushort v23, v38, s[8:9] offset:768
	global_load_ushort v27, v38, s[8:9] offset:896
	s_mov_b32 s8, 0xbf3a00e3
	v_mov_b64_e32 v[18:19], s[8:9]
	s_mov_b32 s10, 0x3f07dc22
	s_mov_b32 s14, 0x3f35f0e3
	s_mov_b32 s16, 0xbe11a98e
	s_mov_b32 s18, 0x3e027906
	s_or_b32 s7, s6, 4
	s_mul_hi_i32 s8, s7, 0x1800
	s_mulk_i32 s7, 0x1800
	s_add_u32 s28, s80, s7
	s_addc_u32 s29, s81, s8
	s_or_b32 s7, s6, 5
	s_mul_hi_i32 s8, s7, 0x1800
	s_mulk_i32 s7, 0x1800
	s_add_u32 s40, s80, s7
	s_addc_u32 s41, s81, s8
	s_or_b32 s7, s6, 6
	v_writelane_b32 v255, s58, 23
	s_mul_hi_i32 s8, s7, 0x1800
	s_mulk_i32 s7, 0x1800
	v_writelane_b32 v255, s59, 24
	s_add_u32 s58, s80, s7
	s_addc_u32 s59, s81, s8
	s_or_b32 s7, s6, 7
	s_mul_hi_i32 s8, s7, 0x1800
	s_mulk_i32 s7, 0x1800
	s_add_u32 s60, s80, s7
	s_addc_u32 s61, s81, s8
	s_or_b32 s7, s6, 8
	s_mul_hi_i32 s8, s7, 0x1800
	s_mulk_i32 s7, 0x1800
	s_add_u32 s46, s80, s7
	s_addc_u32 s47, s81, s8
	s_or_b32 s7, s6, 9
	s_mul_hi_i32 s8, s7, 0x1800
	s_mulk_i32 s7, 0x1800
	s_add_u32 s54, s80, s7
	s_addc_u32 s55, s81, s8
	s_or_b32 s7, s6, 10
	s_mul_hi_i32 s8, s7, 0x1800
	s_mulk_i32 s7, 0x1800
	s_add_u32 s48, s80, s7
	s_addc_u32 s49, s81, s8
	s_or_b32 s7, s6, 11
	s_mul_hi_i32 s8, s7, 0x1800
	s_mulk_i32 s7, 0x1800
	s_add_u32 s56, s80, s7
	s_addc_u32 s57, s81, s8
	s_or_b32 s7, s6, 12
	s_mul_hi_i32 s8, s7, 0x1800
	s_mulk_i32 s7, 0x1800
	s_add_u32 s42, s80, s7
	s_addc_u32 s43, s81, s8
	s_or_b32 s7, s6, 13
	s_mul_hi_i32 s8, s7, 0x1800
	s_mulk_i32 s7, 0x1800
	s_add_u32 s50, s80, s7
	s_addc_u32 s51, s81, s8
	s_or_b32 s7, s6, 14
	s_mul_hi_i32 s8, s7, 0x1800
	s_mulk_i32 s7, 0x1800
	s_waitcnt vmcnt(15)
	v_lshlrev_b32_e32 v3, 16, v3
	v_mul_f32_e32 v7, v3, v3
	v_mul_f32_e32 v7, 0xbf38aa3b, v7
	v_exp_f32_e32 v7, v7
	s_waitcnt vmcnt(11)
	v_lshlrev_b32_e32 v2, 16, v2
	s_waitcnt lgkmcnt(0)
	v_mul_f32_e32 v5, v2, v2
	v_mul_f32_e32 v5, 0xbf38aa3b, v5
	v_fma_f32 v4, |v2|, s92, 1.0
	v_exp_f32_e32 v6, v5
	v_fma_f32 v5, |v3|, s92, 1.0
	v_rcp_f32_e32 v4, v4
	v_rcp_f32_e32 v5, v5
	v_cmp_gt_f32_e32 vcc, 0, v3
	s_add_u32 s44, s80, s7
	s_addc_u32 s45, s81, s8
	v_pk_fma_f32 v[8:9], v[4:5], s[10:11], v[18:19] op_sel_hi:[1,0,0]
	s_or_b32 s6, s6, 15
	v_pk_fma_f32 v[8:9], v[4:5], v[8:9], s[14:15] op_sel_hi:[1,1,0]
	s_mul_hi_i32 s7, s6, 0x1800
	v_pk_fma_f32 v[8:9], v[4:5], v[8:9], s[16:17] op_sel_hi:[1,1,0]
	s_mulk_i32 s6, 0x1800
	v_pk_fma_f32 v[8:9], v[4:5], v[8:9], s[18:19] op_sel_hi:[1,1,0]
	s_add_u32 s52, s80, s6
	v_pk_mul_f32 v[4:5], v[4:5], v[8:9]
	s_addc_u32 s53, s81, s7
	v_pk_mul_f32 v[4:5], v[6:7], v[4:5]
	s_mov_b32 s8, 0x3b800000
	v_pk_mul_f32 v[6:7], v[4:5], v[2:3]
	v_pk_fma_f32 v[4:5], v[4:5], v[2:3], v[2:3] neg_lo:[1,0,0] neg_hi:[1,0,0]
	s_ashr_i32 s5, s5, 7
	v_cndmask_b32_e32 v11, v5, v7, vcc
	v_cmp_gt_f32_e32 vcc, 0, v2
	s_waitcnt vmcnt(3)
	v_lshlrev_b32_e32 v2, 16, v17
	v_fma_f32 v3, |v2|, s92, 1.0
	v_mul_f32_e32 v5, v2, v2
	v_cndmask_b32_e32 v10, v4, v6, vcc
	v_rcp_f32_e32 v4, v3
	v_mul_f32_e32 v5, 0xbf38aa3b, v5
	v_lshlrev_b32_e32 v3, 16, v12
	v_exp_f32_e32 v6, v5
	v_fma_f32 v5, |v3|, s92, 1.0
	v_rcp_f32_e32 v5, v5
	v_mul_f32_e32 v7, v3, v3
	v_mul_f32_e32 v7, 0xbf38aa3b, v7
	v_exp_f32_e32 v7, v7
	v_pk_fma_f32 v[8:9], v[4:5], s[10:11], v[18:19] op_sel_hi:[1,0,0]
	v_cmp_gt_f32_e32 vcc, 0, v3
	v_pk_fma_f32 v[8:9], v[4:5], v[8:9], s[14:15] op_sel_hi:[1,1,0]
	v_lshlrev_b32_e32 v130, 4, v66
	v_pk_fma_f32 v[8:9], v[4:5], v[8:9], s[16:17] op_sel_hi:[1,1,0]
	s_nop 0
	v_pk_fma_f32 v[8:9], v[4:5], v[8:9], s[18:19] op_sel_hi:[1,1,0]
	v_pk_mul_f32 v[4:5], v[4:5], v[8:9]
	v_pk_mul_f32 v[4:5], v[6:7], v[4:5]
	v_pk_mul_f32 v[6:7], v[4:5], v[2:3]
	v_pk_fma_f32 v[4:5], v[4:5], v[2:3], v[2:3] neg_lo:[1,0,0] neg_hi:[1,0,0]
	s_nop 0
	v_cndmask_b32_e32 v3, v5, v7, vcc
	v_cmp_gt_f32_e32 vcc, 0, v2
	s_nop 1
	v_cndmask_b32_e32 v2, v4, v6, vcc
	s_waitcnt vmcnt(2)
	v_lshlrev_b32_e32 v4, 16, v22
	v_fma_f32 v5, |v4|, s92, 1.0
	v_mul_f32_e32 v7, v4, v4
	v_rcp_f32_e32 v6, v5
	v_mul_f32_e32 v7, 0xbf38aa3b, v7
	v_lshlrev_b32_e32 v5, 16, v13
	v_exp_f32_e32 v8, v7
	v_fma_f32 v7, |v5|, s92, 1.0
	v_rcp_f32_e32 v7, v7
	v_mul_f32_e32 v9, v5, v5
	v_mul_f32_e32 v9, 0xbf38aa3b, v9
	v_exp_f32_e32 v9, v9
	v_pk_fma_f32 v[12:13], v[6:7], s[10:11], v[18:19] op_sel_hi:[1,0,0]
	v_cmp_gt_f32_e32 vcc, 0, v5
	v_pk_fma_f32 v[12:13], v[6:7], v[12:13], s[14:15] op_sel_hi:[1,1,0]
	s_nop 0
	v_pk_fma_f32 v[12:13], v[6:7], v[12:13], s[16:17] op_sel_hi:[1,1,0]
	s_nop 0
	v_pk_fma_f32 v[12:13], v[6:7], v[12:13], s[18:19] op_sel_hi:[1,1,0]
	v_pk_mul_f32 v[6:7], v[6:7], v[12:13]
	v_pk_mul_f32 v[6:7], v[8:9], v[6:7]
	v_pk_mul_f32 v[8:9], v[6:7], v[4:5]
	v_pk_fma_f32 v[6:7], v[6:7], v[4:5], v[4:5] neg_lo:[1,0,0] neg_hi:[1,0,0]
	v_lshlrev_b32_e32 v5, 16, v14
	v_cndmask_b32_e32 v7, v7, v9, vcc
	v_cmp_gt_f32_e32 vcc, 0, v4
	v_lshlrev_b32_e32 v4, 16, v15
	v_mul_f32_e32 v9, v4, v4
	v_mul_f32_e32 v9, 0xbf38aa3b, v9
	v_cndmask_b32_e32 v6, v6, v8, vcc
	v_fma_f32 v8, |v4|, s92, 1.0
	v_exp_f32_e32 v12, v9
	v_fma_f32 v9, |v5|, s92, 1.0
	v_rcp_f32_e32 v8, v8
	v_rcp_f32_e32 v9, v9
	v_mul_f32_e32 v13, v5, v5
	v_mul_f32_e32 v13, 0xbf38aa3b, v13
	v_exp_f32_e32 v13, v13
	v_pk_fma_f32 v[14:15], v[8:9], s[10:11], v[18:19] op_sel_hi:[1,0,0]
	v_cmp_gt_f32_e32 vcc, 0, v5
	v_pk_fma_f32 v[14:15], v[8:9], v[14:15], s[14:15] op_sel_hi:[1,1,0]
	s_nop 0
	v_pk_fma_f32 v[14:15], v[8:9], v[14:15], s[16:17] op_sel_hi:[1,1,0]
	s_nop 0
	v_pk_fma_f32 v[14:15], v[8:9], v[14:15], s[18:19] op_sel_hi:[1,1,0]
	v_pk_mul_f32 v[8:9], v[8:9], v[14:15]
	v_pk_mul_f32 v[8:9], v[12:13], v[8:9]
	v_pk_mul_f32 v[12:13], v[8:9], v[4:5]
	v_pk_fma_f32 v[8:9], v[8:9], v[4:5], v[4:5] neg_lo:[1,0,0] neg_hi:[1,0,0]
	v_lshlrev_b32_e32 v5, 16, v16
	v_cndmask_b32_e32 v13, v9, v13, vcc
	v_cmp_gt_f32_e32 vcc, 0, v4
	s_waitcnt vmcnt(1)
	v_lshlrev_b32_e32 v4, 16, v23
	v_fma_f32 v9, |v5|, s92, 1.0
	v_cndmask_b32_e32 v12, v8, v12, vcc
	v_fma_f32 v8, |v4|, s92, 1.0
	v_rcp_f32_e32 v8, v8
	v_rcp_f32_e32 v9, v9
	v_mul_f32_e32 v14, v4, v4
	v_mul_f32_e32 v15, v5, v5
	v_mul_f32_e32 v14, 0xbf38aa3b, v14
	v_pk_fma_f32 v[16:17], v[8:9], s[10:11], v[18:19] op_sel_hi:[1,0,0]
	v_mul_f32_e32 v15, 0xbf38aa3b, v15
	v_exp_f32_e32 v14, v14
	v_pk_fma_f32 v[16:17], v[8:9], v[16:17], s[14:15] op_sel_hi:[1,1,0]
	v_exp_f32_e32 v15, v15
	v_pk_fma_f32 v[16:17], v[8:9], v[16:17], s[16:17] op_sel_hi:[1,1,0]
	v_cmp_gt_f32_e32 vcc, 0, v5
	v_pk_fma_f32 v[16:17], v[8:9], v[16:17], s[18:19] op_sel_hi:[1,1,0]
	s_nop 0
	v_pk_mul_f32 v[8:9], v[8:9], v[16:17]
	v_pk_mul_f32 v[8:9], v[14:15], v[8:9]
	v_pk_mul_f32 v[14:15], v[8:9], v[4:5]
	v_pk_fma_f32 v[8:9], v[8:9], v[4:5], v[4:5] neg_lo:[1,0,0] neg_hi:[1,0,0]
	v_lshlrev_b32_e32 v5, 16, v20
	v_cndmask_b32_e32 v15, v9, v15, vcc
	v_cmp_gt_f32_e32 vcc, 0, v4
	v_lshlrev_b32_e32 v4, 16, v21
	v_mul_f32_e32 v9, v4, v4
	v_mul_f32_e32 v9, 0xbf38aa3b, v9
	v_cndmask_b32_e32 v14, v8, v14, vcc
	v_fma_f32 v8, |v4|, s92, 1.0
	v_exp_f32_e32 v16, v9
	v_fma_f32 v9, |v5|, s92, 1.0
	v_rcp_f32_e32 v8, v8
	v_rcp_f32_e32 v9, v9
	v_mul_f32_e32 v17, v5, v5
	v_mul_f32_e32 v17, 0xbf38aa3b, v17
	v_exp_f32_e32 v17, v17
	v_pk_fma_f32 v[20:21], v[8:9], s[10:11], v[18:19] op_sel_hi:[1,0,0]
	v_cmp_gt_f32_e32 vcc, 0, v5
	v_pk_fma_f32 v[20:21], v[8:9], v[20:21], s[14:15] op_sel_hi:[1,1,0]
	s_nop 0
	v_pk_fma_f32 v[20:21], v[8:9], v[20:21], s[16:17] op_sel_hi:[1,1,0]
	s_nop 0
	v_pk_fma_f32 v[20:21], v[8:9], v[20:21], s[18:19] op_sel_hi:[1,1,0]
	v_pk_mul_f32 v[8:9], v[8:9], v[20:21]
	v_pk_mul_f32 v[8:9], v[16:17], v[8:9]
	v_pk_mul_f32 v[16:17], v[8:9], v[4:5]
	v_pk_fma_f32 v[8:9], v[8:9], v[4:5], v[4:5] neg_lo:[1,0,0] neg_hi:[1,0,0]
	v_lshlrev_b32_e32 v5, 16, v26
	v_cndmask_b32_e32 v23, v9, v17, vcc
	v_cmp_gt_f32_e32 vcc, 0, v4
	s_waitcnt vmcnt(0)
	v_lshlrev_b32_e32 v4, 16, v27
	v_fma_f32 v9, |v5|, s92, 1.0
	v_cndmask_b32_e32 v22, v8, v16, vcc
	v_fma_f32 v8, |v4|, s92, 1.0
	v_rcp_f32_e32 v8, v8
	v_rcp_f32_e32 v9, v9
	v_mul_f32_e32 v16, v4, v4
	v_mul_f32_e32 v17, v5, v5
	v_mul_f32_e32 v16, 0xbf38aa3b, v16
	v_pk_fma_f32 v[20:21], v[8:9], s[10:11], v[18:19] op_sel_hi:[1,0,0]
	v_mul_f32_e32 v17, 0xbf38aa3b, v17
	v_exp_f32_e32 v16, v16
	v_pk_fma_f32 v[20:21], v[8:9], v[20:21], s[14:15] op_sel_hi:[1,1,0]
	v_exp_f32_e32 v17, v17
	v_pk_fma_f32 v[20:21], v[8:9], v[20:21], s[16:17] op_sel_hi:[1,1,0]
	v_cmp_gt_f32_e32 vcc, 0, v5
	v_pk_fma_f32 v[20:21], v[8:9], v[20:21], s[18:19] op_sel_hi:[1,1,0]
	v_mov_b32_e32 v26, v13
	v_pk_mul_f32 v[8:9], v[8:9], v[20:21]
	v_pk_mul_f32 v[8:9], v[16:17], v[8:9]
	v_pk_mul_f32 v[16:17], v[8:9], v[4:5]
	v_pk_fma_f32 v[8:9], v[8:9], v[4:5], v[4:5] neg_lo:[1,0,0] neg_hi:[1,0,0]
	v_lshlrev_b32_e32 v5, 16, v24
	v_cndmask_b32_e32 v17, v9, v17, vcc
	v_cmp_gt_f32_e32 vcc, 0, v4
	v_lshlrev_b32_e32 v4, 16, v25
	v_mul_f32_e32 v9, v4, v4
	v_mul_f32_e32 v9, 0xbf38aa3b, v9
	v_cndmask_b32_e32 v16, v8, v16, vcc
	v_fma_f32 v8, |v4|, s92, 1.0
	v_exp_f32_e32 v20, v9
	v_fma_f32 v9, |v5|, s92, 1.0
	v_rcp_f32_e32 v8, v8
	v_rcp_f32_e32 v9, v9
	v_mul_f32_e32 v21, v5, v5
	v_mul_f32_e32 v21, 0xbf38aa3b, v21
	v_exp_f32_e32 v21, v21
	v_pk_fma_f32 v[24:25], v[8:9], s[10:11], v[18:19] op_sel_hi:[1,0,0]
	v_cmp_gt_f32_e32 vcc, 0, v5
	v_pk_fma_f32 v[24:25], v[8:9], v[24:25], s[14:15] op_sel_hi:[1,1,0]
	s_nop 0
	v_pk_fma_f32 v[24:25], v[8:9], v[24:25], s[16:17] op_sel_hi:[1,1,0]
	s_nop 0
	v_pk_fma_f32 v[24:25], v[8:9], v[24:25], s[18:19] op_sel_hi:[1,1,0]
	v_pk_mul_f32 v[8:9], v[8:9], v[24:25]
	v_pk_mul_f32 v[8:9], v[20:21], v[8:9]
	v_pk_mul_f32 v[20:21], v[8:9], v[4:5]
	v_pk_fma_f32 v[8:9], v[8:9], v[4:5], v[4:5] neg_lo:[1,0,0] neg_hi:[1,0,0]
	v_mov_b32_e32 v5, v14
	v_cndmask_b32_e32 v25, v9, v21, vcc
	v_cmp_gt_f32_e32 vcc, 0, v4
	v_mov_b32_e32 v4, v2
	v_mov_b32_e32 v9, v16
	v_cndmask_b32_e32 v24, v8, v20, vcc
	v_mov_b32_e32 v8, v6
	v_pk_add_f32 v[4:5], v[4:5], v[8:9]
	v_mov_b32_e32 v8, v3
	v_add_f32_e32 v4, v4, v5
	v_mov_b32_e32 v9, v15
	s_nop 0
	v_add_f32_dpp v4, v4, v4 quad_perm:[1,0,3,2] row_mask:0xf bank_mask:0xf bound_ctrl:1
	v_mov_b32_e32 v20, v7
	v_mov_b32_e32 v21, v17
	v_add_f32_dpp v4, v4, v4 quad_perm:[2,3,0,1] row_mask:0xf bank_mask:0xf bound_ctrl:1
	v_pk_add_f32 v[8:9], v[8:9], v[20:21]
	v_mov_b64_e32 v[20:21], s[8:9]
	v_add_f32_dpp v4, v4, v4 row_half_mirror row_mask:0xf bank_mask:0xf bound_ctrl:1
	v_mov_b32_e32 v27, v25
	s_mov_b32 s8, 0x3e027906
	v_add_f32_dpp v4, v4, v4 row_mirror row_mask:0xf bank_mask:0xf bound_ctrl:1
	s_nop 1
	v_add_f32_dpp v4, v4, v4 row_bcast:15 row_mask:0xa bank_mask:0xf
	s_nop 1
	v_add_f32_dpp v4, v4, v4 row_bcast:31 row_mask:0xc bank_mask:0xf
	v_add_f32_e32 v5, v8, v9
	v_readlane_b32 s6, v4, 63
	s_nop 0
	v_add_f32_dpp v5, v5, v5 quad_perm:[1,0,3,2] row_mask:0xf bank_mask:0xf bound_ctrl:1
	s_xor_b32 s6, s6, 0x80000000
	s_nop 0
	v_add_f32_dpp v5, v5, v5 quad_perm:[2,3,0,1] row_mask:0xf bank_mask:0xf bound_ctrl:1
	s_nop 1
	v_add_f32_dpp v5, v5, v5 row_half_mirror row_mask:0xf bank_mask:0xf bound_ctrl:1
	s_nop 1
	v_add_f32_dpp v5, v5, v5 row_mirror row_mask:0xf bank_mask:0xf bound_ctrl:1
	s_nop 1
	v_add_f32_dpp v5, v5, v5 row_bcast:15 row_mask:0xa bank_mask:0xf
	s_nop 1
	v_add_f32_dpp v5, v5, v5 row_bcast:31 row_mask:0xc bank_mask:0xf
	s_nop 0
	v_readlane_b32 s7, v5, 63
	s_xor_b32 s7, s7, 0x80000000
	s_nop 0
	v_pk_fma_f32 v[4:5], s[6:7], v[20:21], v[2:3] op_sel_hi:[1,0,1]
	v_pk_fma_f32 v[8:9], s[6:7], v[20:21], v[6:7] op_sel_hi:[1,0,1]
	v_pk_fma_f32 v[6:7], s[6:7], v[20:21], v[14:15] op_sel_hi:[1,0,1]
	v_pk_fma_f32 v[2:3], s[6:7], v[20:21], v[16:17] op_sel_hi:[1,0,1]
	v_mov_b32_e32 v14, v10
	v_mov_b32_e32 v15, v22
	v_mov_b32_e32 v16, v12
	v_mov_b32_e32 v17, v24
	v_pk_add_f32 v[14:15], v[14:15], v[16:17]
	v_mov_b32_e32 v16, v11
	v_add_f32_e32 v14, v14, v15
	v_mov_b32_e32 v17, v23
	s_nop 0
	v_add_f32_dpp v14, v14, v14 quad_perm:[1,0,3,2] row_mask:0xf bank_mask:0xf bound_ctrl:1
	v_pk_add_f32 v[16:17], v[16:17], v[26:27]
	s_nop 0
	v_add_f32_dpp v14, v14, v14 quad_perm:[2,3,0,1] row_mask:0xf bank_mask:0xf bound_ctrl:1
	s_nop 1
	v_add_f32_dpp v14, v14, v14 row_half_mirror row_mask:0xf bank_mask:0xf bound_ctrl:1
	s_nop 1
	v_add_f32_dpp v14, v14, v14 row_mirror row_mask:0xf bank_mask:0xf bound_ctrl:1
	s_nop 1
	v_add_f32_dpp v14, v14, v14 row_bcast:15 row_mask:0xa bank_mask:0xf
	s_nop 1
	v_add_f32_dpp v14, v14, v14 row_bcast:31 row_mask:0xc bank_mask:0xf
	v_add_f32_e32 v15, v16, v17
	v_readlane_b32 s6, v14, 63
	s_nop 0
	v_add_f32_dpp v15, v15, v15 quad_perm:[1,0,3,2] row_mask:0xf bank_mask:0xf bound_ctrl:1
	s_xor_b32 s6, s6, 0x80000000
	s_nop 0
	v_add_f32_dpp v15, v15, v15 quad_perm:[2,3,0,1] row_mask:0xf bank_mask:0xf bound_ctrl:1
	s_nop 1
	v_add_f32_dpp v15, v15, v15 row_half_mirror row_mask:0xf bank_mask:0xf bound_ctrl:1
	s_nop 1
	v_add_f32_dpp v15, v15, v15 row_mirror row_mask:0xf bank_mask:0xf bound_ctrl:1
	s_nop 1
	v_add_f32_dpp v15, v15, v15 row_bcast:15 row_mask:0xa bank_mask:0xf
	s_nop 1
	v_add_f32_dpp v15, v15, v15 row_bcast:31 row_mask:0xc bank_mask:0xf
	s_nop 0
	v_readlane_b32 s7, v15, 63
	s_xor_b32 s7, s7, 0x80000000
	s_nop 0
	v_pk_fma_f32 v[16:17], s[6:7], v[20:21], v[10:11] op_sel_hi:[1,0,1]
	v_pk_fma_f32 v[14:15], s[6:7], v[20:21], v[12:13] op_sel_hi:[1,0,1]
	v_pk_fma_f32 v[12:13], s[6:7], v[20:21], v[22:23] op_sel_hi:[1,0,1]
	v_pk_fma_f32 v[10:11], s[6:7], v[20:21], v[24:25] op_sel_hi:[1,0,1]
	global_load_ushort v22, v38, s[60:61] offset:512
	global_load_ushort v32, v38, s[60:61] offset:640
	global_load_ushort v36, v38, s[60:61] offset:768
	global_load_ushort v39, v38, s[60:61] offset:896
	global_load_ushort v24, v38, s[58:59] offset:512
	global_load_ushort v33, v38, s[58:59] offset:640
	global_load_ushort v37, v38, s[58:59] offset:768
	global_load_ushort v42, v38, s[58:59] offset:896
	s_waitcnt vmcnt(7)
	v_lshlrev_b32_e32 v23, 16, v22
	v_fma_f32 v25, |v23|, s92, 1.0
	v_rcp_f32_e32 v25, v25
	v_mul_f32_e32 v27, v23, v23
	s_waitcnt vmcnt(3)
	v_lshlrev_b32_e32 v22, 16, v24
	v_fma_f32 v24, |v22|, s92, 1.0
	v_rcp_f32_e32 v24, v24
	v_mul_f32_e32 v26, v22, v22
	v_mul_f32_e32 v26, 0xbf38aa3b, v26
	v_mul_f32_e32 v27, 0xbf38aa3b, v27
	v_pk_fma_f32 v[28:29], v[24:25], s[10:11], v[18:19] op_sel_hi:[1,0,0]
	v_exp_f32_e32 v26, v26
	v_pk_fma_f32 v[28:29], v[24:25], v[28:29], s[14:15] op_sel_hi:[1,1,0]
	v_exp_f32_e32 v27, v27
	v_pk_fma_f32 v[28:29], v[24:25], v[28:29], s[16:17] op_sel_hi:[1,1,0]
	v_cmp_gt_f32_e32 vcc, 0, v23
	v_pk_fma_f32 v[28:29], v[24:25], v[28:29], s[18:19] op_sel_hi:[1,1,0]
	v_readlane_b32 s11, v254, 26
	v_pk_mul_f32 v[24:25], v[24:25], v[28:29]
	s_nop 0
	v_pk_mul_f32 v[24:25], v[26:27], v[24:25]
	v_pk_mul_f32 v[26:27], v[24:25], v[22:23]
	v_pk_fma_f32 v[24:25], v[24:25], v[22:23], v[22:23] neg_lo:[1,0,0] neg_hi:[1,0,0]
	s_nop 0
	v_cndmask_b32_e32 v23, v25, v27, vcc
	v_cmp_gt_f32_e32 vcc, 0, v22
	s_nop 1
	v_cndmask_b32_e32 v22, v24, v26, vcc
	global_load_ushort v24, v38, s[40:41] offset:512
	global_load_ushort v34, v38, s[40:41] offset:640
	global_load_ushort v40, v38, s[40:41] offset:768
	global_load_ushort v44, v38, s[40:41] offset:896
	global_load_ushort v26, v38, s[28:29] offset:512
	global_load_ushort v35, v38, s[28:29] offset:640
	global_load_ushort v41, v38, s[28:29] offset:768
	global_load_ushort v45, v38, s[28:29] offset:896
	s_waitcnt vmcnt(7)
	v_lshlrev_b32_e32 v25, 16, v24
	s_waitcnt vmcnt(3)
	v_lshlrev_b32_e32 v24, 16, v26
	v_mul_f32_e32 v27, v24, v24
	v_mul_f32_e32 v27, 0xbf38aa3b, v27
	v_fma_f32 v26, |v24|, s92, 1.0
	v_exp_f32_e32 v28, v27
	v_fma_f32 v27, |v25|, s92, 1.0
	v_rcp_f32_e32 v26, v26
	v_rcp_f32_e32 v27, v27
	v_mul_f32_e32 v29, v25, v25
	v_mul_f32_e32 v29, 0xbf38aa3b, v29
	v_exp_f32_e32 v29, v29
	v_pk_fma_f32 v[30:31], v[26:27], s[10:11], v[18:19] op_sel_hi:[1,0,0]
	v_cmp_gt_f32_e32 vcc, 0, v25
	v_pk_fma_f32 v[30:31], v[26:27], v[30:31], s[14:15] op_sel_hi:[1,1,0]
	s_nop 0
	v_pk_fma_f32 v[30:31], v[26:27], v[30:31], s[16:17] op_sel_hi:[1,1,0]
	s_nop 0
	v_pk_fma_f32 v[30:31], v[26:27], v[30:31], s[18:19] op_sel_hi:[1,1,0]
	v_pk_mul_f32 v[26:27], v[26:27], v[30:31]
	v_pk_mul_f32 v[26:27], v[28:29], v[26:27]
	v_pk_mul_f32 v[28:29], v[26:27], v[24:25]
	v_pk_fma_f32 v[26:27], v[26:27], v[24:25], v[24:25] neg_lo:[1,0,0] neg_hi:[1,0,0]
	v_lshlrev_b32_e32 v25, 16, v32
	v_cndmask_b32_e32 v31, v27, v29, vcc
	v_cmp_gt_f32_e32 vcc, 0, v24
	v_lshlrev_b32_e32 v24, 16, v33
	v_fma_f32 v27, |v25|, s92, 1.0
	v_cndmask_b32_e32 v30, v26, v28, vcc
	v_fma_f32 v26, |v24|, s92, 1.0
	v_rcp_f32_e32 v26, v26
	v_rcp_f32_e32 v27, v27
	v_mul_f32_e32 v28, v24, v24
	v_mul_f32_e32 v29, v25, v25
	v_mul_f32_e32 v28, 0xbf38aa3b, v28
	v_pk_fma_f32 v[32:33], v[26:27], s[10:11], v[18:19] op_sel_hi:[1,0,0]
	v_mul_f32_e32 v29, 0xbf38aa3b, v29
	v_exp_f32_e32 v28, v28
	v_pk_fma_f32 v[32:33], v[26:27], v[32:33], s[14:15] op_sel_hi:[1,1,0]
	v_exp_f32_e32 v29, v29
	v_pk_fma_f32 v[32:33], v[26:27], v[32:33], s[16:17] op_sel_hi:[1,1,0]
	v_cmp_gt_f32_e32 vcc, 0, v25
	v_pk_fma_f32 v[32:33], v[26:27], v[32:33], s[18:19] op_sel_hi:[1,1,0]
	s_nop 0
	v_pk_mul_f32 v[26:27], v[26:27], v[32:33]
	v_pk_mul_f32 v[26:27], v[28:29], v[26:27]
	v_pk_mul_f32 v[28:29], v[26:27], v[24:25]
	v_pk_fma_f32 v[26:27], v[26:27], v[24:25], v[24:25] neg_lo:[1,0,0] neg_hi:[1,0,0]
	s_nop 0
	v_cndmask_b32_e32 v25, v27, v29, vcc
	v_cmp_gt_f32_e32 vcc, 0, v24
	v_lshlrev_b32_e32 v27, 16, v34
	v_mul_f32_e32 v33, v27, v27
	v_cndmask_b32_e32 v24, v26, v28, vcc
	s_waitcnt vmcnt(2)
	v_lshlrev_b32_e32 v26, 16, v35
	v_mul_f32_e32 v29, v26, v26
	v_mul_f32_e32 v29, 0xbf38aa3b, v29
	v_fma_f32 v28, |v26|, s92, 1.0
	v_exp_f32_e32 v32, v29
	v_fma_f32 v29, |v27|, s92, 1.0
	v_rcp_f32_e32 v28, v28
	v_rcp_f32_e32 v29, v29
	v_mul_f32_e32 v33, 0xbf38aa3b, v33
	v_exp_f32_e32 v33, v33
	v_cmp_gt_f32_e32 vcc, 0, v27
	v_pk_fma_f32 v[34:35], v[28:29], s[10:11], v[18:19] op_sel_hi:[1,0,0]
	s_nop 0
	v_pk_fma_f32 v[34:35], v[28:29], v[34:35], s[14:15] op_sel_hi:[1,1,0]
	s_nop 0
	v_pk_fma_f32 v[34:35], v[28:29], v[34:35], s[16:17] op_sel_hi:[1,1,0]
	s_nop 0
	v_pk_fma_f32 v[34:35], v[28:29], v[34:35], s[18:19] op_sel_hi:[1,1,0]
	v_pk_mul_f32 v[28:29], v[28:29], v[34:35]
	v_pk_mul_f32 v[28:29], v[32:33], v[28:29]
	v_pk_mul_f32 v[32:33], v[28:29], v[26:27]
	v_pk_fma_f32 v[28:29], v[28:29], v[26:27], v[26:27] neg_lo:[1,0,0] neg_hi:[1,0,0]
	v_lshlrev_b32_e32 v27, 16, v36
	v_cndmask_b32_e32 v33, v29, v33, vcc
	v_cmp_gt_f32_e32 vcc, 0, v26
	v_lshlrev_b32_e32 v26, 16, v37
	v_fma_f32 v29, |v27|, s92, 1.0
	v_cndmask_b32_e32 v32, v28, v32, vcc
	v_fma_f32 v28, |v26|, s92, 1.0
	v_rcp_f32_e32 v28, v28
	v_rcp_f32_e32 v29, v29
	v_mul_f32_e32 v34, v26, v26
	v_mul_f32_e32 v35, v27, v27
	v_mul_f32_e32 v34, 0xbf38aa3b, v34
	v_pk_fma_f32 v[36:37], v[28:29], s[10:11], v[18:19] op_sel_hi:[1,0,0]
	v_mul_f32_e32 v35, 0xbf38aa3b, v35
	v_exp_f32_e32 v34, v34
	v_pk_fma_f32 v[36:37], v[28:29], v[36:37], s[14:15] op_sel_hi:[1,1,0]
	v_exp_f32_e32 v35, v35
	v_pk_fma_f32 v[36:37], v[28:29], v[36:37], s[16:17] op_sel_hi:[1,1,0]
	v_cmp_gt_f32_e32 vcc, 0, v27
	v_pk_fma_f32 v[36:37], v[28:29], v[36:37], s[18:19] op_sel_hi:[1,1,0]
	s_nop 0
	v_pk_mul_f32 v[28:29], v[28:29], v[36:37]
	v_pk_mul_f32 v[28:29], v[34:35], v[28:29]
	v_pk_mul_f32 v[34:35], v[28:29], v[26:27]
	v_pk_fma_f32 v[28:29], v[28:29], v[26:27], v[26:27] neg_lo:[1,0,0] neg_hi:[1,0,0]
	v_lshlrev_b32_e32 v27, 16, v40
	v_cndmask_b32_e32 v35, v29, v35, vcc
	v_cmp_gt_f32_e32 vcc, 0, v26
	s_waitcnt vmcnt(1)
	v_lshlrev_b32_e32 v26, 16, v41
	v_mul_f32_e32 v29, v26, v26
	v_mul_f32_e32 v29, 0xbf38aa3b, v29
	v_cndmask_b32_e32 v34, v28, v34, vcc
	v_fma_f32 v28, |v26|, s92, 1.0
	v_exp_f32_e32 v36, v29
	v_fma_f32 v29, |v27|, s92, 1.0
	v_rcp_f32_e32 v28, v28
	v_rcp_f32_e32 v29, v29
	v_mul_f32_e32 v37, v27, v27
	v_mul_f32_e32 v37, 0xbf38aa3b, v37
	v_exp_f32_e32 v37, v37
	v_pk_fma_f32 v[40:41], v[28:29], s[10:11], v[18:19] op_sel_hi:[1,0,0]
	v_cmp_gt_f32_e32 vcc, 0, v27
	v_pk_fma_f32 v[40:41], v[28:29], v[40:41], s[14:15] op_sel_hi:[1,1,0]
	s_nop 0
	v_pk_fma_f32 v[40:41], v[28:29], v[40:41], s[16:17] op_sel_hi:[1,1,0]
	s_nop 0
	v_pk_fma_f32 v[40:41], v[28:29], v[40:41], s[18:19] op_sel_hi:[1,1,0]
	v_pk_mul_f32 v[28:29], v[28:29], v[40:41]
	v_pk_mul_f32 v[28:29], v[36:37], v[28:29]
	v_pk_mul_f32 v[36:37], v[28:29], v[26:27]
	v_pk_fma_f32 v[28:29], v[28:29], v[26:27], v[26:27] neg_lo:[1,0,0] neg_hi:[1,0,0]
	v_lshlrev_b32_e32 v27, 16, v39
	v_cndmask_b32_e32 v41, v29, v37, vcc
	v_cmp_gt_f32_e32 vcc, 0, v26
	v_lshlrev_b32_e32 v26, 16, v42
	v_fma_f32 v29, |v27|, s92, 1.0
	v_cndmask_b32_e32 v40, v28, v36, vcc
	v_fma_f32 v28, |v26|, s92, 1.0
	v_rcp_f32_e32 v28, v28
	v_rcp_f32_e32 v29, v29
	v_mul_f32_e32 v36, v26, v26
	v_mul_f32_e32 v37, v27, v27
	v_mul_f32_e32 v36, 0xbf38aa3b, v36
	v_pk_fma_f32 v[42:43], v[28:29], s[10:11], v[18:19] op_sel_hi:[1,0,0]
	v_mul_f32_e32 v37, 0xbf38aa3b, v37
	v_exp_f32_e32 v36, v36
	v_pk_fma_f32 v[42:43], v[28:29], v[42:43], s[14:15] op_sel_hi:[1,1,0]
	v_exp_f32_e32 v37, v37
	v_pk_fma_f32 v[42:43], v[28:29], v[42:43], s[16:17] op_sel_hi:[1,1,0]
	v_cmp_gt_f32_e32 vcc, 0, v27
	v_pk_fma_f32 v[42:43], v[28:29], v[42:43], s[18:19] op_sel_hi:[1,1,0]
	s_nop 0
	v_pk_mul_f32 v[28:29], v[28:29], v[42:43]
	v_pk_mul_f32 v[28:29], v[36:37], v[28:29]
	v_pk_mul_f32 v[36:37], v[28:29], v[26:27]
	v_pk_fma_f32 v[28:29], v[28:29], v[26:27], v[26:27] neg_lo:[1,0,0] neg_hi:[1,0,0]
	v_lshlrev_b32_e32 v27, 16, v44
	v_cndmask_b32_e32 v37, v29, v37, vcc
	v_cmp_gt_f32_e32 vcc, 0, v26
	s_waitcnt vmcnt(0)
	v_lshlrev_b32_e32 v26, 16, v45
	v_mul_f32_e32 v29, v26, v26
	v_mul_f32_e32 v29, 0xbf38aa3b, v29
	v_cndmask_b32_e32 v36, v28, v36, vcc
	v_fma_f32 v28, |v26|, s92, 1.0
	v_exp_f32_e32 v42, v29
	v_fma_f32 v29, |v27|, s92, 1.0
	v_rcp_f32_e32 v28, v28
	v_rcp_f32_e32 v29, v29
	v_mul_f32_e32 v39, v27, v27
	v_mul_f32_e32 v39, 0xbf38aa3b, v39
	v_exp_f32_e32 v43, v39
	v_pk_fma_f32 v[44:45], v[28:29], s[10:11], v[18:19] op_sel_hi:[1,0,0]
	v_cmp_gt_f32_e32 vcc, 0, v27
	v_pk_fma_f32 v[44:45], v[28:29], v[44:45], s[14:15] op_sel_hi:[1,1,0]
	s_nop 0
	v_pk_fma_f32 v[44:45], v[28:29], v[44:45], s[16:17] op_sel_hi:[1,1,0]
	s_nop 0
	v_pk_fma_f32 v[44:45], v[28:29], v[44:45], s[18:19] op_sel_hi:[1,1,0]
	v_pk_mul_f32 v[28:29], v[28:29], v[44:45]
	v_mov_b32_e32 v44, v25
	v_pk_mul_f32 v[28:29], v[42:43], v[28:29]
	v_mov_b32_e32 v45, v37
	v_pk_mul_f32 v[42:43], v[28:29], v[26:27]
	v_pk_fma_f32 v[28:29], v[28:29], v[26:27], v[26:27] neg_lo:[1,0,0] neg_hi:[1,0,0]
	v_mov_b32_e32 v27, v34
	v_cndmask_b32_e32 v43, v29, v43, vcc
	v_cmp_gt_f32_e32 vcc, 0, v26
	v_mov_b32_e32 v26, v22
	v_mov_b32_e32 v29, v36
	v_cndmask_b32_e32 v42, v28, v42, vcc
	v_mov_b32_e32 v28, v24
	v_pk_add_f32 v[26:27], v[26:27], v[28:29]
	v_mov_b32_e32 v28, v23
	v_add_f32_e32 v26, v26, v27
	v_mov_b32_e32 v29, v35
	s_nop 0
	v_add_f32_dpp v26, v26, v26 quad_perm:[1,0,3,2] row_mask:0xf bank_mask:0xf bound_ctrl:1
	v_pk_add_f32 v[28:29], v[28:29], v[44:45]
	v_mov_b32_e32 v44, v33
	v_add_f32_dpp v26, v26, v26 quad_perm:[2,3,0,1] row_mask:0xf bank_mask:0xf bound_ctrl:1
	v_mov_b32_e32 v45, v43
	s_nop 0
	v_add_f32_dpp v26, v26, v26 row_half_mirror row_mask:0xf bank_mask:0xf bound_ctrl:1
	s_nop 1
	v_add_f32_dpp v26, v26, v26 row_mirror row_mask:0xf bank_mask:0xf bound_ctrl:1
	s_nop 1
	v_add_f32_dpp v26, v26, v26 row_bcast:15 row_mask:0xa bank_mask:0xf
	s_nop 1
	v_add_f32_dpp v26, v26, v26 row_bcast:31 row_mask:0xc bank_mask:0xf
	v_add_f32_e32 v27, v28, v29
	v_readlane_b32 s6, v26, 63
	s_nop 0
	v_add_f32_dpp v27, v27, v27 quad_perm:[1,0,3,2] row_mask:0xf bank_mask:0xf bound_ctrl:1
	s_xor_b32 s6, s6, 0x80000000
	s_nop 0
	v_add_f32_dpp v27, v27, v27 quad_perm:[2,3,0,1] row_mask:0xf bank_mask:0xf bound_ctrl:1
	s_nop 1
	v_add_f32_dpp v27, v27, v27 row_half_mirror row_mask:0xf bank_mask:0xf bound_ctrl:1
	s_nop 1
	v_add_f32_dpp v27, v27, v27 row_mirror row_mask:0xf bank_mask:0xf bound_ctrl:1
	s_nop 1
	v_add_f32_dpp v27, v27, v27 row_bcast:15 row_mask:0xa bank_mask:0xf
	s_nop 1
	v_add_f32_dpp v27, v27, v27 row_bcast:31 row_mask:0xc bank_mask:0xf
	s_nop 0
	v_readlane_b32 s7, v27, 63
	s_xor_b32 s7, s7, 0x80000000
	s_nop 0
	v_pk_fma_f32 v[28:29], s[6:7], v[20:21], v[22:23] op_sel_hi:[1,0,1]
	v_pk_fma_f32 v[26:27], s[6:7], v[20:21], v[24:25] op_sel_hi:[1,0,1]
	v_pk_fma_f32 v[24:25], s[6:7], v[20:21], v[34:35] op_sel_hi:[1,0,1]
	v_pk_fma_f32 v[22:23], s[6:7], v[20:21], v[36:37] op_sel_hi:[1,0,1]
	v_mov_b32_e32 v34, v30
	v_mov_b32_e32 v35, v40
	v_mov_b32_e32 v36, v32
	v_mov_b32_e32 v37, v42
	v_pk_add_f32 v[34:35], v[34:35], v[36:37]
	v_mov_b32_e32 v36, v31
	v_add_f32_e32 v34, v34, v35
	v_mov_b32_e32 v37, v41
	s_nop 0
	v_add_f32_dpp v34, v34, v34 quad_perm:[1,0,3,2] row_mask:0xf bank_mask:0xf bound_ctrl:1
	v_pk_add_f32 v[36:37], v[36:37], v[44:45]
	s_nop 0
	v_add_f32_dpp v34, v34, v34 quad_perm:[2,3,0,1] row_mask:0xf bank_mask:0xf bound_ctrl:1
	s_nop 1
	v_add_f32_dpp v34, v34, v34 row_half_mirror row_mask:0xf bank_mask:0xf bound_ctrl:1
	s_nop 1
	v_add_f32_dpp v34, v34, v34 row_mirror row_mask:0xf bank_mask:0xf bound_ctrl:1
	s_nop 1
	v_add_f32_dpp v34, v34, v34 row_bcast:15 row_mask:0xa bank_mask:0xf
	s_nop 1
	v_add_f32_dpp v34, v34, v34 row_bcast:31 row_mask:0xc bank_mask:0xf
	v_add_f32_e32 v35, v36, v37
	v_readlane_b32 s6, v34, 63
	s_nop 0
	v_add_f32_dpp v35, v35, v35 quad_perm:[1,0,3,2] row_mask:0xf bank_mask:0xf bound_ctrl:1
	s_xor_b32 s6, s6, 0x80000000
	s_nop 0
	v_add_f32_dpp v35, v35, v35 quad_perm:[2,3,0,1] row_mask:0xf bank_mask:0xf bound_ctrl:1
	s_nop 1
	v_add_f32_dpp v35, v35, v35 row_half_mirror row_mask:0xf bank_mask:0xf bound_ctrl:1
	s_nop 1
	v_add_f32_dpp v35, v35, v35 row_mirror row_mask:0xf bank_mask:0xf bound_ctrl:1
	s_nop 1
	v_add_f32_dpp v35, v35, v35 row_bcast:15 row_mask:0xa bank_mask:0xf
	s_nop 1
	v_add_f32_dpp v35, v35, v35 row_bcast:31 row_mask:0xc bank_mask:0xf
	s_nop 0
	v_readlane_b32 s7, v35, 63
	s_xor_b32 s7, s7, 0x80000000
	s_nop 0
	v_pk_fma_f32 v[34:35], s[6:7], v[20:21], v[32:33] op_sel_hi:[1,0,1]
	v_pk_fma_f32 v[32:33], s[6:7], v[20:21], v[40:41] op_sel_hi:[1,0,1]
	global_load_ushort v46, v38, s[54:55] offset:512
	global_load_ushort v50, v38, s[54:55] offset:640
	global_load_ushort v71, v38, s[54:55] offset:768
	global_load_ushort v76, v38, s[54:55] offset:896
	global_load_ushort v47, v38, s[46:47] offset:512
	global_load_ushort v51, v38, s[46:47] offset:640
	global_load_ushort v72, v38, s[46:47] offset:768
	global_load_ushort v77, v38, s[46:47] offset:896
	global_load_ushort v39, v38, s[56:57] offset:512
	global_load_ushort v48, v38, s[56:57] offset:640
	global_load_ushort v52, v38, s[56:57] offset:768
	global_load_ushort v74, v38, s[56:57] offset:896
	global_load_ushort v40, v38, s[48:49] offset:512
	global_load_ushort v49, v38, s[48:49] offset:640
	global_load_ushort v53, v38, s[48:49] offset:768
	global_load_ushort v75, v38, s[48:49] offset:896
	global_load_ushort v60, v38, s[50:51] offset:512
	global_load_ushort v62, v38, s[50:51] offset:640
	global_load_ushort v67, v38, s[50:51] offset:768
	global_load_ushort v58, v38, s[50:51] offset:896
	global_load_ushort v61, v38, s[42:43] offset:512
	global_load_ushort v63, v38, s[42:43] offset:640
	global_load_ushort v68, v38, s[42:43] offset:768
	global_load_ushort v59, v38, s[42:43] offset:896
	global_load_ushort v54, v38, s[52:53] offset:512
	global_load_ushort v56, v38, s[52:53] offset:640
	global_load_ushort v69, v38, s[52:53] offset:768
	global_load_ushort v64, v38, s[52:53] offset:896
	global_load_ushort v55, v38, s[44:45] offset:512
	global_load_ushort v57, v38, s[44:45] offset:640
	global_load_ushort v70, v38, s[44:45] offset:768
	global_load_ushort v65, v38, s[44:45] offset:896
	v_pk_fma_f32 v[36:37], s[6:7], v[20:21], v[30:31] op_sel_hi:[1,0,1]
	v_pk_fma_f32 v[30:31], s[6:7], v[20:21], v[42:43] op_sel_hi:[1,0,1]
	s_load_dwordx2 s[42:43], s[0:1], 0x30
	s_load_dwordx4 s[52:55], s[0:1], 0x18
	s_waitcnt vmcnt(23)
	v_lshlrev_b32_e32 v39, 16, v39
	v_fma_f32 v41, |v39|, s92, 1.0
	v_rcp_f32_e32 v41, v41
	v_mul_f32_e32 v43, v39, v39
	s_waitcnt vmcnt(19)
	v_lshlrev_b32_e32 v38, 16, v40
	v_fma_f32 v40, |v38|, s92, 1.0
	v_rcp_f32_e32 v40, v40
	v_mul_f32_e32 v42, v38, v38
	v_mul_f32_e32 v42, 0xbf38aa3b, v42
	v_mul_f32_e32 v43, 0xbf38aa3b, v43
	v_pk_fma_f32 v[44:45], v[40:41], s[10:11], v[18:19] op_sel_hi:[1,0,0]
	v_exp_f32_e32 v42, v42
	v_pk_fma_f32 v[44:45], v[40:41], v[44:45], s[14:15] op_sel_hi:[1,1,0]
	v_exp_f32_e32 v43, v43
	v_pk_fma_f32 v[44:45], v[40:41], v[44:45], s[16:17] op_sel_hi:[1,1,0]
	v_cmp_gt_f32_e32 vcc, 0, v39
	v_pk_fma_f32 v[44:45], v[40:41], v[44:45], s[18:19] op_sel_hi:[1,1,0]
	s_waitcnt vmcnt(9)
	v_lshlrev_b32_e32 v68, 16, v68
	v_pk_mul_f32 v[40:41], v[40:41], v[44:45]
	s_waitcnt vmcnt(1)
	v_lshlrev_b32_e32 v70, 16, v70
	v_pk_mul_f32 v[40:41], v[42:43], v[40:41]
	v_pk_mul_f32 v[42:43], v[40:41], v[38:39]
	v_pk_fma_f32 v[40:41], v[40:41], v[38:39], v[38:39] neg_lo:[1,0,0] neg_hi:[1,0,0]
	s_nop 0
	v_cndmask_b32_e32 v39, v41, v43, vcc
	v_cmp_gt_f32_e32 vcc, 0, v38
	v_lshlrev_b32_e32 v41, 16, v46
	v_mul_f32_e32 v45, v41, v41
	v_cndmask_b32_e32 v38, v40, v42, vcc
	v_lshlrev_b32_e32 v40, 16, v47
	v_mul_f32_e32 v43, v40, v40
	v_mul_f32_e32 v43, 0xbf38aa3b, v43
	v_fma_f32 v42, |v40|, s92, 1.0
	v_exp_f32_e32 v44, v43
	v_fma_f32 v43, |v41|, s92, 1.0
	v_rcp_f32_e32 v42, v42
	v_rcp_f32_e32 v43, v43
	v_mul_f32_e32 v45, 0xbf38aa3b, v45
	v_exp_f32_e32 v45, v45
	v_cmp_gt_f32_e32 vcc, 0, v41
	v_pk_fma_f32 v[46:47], v[42:43], s[10:11], v[18:19] op_sel_hi:[1,0,0]
	s_nop 0
	v_pk_fma_f32 v[46:47], v[42:43], v[46:47], s[14:15] op_sel_hi:[1,1,0]
	s_nop 0
	v_pk_fma_f32 v[46:47], v[42:43], v[46:47], s[16:17] op_sel_hi:[1,1,0]
	s_nop 0
	v_pk_fma_f32 v[46:47], v[42:43], v[46:47], s[18:19] op_sel_hi:[1,1,0]
	v_pk_mul_f32 v[42:43], v[42:43], v[46:47]
	v_pk_mul_f32 v[42:43], v[44:45], v[42:43]
	v_pk_mul_f32 v[44:45], v[42:43], v[40:41]
	v_pk_fma_f32 v[42:43], v[42:43], v[40:41], v[40:41] neg_lo:[1,0,0] neg_hi:[1,0,0]
	v_lshlrev_b32_e32 v41, 16, v48
	v_cndmask_b32_e32 v47, v43, v45, vcc
	v_cmp_gt_f32_e32 vcc, 0, v40
	v_lshlrev_b32_e32 v40, 16, v49
	v_fma_f32 v43, |v41|, s92, 1.0
	v_cndmask_b32_e32 v46, v42, v44, vcc
	v_fma_f32 v42, |v40|, s92, 1.0
	v_rcp_f32_e32 v42, v42
	v_rcp_f32_e32 v43, v43
	v_mul_f32_e32 v44, v40, v40
	v_mul_f32_e32 v45, v41, v41
	v_mul_f32_e32 v44, 0xbf38aa3b, v44
	v_pk_fma_f32 v[48:49], v[42:43], s[10:11], v[18:19] op_sel_hi:[1,0,0]
	v_mul_f32_e32 v45, 0xbf38aa3b, v45
	v_exp_f32_e32 v44, v44
	v_pk_fma_f32 v[48:49], v[42:43], v[48:49], s[14:15] op_sel_hi:[1,1,0]
	v_exp_f32_e32 v45, v45
	v_pk_fma_f32 v[48:49], v[42:43], v[48:49], s[16:17] op_sel_hi:[1,1,0]
	v_cmp_gt_f32_e32 vcc, 0, v41
	v_pk_fma_f32 v[48:49], v[42:43], v[48:49], s[18:19] op_sel_hi:[1,1,0]
	s_nop 0
	v_pk_mul_f32 v[42:43], v[42:43], v[48:49]
	v_pk_mul_f32 v[42:43], v[44:45], v[42:43]
	v_pk_mul_f32 v[44:45], v[42:43], v[40:41]
	v_pk_fma_f32 v[42:43], v[42:43], v[40:41], v[40:41] neg_lo:[1,0,0] neg_hi:[1,0,0]
	v_lshlrev_b32_e32 v41, 16, v50
	v_cndmask_b32_e32 v43, v43, v45, vcc
	v_cmp_gt_f32_e32 vcc, 0, v40
	v_lshlrev_b32_e32 v40, 16, v51
	v_mul_f32_e32 v45, v40, v40
	v_mul_f32_e32 v45, 0xbf38aa3b, v45
	v_cndmask_b32_e32 v42, v42, v44, vcc
	v_fma_f32 v44, |v40|, s92, 1.0
	v_exp_f32_e32 v48, v45
	v_fma_f32 v45, |v41|, s92, 1.0
	v_rcp_f32_e32 v44, v44
	v_rcp_f32_e32 v45, v45
	v_mul_f32_e32 v49, v41, v41
	v_mul_f32_e32 v49, 0xbf38aa3b, v49
	v_exp_f32_e32 v49, v49
	v_pk_fma_f32 v[50:51], v[44:45], s[10:11], v[18:19] op_sel_hi:[1,0,0]
	v_cmp_gt_f32_e32 vcc, 0, v41
	v_pk_fma_f32 v[50:51], v[44:45], v[50:51], s[14:15] op_sel_hi:[1,1,0]
	s_nop 0
	v_pk_fma_f32 v[50:51], v[44:45], v[50:51], s[16:17] op_sel_hi:[1,1,0]
	s_nop 0
	v_pk_fma_f32 v[50:51], v[44:45], v[50:51], s[18:19] op_sel_hi:[1,1,0]
	v_pk_mul_f32 v[44:45], v[44:45], v[50:51]
	v_pk_mul_f32 v[44:45], v[48:49], v[44:45]
	v_pk_mul_f32 v[48:49], v[44:45], v[40:41]
	v_pk_fma_f32 v[44:45], v[44:45], v[40:41], v[40:41] neg_lo:[1,0,0] neg_hi:[1,0,0]
	v_lshlrev_b32_e32 v41, 16, v52
	v_cndmask_b32_e32 v49, v45, v49, vcc
	v_cmp_gt_f32_e32 vcc, 0, v40
	v_lshlrev_b32_e32 v40, 16, v53
	v_fma_f32 v45, |v41|, s92, 1.0
	v_cndmask_b32_e32 v48, v44, v48, vcc
	v_fma_f32 v44, |v40|, s92, 1.0
	v_rcp_f32_e32 v44, v44
	v_rcp_f32_e32 v45, v45
	v_mul_f32_e32 v50, v40, v40
	v_mul_f32_e32 v51, v41, v41
	v_mul_f32_e32 v50, 0xbf38aa3b, v50
	v_pk_fma_f32 v[52:53], v[44:45], s[10:11], v[18:19] op_sel_hi:[1,0,0]
	v_mul_f32_e32 v51, 0xbf38aa3b, v51
	v_exp_f32_e32 v50, v50
	v_pk_fma_f32 v[52:53], v[44:45], v[52:53], s[14:15] op_sel_hi:[1,1,0]
	v_exp_f32_e32 v51, v51
	v_pk_fma_f32 v[52:53], v[44:45], v[52:53], s[16:17] op_sel_hi:[1,1,0]
	v_cmp_gt_f32_e32 vcc, 0, v41
	v_pk_fma_f32 v[52:53], v[44:45], v[52:53], s[18:19] op_sel_hi:[1,1,0]
	s_nop 0
	v_pk_mul_f32 v[44:45], v[44:45], v[52:53]
	v_pk_mul_f32 v[44:45], v[50:51], v[44:45]
	v_pk_mul_f32 v[50:51], v[44:45], v[40:41]
	v_pk_fma_f32 v[44:45], v[44:45], v[40:41], v[40:41] neg_lo:[1,0,0] neg_hi:[1,0,0]
	v_lshlrev_b32_e32 v41, 16, v71
	v_cndmask_b32_e32 v51, v45, v51, vcc
	v_cmp_gt_f32_e32 vcc, 0, v40
	v_lshlrev_b32_e32 v40, 16, v72
	v_mul_f32_e32 v45, v40, v40
	v_mul_f32_e32 v45, 0xbf38aa3b, v45
	v_cndmask_b32_e32 v50, v44, v50, vcc
	v_fma_f32 v44, |v40|, s92, 1.0
	v_exp_f32_e32 v52, v45
	v_fma_f32 v45, |v41|, s92, 1.0
	v_rcp_f32_e32 v44, v44
	v_rcp_f32_e32 v45, v45
	v_mul_f32_e32 v53, v41, v41
	v_mul_f32_e32 v53, 0xbf38aa3b, v53
	v_exp_f32_e32 v53, v53
	v_pk_fma_f32 v[72:73], v[44:45], s[10:11], v[18:19] op_sel_hi:[1,0,0]
	v_cmp_gt_f32_e32 vcc, 0, v41
	v_pk_fma_f32 v[72:73], v[44:45], v[72:73], s[14:15] op_sel_hi:[1,1,0]
	s_nop 0
	v_pk_fma_f32 v[72:73], v[44:45], v[72:73], s[16:17] op_sel_hi:[1,1,0]
	s_nop 0
	v_pk_fma_f32 v[72:73], v[44:45], v[72:73], s[18:19] op_sel_hi:[1,1,0]
	v_pk_mul_f32 v[44:45], v[44:45], v[72:73]
	v_pk_mul_f32 v[44:45], v[52:53], v[44:45]
	v_pk_mul_f32 v[52:53], v[44:45], v[40:41]
	v_pk_fma_f32 v[44:45], v[44:45], v[40:41], v[40:41] neg_lo:[1,0,0] neg_hi:[1,0,0]
	v_lshlrev_b32_e32 v41, 16, v74
	v_cndmask_b32_e32 v73, v45, v53, vcc
	v_cmp_gt_f32_e32 vcc, 0, v40
	v_lshlrev_b32_e32 v40, 16, v75
	v_fma_f32 v45, |v41|, s92, 1.0
	v_cndmask_b32_e32 v72, v44, v52, vcc
	v_fma_f32 v44, |v40|, s92, 1.0
	v_rcp_f32_e32 v44, v44
	v_rcp_f32_e32 v45, v45
	v_mul_f32_e32 v52, v40, v40
	v_mul_f32_e32 v53, v41, v41
	v_mul_f32_e32 v52, 0xbf38aa3b, v52
	v_pk_fma_f32 v[74:75], v[44:45], s[10:11], v[18:19] op_sel_hi:[1,0,0]
	v_mul_f32_e32 v53, 0xbf38aa3b, v53
	v_exp_f32_e32 v52, v52
	v_pk_fma_f32 v[74:75], v[44:45], v[74:75], s[14:15] op_sel_hi:[1,1,0]
	v_exp_f32_e32 v53, v53
	v_pk_fma_f32 v[74:75], v[44:45], v[74:75], s[16:17] op_sel_hi:[1,1,0]
	v_cmp_gt_f32_e32 vcc, 0, v41
	v_pk_fma_f32 v[74:75], v[44:45], v[74:75], s[18:19] op_sel_hi:[1,1,0]
	s_nop 0
	v_pk_mul_f32 v[44:45], v[44:45], v[74:75]
	v_pk_mul_f32 v[44:45], v[52:53], v[44:45]
	v_pk_mul_f32 v[52:53], v[44:45], v[40:41]
	v_pk_fma_f32 v[44:45], v[44:45], v[40:41], v[40:41] neg_lo:[1,0,0] neg_hi:[1,0,0]
	v_lshlrev_b32_e32 v41, 16, v76
	v_cndmask_b32_e32 v53, v45, v53, vcc
	v_cmp_gt_f32_e32 vcc, 0, v40
	v_lshlrev_b32_e32 v40, 16, v77
	v_mul_f32_e32 v45, v40, v40
	v_mul_f32_e32 v45, 0xbf38aa3b, v45
	v_cndmask_b32_e32 v52, v44, v52, vcc
	v_fma_f32 v44, |v40|, s92, 1.0
	v_exp_f32_e32 v74, v45
	v_fma_f32 v45, |v41|, s92, 1.0
	v_rcp_f32_e32 v44, v44
	v_rcp_f32_e32 v45, v45
	v_mul_f32_e32 v71, v41, v41
	v_mul_f32_e32 v71, 0xbf38aa3b, v71
	v_exp_f32_e32 v75, v71
	v_pk_fma_f32 v[76:77], v[44:45], s[10:11], v[18:19] op_sel_hi:[1,0,0]
	v_cmp_gt_f32_e32 vcc, 0, v41
	v_pk_fma_f32 v[76:77], v[44:45], v[76:77], s[14:15] op_sel_hi:[1,1,0]
	s_nop 0
	v_pk_fma_f32 v[76:77], v[44:45], v[76:77], s[16:17] op_sel_hi:[1,1,0]
	s_nop 0
	v_pk_fma_f32 v[76:77], v[44:45], v[76:77], s[18:19] op_sel_hi:[1,1,0]
	v_pk_mul_f32 v[44:45], v[44:45], v[76:77]
	v_mov_b32_e32 v76, v43
	v_pk_mul_f32 v[44:45], v[74:75], v[44:45]
	v_mov_b32_e32 v77, v53
	v_pk_mul_f32 v[74:75], v[44:45], v[40:41]
	v_pk_fma_f32 v[44:45], v[44:45], v[40:41], v[40:41] neg_lo:[1,0,0] neg_hi:[1,0,0]
	v_mov_b32_e32 v41, v50
	v_cndmask_b32_e32 v75, v45, v75, vcc
	v_cmp_gt_f32_e32 vcc, 0, v40
	v_mov_b32_e32 v40, v38
	v_mov_b32_e32 v45, v52
	v_cndmask_b32_e32 v74, v44, v74, vcc
	v_mov_b32_e32 v44, v42
	v_pk_add_f32 v[40:41], v[40:41], v[44:45]
	v_mov_b32_e32 v44, v39
	v_add_f32_e32 v40, v40, v41
	v_mov_b32_e32 v45, v51
	s_nop 0
	v_add_f32_dpp v40, v40, v40 quad_perm:[1,0,3,2] row_mask:0xf bank_mask:0xf bound_ctrl:1
	v_pk_add_f32 v[44:45], v[44:45], v[76:77]
	v_mov_b32_e32 v76, v49
	v_add_f32_dpp v40, v40, v40 quad_perm:[2,3,0,1] row_mask:0xf bank_mask:0xf bound_ctrl:1
	v_mov_b32_e32 v77, v75
	s_nop 0
	v_add_f32_dpp v40, v40, v40 row_half_mirror row_mask:0xf bank_mask:0xf bound_ctrl:1
	s_nop 1
	v_add_f32_dpp v40, v40, v40 row_mirror row_mask:0xf bank_mask:0xf bound_ctrl:1
	s_nop 1
	v_add_f32_dpp v40, v40, v40 row_bcast:15 row_mask:0xa bank_mask:0xf
	s_nop 1
	v_add_f32_dpp v40, v40, v40 row_bcast:31 row_mask:0xc bank_mask:0xf
	v_add_f32_e32 v41, v44, v45
	v_readlane_b32 s6, v40, 63
	s_nop 0
	v_add_f32_dpp v41, v41, v41 quad_perm:[1,0,3,2] row_mask:0xf bank_mask:0xf bound_ctrl:1
	s_xor_b32 s6, s6, 0x80000000
	s_nop 0
	v_add_f32_dpp v41, v41, v41 quad_perm:[2,3,0,1] row_mask:0xf bank_mask:0xf bound_ctrl:1
	s_nop 1
	v_add_f32_dpp v41, v41, v41 row_half_mirror row_mask:0xf bank_mask:0xf bound_ctrl:1
	s_nop 1
	v_add_f32_dpp v41, v41, v41 row_mirror row_mask:0xf bank_mask:0xf bound_ctrl:1
	s_nop 1
	v_add_f32_dpp v41, v41, v41 row_bcast:15 row_mask:0xa bank_mask:0xf
	s_nop 1
	v_add_f32_dpp v41, v41, v41 row_bcast:31 row_mask:0xc bank_mask:0xf
	s_nop 0
	v_readlane_b32 s7, v41, 63
	s_xor_b32 s7, s7, 0x80000000
	s_nop 0
	v_pk_fma_f32 v[40:41], s[6:7], v[20:21], v[38:39] op_sel_hi:[1,0,1]
	v_pk_fma_f32 v[44:45], s[6:7], v[20:21], v[42:43] op_sel_hi:[1,0,1]
	v_pk_fma_f32 v[42:43], s[6:7], v[20:21], v[50:51] op_sel_hi:[1,0,1]
	v_pk_fma_f32 v[38:39], s[6:7], v[20:21], v[52:53] op_sel_hi:[1,0,1]
	v_mov_b32_e32 v50, v46
	v_mov_b32_e32 v51, v72
	v_mov_b32_e32 v52, v48
	v_mov_b32_e32 v53, v74
	v_pk_add_f32 v[50:51], v[50:51], v[52:53]
	v_mov_b32_e32 v52, v47
	v_add_f32_e32 v50, v50, v51
	v_mov_b32_e32 v53, v73
	s_nop 0
	v_add_f32_dpp v50, v50, v50 quad_perm:[1,0,3,2] row_mask:0xf bank_mask:0xf bound_ctrl:1
	v_pk_add_f32 v[52:53], v[52:53], v[76:77]
	s_nop 0
	v_add_f32_dpp v50, v50, v50 quad_perm:[2,3,0,1] row_mask:0xf bank_mask:0xf bound_ctrl:1
	s_nop 1
	v_add_f32_dpp v50, v50, v50 row_half_mirror row_mask:0xf bank_mask:0xf bound_ctrl:1
	s_nop 1
	v_add_f32_dpp v50, v50, v50 row_mirror row_mask:0xf bank_mask:0xf bound_ctrl:1
	s_nop 1
	v_add_f32_dpp v50, v50, v50 row_bcast:15 row_mask:0xa bank_mask:0xf
	s_nop 1
	v_add_f32_dpp v50, v50, v50 row_bcast:31 row_mask:0xc bank_mask:0xf
	v_add_f32_e32 v51, v52, v53
	v_readlane_b32 s6, v50, 63
	s_nop 0
	v_add_f32_dpp v51, v51, v51 quad_perm:[1,0,3,2] row_mask:0xf bank_mask:0xf bound_ctrl:1
	s_xor_b32 s6, s6, 0x80000000
	s_nop 0
	v_add_f32_dpp v51, v51, v51 quad_perm:[2,3,0,1] row_mask:0xf bank_mask:0xf bound_ctrl:1
	s_nop 1
	v_add_f32_dpp v51, v51, v51 row_half_mirror row_mask:0xf bank_mask:0xf bound_ctrl:1
	s_nop 1
	v_add_f32_dpp v51, v51, v51 row_mirror row_mask:0xf bank_mask:0xf bound_ctrl:1
	s_nop 1
	v_add_f32_dpp v51, v51, v51 row_bcast:15 row_mask:0xa bank_mask:0xf
	s_nop 1
	v_add_f32_dpp v51, v51, v51 row_bcast:31 row_mask:0xc bank_mask:0xf
	s_nop 0
	v_readlane_b32 s7, v51, 63
	s_xor_b32 s7, s7, 0x80000000
	s_nop 0
	v_pk_fma_f32 v[50:51], s[6:7], v[20:21], v[48:49] op_sel_hi:[1,0,1]
	v_pk_fma_f32 v[48:49], s[6:7], v[20:21], v[72:73] op_sel_hi:[1,0,1]
	v_lshlrev_b32_e32 v73, 16, v54
	v_lshlrev_b32_e32 v72, 16, v55
	v_fma_f32 v54, |v72|, s92, 1.0
	v_fma_f32 v55, |v73|, s92, 1.0
	v_rcp_f32_e32 v54, v54
	v_rcp_f32_e32 v55, v55
	v_mul_f32_e32 v71, v72, v72
	v_mul_f32_e32 v71, 0xbf38aa3b, v71
	v_pk_fma_f32 v[52:53], s[6:7], v[20:21], v[46:47] op_sel_hi:[1,0,1]
	v_pk_fma_f32 v[46:47], s[6:7], v[20:21], v[74:75] op_sel_hi:[1,0,1]
	v_exp_f32_e32 v74, v71
	v_mul_f32_e32 v71, v73, v73
	v_pk_fma_f32 v[76:77], v[54:55], s[10:11], v[18:19] op_sel_hi:[1,0,0]
	v_mul_f32_e32 v71, 0xbf38aa3b, v71
	v_pk_fma_f32 v[76:77], v[54:55], v[76:77], s[14:15] op_sel_hi:[1,1,0]
	v_exp_f32_e32 v75, v71
	v_pk_fma_f32 v[76:77], v[54:55], v[76:77], s[16:17] op_sel_hi:[1,1,0]
	v_cmp_gt_f32_e32 vcc, 0, v73
	v_pk_fma_f32 v[76:77], v[54:55], v[76:77], s[18:19] op_sel_hi:[1,1,0]
	s_mov_b32 s6, 0xbe11a98e
	v_pk_mul_f32 v[54:55], v[54:55], v[76:77]
	v_pk_mul_f32 v[54:55], v[74:75], v[54:55]
	v_pk_mul_f32 v[74:75], v[54:55], v[72:73]
	v_pk_fma_f32 v[54:55], v[54:55], v[72:73], v[72:73] neg_lo:[1,0,0] neg_hi:[1,0,0]
	v_lshlrev_b32_e32 v73, 16, v60
	v_cndmask_b32_e32 v55, v55, v75, vcc
	v_cmp_gt_f32_e32 vcc, 0, v72
	v_lshlrev_b32_e32 v72, 16, v61
	v_mul_f32_e32 v61, v72, v72
	v_mul_f32_e32 v61, 0xbf38aa3b, v61
	v_cndmask_b32_e32 v54, v54, v74, vcc
	v_fma_f32 v60, |v72|, s92, 1.0
	v_exp_f32_e32 v74, v61
	v_fma_f32 v61, |v73|, s92, 1.0
	v_rcp_f32_e32 v60, v60
	v_rcp_f32_e32 v61, v61
	v_mul_f32_e32 v71, v73, v73
	v_mul_f32_e32 v71, 0xbf38aa3b, v71
	v_exp_f32_e32 v75, v71
	v_pk_fma_f32 v[76:77], v[60:61], s[10:11], v[18:19] op_sel_hi:[1,0,0]
	v_cmp_gt_f32_e32 vcc, 0, v73
	v_pk_fma_f32 v[76:77], v[60:61], v[76:77], s[14:15] op_sel_hi:[1,1,0]
	s_nop 0
	v_pk_fma_f32 v[76:77], v[60:61], v[76:77], s[16:17] op_sel_hi:[1,1,0]
	s_nop 0
	v_pk_fma_f32 v[76:77], v[60:61], v[76:77], s[18:19] op_sel_hi:[1,1,0]
	v_pk_mul_f32 v[60:61], v[60:61], v[76:77]
	v_pk_mul_f32 v[60:61], v[74:75], v[60:61]
	v_pk_mul_f32 v[74:75], v[60:61], v[72:73]
	v_pk_fma_f32 v[60:61], v[60:61], v[72:73], v[72:73] neg_lo:[1,0,0] neg_hi:[1,0,0]
	v_lshlrev_b32_e32 v73, 16, v56
	v_cndmask_b32_e32 v61, v61, v75, vcc
	v_cmp_gt_f32_e32 vcc, 0, v72
	v_lshlrev_b32_e32 v72, 16, v57
	v_fma_f32 v56, |v72|, s92, 1.0
	v_fma_f32 v57, |v73|, s92, 1.0
	v_rcp_f32_e32 v56, v56
	v_rcp_f32_e32 v57, v57
	v_mul_f32_e32 v71, v72, v72
	v_mul_f32_e32 v71, 0xbf38aa3b, v71
	v_cndmask_b32_e32 v60, v60, v74, vcc
	v_exp_f32_e32 v74, v71
	v_mul_f32_e32 v71, v73, v73
	v_pk_fma_f32 v[76:77], v[56:57], s[10:11], v[18:19] op_sel_hi:[1,0,0]
	v_mul_f32_e32 v71, 0xbf38aa3b, v71
	v_pk_fma_f32 v[76:77], v[56:57], v[76:77], s[14:15] op_sel_hi:[1,1,0]
	v_exp_f32_e32 v75, v71
	v_pk_fma_f32 v[76:77], v[56:57], v[76:77], s[16:17] op_sel_hi:[1,1,0]
	v_cmp_gt_f32_e32 vcc, 0, v73
	v_pk_fma_f32 v[76:77], v[56:57], v[76:77], s[18:19] op_sel_hi:[1,1,0]
	s_nop 0
	v_pk_mul_f32 v[56:57], v[56:57], v[76:77]
	v_pk_mul_f32 v[56:57], v[74:75], v[56:57]
	v_pk_mul_f32 v[74:75], v[56:57], v[72:73]
	v_pk_fma_f32 v[56:57], v[56:57], v[72:73], v[72:73] neg_lo:[1,0,0] neg_hi:[1,0,0]
	v_lshlrev_b32_e32 v73, 16, v62
	v_cndmask_b32_e32 v57, v57, v75, vcc
	v_cmp_gt_f32_e32 vcc, 0, v72
	v_lshlrev_b32_e32 v72, 16, v63
	v_mul_f32_e32 v63, v72, v72
	v_mul_f32_e32 v63, 0xbf38aa3b, v63
	v_cndmask_b32_e32 v56, v56, v74, vcc
	v_fma_f32 v62, |v72|, s92, 1.0
	v_exp_f32_e32 v74, v63
	v_fma_f32 v63, |v73|, s92, 1.0
	v_rcp_f32_e32 v62, v62
	v_rcp_f32_e32 v63, v63
	v_mul_f32_e32 v71, v73, v73
	v_mul_f32_e32 v71, 0xbf38aa3b, v71
	v_exp_f32_e32 v75, v71
	v_pk_fma_f32 v[76:77], v[62:63], s[10:11], v[18:19] op_sel_hi:[1,0,0]
	v_cmp_gt_f32_e32 vcc, 0, v73
	v_pk_fma_f32 v[76:77], v[62:63], v[76:77], s[14:15] op_sel_hi:[1,1,0]
	v_lshlrev_b32_e32 v71, 16, v69
	v_pk_fma_f32 v[76:77], v[62:63], v[76:77], s[16:17] op_sel_hi:[1,1,0]
	v_fma_f32 v69, |v70|, s92, 1.0
	v_pk_fma_f32 v[76:77], v[62:63], v[76:77], s[18:19] op_sel_hi:[1,1,0]
	v_pk_mul_f32 v[62:63], v[62:63], v[76:77]
	v_pk_mul_f32 v[62:63], v[74:75], v[62:63]
	v_pk_mul_f32 v[74:75], v[62:63], v[72:73]
	v_pk_fma_f32 v[62:63], v[62:63], v[72:73], v[72:73] neg_lo:[1,0,0] neg_hi:[1,0,0]
	s_nop 0
	v_cndmask_b32_e32 v63, v63, v75, vcc
	v_cmp_gt_f32_e32 vcc, 0, v72
	v_rcp_f32_e32 v72, v69
	v_fma_f32 v69, |v71|, s92, 1.0
	v_rcp_f32_e32 v73, v69
	v_mul_f32_e32 v69, v70, v70
	v_mul_f32_e32 v69, 0xbf38aa3b, v69
	v_cndmask_b32_e32 v62, v62, v74, vcc
	v_exp_f32_e32 v74, v69
	v_mul_f32_e32 v69, v71, v71
	v_pk_fma_f32 v[76:77], v[72:73], s[10:11], v[18:19] op_sel_hi:[1,0,0]
	v_mul_f32_e32 v69, 0xbf38aa3b, v69
	v_pk_fma_f32 v[76:77], v[72:73], v[76:77], s[14:15] op_sel_hi:[1,1,0]
	v_exp_f32_e32 v75, v69
	v_pk_fma_f32 v[76:77], v[72:73], v[76:77], s[16:17] op_sel_hi:[1,1,0]
	v_cmp_gt_f32_e32 vcc, 0, v71
	v_pk_fma_f32 v[76:77], v[72:73], v[76:77], s[18:19] op_sel_hi:[1,1,0]
	v_lshlrev_b32_e32 v69, 16, v67
	v_pk_mul_f32 v[72:73], v[72:73], v[76:77]
	v_fma_f32 v67, |v68|, s92, 1.0
	v_pk_mul_f32 v[72:73], v[74:75], v[72:73]
	v_pk_mul_f32 v[74:75], v[72:73], v[70:71]
	v_pk_fma_f32 v[72:73], v[72:73], v[70:71], v[70:71] neg_lo:[1,0,0] neg_hi:[1,0,0]
	s_nop 0
	v_cndmask_b32_e32 v71, v73, v75, vcc
	v_cmp_gt_f32_e32 vcc, 0, v70
	s_nop 1
	v_cndmask_b32_e32 v70, v72, v74, vcc
	v_rcp_f32_e32 v72, v67
	v_mul_f32_e32 v67, v68, v68
	v_mul_f32_e32 v67, 0xbf38aa3b, v67
	v_exp_f32_e32 v74, v67
	v_fma_f32 v67, |v69|, s92, 1.0
	v_rcp_f32_e32 v73, v67
	v_mul_f32_e32 v67, v69, v69
	v_mul_f32_e32 v67, 0xbf38aa3b, v67
	v_exp_f32_e32 v75, v67
	v_pk_fma_f32 v[76:77], v[72:73], s[10:11], v[18:19] op_sel_hi:[1,0,0]
	v_cmp_gt_f32_e32 vcc, 0, v69
	v_pk_fma_f32 v[76:77], v[72:73], v[76:77], s[14:15] op_sel_hi:[1,1,0]
	s_nop 0
	v_pk_fma_f32 v[76:77], v[72:73], v[76:77], s[16:17] op_sel_hi:[1,1,0]
	s_nop 0
	v_pk_fma_f32 v[76:77], v[72:73], v[76:77], s[18:19] op_sel_hi:[1,1,0]
	v_pk_mul_f32 v[72:73], v[72:73], v[76:77]
	v_pk_mul_f32 v[72:73], v[74:75], v[72:73]
	v_pk_mul_f32 v[74:75], v[72:73], v[68:69]
	v_pk_fma_f32 v[72:73], v[72:73], v[68:69], v[68:69] neg_lo:[1,0,0] neg_hi:[1,0,0]
	s_nop 0
	v_cndmask_b32_e32 v69, v73, v75, vcc
	v_cmp_gt_f32_e32 vcc, 0, v68
	v_lshlrev_b32_e32 v73, 16, v64
	s_nop 0
	v_cndmask_b32_e32 v68, v72, v74, vcc
	s_waitcnt vmcnt(0)
	v_lshlrev_b32_e32 v72, 16, v65
	v_fma_f32 v64, |v72|, s92, 1.0
	v_fma_f32 v65, |v73|, s92, 1.0
	v_rcp_f32_e32 v64, v64
	v_rcp_f32_e32 v65, v65
	v_mul_f32_e32 v67, v72, v72
	v_mul_f32_e32 v67, 0xbf38aa3b, v67
	v_exp_f32_e32 v74, v67
	v_mul_f32_e32 v67, v73, v73
	v_pk_fma_f32 v[76:77], v[64:65], s[10:11], v[18:19] op_sel_hi:[1,0,0]
	v_mul_f32_e32 v67, 0xbf38aa3b, v67
	v_pk_fma_f32 v[76:77], v[64:65], v[76:77], s[14:15] op_sel_hi:[1,1,0]
	v_exp_f32_e32 v75, v67
	v_pk_fma_f32 v[76:77], v[64:65], v[76:77], s[16:17] op_sel_hi:[1,1,0]
	v_cmp_gt_f32_e32 vcc, 0, v73
	v_pk_fma_f32 v[76:77], v[64:65], v[76:77], s[18:19] op_sel_hi:[1,1,0]
	s_nop 0
	v_pk_mul_f32 v[64:65], v[64:65], v[76:77]
	v_pk_mul_f32 v[64:65], v[74:75], v[64:65]
	v_pk_mul_f32 v[74:75], v[64:65], v[72:73]
	v_pk_fma_f32 v[64:65], v[64:65], v[72:73], v[72:73] neg_lo:[1,0,0] neg_hi:[1,0,0]
	v_lshlrev_b32_e32 v73, 16, v58
	v_cndmask_b32_e32 v65, v65, v75, vcc
	v_cmp_gt_f32_e32 vcc, 0, v72
	v_lshlrev_b32_e32 v72, 16, v59
	v_mul_f32_e32 v59, v72, v72
	v_mul_f32_e32 v59, 0xbf38aa3b, v59
	v_cndmask_b32_e32 v64, v64, v74, vcc
	v_fma_f32 v58, |v72|, s92, 1.0
	v_exp_f32_e32 v74, v59
	v_fma_f32 v59, |v73|, s92, 1.0
	v_rcp_f32_e32 v58, v58
	v_rcp_f32_e32 v59, v59
	v_mul_f32_e32 v67, v73, v73
	v_mul_f32_e32 v67, 0xbf38aa3b, v67
	v_exp_f32_e32 v75, v67
	v_pk_fma_f32 v[18:19], v[58:59], s[10:11], v[18:19] op_sel_hi:[1,0,0]
	v_cmp_gt_f32_e32 vcc, 0, v73
	v_pk_fma_f32 v[18:19], v[58:59], v[18:19], s[14:15] op_sel_hi:[1,1,0]
	v_mov_b32_e32 v67, v131
	v_pk_fma_f32 v[18:19], v[58:59], v[18:19], s[6:7] op_sel_hi:[1,1,0]
	s_nop 0
	v_pk_fma_f32 v[18:19], v[58:59], v[18:19], s[8:9] op_sel_hi:[1,1,0]
	v_readlane_b32 s9, v253, 54
	v_pk_mul_f32 v[18:19], v[58:59], v[18:19]
	s_nop 0
	v_pk_mul_f32 v[18:19], v[74:75], v[18:19]
	v_mov_b32_e32 v74, v57
	v_pk_mul_f32 v[58:59], v[18:19], v[72:73]
	v_pk_fma_f32 v[18:19], v[18:19], v[72:73], v[72:73] neg_lo:[1,0,0] neg_hi:[1,0,0]
	v_mov_b32_e32 v75, v65
	v_cndmask_b32_e32 v73, v19, v59, vcc
	v_cmp_gt_f32_e32 vcc, 0, v72
	v_mov_b32_e32 v19, v70
	v_mov_b32_e32 v59, v64
	v_cndmask_b32_e32 v72, v18, v58, vcc
	v_mov_b32_e32 v18, v54
	v_mov_b32_e32 v58, v56
	v_pk_add_f32 v[18:19], v[18:19], v[58:59]
	v_mov_b32_e32 v58, v55
	v_add_f32_e32 v18, v18, v19
	v_mov_b32_e32 v59, v71
	s_nop 0
	v_add_f32_dpp v18, v18, v18 quad_perm:[1,0,3,2] row_mask:0xf bank_mask:0xf bound_ctrl:1
	v_pk_add_f32 v[58:59], v[58:59], v[74:75]
	v_mov_b32_e32 v74, v63
	v_add_f32_dpp v18, v18, v18 quad_perm:[2,3,0,1] row_mask:0xf bank_mask:0xf bound_ctrl:1
	v_mov_b32_e32 v75, v73
	s_nop 0
	v_add_f32_dpp v18, v18, v18 row_half_mirror row_mask:0xf bank_mask:0xf bound_ctrl:1
	s_nop 1
	v_add_f32_dpp v18, v18, v18 row_mirror row_mask:0xf bank_mask:0xf bound_ctrl:1
	s_nop 1
	v_add_f32_dpp v18, v18, v18 row_bcast:15 row_mask:0xa bank_mask:0xf
	s_nop 1
	v_add_f32_dpp v18, v18, v18 row_bcast:31 row_mask:0xc bank_mask:0xf
	v_add_f32_e32 v19, v58, v59
	v_readlane_b32 s6, v18, 63
	s_nop 0
	v_add_f32_dpp v19, v19, v19 quad_perm:[1,0,3,2] row_mask:0xf bank_mask:0xf bound_ctrl:1
	s_xor_b32 s6, s6, 0x80000000
	s_nop 0
	v_add_f32_dpp v19, v19, v19 quad_perm:[2,3,0,1] row_mask:0xf bank_mask:0xf bound_ctrl:1
	s_nop 1
	v_add_f32_dpp v19, v19, v19 row_half_mirror row_mask:0xf bank_mask:0xf bound_ctrl:1
	s_nop 1
	v_add_f32_dpp v19, v19, v19 row_mirror row_mask:0xf bank_mask:0xf bound_ctrl:1
	s_nop 1
	v_add_f32_dpp v19, v19, v19 row_bcast:15 row_mask:0xa bank_mask:0xf
	s_nop 1
	v_add_f32_dpp v19, v19, v19 row_bcast:31 row_mask:0xc bank_mask:0xf
	s_nop 0
	v_readlane_b32 s7, v19, 63
	s_xor_b32 s7, s7, 0x80000000
	s_nop 0
	v_pk_fma_f32 v[58:59], s[6:7], v[20:21], v[54:55] op_sel_hi:[1,0,1]
	v_pk_fma_f32 v[54:55], s[6:7], v[20:21], v[70:71] op_sel_hi:[1,0,1]
	v_pk_fma_f32 v[18:19], s[6:7], v[20:21], v[64:65] op_sel_hi:[1,0,1]
	v_mov_b32_e32 v64, v60
	v_mov_b32_e32 v65, v68
	v_mov_b32_e32 v70, v62
	v_mov_b32_e32 v71, v72
	v_pk_add_f32 v[64:65], v[64:65], v[70:71]
	v_mov_b32_e32 v70, v61
	v_add_f32_e32 v64, v64, v65
	v_mov_b32_e32 v71, v69
	s_nop 0
	v_add_f32_dpp v64, v64, v64 quad_perm:[1,0,3,2] row_mask:0xf bank_mask:0xf bound_ctrl:1
	v_pk_add_f32 v[70:71], v[70:71], v[74:75]
	v_pk_fma_f32 v[56:57], s[6:7], v[20:21], v[56:57] op_sel_hi:[1,0,1]
	v_add_f32_dpp v64, v64, v64 quad_perm:[2,3,0,1] row_mask:0xf bank_mask:0xf bound_ctrl:1
	s_nop 1
	v_add_f32_dpp v64, v64, v64 row_half_mirror row_mask:0xf bank_mask:0xf bound_ctrl:1
	s_nop 1
	v_add_f32_dpp v64, v64, v64 row_mirror row_mask:0xf bank_mask:0xf bound_ctrl:1
	s_nop 1
	v_add_f32_dpp v64, v64, v64 row_bcast:15 row_mask:0xa bank_mask:0xf
	s_nop 1
	v_add_f32_dpp v64, v64, v64 row_bcast:31 row_mask:0xc bank_mask:0xf
	v_add_f32_e32 v65, v70, v71
	v_readlane_b32 s6, v64, 63
	s_xor_b32 s6, s6, 0x80000000
	v_add_f32_dpp v65, v65, v65 quad_perm:[1,0,3,2] row_mask:0xf bank_mask:0xf bound_ctrl:1
	v_mov_b32_e32 v70, v14
	v_mov_b32_e32 v71, v10
	v_add_f32_dpp v65, v65, v65 quad_perm:[2,3,0,1] row_mask:0xf bank_mask:0xf bound_ctrl:1
	v_pk_mul_f32 v[70:71], v[70:71], v[70:71]
	s_nop 0
	v_add_f32_dpp v65, v65, v65 row_half_mirror row_mask:0xf bank_mask:0xf bound_ctrl:1
	s_nop 1
	v_add_f32_dpp v65, v65, v65 row_mirror row_mask:0xf bank_mask:0xf bound_ctrl:1
	s_nop 1
	v_mov_b32_dpp v67, v65 row_bcast:15 row_mask:0xa bank_mask:0xf
	v_add_f32_e32 v65, v65, v67
	s_nop 1
	v_add_f32_dpp v65, v65, v65 row_bcast:31 row_mask:0xc bank_mask:0xf
	s_nop 0
	v_readlane_b32 s7, v65, 63
	s_xor_b32 s7, s7, 0x80000000
	s_nop 0
	v_pk_fma_f32 v[64:65], s[6:7], v[20:21], v[60:61] op_sel_hi:[1,0,1]
	v_pk_fma_f32 v[60:61], s[6:7], v[20:21], v[68:69] op_sel_hi:[1,0,1]
	v_mov_b32_e32 v68, v16
	v_mov_b32_e32 v69, v12
	v_pk_fma_f32 v[68:69], v[68:69], v[68:69], v[70:71]
	v_pk_fma_f32 v[62:63], s[6:7], v[20:21], v[62:63] op_sel_hi:[1,0,1]
	v_add_f32_e32 v68, v68, v69
	v_pk_fma_f32 v[20:21], s[6:7], v[20:21], v[72:73] op_sel_hi:[1,0,1]
	s_nop 0
	v_add_f32_dpp v68, v68, v68 quad_perm:[1,0,3,2] row_mask:0xf bank_mask:0xf bound_ctrl:1
	s_lshl_b32 s6, s34, 5
	s_add_i32 s7, s6, 0
	v_add_f32_dpp v68, v68, v68 quad_perm:[2,3,0,1] row_mask:0xf bank_mask:0xf bound_ctrl:1
	v_mov_b32_e32 v70, v15
	v_mov_b32_e32 v71, v11
	v_add_f32_dpp v68, v68, v68 row_half_mirror row_mask:0xf bank_mask:0xf bound_ctrl:1
	v_mov_b32_e32 v67, s7
	v_pk_mul_f32 v[70:71], v[70:71], v[70:71]
	v_add_f32_dpp v68, v68, v68 row_mirror row_mask:0xf bank_mask:0xf bound_ctrl:1
	s_nop 1
	v_add_f32_dpp v68, v68, v68 row_bcast:15 row_mask:0xa bank_mask:0xf
	s_nop 1
	v_add_f32_dpp v68, v68, v68 row_bcast:31 row_mask:0xc bank_mask:0xf
	v_mov_b32_e32 v69, v13
	v_readlane_b32 s7, v68, 63
	v_mov_b32_e32 v68, v17
	v_pk_fma_f32 v[68:69], v[68:69], v[68:69], v[70:71]
	v_mov_b32_e32 v70, v8
	v_add_f32_e32 v68, v68, v69
	v_mov_b32_e32 v71, v2
	s_nop 0
	v_add_f32_dpp v68, v68, v68 quad_perm:[1,0,3,2] row_mask:0xf bank_mask:0xf bound_ctrl:1
	v_fma_f32 v73, s7, v235, v225
	v_pk_mul_f32 v[70:71], v[70:71], v[70:71]
	v_add_f32_dpp v68, v68, v68 quad_perm:[2,3,0,1] row_mask:0xf bank_mask:0xf bound_ctrl:1
	v_rsq_f32_e32 v84, v73
	s_nop 0
	v_add_f32_dpp v68, v68, v68 row_half_mirror row_mask:0xf bank_mask:0xf bound_ctrl:1
	s_nop 1
	v_add_f32_dpp v68, v68, v68 row_mirror row_mask:0xf bank_mask:0xf bound_ctrl:1
	s_nop 1
	v_add_f32_dpp v68, v68, v68 row_bcast:15 row_mask:0xa bank_mask:0xf
	s_nop 1
	v_add_f32_dpp v68, v68, v68 row_bcast:31 row_mask:0xc bank_mask:0xf
	v_mov_b32_e32 v69, v6
	v_readlane_b32 s7, v68, 63
	v_mov_b32_e32 v68, v4
	v_pk_fma_f32 v[68:69], v[68:69], v[68:69], v[70:71]
	v_mov_b32_e32 v70, v9
	v_add_f32_e32 v68, v68, v69
	v_mov_b32_e32 v71, v3
	s_nop 0
	v_add_f32_dpp v68, v68, v68 quad_perm:[1,0,3,2] row_mask:0xf bank_mask:0xf bound_ctrl:1
	v_fma_f32 v75, s7, v235, v225
	v_pk_mul_f32 v[70:71], v[70:71], v[70:71]
	v_add_f32_dpp v68, v68, v68 quad_perm:[2,3,0,1] row_mask:0xf bank_mask:0xf bound_ctrl:1
	v_rsq_f32_e32 v85, v75
	s_nop 0
	v_add_f32_dpp v68, v68, v68 row_half_mirror row_mask:0xf bank_mask:0xf bound_ctrl:1
	v_pk_mul_f32 v[16:17], v[16:17], v[84:85]
	s_nop 0
	v_add_f32_dpp v68, v68, v68 row_mirror row_mask:0xf bank_mask:0xf bound_ctrl:1
	s_nop 1
	v_add_f32_dpp v68, v68, v68 row_bcast:15 row_mask:0xa bank_mask:0xf
	s_nop 1
	v_add_f32_dpp v68, v68, v68 row_bcast:31 row_mask:0xc bank_mask:0xf
	v_mov_b32_e32 v69, v7
	v_readlane_b32 s7, v68, 63
	v_mov_b32_e32 v68, v5
	v_pk_fma_f32 v[68:69], v[68:69], v[68:69], v[70:71]
	v_mov_b32_e32 v70, v34
	v_add_f32_e32 v68, v68, v69
	v_mov_b32_e32 v71, v30
	s_nop 0
	v_add_f32_dpp v68, v68, v68 quad_perm:[1,0,3,2] row_mask:0xf bank_mask:0xf bound_ctrl:1
	v_fma_f32 v77, s7, v235, v225
	v_pk_mul_f32 v[70:71], v[70:71], v[70:71]
	v_add_f32_dpp v68, v68, v68 quad_perm:[2,3,0,1] row_mask:0xf bank_mask:0xf bound_ctrl:1
	v_rsq_f32_e32 v86, v77
	s_nop 0
	v_add_f32_dpp v68, v68, v68 row_half_mirror row_mask:0xf bank_mask:0xf bound_ctrl:1
	s_nop 1
	v_add_f32_dpp v68, v68, v68 row_mirror row_mask:0xf bank_mask:0xf bound_ctrl:1
	s_nop 1
	v_add_f32_dpp v68, v68, v68 row_bcast:15 row_mask:0xa bank_mask:0xf
	s_nop 1
	v_add_f32_dpp v68, v68, v68 row_bcast:31 row_mask:0xc bank_mask:0xf
	v_mov_b32_e32 v69, v32
	v_readlane_b32 s7, v68, 63
	v_mov_b32_e32 v68, v36
	v_pk_fma_f32 v[68:69], v[68:69], v[68:69], v[70:71]
	v_mov_b32_e32 v70, v35
	v_add_f32_e32 v68, v68, v69
	v_mov_b32_e32 v71, v31
	s_nop 0
	v_add_f32_dpp v68, v68, v68 quad_perm:[1,0,3,2] row_mask:0xf bank_mask:0xf bound_ctrl:1
	v_fma_f32 v79, s7, v235, v225
	v_pk_mul_f32 v[70:71], v[70:71], v[70:71]
	v_add_f32_dpp v68, v68, v68 quad_perm:[2,3,0,1] row_mask:0xf bank_mask:0xf bound_ctrl:1
	v_rsq_f32_e32 v87, v79
	s_nop 0
	v_add_f32_dpp v68, v68, v68 row_half_mirror row_mask:0xf bank_mask:0xf bound_ctrl:1
	v_pk_mul_f32 v[4:5], v[4:5], v[86:87]
	s_nop 0
	v_add_f32_dpp v68, v68, v68 row_mirror row_mask:0xf bank_mask:0xf bound_ctrl:1
	v_pk_mul_f32 v[2:3], v[2:3], v[86:87]
	v_pk_mul_f32 v[8:9], v[8:9], v[86:87]
	v_add_f32_dpp v68, v68, v68 row_bcast:15 row_mask:0xa bank_mask:0xf
	v_pk_mul_f32 v[6:7], v[6:7], v[86:87]
	s_nop 0
	v_add_f32_dpp v68, v68, v68 row_bcast:31 row_mask:0xc bank_mask:0xf
	v_mov_b32_e32 v69, v33
	v_readlane_b32 s7, v68, 63
	v_mov_b32_e32 v68, v37
	v_pk_fma_f32 v[68:69], v[68:69], v[68:69], v[70:71]
	v_mov_b32_e32 v70, v26
	v_add_f32_e32 v68, v68, v69
	v_mov_b32_e32 v71, v22
	s_nop 0
	v_add_f32_dpp v68, v68, v68 quad_perm:[1,0,3,2] row_mask:0xf bank_mask:0xf bound_ctrl:1
	v_fma_f32 v81, s7, v235, v225
	v_pk_mul_f32 v[70:71], v[70:71], v[70:71]
	v_add_f32_dpp v68, v68, v68 quad_perm:[2,3,0,1] row_mask:0xf bank_mask:0xf bound_ctrl:1
	s_nop 1
	v_add_f32_dpp v68, v68, v68 row_half_mirror row_mask:0xf bank_mask:0xf bound_ctrl:1
	s_nop 1
	v_add_f32_dpp v68, v68, v68 row_mirror row_mask:0xf bank_mask:0xf bound_ctrl:1
	s_nop 1
	v_add_f32_dpp v68, v68, v68 row_bcast:15 row_mask:0xa bank_mask:0xf
	s_nop 1
	v_add_f32_dpp v68, v68, v68 row_bcast:31 row_mask:0xc bank_mask:0xf
	v_mov_b32_e32 v69, v24
	v_readlane_b32 s7, v68, 63
	v_mov_b32_e32 v68, v28
	v_pk_fma_f32 v[68:69], v[68:69], v[68:69], v[70:71]
	v_mov_b32_e32 v70, v27
	v_add_f32_e32 v68, v68, v69
	v_mov_b32_e32 v71, v23
	s_nop 0
	v_add_f32_dpp v68, v68, v68 quad_perm:[1,0,3,2] row_mask:0xf bank_mask:0xf bound_ctrl:1
	v_fma_f32 v83, s7, v235, v225
	v_pk_mul_f32 v[70:71], v[70:71], v[70:71]
	v_add_f32_dpp v68, v68, v68 quad_perm:[2,3,0,1] row_mask:0xf bank_mask:0xf bound_ctrl:1
	s_nop 1
	v_add_f32_dpp v68, v68, v68 row_half_mirror row_mask:0xf bank_mask:0xf bound_ctrl:1
	s_nop 1
	v_add_f32_dpp v68, v68, v68 row_mirror row_mask:0xf bank_mask:0xf bound_ctrl:1
	s_nop 1
	v_add_f32_dpp v68, v68, v68 row_bcast:15 row_mask:0xa bank_mask:0xf
	s_nop 1
	v_add_f32_dpp v68, v68, v68 row_bcast:31 row_mask:0xc bank_mask:0xf
	v_mov_b32_e32 v69, v25
	v_readlane_b32 s7, v68, 63
	v_mov_b32_e32 v68, v29
	v_pk_fma_f32 v[68:69], v[68:69], v[68:69], v[70:71]
	v_mov_b32_e32 v70, v50
	v_add_f32_e32 v68, v68, v69
	v_mov_b32_e32 v71, v46
	s_nop 0
	v_add_f32_dpp v68, v68, v68 quad_perm:[1,0,3,2] row_mask:0xf bank_mask:0xf bound_ctrl:1
	v_fma_f32 v90, s7, v235, v225
	v_pk_mul_f32 v[70:71], v[70:71], v[70:71]
	v_add_f32_dpp v68, v68, v68 quad_perm:[2,3,0,1] row_mask:0xf bank_mask:0xf bound_ctrl:1
	s_nop 1
	v_add_f32_dpp v68, v68, v68 row_half_mirror row_mask:0xf bank_mask:0xf bound_ctrl:1
	s_nop 1
	v_add_f32_dpp v68, v68, v68 row_mirror row_mask:0xf bank_mask:0xf bound_ctrl:1
	s_nop 1
	v_add_f32_dpp v68, v68, v68 row_bcast:15 row_mask:0xa bank_mask:0xf
	s_nop 1
	v_add_f32_dpp v68, v68, v68 row_bcast:31 row_mask:0xc bank_mask:0xf
	v_mov_b32_e32 v69, v48
	v_readlane_b32 s7, v68, 63
	v_mov_b32_e32 v68, v52
	v_pk_fma_f32 v[68:69], v[68:69], v[68:69], v[70:71]
	v_mov_b32_e32 v70, v51
	v_add_f32_e32 v68, v68, v69
	v_mov_b32_e32 v71, v47
	s_nop 0
	v_add_f32_dpp v68, v68, v68 quad_perm:[1,0,3,2] row_mask:0xf bank_mask:0xf bound_ctrl:1
	v_fma_f32 v91, s7, v235, v225
	v_pk_mul_f32 v[70:71], v[70:71], v[70:71]
	v_add_f32_dpp v68, v68, v68 quad_perm:[2,3,0,1] row_mask:0xf bank_mask:0xf bound_ctrl:1
	s_nop 1
	v_add_f32_dpp v68, v68, v68 row_half_mirror row_mask:0xf bank_mask:0xf bound_ctrl:1
	s_nop 1
	v_add_f32_dpp v68, v68, v68 row_mirror row_mask:0xf bank_mask:0xf bound_ctrl:1
	s_nop 1
	v_add_f32_dpp v68, v68, v68 row_bcast:15 row_mask:0xa bank_mask:0xf
	s_nop 1
	v_add_f32_dpp v68, v68, v68 row_bcast:31 row_mask:0xc bank_mask:0xf
	v_mov_b32_e32 v69, v49
	v_readlane_b32 s7, v68, 63
	v_mov_b32_e32 v68, v53
	v_pk_fma_f32 v[68:69], v[68:69], v[68:69], v[70:71]
	v_mov_b32_e32 v70, v44
	v_add_f32_e32 v68, v68, v69
	v_mov_b32_e32 v71, v38
	s_nop 0
	v_add_f32_dpp v68, v68, v68 quad_perm:[1,0,3,2] row_mask:0xf bank_mask:0xf bound_ctrl:1
	v_fma_f32 v92, s7, v235, v225
	v_pk_mul_f32 v[70:71], v[70:71], v[70:71]
	v_add_f32_dpp v68, v68, v68 quad_perm:[2,3,0,1] row_mask:0xf bank_mask:0xf bound_ctrl:1
	s_nop 1
	v_add_f32_dpp v68, v68, v68 row_half_mirror row_mask:0xf bank_mask:0xf bound_ctrl:1
	s_nop 1
	v_add_f32_dpp v68, v68, v68 row_mirror row_mask:0xf bank_mask:0xf bound_ctrl:1
	s_nop 1
	v_add_f32_dpp v68, v68, v68 row_bcast:15 row_mask:0xa bank_mask:0xf
	s_nop 1
	v_add_f32_dpp v68, v68, v68 row_bcast:31 row_mask:0xc bank_mask:0xf
	v_mov_b32_e32 v69, v42
	v_readlane_b32 s7, v68, 63
	v_mov_b32_e32 v68, v40
	v_pk_fma_f32 v[68:69], v[68:69], v[68:69], v[70:71]
	v_mov_b32_e32 v70, v45
	v_add_f32_e32 v68, v68, v69
	v_mov_b32_e32 v71, v39
	s_nop 0
	v_add_f32_dpp v68, v68, v68 quad_perm:[1,0,3,2] row_mask:0xf bank_mask:0xf bound_ctrl:1
	v_fma_f32 v93, s7, v235, v225
	v_pk_mul_f32 v[70:71], v[70:71], v[70:71]
	v_add_f32_dpp v68, v68, v68 quad_perm:[2,3,0,1] row_mask:0xf bank_mask:0xf bound_ctrl:1
	s_nop 1
	v_add_f32_dpp v68, v68, v68 row_half_mirror row_mask:0xf bank_mask:0xf bound_ctrl:1
	s_nop 1
	v_add_f32_dpp v68, v68, v68 row_mirror row_mask:0xf bank_mask:0xf bound_ctrl:1
	s_nop 1
	v_add_f32_dpp v68, v68, v68 row_bcast:15 row_mask:0xa bank_mask:0xf
	s_nop 1
	v_add_f32_dpp v68, v68, v68 row_bcast:31 row_mask:0xc bank_mask:0xf
	v_mov_b32_e32 v69, v43
	v_readlane_b32 s7, v68, 63
	v_mov_b32_e32 v68, v41
	v_pk_fma_f32 v[68:69], v[68:69], v[68:69], v[70:71]
	v_mov_b32_e32 v70, v62
	v_add_f32_e32 v68, v68, v69
	v_mov_b32_e32 v71, v20
	s_nop 0
	v_add_f32_dpp v68, v68, v68 quad_perm:[1,0,3,2] row_mask:0xf bank_mask:0xf bound_ctrl:1
	v_fma_f32 v94, s7, v235, v225
	v_pk_mul_f32 v[70:71], v[70:71], v[70:71]
	v_add_f32_dpp v68, v68, v68 quad_perm:[2,3,0,1] row_mask:0xf bank_mask:0xf bound_ctrl:1
	s_nop 1
	v_add_f32_dpp v68, v68, v68 row_half_mirror row_mask:0xf bank_mask:0xf bound_ctrl:1
	s_nop 1
	v_add_f32_dpp v68, v68, v68 row_mirror row_mask:0xf bank_mask:0xf bound_ctrl:1
	s_nop 1
	v_add_f32_dpp v68, v68, v68 row_bcast:15 row_mask:0xa bank_mask:0xf
	s_nop 1
	v_add_f32_dpp v68, v68, v68 row_bcast:31 row_mask:0xc bank_mask:0xf
	v_mov_b32_e32 v69, v60
	v_readlane_b32 s7, v68, 63
	v_mov_b32_e32 v68, v64
	v_pk_fma_f32 v[68:69], v[68:69], v[68:69], v[70:71]
	v_mov_b32_e32 v70, v63
	v_add_f32_e32 v68, v68, v69
	v_mov_b32_e32 v71, v21
	s_nop 0
	v_add_f32_dpp v68, v68, v68 quad_perm:[1,0,3,2] row_mask:0xf bank_mask:0xf bound_ctrl:1
	v_fma_f32 v95, s7, v235, v225
	v_pk_mul_f32 v[70:71], v[70:71], v[70:71]
	v_add_f32_dpp v68, v68, v68 quad_perm:[2,3,0,1] row_mask:0xf bank_mask:0xf bound_ctrl:1
	s_nop 1
	v_add_f32_dpp v68, v68, v68 row_half_mirror row_mask:0xf bank_mask:0xf bound_ctrl:1
	s_nop 1
	v_add_f32_dpp v68, v68, v68 row_mirror row_mask:0xf bank_mask:0xf bound_ctrl:1
	s_nop 1
	v_add_f32_dpp v68, v68, v68 row_bcast:15 row_mask:0xa bank_mask:0xf
	s_nop 1
	v_add_f32_dpp v68, v68, v68 row_bcast:31 row_mask:0xc bank_mask:0xf
	v_mov_b32_e32 v69, v61
	v_readlane_b32 s7, v68, 63
	v_mov_b32_e32 v68, v65
	v_pk_fma_f32 v[68:69], v[68:69], v[68:69], v[70:71]
	v_mov_b32_e32 v70, v56
	v_add_f32_e32 v68, v68, v69
	v_mov_b32_e32 v71, v18
	s_nop 0
	v_add_f32_dpp v68, v68, v68 quad_perm:[1,0,3,2] row_mask:0xf bank_mask:0xf bound_ctrl:1
	v_fma_f32 v96, s7, v235, v225
	v_pk_mul_f32 v[70:71], v[70:71], v[70:71]
	v_add_f32_dpp v68, v68, v68 quad_perm:[2,3,0,1] row_mask:0xf bank_mask:0xf bound_ctrl:1
	s_nop 1
	v_add_f32_dpp v68, v68, v68 row_half_mirror row_mask:0xf bank_mask:0xf bound_ctrl:1
	s_nop 1
	v_add_f32_dpp v68, v68, v68 row_mirror row_mask:0xf bank_mask:0xf bound_ctrl:1
	s_nop 1
	v_add_f32_dpp v68, v68, v68 row_bcast:15 row_mask:0xa bank_mask:0xf
	s_nop 1
	v_add_f32_dpp v68, v68, v68 row_bcast:31 row_mask:0xc bank_mask:0xf
	v_mov_b32_e32 v69, v54
	v_readlane_b32 s7, v68, 63
	v_mov_b32_e32 v68, v58
	v_pk_fma_f32 v[68:69], v[68:69], v[68:69], v[70:71]
	v_mov_b32_e32 v70, v57
	v_add_f32_e32 v68, v68, v69
	v_mov_b32_e32 v71, v19
	s_nop 0
	v_add_f32_dpp v68, v68, v68 quad_perm:[1,0,3,2] row_mask:0xf bank_mask:0xf bound_ctrl:1
	v_fma_f32 v97, s7, v235, v225
	v_pk_mul_f32 v[70:71], v[70:71], v[70:71]
	v_add_f32_dpp v68, v68, v68 quad_perm:[2,3,0,1] row_mask:0xf bank_mask:0xf bound_ctrl:1
	s_nop 1
	v_add_f32_dpp v68, v68, v68 row_half_mirror row_mask:0xf bank_mask:0xf bound_ctrl:1
	s_nop 1
	v_add_f32_dpp v68, v68, v68 row_mirror row_mask:0xf bank_mask:0xf bound_ctrl:1
	s_nop 1
	v_add_f32_dpp v68, v68, v68 row_bcast:15 row_mask:0xa bank_mask:0xf
	s_nop 1
	v_add_f32_dpp v68, v68, v68 row_bcast:31 row_mask:0xc bank_mask:0xf
	v_mov_b32_e32 v69, v55
	v_readlane_b32 s7, v68, 63
	v_mov_b32_e32 v68, v59
	v_pk_fma_f32 v[68:69], v[68:69], v[68:69], v[70:71]
	v_fma_f32 v98, s7, v235, v225
	v_add_f32_e32 v68, v68, v69
	s_nop 0
	s_nop 0
	v_add_f32_dpp v68, v68, v68 quad_perm:[1,0,3,2] row_mask:0xf bank_mask:0xf bound_ctrl:1
	s_nop 1
	v_add_f32_dpp v68, v68, v68 quad_perm:[2,3,0,1] row_mask:0xf bank_mask:0xf bound_ctrl:1
	s_nop 1
	v_add_f32_dpp v68, v68, v68 row_half_mirror row_mask:0xf bank_mask:0xf bound_ctrl:1
	s_nop 1
	v_add_f32_dpp v68, v68, v68 row_mirror row_mask:0xf bank_mask:0xf bound_ctrl:1
	s_nop 1
	v_add_f32_dpp v68, v68, v68 row_bcast:15 row_mask:0xa bank_mask:0xf
	s_nop 1
	v_add_f32_dpp v68, v68, v68 row_bcast:31 row_mask:0xc bank_mask:0xf
	s_nop 0
	v_readlane_b32 s7, v68, 63
	v_add_u32_e32 v68, s66, v1
	v_ashrrev_i32_e32 v69, 31, v68
	s_waitcnt lgkmcnt(0)
	v_lshl_add_u64 v[68:69], v[68:69], 2, s[42:43]
	global_load_dword v88, v[68:69], off
	v_or_b32_e32 v68, s84, v66
	v_ashrrev_i32_e32 v69, 31, v68
	v_lshlrev_b64 v[68:69], 2, v[68:69]
	v_lshl_add_u64 v[70:71], s[52:53], 0, v[68:69]
	v_lshl_add_u64 v[68:69], s[54:55], 0, v[68:69]
	global_load_dword v72, v[68:69], off
	global_load_dword v74, v[70:71], off
	global_load_dword v76, v[70:71], off offset:256
	global_load_dword v78, v[68:69], off offset:256
	global_load_dword v80, v[68:69], off offset:512
	global_load_dword v82, v[70:71], off offset:512
	s_nop 0
	global_load_dword v70, v[70:71], off offset:768
	s_nop 0
	global_load_dword v68, v[68:69], off offset:768
	v_lshl_add_u32 v69, v1, 2, s9
	v_fma_f32 v99, s7, v235, v225
	s_add_i32 s7, s5, s11
	s_lshl_b32 s5, s5, 9
	s_add_u32 s34, s78, 0x3420000
	s_mul_hi_i32 s8, s7, 0x5000
	s_mulk_i32 s7, 0x5000
	s_addc_u32 s64, s79, 0
	s_add_u32 s28, s34, s7
	s_addc_u32 s29, s64, s8
	s_movk_i32 s8, 0x110
	v_mad_u32_u24 v67, v66, s8, v67
	s_movk_i32 s7, 0x2000
	s_add_i32 s5, s9, s5
	s_waitcnt vmcnt(8)
	ds_write_b32 v69, v88
	s_waitcnt vmcnt(6)
	v_pk_fma_f32 v[88:89], v[74:75], v[4:5], v[72:73] op_sel_hi:[0,1,0]
	v_pk_mul_f32 v[4:5], v[14:15], v[84:85]
	v_pk_fma_f32 v[16:17], v[74:75], v[16:17], v[72:73] op_sel_hi:[0,1,0]
	s_waitcnt vmcnt(4)
	v_pk_fma_f32 v[14:15], v[76:77], v[4:5], v[78:79] op_sel_hi:[0,1,0]
	v_pk_mul_f32 v[4:5], v[12:13], v[84:85]
	s_waitcnt vmcnt(0)
	v_pk_fma_f32 v[86:87], v[70:71], v[2:3], v[68:69] op_sel_hi:[0,1,0]
	v_pk_fma_f32 v[12:13], v[82:83], v[4:5], v[80:81] op_sel_hi:[0,1,0]
	v_pk_mul_f32 v[4:5], v[10:11], v[84:85]
	v_rsq_f32_e32 v10, v81
	v_rsq_f32_e32 v11, v83
	v_rsq_f32_e32 v84, v90
	v_rsq_f32_e32 v85, v91
	v_pk_fma_f32 v[90:91], v[70:71], v[4:5], v[68:69] op_sel_hi:[0,1,0]
	v_pk_mul_f32 v[2:3], v[36:37], v[10:11]
	v_pk_fma_f32 v[8:9], v[76:77], v[8:9], v[78:79] op_sel_hi:[0,1,0]
	v_pk_mul_f32 v[4:5], v[28:29], v[84:85]
	v_pk_fma_f32 v[2:3], v[74:75], v[2:3], v[72:73] op_sel_hi:[0,1,0]
	v_pk_fma_f32 v[4:5], v[74:75], v[4:5], v[72:73] op_sel_hi:[0,1,0]
	v_cvt_pk_bf16_f32 v5, v4, v5
	v_cvt_pk_bf16_f32 v4, v2, v3
	v_cvt_pk_bf16_f32 v3, v88, v89
	v_cvt_pk_bf16_f32 v2, v16, v17
	ds_write_b128 v67, v[2:5]
	v_pk_mul_f32 v[2:3], v[34:35], v[10:11]
	v_pk_mul_f32 v[4:5], v[26:27], v[84:85]
	v_pk_fma_f32 v[2:3], v[76:77], v[2:3], v[78:79] op_sel_hi:[0,1,0]
	v_pk_fma_f32 v[4:5], v[76:77], v[4:5], v[78:79] op_sel_hi:[0,1,0]
	v_cvt_pk_bf16_f32 v5, v4, v5
	v_cvt_pk_bf16_f32 v4, v2, v3
	v_cvt_pk_bf16_f32 v3, v8, v9
	v_cvt_pk_bf16_f32 v2, v14, v15
	ds_write_b128 v67, v[2:5] offset:17408
	v_pk_mul_f32 v[2:3], v[32:33], v[10:11]
	v_pk_mul_f32 v[4:5], v[24:25], v[84:85]
	v_pk_fma_f32 v[6:7], v[82:83], v[6:7], v[80:81] op_sel_hi:[0,1,0]
	v_pk_fma_f32 v[4:5], v[82:83], v[4:5], v[80:81] op_sel_hi:[0,1,0]
	v_pk_fma_f32 v[2:3], v[82:83], v[2:3], v[80:81] op_sel_hi:[0,1,0]
	v_cvt_pk_bf16_f32 v5, v4, v5
	v_cvt_pk_bf16_f32 v4, v2, v3
	v_cvt_pk_bf16_f32 v3, v6, v7
	v_cvt_pk_bf16_f32 v2, v12, v13
	v_rsq_f32_e32 v6, v92
	v_rsq_f32_e32 v7, v93
	v_rsq_f32_e32 v8, v94
	v_rsq_f32_e32 v9, v95
	ds_write_b128 v67, v[2:5] offset:34816
	v_pk_mul_f32 v[2:3], v[30:31], v[10:11]
	v_pk_mul_f32 v[4:5], v[22:23], v[84:85]
	v_pk_fma_f32 v[2:3], v[70:71], v[2:3], v[68:69] op_sel_hi:[0,1,0]
	v_pk_fma_f32 v[4:5], v[70:71], v[4:5], v[68:69] op_sel_hi:[0,1,0]
	v_cvt_pk_bf16_f32 v5, v4, v5
	v_cvt_pk_bf16_f32 v4, v2, v3
	v_cvt_pk_bf16_f32 v3, v86, v87
	v_cvt_pk_bf16_f32 v2, v90, v91
	ds_write_b128 v67, v[2:5] offset:52224
	v_pk_mul_f32 v[2:3], v[52:53], v[6:7]
	v_pk_mul_f32 v[4:5], v[40:41], v[8:9]
	v_pk_fma_f32 v[12:13], v[74:75], v[2:3], v[72:73] op_sel_hi:[0,1,0]
	v_pk_fma_f32 v[10:11], v[74:75], v[4:5], v[72:73] op_sel_hi:[0,1,0]
	v_pk_mul_f32 v[2:3], v[50:51], v[6:7]
	v_pk_mul_f32 v[4:5], v[44:45], v[8:9]
	v_pk_fma_f32 v[16:17], v[76:77], v[2:3], v[78:79] op_sel_hi:[0,1,0]
	v_pk_fma_f32 v[14:15], v[76:77], v[4:5], v[78:79] op_sel_hi:[0,1,0]
	v_pk_mul_f32 v[2:3], v[48:49], v[6:7]
	v_pk_mul_f32 v[4:5], v[42:43], v[8:9]
	v_pk_fma_f32 v[24:25], v[82:83], v[2:3], v[80:81] op_sel_hi:[0,1,0]
	v_pk_fma_f32 v[22:23], v[82:83], v[4:5], v[80:81] op_sel_hi:[0,1,0]
	v_pk_mul_f32 v[2:3], v[46:47], v[6:7]
	v_pk_mul_f32 v[4:5], v[38:39], v[8:9]
	v_rsq_f32_e32 v6, v96
	v_rsq_f32_e32 v7, v97
	v_rsq_f32_e32 v8, v98
	v_rsq_f32_e32 v9, v99
	v_pk_fma_f32 v[26:27], v[70:71], v[4:5], v[68:69] op_sel_hi:[0,1,0]
	v_pk_fma_f32 v[28:29], v[70:71], v[2:3], v[68:69] op_sel_hi:[0,1,0]
	v_pk_mul_f32 v[2:3], v[64:65], v[6:7]
	v_pk_mul_f32 v[4:5], v[58:59], v[8:9]
	v_pk_fma_f32 v[2:3], v[74:75], v[2:3], v[72:73] op_sel_hi:[0,1,0]
	v_pk_fma_f32 v[4:5], v[74:75], v[4:5], v[72:73] op_sel_hi:[0,1,0]
	v_cvt_pk_bf16_f32 v5, v4, v5
	v_cvt_pk_bf16_f32 v4, v2, v3
	v_cvt_pk_bf16_f32 v3, v10, v11
	v_cvt_pk_bf16_f32 v2, v12, v13
	ds_write_b128 v67, v[2:5] offset:16
	v_pk_mul_f32 v[2:3], v[62:63], v[6:7]
	v_pk_mul_f32 v[4:5], v[56:57], v[8:9]
	v_pk_fma_f32 v[2:3], v[76:77], v[2:3], v[78:79] op_sel_hi:[0,1,0]
	v_pk_fma_f32 v[4:5], v[76:77], v[4:5], v[78:79] op_sel_hi:[0,1,0]
	v_cvt_pk_bf16_f32 v5, v4, v5
	v_cvt_pk_bf16_f32 v4, v2, v3
	v_cvt_pk_bf16_f32 v3, v14, v15
	v_cvt_pk_bf16_f32 v2, v16, v17
	ds_write_b128 v67, v[2:5] offset:17424
	v_pk_mul_f32 v[2:3], v[60:61], v[6:7]
	v_pk_mul_f32 v[4:5], v[54:55], v[8:9]
	v_pk_fma_f32 v[2:3], v[82:83], v[2:3], v[80:81] op_sel_hi:[0,1,0]
	v_pk_fma_f32 v[4:5], v[82:83], v[4:5], v[80:81] op_sel_hi:[0,1,0]
	v_cvt_pk_bf16_f32 v5, v4, v5
	v_cvt_pk_bf16_f32 v4, v2, v3
	v_cvt_pk_bf16_f32 v3, v22, v23
	v_cvt_pk_bf16_f32 v2, v24, v25
	ds_write_b128 v67, v[2:5] offset:34832
	v_pk_mul_f32 v[2:3], v[20:21], v[6:7]
	v_pk_mul_f32 v[4:5], v[18:19], v[8:9]
	v_and_or_b32 v8, v1, 31, s6
	v_pk_fma_f32 v[4:5], v[70:71], v[4:5], v[68:69] op_sel_hi:[0,1,0]
	v_pk_fma_f32 v[2:3], v[70:71], v[2:3], v[68:69] op_sel_hi:[0,1,0]
	v_lshl_add_u64 v[6:7], s[28:29], 0, v[130:131]
	v_bfe_u32 v10, v1, 5, 1
	v_ashrrev_i32_e32 v9, 31, v8
	v_cvt_pk_bf16_f32 v5, v4, v5
	v_cvt_pk_bf16_f32 v4, v2, v3
	v_cvt_pk_bf16_f32 v3, v26, v27
	v_cvt_pk_bf16_f32 v2, v28, v29
	v_add_co_u32_e32 v66, vcc, s90, v6
	v_lshlrev_b32_e32 v1, 2, v10
	v_lshlrev_b64 v[68:69], 1, v[8:9]
	ds_write_b128 v67, v[2:5] offset:52240
	v_addc_co_u32_e32 v67, vcc, 0, v7, vcc
	v_or_b32_e32 v82, s65, v1
	v_lshl_add_u64 v[84:85], s[80:81], 0, v[68:69]
	v_add_co_u32_e32 v86, vcc, s7, v6
	v_mad_u64_u32 v[12:13], s[6:7], v82, s87, v[84:85]
	s_waitcnt lgkmcnt(0)
	s_barrier
	global_load_dwordx4 v[2:5], v130, s[28:29]
	global_load_dwordx4 v[58:61], v130, s[28:29] offset:1024
	global_load_dwordx4 v[22:25], v130, s[28:29] offset:2048
	global_load_dwordx4 v[18:21], v130, s[28:29] offset:3072
	global_load_ushort v9, v[12:13], off
	v_or_b32_e32 v11, 1, v82
	v_mad_u64_u32 v[12:13], s[6:7], v11, s87, v[84:85]
	global_load_ushort v11, v[12:13], off
	v_or_b32_e32 v12, 2, v82
	v_mad_u64_u32 v[12:13], s[6:7], v12, s87, v[84:85]
	global_load_ushort v28, v[12:13], off
	v_or_b32_e32 v12, 3, v82
	v_mad_u64_u32 v[12:13], s[6:7], v12, s87, v[84:85]
	global_load_ushort v29, v[12:13], off
	v_or_b32_e32 v12, 8, v82
	v_or_b32_e32 v14, 9, v82
	v_mad_u64_u32 v[12:13], s[6:7], v12, s87, v[84:85]
	v_mad_u64_u32 v[14:15], s[6:7], v14, s87, v[84:85]
	v_or_b32_e32 v16, 10, v82
	v_or_b32_e32 v26, 11, v82
	v_mad_u64_u32 v[16:17], s[6:7], v16, s87, v[84:85]
	v_mad_u64_u32 v[26:27], s[6:7], v26, s87, v[84:85]
	global_load_ushort v12, v[12:13], off
	s_nop 0
	global_load_ushort v13, v[14:15], off
	s_nop 0
	global_load_ushort v14, v[16:17], off
	global_load_ushort v15, v[26:27], off
	v_addc_co_u32_e32 v87, vcc, 0, v7, vcc
	v_mov_b32_e32 v83, v131
	v_lshl_add_u64 v[88:89], s[76:77], 0, v[68:69]
	v_lshlrev_b64 v[68:69], 11, v[82:83]
	v_lshl_add_u64 v[68:69], v[88:89], 0, v[68:69]
	s_mov_b64 s[28:29], -1
	s_waitcnt vmcnt(7)
	v_lshlrev_b32_e32 v9, 16, v9
	v_fma_f32 v16, |v9|, s92, 1.0
	v_rcp_f32_e32 v16, v16
	v_mul_f32_e32 v26, v9, v9
	v_mul_f32_e32 v26, 0xbf38aa3b, v26
	v_exp_f32_e32 v26, v26
	v_fmamk_f32 v17, v16, 0x3f07dc22, v236
	v_fmaak_f32 v17, v16, v17, 0x3f35f0e3
	v_fmaak_f32 v17, v16, v17, 0xbe11a98e
	v_fmaak_f32 v17, v16, v17, 0x3e027906
	v_mul_f32_e32 v16, v16, v17
	v_mul_f32_e32 v16, v26, v16
	v_mul_f32_e32 v17, v16, v9
	v_fma_f32 v16, -v16, v9, v9
	v_cmp_gt_f32_e32 vcc, 0, v9
	s_waitcnt vmcnt(6)
	v_lshlrev_b32_e32 v9, 16, v11
	v_fma_f32 v11, |v9|, s92, 1.0
	v_rcp_f32_e32 v11, v11
	v_cndmask_b32_e32 v70, v16, v17, vcc
	v_mul_f32_e32 v17, v9, v9
	v_mul_f32_e32 v17, 0xbf38aa3b, v17
	v_fmamk_f32 v16, v11, 0x3f07dc22, v236
	v_fmaak_f32 v16, v11, v16, 0x3f35f0e3
	v_exp_f32_e32 v17, v17
	v_fmaak_f32 v16, v11, v16, 0xbe11a98e
	v_fmaak_f32 v16, v11, v16, 0x3e027906
	v_mul_f32_e32 v11, v11, v16
	v_mul_f32_e32 v11, v17, v11
	v_mul_f32_e32 v16, v11, v9
	v_fma_f32 v11, -v11, v9, v9
	v_cmp_gt_f32_e32 vcc, 0, v9
	s_waitcnt vmcnt(5)
	v_lshlrev_b32_e32 v9, 16, v28
	v_mul_f32_e32 v17, v9, v9
	v_cndmask_b32_e32 v71, v11, v16, vcc
	v_fma_f32 v11, |v9|, s92, 1.0
	v_rcp_f32_e32 v11, v11
	v_mul_f32_e32 v17, 0xbf38aa3b, v17
	v_exp_f32_e32 v17, v17
	v_cmp_gt_f32_e32 vcc, 0, v9
	v_fmamk_f32 v16, v11, 0x3f07dc22, v236
	v_fmaak_f32 v16, v11, v16, 0x3f35f0e3
	v_fmaak_f32 v16, v11, v16, 0xbe11a98e
	v_fmaak_f32 v16, v11, v16, 0x3e027906
	v_mul_f32_e32 v11, v11, v16
	v_mul_f32_e32 v11, v17, v11
	v_mul_f32_e32 v16, v11, v9
	v_fma_f32 v11, -v11, v9, v9
	s_waitcnt vmcnt(4)
	v_lshlrev_b32_e32 v9, 16, v29
	v_cndmask_b32_e32 v72, v11, v16, vcc
	v_fma_f32 v11, |v9|, s92, 1.0
	v_rcp_f32_e32 v11, v11
	v_mul_f32_e32 v17, v9, v9
	v_mul_f32_e32 v17, 0xbf38aa3b, v17
	v_exp_f32_e32 v17, v17
	v_fmamk_f32 v16, v11, 0x3f07dc22, v236
	v_fmaak_f32 v16, v11, v16, 0x3f35f0e3
	v_fmaak_f32 v16, v11, v16, 0xbe11a98e
	v_fmaak_f32 v16, v11, v16, 0x3e027906
	v_mul_f32_e32 v11, v11, v16
	v_mul_f32_e32 v11, v17, v11
	v_mul_f32_e32 v16, v11, v9
	v_fma_f32 v11, -v11, v9, v9
	v_cmp_gt_f32_e32 vcc, 0, v9
	s_waitcnt vmcnt(3)
	v_lshlrev_b32_e32 v9, 16, v12
	v_or_b32_e32 v26, 27, v82
	v_cndmask_b32_e32 v73, v11, v16, vcc
	v_fma_f32 v11, |v9|, s92, 1.0
	v_rcp_f32_e32 v11, v11
	v_mul_f32_e32 v16, v9, v9
	v_mul_f32_e32 v16, 0xbf38aa3b, v16
	v_exp_f32_e32 v16, v16
	v_fmamk_f32 v12, v11, 0x3f07dc22, v236
	v_fmaak_f32 v12, v11, v12, 0x3f35f0e3
	v_fmaak_f32 v12, v11, v12, 0xbe11a98e
	v_fmaak_f32 v12, v11, v12, 0x3e027906
	v_mul_f32_e32 v11, v11, v12
	v_mul_f32_e32 v11, v16, v11
	v_mul_f32_e32 v12, v11, v9
	v_fma_f32 v11, -v11, v9, v9
	v_cmp_gt_f32_e32 vcc, 0, v9
	s_waitcnt vmcnt(2)
	v_lshlrev_b32_e32 v9, 16, v13
	v_mul_f32_e32 v13, v9, v9
	v_cndmask_b32_e32 v74, v11, v12, vcc
	v_fma_f32 v11, |v9|, s92, 1.0
	v_rcp_f32_e32 v11, v11
	v_mul_f32_e32 v13, 0xbf38aa3b, v13
	v_exp_f32_e32 v13, v13
	v_cmp_gt_f32_e32 vcc, 0, v9
	v_fmamk_f32 v12, v11, 0x3f07dc22, v236
	v_fmaak_f32 v12, v11, v12, 0x3f35f0e3
	v_fmaak_f32 v12, v11, v12, 0xbe11a98e
	v_fmaak_f32 v12, v11, v12, 0x3e027906
	v_mul_f32_e32 v11, v11, v12
	v_mul_f32_e32 v11, v13, v11
	v_mul_f32_e32 v12, v11, v9
	v_fma_f32 v11, -v11, v9, v9
	s_waitcnt vmcnt(1)
	v_lshlrev_b32_e32 v9, 16, v14
	v_cndmask_b32_e32 v75, v11, v12, vcc
	v_fma_f32 v11, |v9|, s92, 1.0
	v_rcp_f32_e32 v11, v11
	v_mul_f32_e32 v13, v9, v9
	v_mul_f32_e32 v13, 0xbf38aa3b, v13
	v_exp_f32_e32 v13, v13
	v_fmamk_f32 v12, v11, 0x3f07dc22, v236
	v_fmaak_f32 v12, v11, v12, 0x3f35f0e3
	v_fmaak_f32 v12, v11, v12, 0xbe11a98e
	v_fmaak_f32 v12, v11, v12, 0x3e027906
	v_mul_f32_e32 v11, v11, v12
	v_mul_f32_e32 v11, v13, v11
	v_mul_f32_e32 v12, v11, v9
	v_fma_f32 v11, -v11, v9, v9
	v_cmp_gt_f32_e32 vcc, 0, v9
	s_waitcnt vmcnt(0)
	v_lshlrev_b32_e32 v9, 16, v15
	v_mul_f32_e32 v13, v9, v9
	v_cndmask_b32_e32 v76, v11, v12, vcc
	v_fma_f32 v11, |v9|, s92, 1.0
	v_rcp_f32_e32 v11, v11
	v_mul_f32_e32 v13, 0xbf38aa3b, v13
	v_exp_f32_e32 v13, v13
	v_cmp_gt_f32_e32 vcc, 0, v9
	v_fmamk_f32 v12, v11, 0x3f07dc22, v236
	v_fmaak_f32 v12, v11, v12, 0x3f35f0e3
	v_fmaak_f32 v12, v11, v12, 0xbe11a98e
	v_fmaak_f32 v12, v11, v12, 0x3e027906
	v_mul_f32_e32 v11, v11, v12
	v_mul_f32_e32 v11, v13, v11
	v_mul_f32_e32 v12, v11, v9
	v_fma_f32 v11, -v11, v9, v9
	v_or_b32_e32 v9, 16, v82
	v_cndmask_b32_e32 v77, v11, v12, vcc
	v_mad_u64_u32 v[12:13], s[6:7], v9, s87, v[84:85]
	global_load_ushort v9, v[12:13], off
	v_or_b32_e32 v11, 17, v82
	v_mad_u64_u32 v[12:13], s[6:7], v11, s87, v[84:85]
	global_load_ushort v11, v[12:13], off
	v_or_b32_e32 v12, 18, v82
	v_mad_u64_u32 v[12:13], s[6:7], v12, s87, v[84:85]
	global_load_ushort v28, v[12:13], off
	v_or_b32_e32 v12, 19, v82
	v_mad_u64_u32 v[12:13], s[6:7], v12, s87, v[84:85]
	global_load_ushort v29, v[12:13], off
	v_or_b32_e32 v12, 24, v82
	v_or_b32_e32 v14, 25, v82
	v_mad_u64_u32 v[12:13], s[6:7], v12, s87, v[84:85]
	v_mad_u64_u32 v[14:15], s[6:7], v14, s87, v[84:85]
	v_or_b32_e32 v16, 26, v82
	v_mad_u64_u32 v[16:17], s[6:7], v16, s87, v[84:85]
	v_mad_u64_u32 v[26:27], s[6:7], v26, s87, v[84:85]
	global_load_ushort v12, v[12:13], off
	s_nop 0
	global_load_ushort v13, v[14:15], off
	s_nop 0
	global_load_ushort v14, v[16:17], off
	global_load_ushort v15, v[26:27], off
	s_waitcnt vmcnt(7)
	v_lshlrev_b32_e32 v9, 16, v9
	v_fma_f32 v16, |v9|, s92, 1.0
	v_rcp_f32_e32 v16, v16
	v_mul_f32_e32 v26, v9, v9
	v_mul_f32_e32 v26, 0xbf38aa3b, v26
	v_exp_f32_e32 v26, v26
	v_fmamk_f32 v17, v16, 0x3f07dc22, v236
	v_fmaak_f32 v17, v16, v17, 0x3f35f0e3
	v_fmaak_f32 v17, v16, v17, 0xbe11a98e
	v_fmaak_f32 v17, v16, v17, 0x3e027906
	v_mul_f32_e32 v16, v16, v17
	v_mul_f32_e32 v16, v26, v16
	v_mul_f32_e32 v17, v16, v9
	v_fma_f32 v16, -v16, v9, v9
	v_cmp_gt_f32_e32 vcc, 0, v9
	s_waitcnt vmcnt(6)
	v_lshlrev_b32_e32 v9, 16, v11
	v_fma_f32 v11, |v9|, s92, 1.0
	v_rcp_f32_e32 v11, v11
	v_cndmask_b32_e32 v95, v16, v17, vcc
	v_mul_f32_e32 v17, v9, v9
	v_mul_f32_e32 v17, 0xbf38aa3b, v17
	v_fmamk_f32 v16, v11, 0x3f07dc22, v236
	v_fmaak_f32 v16, v11, v16, 0x3f35f0e3
	v_exp_f32_e32 v17, v17
	v_fmaak_f32 v16, v11, v16, 0xbe11a98e
	v_fmaak_f32 v16, v11, v16, 0x3e027906
	v_mul_f32_e32 v11, v11, v16
	v_mul_f32_e32 v11, v17, v11
	v_mul_f32_e32 v16, v11, v9
	v_fma_f32 v11, -v11, v9, v9
	v_cmp_gt_f32_e32 vcc, 0, v9
	s_waitcnt vmcnt(5)
	v_lshlrev_b32_e32 v9, 16, v28
	v_mul_f32_e32 v17, v9, v9
	v_cndmask_b32_e32 v96, v11, v16, vcc
	v_fma_f32 v11, |v9|, s92, 1.0
	v_rcp_f32_e32 v11, v11
	v_mul_f32_e32 v17, 0xbf38aa3b, v17
	v_exp_f32_e32 v17, v17
	v_cmp_gt_f32_e32 vcc, 0, v9
	v_fmamk_f32 v16, v11, 0x3f07dc22, v236
	v_fmaak_f32 v16, v11, v16, 0x3f35f0e3
	v_fmaak_f32 v16, v11, v16, 0xbe11a98e
	v_fmaak_f32 v16, v11, v16, 0x3e027906
	v_mul_f32_e32 v11, v11, v16
	v_mul_f32_e32 v11, v17, v11
	v_mul_f32_e32 v16, v11, v9
	v_fma_f32 v11, -v11, v9, v9
	s_waitcnt vmcnt(4)
	v_lshlrev_b32_e32 v9, 16, v29
	v_cndmask_b32_e32 v98, v11, v16, vcc
	v_fma_f32 v11, |v9|, s92, 1.0
	v_rcp_f32_e32 v11, v11
	v_mul_f32_e32 v17, v9, v9
	v_mul_f32_e32 v17, 0xbf38aa3b, v17
	v_exp_f32_e32 v17, v17
	v_fmamk_f32 v16, v11, 0x3f07dc22, v236
	v_fmaak_f32 v16, v11, v16, 0x3f35f0e3
	v_fmaak_f32 v16, v11, v16, 0xbe11a98e
	v_fmaak_f32 v16, v11, v16, 0x3e027906
	v_mul_f32_e32 v11, v11, v16
	v_mul_f32_e32 v11, v17, v11
	v_mul_f32_e32 v16, v11, v9
	v_fma_f32 v11, -v11, v9, v9
	v_cmp_gt_f32_e32 vcc, 0, v9
	s_waitcnt vmcnt(3)
	v_lshlrev_b32_e32 v9, 16, v12
	v_or_b32_e32 v26, 43, v82
	v_cndmask_b32_e32 v100, v11, v16, vcc
	v_fma_f32 v11, |v9|, s92, 1.0
	v_rcp_f32_e32 v11, v11
	v_mul_f32_e32 v16, v9, v9
	v_mul_f32_e32 v16, 0xbf38aa3b, v16
	v_exp_f32_e32 v16, v16
	v_fmamk_f32 v12, v11, 0x3f07dc22, v236
	v_fmaak_f32 v12, v11, v12, 0x3f35f0e3
	v_fmaak_f32 v12, v11, v12, 0xbe11a98e
	v_fmaak_f32 v12, v11, v12, 0x3e027906
	v_mul_f32_e32 v11, v11, v12
	v_mul_f32_e32 v11, v16, v11
	v_mul_f32_e32 v12, v11, v9
	v_fma_f32 v11, -v11, v9, v9
	v_cmp_gt_f32_e32 vcc, 0, v9
	s_waitcnt vmcnt(2)
	v_lshlrev_b32_e32 v9, 16, v13
	v_mul_f32_e32 v13, v9, v9
	v_cndmask_b32_e32 v102, v11, v12, vcc
	v_fma_f32 v11, |v9|, s92, 1.0
	v_rcp_f32_e32 v11, v11
	v_mul_f32_e32 v13, 0xbf38aa3b, v13
	v_exp_f32_e32 v13, v13
	v_cmp_gt_f32_e32 vcc, 0, v9
	v_fmamk_f32 v12, v11, 0x3f07dc22, v236
	v_fmaak_f32 v12, v11, v12, 0x3f35f0e3
	v_fmaak_f32 v12, v11, v12, 0xbe11a98e
	v_fmaak_f32 v12, v11, v12, 0x3e027906
	v_mul_f32_e32 v11, v11, v12
	v_mul_f32_e32 v11, v13, v11
	v_mul_f32_e32 v12, v11, v9
	v_fma_f32 v11, -v11, v9, v9
	s_waitcnt vmcnt(1)
	v_lshlrev_b32_e32 v9, 16, v14
	v_cndmask_b32_e32 v104, v11, v12, vcc
	v_fma_f32 v11, |v9|, s92, 1.0
	v_rcp_f32_e32 v11, v11
	v_mul_f32_e32 v13, v9, v9
	v_mul_f32_e32 v13, 0xbf38aa3b, v13
	v_exp_f32_e32 v13, v13
	v_fmamk_f32 v12, v11, 0x3f07dc22, v236
	v_fmaak_f32 v12, v11, v12, 0x3f35f0e3
	v_fmaak_f32 v12, v11, v12, 0xbe11a98e
	v_fmaak_f32 v12, v11, v12, 0x3e027906
	v_mul_f32_e32 v11, v11, v12
	v_mul_f32_e32 v11, v13, v11
	v_mul_f32_e32 v12, v11, v9
	v_fma_f32 v11, -v11, v9, v9
	v_cmp_gt_f32_e32 vcc, 0, v9
	s_waitcnt vmcnt(0)
	v_lshlrev_b32_e32 v9, 16, v15
	v_mul_f32_e32 v13, v9, v9
	v_cndmask_b32_e32 v106, v11, v12, vcc
	v_fma_f32 v11, |v9|, s92, 1.0
	v_rcp_f32_e32 v11, v11
	v_mul_f32_e32 v13, 0xbf38aa3b, v13
	v_exp_f32_e32 v13, v13
	v_cmp_gt_f32_e32 vcc, 0, v9
	v_fmamk_f32 v12, v11, 0x3f07dc22, v236
	v_fmaak_f32 v12, v11, v12, 0x3f35f0e3
	v_fmaak_f32 v12, v11, v12, 0xbe11a98e
	v_fmaak_f32 v12, v11, v12, 0x3e027906
	v_mul_f32_e32 v11, v11, v12
	v_mul_f32_e32 v11, v13, v11
	v_mul_f32_e32 v12, v11, v9
	v_fma_f32 v11, -v11, v9, v9
	v_or_b32_e32 v9, 32, v82
	v_cndmask_b32_e32 v110, v11, v12, vcc
	v_mad_u64_u32 v[12:13], s[6:7], v9, s87, v[84:85]
	global_load_ushort v9, v[12:13], off
	v_or_b32_e32 v11, 33, v82
	v_mad_u64_u32 v[12:13], s[6:7], v11, s87, v[84:85]
	global_load_ushort v11, v[12:13], off
	v_or_b32_e32 v12, 34, v82
	v_mad_u64_u32 v[12:13], s[6:7], v12, s87, v[84:85]
	global_load_ushort v28, v[12:13], off
	v_or_b32_e32 v12, 35, v82
	v_mad_u64_u32 v[12:13], s[6:7], v12, s87, v[84:85]
	global_load_ushort v29, v[12:13], off
	v_or_b32_e32 v12, 40, v82
	v_or_b32_e32 v14, 41, v82
	v_mad_u64_u32 v[12:13], s[6:7], v12, s87, v[84:85]
	v_mad_u64_u32 v[14:15], s[6:7], v14, s87, v[84:85]
	v_or_b32_e32 v16, 42, v82
	v_mad_u64_u32 v[16:17], s[6:7], v16, s87, v[84:85]
	v_mad_u64_u32 v[26:27], s[6:7], v26, s87, v[84:85]
	global_load_ushort v12, v[12:13], off
	s_nop 0
	global_load_ushort v13, v[14:15], off
	s_nop 0
	global_load_ushort v14, v[16:17], off
	global_load_ushort v15, v[26:27], off
	s_waitcnt vmcnt(7)
	v_lshlrev_b32_e32 v9, 16, v9
	v_fma_f32 v16, |v9|, s92, 1.0
	v_rcp_f32_e32 v16, v16
	v_mul_f32_e32 v26, v9, v9
	v_mul_f32_e32 v26, 0xbf38aa3b, v26
	v_exp_f32_e32 v26, v26
	v_fmamk_f32 v17, v16, 0x3f07dc22, v236
	v_fmaak_f32 v17, v16, v17, 0x3f35f0e3
	v_fmaak_f32 v17, v16, v17, 0xbe11a98e
	v_fmaak_f32 v17, v16, v17, 0x3e027906
	v_mul_f32_e32 v16, v16, v17
	v_mul_f32_e32 v16, v26, v16
	v_mul_f32_e32 v17, v16, v9
	v_fma_f32 v16, -v16, v9, v9
	v_cmp_gt_f32_e32 vcc, 0, v9
	s_waitcnt vmcnt(6)
	v_lshlrev_b32_e32 v9, 16, v11
	v_fma_f32 v11, |v9|, s92, 1.0
	v_rcp_f32_e32 v11, v11
	v_cndmask_b32_e32 v97, v16, v17, vcc
	v_mul_f32_e32 v17, v9, v9
	v_mul_f32_e32 v17, 0xbf38aa3b, v17
	v_fmamk_f32 v16, v11, 0x3f07dc22, v236
	v_fmaak_f32 v16, v11, v16, 0x3f35f0e3
	v_exp_f32_e32 v17, v17
	v_fmaak_f32 v16, v11, v16, 0xbe11a98e
	v_fmaak_f32 v16, v11, v16, 0x3e027906
	v_mul_f32_e32 v11, v11, v16
	v_mul_f32_e32 v11, v17, v11
	v_mul_f32_e32 v16, v11, v9
	v_fma_f32 v11, -v11, v9, v9
	v_cmp_gt_f32_e32 vcc, 0, v9
	s_waitcnt vmcnt(5)
	v_lshlrev_b32_e32 v9, 16, v28
	v_mul_f32_e32 v17, v9, v9
	v_cndmask_b32_e32 v99, v11, v16, vcc
	v_fma_f32 v11, |v9|, s92, 1.0
	v_rcp_f32_e32 v11, v11
	v_mul_f32_e32 v17, 0xbf38aa3b, v17
	v_exp_f32_e32 v17, v17
	v_cmp_gt_f32_e32 vcc, 0, v9
	v_fmamk_f32 v16, v11, 0x3f07dc22, v236
	v_fmaak_f32 v16, v11, v16, 0x3f35f0e3
	v_fmaak_f32 v16, v11, v16, 0xbe11a98e
	v_fmaak_f32 v16, v11, v16, 0x3e027906
	v_mul_f32_e32 v11, v11, v16
	v_mul_f32_e32 v11, v17, v11
	v_mul_f32_e32 v16, v11, v9
	v_fma_f32 v11, -v11, v9, v9
	s_waitcnt vmcnt(4)
	v_lshlrev_b32_e32 v9, 16, v29
	v_cndmask_b32_e32 v101, v11, v16, vcc
	v_fma_f32 v11, |v9|, s92, 1.0
	v_rcp_f32_e32 v11, v11
	v_mul_f32_e32 v17, v9, v9
	v_mul_f32_e32 v17, 0xbf38aa3b, v17
	v_exp_f32_e32 v17, v17
	v_fmamk_f32 v16, v11, 0x3f07dc22, v236
	v_fmaak_f32 v16, v11, v16, 0x3f35f0e3
	v_fmaak_f32 v16, v11, v16, 0xbe11a98e
	v_fmaak_f32 v16, v11, v16, 0x3e027906
	v_mul_f32_e32 v11, v11, v16
	v_mul_f32_e32 v11, v17, v11
	v_mul_f32_e32 v16, v11, v9
	v_fma_f32 v11, -v11, v9, v9
	v_cmp_gt_f32_e32 vcc, 0, v9
	s_waitcnt vmcnt(3)
	v_lshlrev_b32_e32 v9, 16, v12
	v_or_b32_e32 v26, 59, v82
	v_cndmask_b32_e32 v103, v11, v16, vcc
	v_fma_f32 v11, |v9|, s92, 1.0
	v_rcp_f32_e32 v11, v11
	v_mul_f32_e32 v16, v9, v9
	v_mul_f32_e32 v16, 0xbf38aa3b, v16
	v_exp_f32_e32 v16, v16
	v_fmamk_f32 v12, v11, 0x3f07dc22, v236
	v_fmaak_f32 v12, v11, v12, 0x3f35f0e3
	v_fmaak_f32 v12, v11, v12, 0xbe11a98e
	v_fmaak_f32 v12, v11, v12, 0x3e027906
	v_mul_f32_e32 v11, v11, v12
	v_mul_f32_e32 v11, v16, v11
	v_mul_f32_e32 v12, v11, v9
	v_fma_f32 v11, -v11, v9, v9
	v_cmp_gt_f32_e32 vcc, 0, v9
	s_waitcnt vmcnt(2)
	v_lshlrev_b32_e32 v9, 16, v13
	v_mul_f32_e32 v13, v9, v9
	v_cndmask_b32_e32 v105, v11, v12, vcc
	v_fma_f32 v11, |v9|, s92, 1.0
	v_rcp_f32_e32 v11, v11
	v_mul_f32_e32 v13, 0xbf38aa3b, v13
	v_exp_f32_e32 v13, v13
	v_cmp_gt_f32_e32 vcc, 0, v9
	v_fmamk_f32 v12, v11, 0x3f07dc22, v236
	v_fmaak_f32 v12, v11, v12, 0x3f35f0e3
	v_fmaak_f32 v12, v11, v12, 0xbe11a98e
	v_fmaak_f32 v12, v11, v12, 0x3e027906
	v_mul_f32_e32 v11, v11, v12
	v_mul_f32_e32 v11, v13, v11
	v_mul_f32_e32 v12, v11, v9
	v_fma_f32 v11, -v11, v9, v9
	s_waitcnt vmcnt(1)
	v_lshlrev_b32_e32 v9, 16, v14
	v_cndmask_b32_e32 v107, v11, v12, vcc
	v_fma_f32 v11, |v9|, s92, 1.0
	v_rcp_f32_e32 v11, v11
	v_mul_f32_e32 v13, v9, v9
	v_mul_f32_e32 v13, 0xbf38aa3b, v13
	v_exp_f32_e32 v13, v13
	v_fmamk_f32 v12, v11, 0x3f07dc22, v236
	v_fmaak_f32 v12, v11, v12, 0x3f35f0e3
	v_fmaak_f32 v12, v11, v12, 0xbe11a98e
	v_fmaak_f32 v12, v11, v12, 0x3e027906
	v_mul_f32_e32 v11, v11, v12
	v_mul_f32_e32 v11, v13, v11
	v_mul_f32_e32 v12, v11, v9
	v_fma_f32 v11, -v11, v9, v9
	v_cmp_gt_f32_e32 vcc, 0, v9
	s_waitcnt vmcnt(0)
	v_lshlrev_b32_e32 v9, 16, v15
	v_mul_f32_e32 v13, v9, v9
	v_cndmask_b32_e32 v108, v11, v12, vcc
	v_fma_f32 v11, |v9|, s92, 1.0
	v_rcp_f32_e32 v11, v11
	v_mul_f32_e32 v13, 0xbf38aa3b, v13
	v_exp_f32_e32 v13, v13
	v_cmp_gt_f32_e32 vcc, 0, v9
	v_fmamk_f32 v12, v11, 0x3f07dc22, v236
	v_fmaak_f32 v12, v11, v12, 0x3f35f0e3
	v_fmaak_f32 v12, v11, v12, 0xbe11a98e
	v_fmaak_f32 v12, v11, v12, 0x3e027906
	v_mul_f32_e32 v11, v11, v12
	v_mul_f32_e32 v11, v13, v11
	v_mul_f32_e32 v12, v11, v9
	v_fma_f32 v11, -v11, v9, v9
	v_or_b32_e32 v9, 48, v82
	v_cndmask_b32_e32 v109, v11, v12, vcc
	v_mad_u64_u32 v[12:13], s[6:7], v9, s87, v[84:85]
	global_load_ushort v9, v[12:13], off
	v_or_b32_e32 v11, 49, v82
	v_mad_u64_u32 v[12:13], s[6:7], v11, s87, v[84:85]
	global_load_ushort v11, v[12:13], off
	v_or_b32_e32 v12, 50, v82
	v_mad_u64_u32 v[12:13], s[6:7], v12, s87, v[84:85]
	global_load_ushort v28, v[12:13], off
	v_or_b32_e32 v12, 51, v82
	v_mad_u64_u32 v[12:13], s[6:7], v12, s87, v[84:85]
	global_load_ushort v29, v[12:13], off
	v_or_b32_e32 v12, 56, v82
	v_or_b32_e32 v14, 57, v82
	v_mad_u64_u32 v[12:13], s[6:7], v12, s87, v[84:85]
	v_mad_u64_u32 v[14:15], s[6:7], v14, s87, v[84:85]
	v_or_b32_e32 v16, 58, v82
	v_mad_u64_u32 v[16:17], s[6:7], v16, s87, v[84:85]
	v_mad_u64_u32 v[26:27], s[6:7], v26, s87, v[84:85]
	global_load_ushort v12, v[12:13], off
	s_nop 0
	global_load_ushort v13, v[14:15], off
	s_nop 0
	global_load_ushort v14, v[16:17], off
	global_load_ushort v15, v[26:27], off
	s_movk_i32 s6, 0x3000
	s_waitcnt vmcnt(7)
	v_lshlrev_b32_e32 v9, 16, v9
	v_fma_f32 v16, |v9|, s92, 1.0
	v_rcp_f32_e32 v16, v16
	v_mul_f32_e32 v26, v9, v9
	v_mul_f32_e32 v26, 0xbf38aa3b, v26
	v_exp_f32_e32 v26, v26
	v_fmamk_f32 v17, v16, 0x3f07dc22, v236
	v_fmaak_f32 v17, v16, v17, 0x3f35f0e3
	v_fmaak_f32 v17, v16, v17, 0xbe11a98e
	v_fmaak_f32 v17, v16, v17, 0x3e027906
	v_mul_f32_e32 v16, v16, v17
	v_mul_f32_e32 v16, v26, v16
	v_mul_f32_e32 v17, v16, v9
	v_fma_f32 v16, -v16, v9, v9
	v_cmp_gt_f32_e32 vcc, 0, v9
	s_waitcnt vmcnt(6)
	v_lshlrev_b32_e32 v9, 16, v11
	v_fma_f32 v11, |v9|, s92, 1.0
	v_rcp_f32_e32 v11, v11
	v_cndmask_b32_e32 v113, v16, v17, vcc
	v_mul_f32_e32 v17, v9, v9
	v_mul_f32_e32 v17, 0xbf38aa3b, v17
	v_fmamk_f32 v16, v11, 0x3f07dc22, v236
	v_fmaak_f32 v16, v11, v16, 0x3f35f0e3
	v_exp_f32_e32 v17, v17
	v_fmaak_f32 v16, v11, v16, 0xbe11a98e
	v_fmaak_f32 v16, v11, v16, 0x3e027906
	v_mul_f32_e32 v11, v11, v16
	v_mul_f32_e32 v11, v17, v11
	v_mul_f32_e32 v16, v11, v9
	v_fma_f32 v11, -v11, v9, v9
	v_cmp_gt_f32_e32 vcc, 0, v9
	s_waitcnt vmcnt(5)
	v_lshlrev_b32_e32 v9, 16, v28
	v_mul_f32_e32 v17, v9, v9
	v_cndmask_b32_e32 v115, v11, v16, vcc
	v_fma_f32 v11, |v9|, s92, 1.0
	v_rcp_f32_e32 v11, v11
	v_mul_f32_e32 v17, 0xbf38aa3b, v17
	v_exp_f32_e32 v17, v17
	v_cmp_gt_f32_e32 vcc, 0, v9
	v_fmamk_f32 v16, v11, 0x3f07dc22, v236
	v_fmaak_f32 v16, v11, v16, 0x3f35f0e3
	v_fmaak_f32 v16, v11, v16, 0xbe11a98e
	v_fmaak_f32 v16, v11, v16, 0x3e027906
	v_mul_f32_e32 v11, v11, v16
	v_mul_f32_e32 v11, v17, v11
	v_mul_f32_e32 v16, v11, v9
	v_fma_f32 v11, -v11, v9, v9
	s_waitcnt vmcnt(4)
	v_lshlrev_b32_e32 v9, 16, v29
	v_cndmask_b32_e32 v117, v11, v16, vcc
	v_fma_f32 v11, |v9|, s92, 1.0
	v_rcp_f32_e32 v11, v11
	v_mul_f32_e32 v17, v9, v9
	v_mul_f32_e32 v17, 0xbf38aa3b, v17
	v_exp_f32_e32 v17, v17
	v_fmamk_f32 v16, v11, 0x3f07dc22, v236
	v_fmaak_f32 v16, v11, v16, 0x3f35f0e3
	v_fmaak_f32 v16, v11, v16, 0xbe11a98e
	v_fmaak_f32 v16, v11, v16, 0x3e027906
	v_mul_f32_e32 v11, v11, v16
	v_mul_f32_e32 v11, v17, v11
	v_mul_f32_e32 v16, v11, v9
	v_fma_f32 v11, -v11, v9, v9
	v_cmp_gt_f32_e32 vcc, 0, v9
	s_waitcnt vmcnt(3)
	v_lshlrev_b32_e32 v9, 16, v12
	v_cndmask_b32_e32 v119, v11, v16, vcc
	v_fma_f32 v11, |v9|, s92, 1.0
	v_rcp_f32_e32 v11, v11
	v_mul_f32_e32 v16, v9, v9
	v_mul_f32_e32 v16, 0xbf38aa3b, v16
	v_exp_f32_e32 v16, v16
	v_fmamk_f32 v12, v11, 0x3f07dc22, v236
	v_fmaak_f32 v12, v11, v12, 0x3f35f0e3
	v_fmaak_f32 v12, v11, v12, 0xbe11a98e
	v_fmaak_f32 v12, v11, v12, 0x3e027906
	v_mul_f32_e32 v11, v11, v12
	v_mul_f32_e32 v11, v16, v11
	v_mul_f32_e32 v12, v11, v9
	v_fma_f32 v11, -v11, v9, v9
	v_cmp_gt_f32_e32 vcc, 0, v9
	s_waitcnt vmcnt(2)
	v_lshlrev_b32_e32 v9, 16, v13
	v_mul_f32_e32 v13, v9, v9
	v_cndmask_b32_e32 v120, v11, v12, vcc
	v_fma_f32 v11, |v9|, s92, 1.0
	v_rcp_f32_e32 v11, v11
	v_mul_f32_e32 v13, 0xbf38aa3b, v13
	v_exp_f32_e32 v13, v13
	v_cmp_gt_f32_e32 vcc, 0, v9
	v_fmamk_f32 v12, v11, 0x3f07dc22, v236
	v_fmaak_f32 v12, v11, v12, 0x3f35f0e3
	v_fmaak_f32 v12, v11, v12, 0xbe11a98e
	v_fmaak_f32 v12, v11, v12, 0x3e027906
	v_mul_f32_e32 v11, v11, v12
	v_mul_f32_e32 v11, v13, v11
	v_mul_f32_e32 v12, v11, v9
	v_fma_f32 v11, -v11, v9, v9
	s_waitcnt vmcnt(1)
	v_lshlrev_b32_e32 v9, 16, v14
	v_cndmask_b32_e32 v121, v11, v12, vcc
	v_fma_f32 v11, |v9|, s92, 1.0
	v_rcp_f32_e32 v11, v11
	v_mul_f32_e32 v13, v9, v9
	v_mul_f32_e32 v13, 0xbf38aa3b, v13
	v_exp_f32_e32 v13, v13
	v_fmamk_f32 v12, v11, 0x3f07dc22, v236
	v_fmaak_f32 v12, v11, v12, 0x3f35f0e3
	v_fmaak_f32 v12, v11, v12, 0xbe11a98e
	v_fmaak_f32 v12, v11, v12, 0x3e027906
	v_mul_f32_e32 v11, v11, v12
	v_mul_f32_e32 v11, v13, v11
	v_mul_f32_e32 v12, v11, v9
	v_fma_f32 v11, -v11, v9, v9
	v_cmp_gt_f32_e32 vcc, 0, v9
	s_waitcnt vmcnt(0)
	v_lshlrev_b32_e32 v9, 16, v15
	v_mul_f32_e32 v13, v9, v9
	v_cndmask_b32_e32 v122, v11, v12, vcc
	v_fma_f32 v11, |v9|, s92, 1.0
	v_rcp_f32_e32 v11, v11
	v_mul_f32_e32 v13, 0xbf38aa3b, v13
	v_exp_f32_e32 v13, v13
	v_cmp_gt_f32_e32 vcc, 0, v9
	v_fmamk_f32 v12, v11, 0x3f07dc22, v236
	v_fmaak_f32 v12, v11, v12, 0x3f35f0e3
	v_fmaak_f32 v12, v11, v12, 0xbe11a98e
	v_fmaak_f32 v12, v11, v12, 0x3e027906
	v_mul_f32_e32 v11, v11, v12
	v_mul_f32_e32 v11, v13, v11
	v_mul_f32_e32 v12, v11, v9
	v_fma_f32 v11, -v11, v9, v9
	v_cndmask_b32_e32 v123, v11, v12, vcc
	v_add_co_u32_e32 v90, vcc, s6, v6
	s_nop 1
	v_addc_co_u32_e32 v91, vcc, 0, v7, vcc
	v_add_co_u32_e32 v92, vcc, s97, v6
	v_lshlrev_b32_e32 v6, 4, v10
	s_nop 0
	v_addc_co_u32_e32 v93, vcc, 0, v7, vcc
	v_mul_lo_u32 v7, v8, s8
	v_add3_u32 v26, 0, v7, v6
	ds_read_b128 v[54:57], v26
	ds_read_b128 v[50:53], v26 offset:32
	ds_read_b128 v[46:49], v26 offset:64
	ds_read_b128 v[42:45], v26 offset:96
	v_add_u32_e32 v94, s5, v6
	s_waitcnt lgkmcnt(3)
	v_mfma_f32_32x32x16_bf16 v[2:17], v[2:5], v[54:57], 0
	global_load_dwordx4 v[78:81], v[66:67], off offset:1024
	ds_read_b128 v[38:41], v26 offset:128
	ds_read_b128 v[34:37], v26 offset:160
	ds_read_b128 v[30:33], v26 offset:192
	ds_read_b128 v[26:29], v26 offset:224
	global_load_dwordx4 v[62:65], v[86:87], off offset:-4096
	ds_read_b128 v[124:127], v94
	v_readlane_b32 s5, v251, 32
	s_waitcnt lgkmcnt(7)
	v_mfma_f32_32x32x16_bf16 v[2:17], v[58:61], v[50:53], v[2:17]
	ds_read_b128 v[58:61], v94 offset:32
	v_or_b32_e32 v130, s5, v1
	v_readlane_b32 s5, v251, 33
	s_waitcnt lgkmcnt(1)
	s_nop 7
	v_add_f32_e32 v2, v2, v124
	v_mul_f32_e32 v2, v70, v2
	v_cvt_pk_bf16_f32 v2, v2, s0
	global_store_short v[68:69], v2, off sc1
	v_add_f32_e32 v2, v3, v125
	v_mul_f32_e32 v2, v71, v2
	v_cvt_pk_bf16_f32 v68, v2, s0
	v_lshlrev_b64 v[2:3], 11, v[130:131]
	v_lshl_add_u64 v[2:3], v[88:89], 0, v[2:3]
	global_store_short v[2:3], v68, off sc1
	v_add_f32_e32 v2, v4, v126
	v_mul_f32_e32 v2, v72, v2
	v_or_b32_e32 v130, s5, v1
	v_cvt_pk_bf16_f32 v4, v2, s0
	v_lshlrev_b64 v[2:3], 11, v[130:131]
	v_lshl_add_u64 v[2:3], v[88:89], 0, v[2:3]
	global_store_short v[2:3], v4, off sc1
	v_add_f32_e32 v2, v5, v127
	v_readlane_b32 s5, v251, 34
	v_mul_f32_e32 v2, v73, v2
	v_cvt_pk_bf16_f32 v4, v2, s0
	v_or_b32_e32 v130, s5, v1
	v_lshlrev_b64 v[2:3], 11, v[130:131]
	v_lshl_add_u64 v[2:3], v[88:89], 0, v[2:3]
	global_store_short v[2:3], v4, off sc1
	s_waitcnt lgkmcnt(0)
	v_add_f32_e32 v2, v6, v58
	v_readlane_b32 s5, v251, 35
	v_mul_f32_e32 v2, v74, v2
	v_cvt_pk_bf16_f32 v4, v2, s0
	v_or_b32_e32 v130, s5, v1
	v_lshlrev_b64 v[2:3], 11, v[130:131]
	v_lshl_add_u64 v[2:3], v[88:89], 0, v[2:3]
	global_store_short v[2:3], v4, off sc1
	v_add_f32_e32 v2, v7, v59
	v_readlane_b32 s5, v251, 36
	v_mul_f32_e32 v2, v75, v2
	v_cvt_pk_bf16_f32 v4, v2, s0
	v_or_b32_e32 v130, s5, v1
	v_lshlrev_b64 v[2:3], 11, v[130:131]
	v_lshl_add_u64 v[2:3], v[88:89], 0, v[2:3]
	global_store_short v[2:3], v4, off sc1
	v_add_f32_e32 v2, v8, v60
	v_readlane_b32 s5, v251, 37
	v_mul_f32_e32 v2, v76, v2
	v_cvt_pk_bf16_f32 v4, v2, s0
	v_or_b32_e32 v130, s5, v1
	v_lshlrev_b64 v[2:3], 11, v[130:131]
	v_lshl_add_u64 v[2:3], v[88:89], 0, v[2:3]
	global_store_short v[2:3], v4, off sc1
	v_add_f32_e32 v2, v9, v61
	v_mul_f32_e32 v2, v77, v2
	v_cvt_pk_bf16_f32 v8, v2, s0
	ds_read_b128 v[2:5], v94 offset:64
	v_readlane_b32 s5, v251, 38
	s_nop 1
	v_or_b32_e32 v130, s5, v1
	v_lshlrev_b64 v[6:7], 11, v[130:131]
	v_lshl_add_u64 v[6:7], v[88:89], 0, v[6:7]
	v_readlane_b32 s5, v251, 39
	global_store_short v[6:7], v8, off sc1
	ds_read_b128 v[6:9], v94 offset:96
	s_waitcnt lgkmcnt(1)
	v_add_f32_e32 v2, v10, v2
	v_or_b32_e32 v130, s5, v1
	v_mul_f32_e32 v2, v95, v2
	v_lshlrev_b64 v[58:59], 11, v[130:131]
	v_cvt_pk_bf16_f32 v2, v2, s0
	v_lshl_add_u64 v[58:59], v[88:89], 0, v[58:59]
	global_store_short v[58:59], v2, off sc1
	v_add_f32_e32 v2, v11, v3
	v_readlane_b32 s5, v251, 40
	v_mul_f32_e32 v2, v96, v2
	v_cvt_pk_bf16_f32 v10, v2, s0
	v_or_b32_e32 v130, s5, v1
	v_lshlrev_b64 v[2:3], 11, v[130:131]
	v_lshl_add_u64 v[2:3], v[88:89], 0, v[2:3]
	global_store_short v[2:3], v10, off sc1
	v_add_f32_e32 v2, v12, v4
	v_readlane_b32 s5, v251, 41
	v_mul_f32_e32 v2, v98, v2
	v_cvt_pk_bf16_f32 v4, v2, s0
	v_or_b32_e32 v130, s5, v1
	v_lshlrev_b64 v[2:3], 11, v[130:131]
	v_lshl_add_u64 v[2:3], v[88:89], 0, v[2:3]
	global_store_short v[2:3], v4, off sc1
	v_add_f32_e32 v2, v13, v5
	v_readlane_b32 s5, v251, 42
	v_mul_f32_e32 v2, v100, v2
	v_cvt_pk_bf16_f32 v4, v2, s0
	v_or_b32_e32 v130, s5, v1
	v_lshlrev_b64 v[2:3], 11, v[130:131]
	v_lshl_add_u64 v[2:3], v[88:89], 0, v[2:3]
	global_store_short v[2:3], v4, off sc1
	s_waitcnt lgkmcnt(0)
	v_add_f32_e32 v2, v14, v6
	v_readlane_b32 s5, v251, 43
	v_mul_f32_e32 v2, v102, v2
	v_cvt_pk_bf16_f32 v4, v2, s0
	v_or_b32_e32 v130, s5, v1
	v_lshlrev_b64 v[2:3], 11, v[130:131]
	v_lshl_add_u64 v[2:3], v[88:89], 0, v[2:3]
	global_store_short v[2:3], v4, off sc1
	v_add_f32_e32 v2, v15, v7
	v_readlane_b32 s5, v251, 44
	v_mul_f32_e32 v2, v104, v2
	v_cvt_pk_bf16_f32 v4, v2, s0
	v_or_b32_e32 v130, s5, v1
	v_lshlrev_b64 v[2:3], 11, v[130:131]
	v_lshl_add_u64 v[2:3], v[88:89], 0, v[2:3]
	global_store_short v[2:3], v4, off sc1
	v_add_f32_e32 v2, v16, v8
	v_readlane_b32 s5, v251, 45
	v_mul_f32_e32 v2, v106, v2
	v_cvt_pk_bf16_f32 v4, v2, s0
	v_or_b32_e32 v130, s5, v1
	v_lshlrev_b64 v[2:3], 11, v[130:131]
	v_lshl_add_u64 v[2:3], v[88:89], 0, v[2:3]
	global_store_short v[2:3], v4, off sc1
	v_add_f32_e32 v2, v17, v9
	v_readlane_b32 s5, v251, 46
	v_mul_f32_e32 v2, v110, v2
	v_cvt_pk_bf16_f32 v4, v2, s0
	v_or_b32_e32 v130, s5, v1
	v_lshlrev_b64 v[2:3], 11, v[130:131]
	v_lshl_add_u64 v[2:3], v[88:89], 0, v[2:3]
	global_store_short v[2:3], v4, off sc1
	v_or_b32_e32 v2, 64, v82
	v_mad_i64_i32 v[2:3], s[6:7], v2, s87, v[84:85]
	global_load_ushort v10, v[2:3], off
	v_or_b32_e32 v2, 0x41, v82
	v_mad_i64_i32 v[2:3], s[6:7], v2, s87, v[84:85]
	global_load_ushort v11, v[2:3], off
	v_or_b32_e32 v2, 0x42, v82
	v_mad_i64_i32 v[2:3], s[6:7], v2, s87, v[84:85]
	global_load_ushort v12, v[2:3], off
	v_or_b32_e32 v2, 0x43, v82
	v_mad_i64_i32 v[2:3], s[6:7], v2, s87, v[84:85]
	global_load_ushort v13, v[2:3], off
	v_or_b32_e32 v2, 0x48, v82
	v_or_b32_e32 v4, 0x49, v82
	v_mad_i64_i32 v[2:3], s[6:7], v2, s87, v[84:85]
	v_mad_i64_i32 v[4:5], s[6:7], v4, s87, v[84:85]
	v_or_b32_e32 v6, 0x4a, v82
	v_or_b32_e32 v8, 0x4b, v82
	v_mad_i64_i32 v[6:7], s[6:7], v6, s87, v[84:85]
	v_mad_i64_i32 v[8:9], s[6:7], v8, s87, v[84:85]
	global_load_ushort v2, v[2:3], off
	s_nop 0
	global_load_ushort v3, v[4:5], off
	s_nop 0
	global_load_ushort v4, v[6:7], off
	global_load_ushort v5, v[8:9], off
	v_readlane_b32 s5, v251, 47
	s_waitcnt vmcnt(7)
	v_lshlrev_b32_e32 v6, 16, v10
	v_fma_f32 v7, |v6|, s92, 1.0
	v_rcp_f32_e32 v7, v7
	v_mul_f32_e32 v9, v6, v6
	v_mul_f32_e32 v9, 0xbf38aa3b, v9
	v_exp_f32_e32 v9, v9
	v_fmamk_f32 v8, v7, 0x3f07dc22, v236
	v_fmaak_f32 v8, v7, v8, 0x3f35f0e3
	v_fmaak_f32 v8, v7, v8, 0xbe11a98e
	v_fmaak_f32 v8, v7, v8, 0x3e027906
	v_mul_f32_e32 v7, v7, v8
	v_mul_f32_e32 v7, v9, v7
	v_mul_f32_e32 v8, v7, v6
	v_fma_f32 v7, -v7, v6, v6
	v_cmp_gt_f32_e32 vcc, 0, v6
	s_waitcnt vmcnt(6)
	v_lshlrev_b32_e32 v6, 16, v11
	v_mul_f32_e32 v9, v6, v6
	v_cndmask_b32_e32 v83, v7, v8, vcc
	v_fma_f32 v7, |v6|, s92, 1.0
	v_rcp_f32_e32 v7, v7
	v_mul_f32_e32 v9, 0xbf38aa3b, v9
	v_exp_f32_e32 v9, v9
	v_cmp_gt_f32_e32 vcc, 0, v6
	v_fmamk_f32 v8, v7, 0x3f07dc22, v236
	v_fmaak_f32 v8, v7, v8, 0x3f35f0e3
	v_fmaak_f32 v8, v7, v8, 0xbe11a98e
	v_fmaak_f32 v8, v7, v8, 0x3e027906
	v_mul_f32_e32 v7, v7, v8
	v_mul_f32_e32 v7, v9, v7
	v_mul_f32_e32 v8, v7, v6
	v_fma_f32 v7, -v7, v6, v6
	s_waitcnt vmcnt(5)
	v_lshlrev_b32_e32 v6, 16, v12
	v_cndmask_b32_e32 v95, v7, v8, vcc
	v_fma_f32 v7, |v6|, s92, 1.0
	v_rcp_f32_e32 v7, v7
	v_mul_f32_e32 v9, v6, v6
	v_mul_f32_e32 v9, 0xbf38aa3b, v9
	v_exp_f32_e32 v9, v9
	v_fmamk_f32 v8, v7, 0x3f07dc22, v236
	v_fmaak_f32 v8, v7, v8, 0x3f35f0e3
	v_fmaak_f32 v8, v7, v8, 0xbe11a98e
	v_fmaak_f32 v8, v7, v8, 0x3e027906
	v_mul_f32_e32 v7, v7, v8
	v_mul_f32_e32 v7, v9, v7
	v_mul_f32_e32 v8, v7, v6
	v_fma_f32 v7, -v7, v6, v6
	v_cmp_gt_f32_e32 vcc, 0, v6
	s_waitcnt vmcnt(4)
	v_lshlrev_b32_e32 v6, 16, v13
	v_mul_f32_e32 v9, v6, v6
	v_cndmask_b32_e32 v96, v7, v8, vcc
	v_fma_f32 v7, |v6|, s92, 1.0
	v_rcp_f32_e32 v7, v7
	v_mul_f32_e32 v9, 0xbf38aa3b, v9
	v_exp_f32_e32 v9, v9
	s_waitcnt vmcnt(3)
	v_lshlrev_b32_e32 v2, 16, v2
	v_fmamk_f32 v8, v7, 0x3f07dc22, v236
	v_fmaak_f32 v8, v7, v8, 0x3f35f0e3
	v_fmaak_f32 v8, v7, v8, 0xbe11a98e
	v_fmaak_f32 v8, v7, v8, 0x3e027906
	v_mul_f32_e32 v7, v7, v8
	v_mul_f32_e32 v7, v9, v7
	v_mul_f32_e32 v8, v7, v6
	v_fma_f32 v7, -v7, v6, v6
	v_cmp_gt_f32_e32 vcc, 0, v6
	v_fma_f32 v6, |v2|, s92, 1.0
	v_rcp_f32_e32 v6, v6
	v_cndmask_b32_e32 v98, v7, v8, vcc
	v_mul_f32_e32 v8, v2, v2
	v_mul_f32_e32 v8, 0xbf38aa3b, v8
	v_fmamk_f32 v7, v6, 0x3f07dc22, v236
	v_fmaak_f32 v7, v6, v7, 0x3f35f0e3
	v_exp_f32_e32 v8, v8
	v_fmaak_f32 v7, v6, v7, 0xbe11a98e
	v_fmaak_f32 v7, v6, v7, 0x3e027906
	v_mul_f32_e32 v6, v6, v7
	v_mul_f32_e32 v6, v8, v6
	v_mul_f32_e32 v7, v6, v2
	v_fma_f32 v6, -v6, v2, v2
	v_cmp_gt_f32_e32 vcc, 0, v2
	s_waitcnt vmcnt(2)
	v_lshlrev_b32_e32 v2, 16, v3
	v_fma_f32 v3, |v2|, s92, 1.0
	v_rcp_f32_e32 v3, v3
	v_cndmask_b32_e32 v100, v6, v7, vcc
	v_mul_f32_e32 v7, v2, v2
	v_mul_f32_e32 v7, 0xbf38aa3b, v7
	v_fmamk_f32 v6, v3, 0x3f07dc22, v236
	v_fmaak_f32 v6, v3, v6, 0x3f35f0e3
	v_exp_f32_e32 v7, v7
	v_fmaak_f32 v6, v3, v6, 0xbe11a98e
	v_fmaak_f32 v6, v3, v6, 0x3e027906
	v_mul_f32_e32 v3, v3, v6
	v_mul_f32_e32 v3, v7, v3
	v_mul_f32_e32 v6, v3, v2
	v_fma_f32 v3, -v3, v2, v2
	v_cmp_gt_f32_e32 vcc, 0, v2
	s_waitcnt vmcnt(1)
	v_lshlrev_b32_e32 v2, 16, v4
	v_or_b32_e32 v8, 0x5b, v82
	v_cndmask_b32_e32 v102, v3, v6, vcc
	v_fma_f32 v3, |v2|, s92, 1.0
	v_rcp_f32_e32 v3, v3
	v_mul_f32_e32 v6, v2, v2
	v_mul_f32_e32 v6, 0xbf38aa3b, v6
	v_exp_f32_e32 v6, v6
	v_fmamk_f32 v4, v3, 0x3f07dc22, v236
	v_fmaak_f32 v4, v3, v4, 0x3f35f0e3
	v_fmaak_f32 v4, v3, v4, 0xbe11a98e
	v_fmaak_f32 v4, v3, v4, 0x3e027906
	v_mul_f32_e32 v3, v3, v4
	v_mul_f32_e32 v3, v6, v3
	v_mul_f32_e32 v4, v3, v2
	v_fma_f32 v3, -v3, v2, v2
	v_cmp_gt_f32_e32 vcc, 0, v2
	s_waitcnt vmcnt(0)
	v_lshlrev_b32_e32 v2, 16, v5
	v_mul_f32_e32 v5, v2, v2
	v_cndmask_b32_e32 v104, v3, v4, vcc
	v_fma_f32 v3, |v2|, s92, 1.0
	v_rcp_f32_e32 v3, v3
	v_mul_f32_e32 v5, 0xbf38aa3b, v5
	v_exp_f32_e32 v5, v5
	v_cmp_gt_f32_e32 vcc, 0, v2
	v_fmamk_f32 v4, v3, 0x3f07dc22, v236
	v_fmaak_f32 v4, v3, v4, 0x3f35f0e3
	v_fmaak_f32 v4, v3, v4, 0xbe11a98e
	v_fmaak_f32 v4, v3, v4, 0x3e027906
	v_mul_f32_e32 v3, v3, v4
	v_mul_f32_e32 v3, v5, v3
	v_mul_f32_e32 v4, v3, v2
	v_fma_f32 v3, -v3, v2, v2
	v_or_b32_e32 v2, 0x50, v82
	v_cndmask_b32_e32 v106, v3, v4, vcc
	v_mad_i64_i32 v[2:3], s[6:7], v2, s87, v[84:85]
	global_load_ushort v10, v[2:3], off
	v_or_b32_e32 v2, 0x51, v82
	v_mad_i64_i32 v[2:3], s[6:7], v2, s87, v[84:85]
	global_load_ushort v11, v[2:3], off
	v_or_b32_e32 v2, 0x52, v82
	v_mad_i64_i32 v[2:3], s[6:7], v2, s87, v[84:85]
	global_load_ushort v12, v[2:3], off
	v_or_b32_e32 v2, 0x53, v82
	v_mad_i64_i32 v[2:3], s[6:7], v2, s87, v[84:85]
	global_load_ushort v13, v[2:3], off
	v_or_b32_e32 v2, 0x58, v82
	v_or_b32_e32 v4, 0x59, v82
	v_mad_i64_i32 v[2:3], s[6:7], v2, s87, v[84:85]
	v_mad_i64_i32 v[4:5], s[6:7], v4, s87, v[84:85]
	v_or_b32_e32 v6, 0x5a, v82
	v_mad_i64_i32 v[6:7], s[6:7], v6, s87, v[84:85]
	v_mad_i64_i32 v[8:9], s[6:7], v8, s87, v[84:85]
	global_load_ushort v2, v[2:3], off
	s_nop 0
	global_load_ushort v3, v[4:5], off
	s_nop 0
	global_load_ushort v4, v[6:7], off
	global_load_ushort v58, v[8:9], off
	v_or_b32_e32 v130, s5, v1
	v_readlane_b32 s5, v251, 48
	s_waitcnt vmcnt(7)
	v_lshlrev_b32_e32 v5, 16, v10
	v_fma_f32 v6, |v5|, s92, 1.0
	v_rcp_f32_e32 v6, v6
	v_mul_f32_e32 v8, v5, v5
	v_mul_f32_e32 v8, 0xbf38aa3b, v8
	v_exp_f32_e32 v8, v8
	v_fmamk_f32 v7, v6, 0x3f07dc22, v236
	v_fmaak_f32 v7, v6, v7, 0x3f35f0e3
	v_fmaak_f32 v7, v6, v7, 0xbe11a98e
	v_fmaak_f32 v7, v6, v7, 0x3e027906
	v_mul_f32_e32 v6, v6, v7
	v_mul_f32_e32 v6, v8, v6
	v_mul_f32_e32 v7, v6, v5
	v_fma_f32 v6, -v6, v5, v5
	v_cmp_gt_f32_e32 vcc, 0, v5
	s_waitcnt vmcnt(6)
	v_lshlrev_b32_e32 v5, 16, v11
	v_mul_f32_e32 v8, v5, v5
	v_cndmask_b32_e32 v110, v6, v7, vcc
	v_fma_f32 v6, |v5|, s92, 1.0
	v_rcp_f32_e32 v6, v6
	v_mul_f32_e32 v8, 0xbf38aa3b, v8
	v_exp_f32_e32 v8, v8
	v_cmp_gt_f32_e32 vcc, 0, v5
	v_fmamk_f32 v7, v6, 0x3f07dc22, v236
	v_fmaak_f32 v7, v6, v7, 0x3f35f0e3
	v_fmaak_f32 v7, v6, v7, 0xbe11a98e
	v_fmaak_f32 v7, v6, v7, 0x3e027906
	v_mul_f32_e32 v6, v6, v7
	v_mul_f32_e32 v6, v8, v6
	v_mul_f32_e32 v7, v6, v5
	v_fma_f32 v6, -v6, v5, v5
	s_waitcnt vmcnt(5)
	v_lshlrev_b32_e32 v5, 16, v12
	v_cndmask_b32_e32 v111, v6, v7, vcc
	v_fma_f32 v6, |v5|, s92, 1.0
	v_rcp_f32_e32 v6, v6
	v_mul_f32_e32 v8, v5, v5
	v_mul_f32_e32 v8, 0xbf38aa3b, v8
	v_exp_f32_e32 v8, v8
	v_fmamk_f32 v7, v6, 0x3f07dc22, v236
	v_fmaak_f32 v7, v6, v7, 0x3f35f0e3
	v_fmaak_f32 v7, v6, v7, 0xbe11a98e
	v_fmaak_f32 v7, v6, v7, 0x3e027906
	v_mul_f32_e32 v6, v6, v7
	v_mul_f32_e32 v6, v8, v6
	v_mul_f32_e32 v7, v6, v5
	v_fma_f32 v6, -v6, v5, v5
	v_cmp_gt_f32_e32 vcc, 0, v5
	s_waitcnt vmcnt(4)
	v_lshlrev_b32_e32 v5, 16, v13
	v_mul_f32_e32 v8, v5, v5
	v_cndmask_b32_e32 v112, v6, v7, vcc
	v_fma_f32 v6, |v5|, s92, 1.0
	v_rcp_f32_e32 v6, v6
	v_mul_f32_e32 v8, 0xbf38aa3b, v8
	v_exp_f32_e32 v8, v8
	s_waitcnt vmcnt(3)
	v_lshlrev_b32_e32 v2, 16, v2
	v_fmamk_f32 v7, v6, 0x3f07dc22, v236
	v_fmaak_f32 v7, v6, v7, 0x3f35f0e3
	v_fmaak_f32 v7, v6, v7, 0xbe11a98e
	v_fmaak_f32 v7, v6, v7, 0x3e027906
	v_mul_f32_e32 v6, v6, v7
	v_mul_f32_e32 v6, v8, v6
	v_mul_f32_e32 v7, v6, v5
	v_fma_f32 v6, -v6, v5, v5
	v_cmp_gt_f32_e32 vcc, 0, v5
	v_fma_f32 v5, |v2|, s92, 1.0
	v_rcp_f32_e32 v5, v5
	v_cndmask_b32_e32 v114, v6, v7, vcc
	v_mul_f32_e32 v7, v2, v2
	v_mul_f32_e32 v7, 0xbf38aa3b, v7
	v_fmamk_f32 v6, v5, 0x3f07dc22, v236
	v_fmaak_f32 v6, v5, v6, 0x3f35f0e3
	v_exp_f32_e32 v7, v7
	v_fmaak_f32 v6, v5, v6, 0xbe11a98e
	v_fmaak_f32 v6, v5, v6, 0x3e027906
	v_mul_f32_e32 v5, v5, v6
	v_mul_f32_e32 v5, v7, v5
	v_mul_f32_e32 v6, v5, v2
	v_fma_f32 v5, -v5, v2, v2
	v_cmp_gt_f32_e32 vcc, 0, v2
	s_waitcnt vmcnt(2)
	v_lshlrev_b32_e32 v2, 16, v3
	v_fma_f32 v3, |v2|, s92, 1.0
	v_rcp_f32_e32 v3, v3
	v_cndmask_b32_e32 v116, v5, v6, vcc
	v_mul_f32_e32 v6, v2, v2
	v_mul_f32_e32 v6, 0xbf38aa3b, v6
	v_fmamk_f32 v5, v3, 0x3f07dc22, v236
	v_fmaak_f32 v5, v3, v5, 0x3f35f0e3
	v_exp_f32_e32 v6, v6
	v_fmaak_f32 v5, v3, v5, 0xbe11a98e
	v_fmaak_f32 v5, v3, v5, 0x3e027906
	v_mul_f32_e32 v3, v3, v5
	v_mul_f32_e32 v3, v6, v3
	s_waitcnt vmcnt(1)
	v_lshlrev_b32_e32 v59, 16, v4
	v_mul_f32_e32 v5, v3, v2
	v_fma_f32 v3, -v3, v2, v2
	v_cmp_gt_f32_e32 vcc, 0, v2
	v_fma_f32 v2, |v59|, s92, 1.0
	v_rcp_f32_e32 v60, v2
	v_cndmask_b32_e32 v118, v3, v5, vcc
	v_mfma_f32_32x32x16_bf16 v[2:17], v[22:25], v[54:57], 0
	v_mul_f32_e32 v23, v59, v59
	v_fmamk_f32 v22, v60, 0x3f07dc22, v236
	v_mul_f32_e32 v23, 0xbf38aa3b, v23
	v_fmaak_f32 v22, v60, v22, 0x3f35f0e3
	v_exp_f32_e32 v23, v23
	v_fmaak_f32 v22, v60, v22, 0xbe11a98e
	v_fmaak_f32 v22, v60, v22, 0x3e027906
	v_mfma_f32_32x32x16_bf16 v[2:17], v[18:21], v[50:53], v[2:17]
	v_mul_f32_e32 v22, v60, v22
	v_mul_f32_e32 v22, v23, v22
	v_mul_f32_e32 v23, v22, v59
	v_fma_f32 v22, -v22, v59, v59
	v_cmp_gt_f32_e32 vcc, 0, v59
	s_nop 1
	v_cndmask_b32_e32 v24, v22, v23, vcc
	s_waitcnt vmcnt(0)
	v_lshlrev_b32_e32 v22, 16, v58
	v_fma_f32 v23, |v22|, s92, 1.0
	v_rcp_f32_e32 v23, v23
	v_mfma_f32_32x32x16_bf16 v[2:17], v[62:65], v[46:49], v[2:17]
	v_mul_f32_e32 v19, v22, v22
	v_mul_f32_e32 v19, 0xbf38aa3b, v19
	v_fmamk_f32 v18, v23, 0x3f07dc22, v236
	v_fmaak_f32 v18, v23, v18, 0x3f35f0e3
	v_exp_f32_e32 v19, v19
	v_fmaak_f32 v18, v23, v18, 0xbe11a98e
	v_fmaak_f32 v18, v23, v18, 0x3e027906
	v_mul_f32_e32 v18, v23, v18
	v_mul_f32_e32 v18, v19, v18
	v_mfma_f32_32x32x16_bf16 v[2:17], v[78:81], v[42:45], v[2:17]
	v_mul_f32_e32 v19, v18, v22
	v_fma_f32 v18, -v18, v22, v22
	v_cmp_gt_f32_e32 vcc, 0, v22
	v_lshlrev_b64 v[22:23], 11, v[130:131]
	v_lshl_add_u64 v[22:23], v[88:89], 0, v[22:23]
	v_cndmask_b32_e32 v25, v18, v19, vcc
	global_load_dwordx4 v[18:21], v[66:67], off offset:2048
	global_load_dwordx4 v[74:77], v[66:67], off offset:3072
	global_load_dwordx4 v[70:73], v[86:87], off
	s_nop 0
	global_load_dwordx4 v[66:69], v[86:87], off offset:1024
	global_load_dwordx4 v[62:65], v[86:87], off offset:2048
	global_load_dwordx4 v[58:61], v[86:87], off offset:3072
	ds_read_b128 v[124:127], v94 offset:128
	ds_read_b128 v[78:81], v94 offset:160
	v_or_b32_e32 v130, s5, v1
	v_readlane_b32 s5, v251, 49
	s_waitcnt lgkmcnt(1)
	v_add_f32_e32 v2, v2, v124
	v_mul_f32_e32 v2, v97, v2
	v_cvt_pk_bf16_f32 v2, v2, s0
	global_store_short v[22:23], v2, off sc1
	v_add_f32_e32 v2, v3, v125
	v_mul_f32_e32 v2, v99, v2
	v_cvt_pk_bf16_f32 v22, v2, s0
	v_lshlrev_b64 v[2:3], 11, v[130:131]
	v_lshl_add_u64 v[2:3], v[88:89], 0, v[2:3]
	global_store_short v[2:3], v22, off sc1
	v_add_f32_e32 v2, v4, v126
	v_mul_f32_e32 v2, v101, v2
	v_or_b32_e32 v130, s5, v1
	v_cvt_pk_bf16_f32 v4, v2, s0
	v_lshlrev_b64 v[2:3], 11, v[130:131]
	v_lshl_add_u64 v[2:3], v[88:89], 0, v[2:3]
	global_store_short v[2:3], v4, off sc1
	v_add_f32_e32 v2, v5, v127
	v_readlane_b32 s5, v251, 50
	v_mul_f32_e32 v2, v103, v2
	v_cvt_pk_bf16_f32 v4, v2, s0
	v_or_b32_e32 v130, s5, v1
	v_lshlrev_b64 v[2:3], 11, v[130:131]
	v_lshl_add_u64 v[2:3], v[88:89], 0, v[2:3]
	global_store_short v[2:3], v4, off sc1
	s_waitcnt lgkmcnt(0)
	v_add_f32_e32 v2, v6, v78
	v_readlane_b32 s5, v251, 51
	v_mul_f32_e32 v2, v105, v2
	v_cvt_pk_bf16_f32 v4, v2, s0
	v_or_b32_e32 v130, s5, v1
	v_lshlrev_b64 v[2:3], 11, v[130:131]
	v_lshl_add_u64 v[2:3], v[88:89], 0, v[2:3]
	global_store_short v[2:3], v4, off sc1
	v_add_f32_e32 v2, v7, v79
	v_readlane_b32 s5, v251, 52
	v_mul_f32_e32 v2, v107, v2
	v_cvt_pk_bf16_f32 v4, v2, s0
	v_or_b32_e32 v130, s5, v1
	v_lshlrev_b64 v[2:3], 11, v[130:131]
	v_lshl_add_u64 v[2:3], v[88:89], 0, v[2:3]
	global_store_short v[2:3], v4, off sc1
	v_add_f32_e32 v2, v8, v80
	v_readlane_b32 s5, v251, 53
	v_mul_f32_e32 v2, v108, v2
	v_cvt_pk_bf16_f32 v4, v2, s0
	v_or_b32_e32 v130, s5, v1
	v_lshlrev_b64 v[2:3], 11, v[130:131]
	v_lshl_add_u64 v[2:3], v[88:89], 0, v[2:3]
	global_store_short v[2:3], v4, off sc1
	v_add_f32_e32 v2, v9, v81
	v_mul_f32_e32 v2, v109, v2
	v_cvt_pk_bf16_f32 v8, v2, s0
	ds_read_b128 v[2:5], v94 offset:192
	v_readlane_b32 s5, v251, 54
	s_nop 1
	v_or_b32_e32 v130, s5, v1
	v_lshlrev_b64 v[6:7], 11, v[130:131]
	v_lshl_add_u64 v[6:7], v[88:89], 0, v[6:7]
	v_readlane_b32 s5, v251, 55
	global_store_short v[6:7], v8, off sc1
	ds_read_b128 v[6:9], v94 offset:224
	s_waitcnt lgkmcnt(1)
	v_add_f32_e32 v2, v10, v2
	v_or_b32_e32 v130, s5, v1
	v_mul_f32_e32 v2, v113, v2
	v_lshlrev_b64 v[22:23], 11, v[130:131]
	v_cvt_pk_bf16_f32 v2, v2, s0
	v_lshl_add_u64 v[22:23], v[88:89], 0, v[22:23]
	global_store_short v[22:23], v2, off sc1
	v_add_f32_e32 v2, v11, v3
	v_readlane_b32 s5, v251, 56
	v_mul_f32_e32 v2, v115, v2
	v_cvt_pk_bf16_f32 v10, v2, s0
	v_or_b32_e32 v130, s5, v1
	v_lshlrev_b64 v[2:3], 11, v[130:131]
	v_lshl_add_u64 v[2:3], v[88:89], 0, v[2:3]
	global_store_short v[2:3], v10, off sc1
	v_add_f32_e32 v2, v12, v4
	v_readlane_b32 s5, v251, 57
	v_mul_f32_e32 v2, v117, v2
	v_cvt_pk_bf16_f32 v4, v2, s0
	v_or_b32_e32 v130, s5, v1
	v_lshlrev_b64 v[2:3], 11, v[130:131]
	v_lshl_add_u64 v[2:3], v[88:89], 0, v[2:3]
	global_store_short v[2:3], v4, off sc1
	v_add_f32_e32 v2, v13, v5
	v_readlane_b32 s5, v251, 58
	v_mul_f32_e32 v2, v119, v2
	v_cvt_pk_bf16_f32 v4, v2, s0
	v_or_b32_e32 v130, s5, v1
	v_lshlrev_b64 v[2:3], 11, v[130:131]
	v_lshl_add_u64 v[2:3], v[88:89], 0, v[2:3]
	global_store_short v[2:3], v4, off sc1
	s_waitcnt lgkmcnt(0)
	v_add_f32_e32 v2, v14, v6
	v_readlane_b32 s5, v251, 59
	v_mul_f32_e32 v2, v120, v2
	v_cvt_pk_bf16_f32 v4, v2, s0
	v_or_b32_e32 v130, s5, v1
	v_lshlrev_b64 v[2:3], 11, v[130:131]
	v_lshl_add_u64 v[2:3], v[88:89], 0, v[2:3]
	global_store_short v[2:3], v4, off sc1
	v_add_f32_e32 v2, v15, v7
	v_readlane_b32 s5, v251, 60
	v_mul_f32_e32 v2, v121, v2
	v_cvt_pk_bf16_f32 v4, v2, s0
	v_or_b32_e32 v130, s5, v1
	v_lshlrev_b64 v[2:3], 11, v[130:131]
	v_lshl_add_u64 v[2:3], v[88:89], 0, v[2:3]
	global_store_short v[2:3], v4, off sc1
	v_add_f32_e32 v2, v16, v8
	v_readlane_b32 s5, v251, 61
	v_mul_f32_e32 v2, v122, v2
	v_cvt_pk_bf16_f32 v4, v2, s0
	v_or_b32_e32 v130, s5, v1
	v_lshlrev_b64 v[2:3], 11, v[130:131]
	v_lshl_add_u64 v[2:3], v[88:89], 0, v[2:3]
	global_store_short v[2:3], v4, off sc1
	v_add_f32_e32 v2, v17, v9
	v_readlane_b32 s5, v251, 62
	v_mul_f32_e32 v2, v123, v2
	v_cvt_pk_bf16_f32 v4, v2, s0
	v_or_b32_e32 v130, s5, v1
	v_lshlrev_b64 v[2:3], 11, v[130:131]
	v_lshl_add_u64 v[2:3], v[88:89], 0, v[2:3]
	global_store_short v[2:3], v4, off sc1
	v_or_b32_e32 v2, 0x60, v82
	v_mad_i64_i32 v[2:3], s[6:7], v2, s87, v[84:85]
	global_load_ushort v10, v[2:3], off
	v_or_b32_e32 v2, 0x61, v82
	v_mad_i64_i32 v[2:3], s[6:7], v2, s87, v[84:85]
	global_load_ushort v11, v[2:3], off
	v_or_b32_e32 v2, 0x62, v82
	v_mad_i64_i32 v[2:3], s[6:7], v2, s87, v[84:85]
	global_load_ushort v12, v[2:3], off
	v_or_b32_e32 v2, 0x63, v82
	v_mad_i64_i32 v[2:3], s[6:7], v2, s87, v[84:85]
	global_load_ushort v13, v[2:3], off
	v_or_b32_e32 v2, 0x68, v82
	v_or_b32_e32 v4, 0x69, v82
	v_mad_i64_i32 v[2:3], s[6:7], v2, s87, v[84:85]
	v_mad_i64_i32 v[4:5], s[6:7], v4, s87, v[84:85]
	v_or_b32_e32 v6, 0x6a, v82
	v_or_b32_e32 v8, 0x6b, v82
	v_mad_i64_i32 v[6:7], s[6:7], v6, s87, v[84:85]
	v_mad_i64_i32 v[8:9], s[6:7], v8, s87, v[84:85]
	global_load_ushort v2, v[2:3], off
	s_nop 0
	global_load_ushort v3, v[4:5], off
	s_nop 0
	global_load_ushort v4, v[6:7], off
	global_load_ushort v5, v[8:9], off
	v_readlane_b32 s5, v251, 63
	s_waitcnt vmcnt(7)
	v_lshlrev_b32_e32 v6, 16, v10
	v_fma_f32 v7, |v6|, s92, 1.0
	v_rcp_f32_e32 v7, v7
	v_mul_f32_e32 v9, v6, v6
	v_mul_f32_e32 v9, 0xbf38aa3b, v9
	v_exp_f32_e32 v9, v9
	v_fmamk_f32 v8, v7, 0x3f07dc22, v236
	v_fmaak_f32 v8, v7, v8, 0x3f35f0e3
	v_fmaak_f32 v8, v7, v8, 0xbe11a98e
	v_fmaak_f32 v8, v7, v8, 0x3e027906
	v_mul_f32_e32 v7, v7, v8
	v_mul_f32_e32 v7, v9, v7
	v_mul_f32_e32 v8, v7, v6
	v_fma_f32 v7, -v7, v6, v6
	v_cmp_gt_f32_e32 vcc, 0, v6
	s_waitcnt vmcnt(6)
	v_lshlrev_b32_e32 v6, 16, v11
	v_mul_f32_e32 v9, v6, v6
	v_cndmask_b32_e32 v78, v7, v8, vcc
	v_fma_f32 v7, |v6|, s92, 1.0
	v_rcp_f32_e32 v7, v7
	v_mul_f32_e32 v9, 0xbf38aa3b, v9
	v_exp_f32_e32 v9, v9
	v_cmp_gt_f32_e32 vcc, 0, v6
	v_fmamk_f32 v8, v7, 0x3f07dc22, v236
	v_fmaak_f32 v8, v7, v8, 0x3f35f0e3
	v_fmaak_f32 v8, v7, v8, 0xbe11a98e
	v_fmaak_f32 v8, v7, v8, 0x3e027906
	v_mul_f32_e32 v7, v7, v8
	v_mul_f32_e32 v7, v9, v7
	v_mul_f32_e32 v8, v7, v6
	v_fma_f32 v7, -v7, v6, v6
	s_waitcnt vmcnt(5)
	v_lshlrev_b32_e32 v6, 16, v12
	v_cndmask_b32_e32 v79, v7, v8, vcc
	v_fma_f32 v7, |v6|, s92, 1.0
	v_rcp_f32_e32 v7, v7
	v_mul_f32_e32 v9, v6, v6
	v_mul_f32_e32 v9, 0xbf38aa3b, v9
	v_exp_f32_e32 v9, v9
	v_fmamk_f32 v8, v7, 0x3f07dc22, v236
	v_fmaak_f32 v8, v7, v8, 0x3f35f0e3
	v_fmaak_f32 v8, v7, v8, 0xbe11a98e
	v_fmaak_f32 v8, v7, v8, 0x3e027906
	v_mul_f32_e32 v7, v7, v8
	v_mul_f32_e32 v7, v9, v7
	v_mul_f32_e32 v8, v7, v6
	v_fma_f32 v7, -v7, v6, v6
	v_cmp_gt_f32_e32 vcc, 0, v6
	s_waitcnt vmcnt(4)
	v_lshlrev_b32_e32 v6, 16, v13
	v_mul_f32_e32 v9, v6, v6
	v_cndmask_b32_e32 v80, v7, v8, vcc
	v_fma_f32 v7, |v6|, s92, 1.0
	v_rcp_f32_e32 v7, v7
	v_mul_f32_e32 v9, 0xbf38aa3b, v9
	v_exp_f32_e32 v9, v9
	s_waitcnt vmcnt(3)
	v_lshlrev_b32_e32 v2, 16, v2
	v_fmamk_f32 v8, v7, 0x3f07dc22, v236
	v_fmaak_f32 v8, v7, v8, 0x3f35f0e3
	v_fmaak_f32 v8, v7, v8, 0xbe11a98e
	v_fmaak_f32 v8, v7, v8, 0x3e027906
	v_mul_f32_e32 v7, v7, v8
	v_mul_f32_e32 v7, v9, v7
	v_mul_f32_e32 v8, v7, v6
	v_fma_f32 v7, -v7, v6, v6
	v_cmp_gt_f32_e32 vcc, 0, v6
	v_fma_f32 v6, |v2|, s92, 1.0
	v_rcp_f32_e32 v6, v6
	v_cndmask_b32_e32 v81, v7, v8, vcc
	v_mul_f32_e32 v8, v2, v2
	v_mul_f32_e32 v8, 0xbf38aa3b, v8
	v_fmamk_f32 v7, v6, 0x3f07dc22, v236
	v_fmaak_f32 v7, v6, v7, 0x3f35f0e3
	v_exp_f32_e32 v8, v8
	v_fmaak_f32 v7, v6, v7, 0xbe11a98e
	v_fmaak_f32 v7, v6, v7, 0x3e027906
	v_mul_f32_e32 v6, v6, v7
	v_mul_f32_e32 v6, v8, v6
	v_mul_f32_e32 v7, v6, v2
	v_fma_f32 v6, -v6, v2, v2
	v_cmp_gt_f32_e32 vcc, 0, v2
	s_waitcnt vmcnt(2)
	v_lshlrev_b32_e32 v2, 16, v3
	v_fma_f32 v3, |v2|, s92, 1.0
	v_rcp_f32_e32 v3, v3
	v_cndmask_b32_e32 v86, v6, v7, vcc
	v_mul_f32_e32 v7, v2, v2
	v_mul_f32_e32 v7, 0xbf38aa3b, v7
	v_fmamk_f32 v6, v3, 0x3f07dc22, v236
	v_fmaak_f32 v6, v3, v6, 0x3f35f0e3
	v_exp_f32_e32 v7, v7
	v_fmaak_f32 v6, v3, v6, 0xbe11a98e
	v_fmaak_f32 v6, v3, v6, 0x3e027906
	v_mul_f32_e32 v3, v3, v6
	v_mul_f32_e32 v3, v7, v3
	v_mul_f32_e32 v6, v3, v2
	v_fma_f32 v3, -v3, v2, v2
	v_cmp_gt_f32_e32 vcc, 0, v2
	s_waitcnt vmcnt(1)
	v_lshlrev_b32_e32 v2, 16, v4
	v_or_b32_e32 v8, 0x7b, v82
	v_cndmask_b32_e32 v87, v3, v6, vcc
	v_fma_f32 v3, |v2|, s92, 1.0
	v_rcp_f32_e32 v3, v3
	v_mul_f32_e32 v6, v2, v2
	v_mul_f32_e32 v6, 0xbf38aa3b, v6
	v_exp_f32_e32 v6, v6
	v_fmamk_f32 v4, v3, 0x3f07dc22, v236
	v_fmaak_f32 v4, v3, v4, 0x3f35f0e3
	v_fmaak_f32 v4, v3, v4, 0xbe11a98e
	v_fmaak_f32 v4, v3, v4, 0x3e027906
	v_mul_f32_e32 v3, v3, v4
	v_mul_f32_e32 v3, v6, v3
	v_mul_f32_e32 v4, v3, v2
	v_fma_f32 v3, -v3, v2, v2
	v_cmp_gt_f32_e32 vcc, 0, v2
	s_waitcnt vmcnt(0)
	v_lshlrev_b32_e32 v2, 16, v5
	v_mul_f32_e32 v5, v2, v2
	v_cndmask_b32_e32 v97, v3, v4, vcc
	v_fma_f32 v3, |v2|, s92, 1.0
	v_rcp_f32_e32 v3, v3
	v_mul_f32_e32 v5, 0xbf38aa3b, v5
	v_exp_f32_e32 v5, v5
	v_cmp_gt_f32_e32 vcc, 0, v2
	v_fmamk_f32 v4, v3, 0x3f07dc22, v236
	v_fmaak_f32 v4, v3, v4, 0x3f35f0e3
	v_fmaak_f32 v4, v3, v4, 0xbe11a98e
	v_fmaak_f32 v4, v3, v4, 0x3e027906
	v_mul_f32_e32 v3, v3, v4
	v_mul_f32_e32 v3, v5, v3
	v_mul_f32_e32 v4, v3, v2
	v_fma_f32 v3, -v3, v2, v2
	v_or_b32_e32 v2, 0x70, v82
	v_cndmask_b32_e32 v99, v3, v4, vcc
	v_mad_i64_i32 v[2:3], s[6:7], v2, s87, v[84:85]
	global_load_ushort v10, v[2:3], off
	v_or_b32_e32 v2, 0x71, v82
	v_mad_i64_i32 v[2:3], s[6:7], v2, s87, v[84:85]
	global_load_ushort v11, v[2:3], off
	v_or_b32_e32 v2, 0x72, v82
	v_mad_i64_i32 v[2:3], s[6:7], v2, s87, v[84:85]
	global_load_ushort v12, v[2:3], off
	v_or_b32_e32 v2, 0x73, v82
	v_mad_i64_i32 v[2:3], s[6:7], v2, s87, v[84:85]
	global_load_ushort v13, v[2:3], off
	v_or_b32_e32 v2, 0x78, v82
	v_or_b32_e32 v4, 0x79, v82
	v_mad_i64_i32 v[2:3], s[6:7], v2, s87, v[84:85]
	v_mad_i64_i32 v[4:5], s[6:7], v4, s87, v[84:85]
	v_or_b32_e32 v6, 0x7a, v82
	v_mad_i64_i32 v[6:7], s[6:7], v6, s87, v[84:85]
	v_mad_i64_i32 v[8:9], s[6:7], v8, s87, v[84:85]
	global_load_ushort v2, v[2:3], off
	s_nop 0
	global_load_ushort v3, v[4:5], off
	s_nop 0
	global_load_ushort v4, v[6:7], off
	global_load_ushort v5, v[8:9], off
	v_or_b32_e32 v130, s5, v1
	v_readlane_b32 s5, v252, 0
	v_readlane_b32 s6, v250, 27
	v_readlane_b32 s7, v250, 28
	s_waitcnt vmcnt(7)
	v_lshlrev_b32_e32 v6, 16, v10
	v_fma_f32 v7, |v6|, s92, 1.0
	v_rcp_f32_e32 v7, v7
	v_mul_f32_e32 v9, v6, v6
	v_mul_f32_e32 v9, 0xbf38aa3b, v9
	v_exp_f32_e32 v9, v9
	v_fmamk_f32 v8, v7, 0x3f07dc22, v236
	v_fmaak_f32 v8, v7, v8, 0x3f35f0e3
	v_fmaak_f32 v8, v7, v8, 0xbe11a98e
	v_fmaak_f32 v8, v7, v8, 0x3e027906
	v_mul_f32_e32 v7, v7, v8
	v_mul_f32_e32 v7, v9, v7
	v_mul_f32_e32 v8, v7, v6
	v_fma_f32 v7, -v7, v6, v6
	v_cmp_gt_f32_e32 vcc, 0, v6
	s_waitcnt vmcnt(6)
	v_lshlrev_b32_e32 v6, 16, v11
	v_mul_f32_e32 v9, v6, v6
	v_cndmask_b32_e32 v82, v7, v8, vcc
	v_fma_f32 v7, |v6|, s92, 1.0
	v_rcp_f32_e32 v7, v7
	v_mul_f32_e32 v9, 0xbf38aa3b, v9
	v_exp_f32_e32 v9, v9
	v_cmp_gt_f32_e32 vcc, 0, v6
	v_fmamk_f32 v8, v7, 0x3f07dc22, v236
	v_fmaak_f32 v8, v7, v8, 0x3f35f0e3
	v_fmaak_f32 v8, v7, v8, 0xbe11a98e
	v_fmaak_f32 v8, v7, v8, 0x3e027906
	v_mul_f32_e32 v7, v7, v8
	v_mul_f32_e32 v7, v9, v7
	v_mul_f32_e32 v8, v7, v6
	v_fma_f32 v7, -v7, v6, v6
	s_waitcnt vmcnt(5)
	v_lshlrev_b32_e32 v6, 16, v12
	v_cndmask_b32_e32 v84, v7, v8, vcc
	v_fma_f32 v7, |v6|, s92, 1.0
	v_rcp_f32_e32 v7, v7
	v_mul_f32_e32 v9, v6, v6
	v_mul_f32_e32 v9, 0xbf38aa3b, v9
	v_exp_f32_e32 v9, v9
	v_fmamk_f32 v8, v7, 0x3f07dc22, v236
	v_fmaak_f32 v8, v7, v8, 0x3f35f0e3
	v_fmaak_f32 v8, v7, v8, 0xbe11a98e
	v_fmaak_f32 v8, v7, v8, 0x3e027906
	v_mul_f32_e32 v7, v7, v8
	v_mul_f32_e32 v7, v9, v7
	v_mul_f32_e32 v8, v7, v6
	v_fma_f32 v7, -v7, v6, v6
	v_cmp_gt_f32_e32 vcc, 0, v6
	s_waitcnt vmcnt(4)
	v_lshlrev_b32_e32 v6, 16, v13
	v_mul_f32_e32 v9, v6, v6
	v_cndmask_b32_e32 v85, v7, v8, vcc
	v_fma_f32 v7, |v6|, s92, 1.0
	v_rcp_f32_e32 v7, v7
	v_mul_f32_e32 v9, 0xbf38aa3b, v9
	v_exp_f32_e32 v9, v9
	s_waitcnt vmcnt(3)
	v_lshlrev_b32_e32 v2, 16, v2
	v_fmamk_f32 v8, v7, 0x3f07dc22, v236
	v_fmaak_f32 v8, v7, v8, 0x3f35f0e3
	v_fmaak_f32 v8, v7, v8, 0xbe11a98e
	v_fmaak_f32 v8, v7, v8, 0x3e027906
	v_mul_f32_e32 v7, v7, v8
	v_mul_f32_e32 v7, v9, v7
	v_mul_f32_e32 v8, v7, v6
	v_fma_f32 v7, -v7, v6, v6
	v_cmp_gt_f32_e32 vcc, 0, v6
	v_fma_f32 v6, |v2|, s92, 1.0
	v_rcp_f32_e32 v6, v6
	v_cndmask_b32_e32 v101, v7, v8, vcc
	v_mul_f32_e32 v8, v2, v2
	v_mul_f32_e32 v8, 0xbf38aa3b, v8
	v_fmamk_f32 v7, v6, 0x3f07dc22, v236
	v_fmaak_f32 v7, v6, v7, 0x3f35f0e3
	v_exp_f32_e32 v8, v8
	v_fmaak_f32 v7, v6, v7, 0xbe11a98e
	v_fmaak_f32 v7, v6, v7, 0x3e027906
	v_mul_f32_e32 v6, v6, v7
	v_mul_f32_e32 v6, v8, v6
	v_mul_f32_e32 v7, v6, v2
	v_fma_f32 v6, -v6, v2, v2
	v_cmp_gt_f32_e32 vcc, 0, v2
	s_waitcnt vmcnt(2)
	v_lshlrev_b32_e32 v2, 16, v3
	v_fma_f32 v3, |v2|, s92, 1.0
	v_rcp_f32_e32 v3, v3
	v_cndmask_b32_e32 v107, v6, v7, vcc
	v_mul_f32_e32 v7, v2, v2
	v_mul_f32_e32 v7, 0xbf38aa3b, v7
	v_fmamk_f32 v6, v3, 0x3f07dc22, v236
	v_fmaak_f32 v6, v3, v6, 0x3f35f0e3
	v_exp_f32_e32 v7, v7
	v_fmaak_f32 v6, v3, v6, 0xbe11a98e
	v_fmaak_f32 v6, v3, v6, 0x3e027906
	v_mul_f32_e32 v3, v3, v6
	v_mul_f32_e32 v3, v7, v3
	v_mul_f32_e32 v6, v3, v2
	v_fma_f32 v3, -v3, v2, v2
	v_cmp_gt_f32_e32 vcc, 0, v2
	s_waitcnt vmcnt(1)
	v_lshlrev_b32_e32 v2, 16, v4
	v_mfma_f32_32x32x16_bf16 v[8:23], v[18:21], v[54:57], 0
	v_cndmask_b32_e32 v108, v3, v6, vcc
	v_fma_f32 v3, |v2|, s92, 1.0
	v_rcp_f32_e32 v3, v3
	v_mul_f32_e32 v6, v2, v2
	v_mul_f32_e32 v6, 0xbf38aa3b, v6
	v_exp_f32_e32 v6, v6
	v_fmamk_f32 v4, v3, 0x3f07dc22, v236
	v_fmaak_f32 v4, v3, v4, 0x3f35f0e3
	v_fmaak_f32 v4, v3, v4, 0xbe11a98e
	v_fmaak_f32 v4, v3, v4, 0x3e027906
	v_mfma_f32_32x32x16_bf16 v[8:23], v[74:77], v[50:53], v[8:23]
	v_mul_f32_e32 v3, v3, v4
	v_mul_f32_e32 v3, v6, v3
	v_mul_f32_e32 v4, v3, v2
	v_fma_f32 v3, -v3, v2, v2
	v_cmp_gt_f32_e32 vcc, 0, v2
	s_waitcnt vmcnt(0)
	v_lshlrev_b32_e32 v2, 16, v5
	v_mul_f32_e32 v5, v2, v2
	v_cndmask_b32_e32 v109, v3, v4, vcc
	v_fma_f32 v3, |v2|, s92, 1.0
	v_rcp_f32_e32 v3, v3
	v_mfma_f32_32x32x16_bf16 v[8:23], v[70:73], v[46:49], v[8:23]
	v_mul_f32_e32 v5, 0xbf38aa3b, v5
	v_exp_f32_e32 v5, v5
	v_fmamk_f32 v4, v3, 0x3f07dc22, v236
	v_fmaak_f32 v4, v3, v4, 0x3f35f0e3
	v_fmaak_f32 v4, v3, v4, 0xbe11a98e
	v_fmaak_f32 v4, v3, v4, 0x3e027906
	v_mul_f32_e32 v3, v3, v4
	v_mul_f32_e32 v3, v5, v3
	v_mul_f32_e32 v4, v3, v2
	v_fma_f32 v3, -v3, v2, v2
	v_cmp_gt_f32_e32 vcc, 0, v2
	v_mfma_f32_32x32x16_bf16 v[8:23], v[66:69], v[42:45], v[8:23]
	s_nop 0
	v_cndmask_b32_e32 v113, v3, v4, vcc
	global_load_dwordx4 v[2:5], v[92:93], off offset:-4096
	global_load_dwordx4 v[66:69], v[90:91], off offset:1024
	global_load_dwordx4 v[70:73], v[90:91], off offset:2048
	s_and_b64 vcc, exec, s[6:7]
	v_mfma_f32_32x32x16_bf16 v[8:23], v[62:65], v[38:41], v[8:23]
	global_load_dwordx4 v[62:65], v[90:91], off offset:3072
	global_load_dwordx4 v[74:77], v[92:93], off
	global_load_dwordx4 v[120:123], v[92:93], off offset:1024
	global_load_dwordx4 v[124:127], v[92:93], off offset:2048
	s_nop 0
	global_load_dwordx4 v[90:93], v[92:93], off offset:3072
	ds_read_b128 v[132:135], v94 offset:256
	v_mfma_f32_32x32x16_bf16 v[8:23], v[58:61], v[34:37], v[8:23]
	ds_read_b128 v[58:61], v94 offset:288
	s_waitcnt lgkmcnt(1)
	s_nop 9
	v_add_f32_e32 v6, v8, v132
	v_mul_f32_e32 v6, v83, v6
	v_cvt_pk_bf16_f32 v8, v6, s0
	v_lshlrev_b64 v[6:7], 11, v[130:131]
	v_lshl_add_u64 v[6:7], v[88:89], 0, v[6:7]
	global_store_short v[6:7], v8, off sc1
	v_add_f32_e32 v6, v9, v133
	v_mul_f32_e32 v6, v95, v6
	v_or_b32_e32 v130, s5, v1
	v_cvt_pk_bf16_f32 v8, v6, s0
	v_lshlrev_b64 v[6:7], 11, v[130:131]
	v_lshl_add_u64 v[6:7], v[88:89], 0, v[6:7]
	global_store_short v[6:7], v8, off sc1
	v_add_f32_e32 v6, v10, v134
	v_readlane_b32 s5, v252, 1
	v_mul_f32_e32 v6, v96, v6
	v_cvt_pk_bf16_f32 v8, v6, s0
	v_or_b32_e32 v130, s5, v1
	v_lshlrev_b64 v[6:7], 11, v[130:131]
	v_lshl_add_u64 v[6:7], v[88:89], 0, v[6:7]
	global_store_short v[6:7], v8, off sc1
	v_add_f32_e32 v6, v11, v135
	v_readlane_b32 s5, v252, 2
	v_mul_f32_e32 v6, v98, v6
	v_cvt_pk_bf16_f32 v8, v6, s0
	v_or_b32_e32 v130, s5, v1
	v_lshlrev_b64 v[6:7], 11, v[130:131]
	v_lshl_add_u64 v[6:7], v[88:89], 0, v[6:7]
	global_store_short v[6:7], v8, off sc1
	s_waitcnt lgkmcnt(0)
	v_add_f32_e32 v6, v12, v58
	v_readlane_b32 s5, v252, 3
	v_mul_f32_e32 v6, v100, v6
	v_cvt_pk_bf16_f32 v8, v6, s0
	v_or_b32_e32 v130, s5, v1
	v_lshlrev_b64 v[6:7], 11, v[130:131]
	v_lshl_add_u64 v[6:7], v[88:89], 0, v[6:7]
	global_store_short v[6:7], v8, off sc1
	v_add_f32_e32 v6, v13, v59
	v_readlane_b32 s5, v252, 4
	v_mul_f32_e32 v6, v102, v6
	v_cvt_pk_bf16_f32 v8, v6, s0
	v_or_b32_e32 v130, s5, v1
	v_lshlrev_b64 v[6:7], 11, v[130:131]
	v_lshl_add_u64 v[6:7], v[88:89], 0, v[6:7]
	global_store_short v[6:7], v8, off sc1
	v_add_f32_e32 v6, v14, v60
	v_readlane_b32 s5, v252, 5
	v_mul_f32_e32 v6, v104, v6
	v_cvt_pk_bf16_f32 v8, v6, s0
	v_or_b32_e32 v130, s5, v1
	v_lshlrev_b64 v[6:7], 11, v[130:131]
	v_lshl_add_u64 v[6:7], v[88:89], 0, v[6:7]
	global_store_short v[6:7], v8, off sc1
	v_add_f32_e32 v6, v15, v61
	ds_read_b128 v[58:61], v94 offset:320
	ds_read_b128 v[102:105], v94 offset:352
	v_readlane_b32 s5, v252, 6
	v_mul_f32_e32 v6, v106, v6
	v_cvt_pk_bf16_f32 v8, v6, s0
	v_or_b32_e32 v130, s5, v1
	v_lshlrev_b64 v[6:7], 11, v[130:131]
	v_lshl_add_u64 v[6:7], v[88:89], 0, v[6:7]
	global_store_short v[6:7], v8, off sc1
	s_waitcnt lgkmcnt(1)
	v_add_f32_e32 v6, v16, v58
	v_readlane_b32 s5, v252, 7
	v_mul_f32_e32 v6, v110, v6
	v_cvt_pk_bf16_f32 v8, v6, s0
	v_or_b32_e32 v130, s5, v1
	v_lshlrev_b64 v[6:7], 11, v[130:131]
	v_lshl_add_u64 v[6:7], v[88:89], 0, v[6:7]
	global_store_short v[6:7], v8, off sc1
	v_add_f32_e32 v6, v17, v59
	v_mul_f32_e32 v58, v111, v6
	s_waitcnt vmcnt(16)
	v_mfma_f32_32x32x16_bf16 v[2:17], v[2:5], v[54:57], 0
	v_readlane_b32 s5, v252, 8
	v_add_f32_e32 v18, v18, v60
	v_mul_f32_e32 v18, v112, v18
	v_or_b32_e32 v130, s5, v1
	v_readlane_b32 s5, v252, 9
	v_lshlrev_b64 v[54:55], 11, v[130:131]
	v_cvt_pk_bf16_f32 v18, v18, s0
	s_waitcnt vmcnt(15)
	v_mfma_f32_32x32x16_bf16 v[2:17], v[66:69], v[50:53], v[2:17]
	v_or_b32_e32 v130, s5, v1
	v_lshlrev_b64 v[50:51], 11, v[130:131]
	v_lshl_add_u64 v[50:51], v[88:89], 0, v[50:51]
	global_store_short v[50:51], v18, off sc1
	v_add_f32_e32 v18, v19, v61
	v_readlane_b32 s5, v252, 10
	v_mul_f32_e32 v18, v114, v18
	s_waitcnt vmcnt(15)
	v_mfma_f32_32x32x16_bf16 v[2:17], v[70:73], v[46:49], v[2:17]
	v_or_b32_e32 v130, s5, v1
	v_cvt_pk_bf16_f32 v46, v18, s0
	v_lshlrev_b64 v[18:19], 11, v[130:131]
	v_lshl_add_u64 v[18:19], v[88:89], 0, v[18:19]
	global_store_short v[18:19], v46, off sc1
	s_waitcnt lgkmcnt(0)
	v_add_f32_e32 v18, v20, v102
	v_readlane_b32 s5, v252, 11
	s_waitcnt vmcnt(15)
	v_mfma_f32_32x32x16_bf16 v[2:17], v[62:65], v[42:45], v[2:17]
	v_mul_f32_e32 v18, v116, v18
	v_or_b32_e32 v130, s5, v1
	v_cvt_pk_bf16_f32 v20, v18, s0
	v_lshlrev_b64 v[18:19], 11, v[130:131]
	v_lshl_add_u64 v[18:19], v[88:89], 0, v[18:19]
	global_store_short v[18:19], v20, off sc1
	v_add_f32_e32 v18, v21, v103
	s_waitcnt vmcnt(15)
	v_mfma_f32_32x32x16_bf16 v[2:17], v[74:77], v[38:41], v[2:17]
	v_readlane_b32 s5, v252, 12
	v_mul_f32_e32 v18, v118, v18
	v_cvt_pk_bf16_f32 v20, v18, s0
	v_or_b32_e32 v130, s5, v1
	v_lshlrev_b64 v[18:19], 11, v[130:131]
	v_lshl_add_u64 v[18:19], v[88:89], 0, v[18:19]
	global_store_short v[18:19], v20, off sc1
	s_waitcnt vmcnt(15)
	v_mfma_f32_32x32x16_bf16 v[2:17], v[120:123], v[34:37], v[2:17]
	v_add_f32_e32 v18, v22, v104
	v_readlane_b32 s5, v252, 13
	v_mul_f32_e32 v18, v24, v18
	v_cvt_pk_bf16_f32 v20, v18, s0
	v_or_b32_e32 v130, s5, v1
	v_lshlrev_b64 v[18:19], 11, v[130:131]
	v_lshl_add_u64 v[18:19], v[88:89], 0, v[18:19]
	s_waitcnt vmcnt(14)
	v_mfma_f32_32x32x16_bf16 v[2:17], v[124:127], v[30:33], v[2:17]
	global_store_short v[18:19], v20, off sc1
	v_add_f32_e32 v18, v23, v105
	v_readlane_b32 s5, v252, 14
	v_mul_f32_e32 v18, v25, v18
	v_cvt_pk_bf16_f32 v20, v18, s0
	v_or_b32_e32 v130, s5, v1
	v_lshlrev_b64 v[18:19], 11, v[130:131]
	v_cvt_pk_bf16_f32 v56, v58, s0
	v_lshl_add_u64 v[54:55], v[88:89], 0, v[54:55]
	v_lshl_add_u64 v[18:19], v[88:89], 0, v[18:19]
	s_waitcnt vmcnt(14)
	v_mfma_f32_32x32x16_bf16 v[2:17], v[90:93], v[26:29], v[2:17]
	global_store_short v[54:55], v56, off sc1
	global_store_short v[18:19], v20, off sc1
	ds_read_b128 v[18:21], v94 offset:384
	ds_read_b128 v[22:25], v94 offset:416
	v_readlane_b32 s5, v252, 15
	s_waitcnt lgkmcnt(1)
	s_nop 5
	v_add_f32_e32 v2, v2, v18
	v_or_b32_e32 v130, s5, v1
	v_mul_f32_e32 v2, v78, v2
	v_lshlrev_b64 v[26:27], 11, v[130:131]
	v_cvt_pk_bf16_f32 v2, v2, s0
	v_lshl_add_u64 v[26:27], v[88:89], 0, v[26:27]
	global_store_short v[26:27], v2, off sc1
	v_add_f32_e32 v2, v3, v19
	v_readlane_b32 s5, v252, 16
	v_mul_f32_e32 v2, v79, v2
	v_cvt_pk_bf16_f32 v18, v2, s0
	v_or_b32_e32 v130, s5, v1
	v_lshlrev_b64 v[2:3], 11, v[130:131]
	v_lshl_add_u64 v[2:3], v[88:89], 0, v[2:3]
	global_store_short v[2:3], v18, off sc1
	v_add_f32_e32 v2, v4, v20
	v_readlane_b32 s5, v252, 17
	v_mul_f32_e32 v2, v80, v2
	v_cvt_pk_bf16_f32 v4, v2, s0
	v_or_b32_e32 v130, s5, v1
	v_lshlrev_b64 v[2:3], 11, v[130:131]
	v_lshl_add_u64 v[2:3], v[88:89], 0, v[2:3]
	global_store_short v[2:3], v4, off sc1
	v_add_f32_e32 v2, v5, v21
	v_readlane_b32 s5, v252, 18
	v_mul_f32_e32 v2, v81, v2
	v_cvt_pk_bf16_f32 v4, v2, s0
	v_or_b32_e32 v130, s5, v1
	v_lshlrev_b64 v[2:3], 11, v[130:131]
	v_lshl_add_u64 v[2:3], v[88:89], 0, v[2:3]
	global_store_short v[2:3], v4, off sc1
	s_waitcnt lgkmcnt(0)
	v_add_f32_e32 v2, v6, v22
	v_readlane_b32 s5, v252, 19
	v_mul_f32_e32 v2, v86, v2
	v_cvt_pk_bf16_f32 v4, v2, s0
	v_or_b32_e32 v130, s5, v1
	v_lshlrev_b64 v[2:3], 11, v[130:131]
	v_lshl_add_u64 v[2:3], v[88:89], 0, v[2:3]
	global_store_short v[2:3], v4, off sc1
	v_add_f32_e32 v2, v7, v23
	v_readlane_b32 s5, v252, 20
	v_mul_f32_e32 v2, v87, v2
	v_cvt_pk_bf16_f32 v4, v2, s0
	v_or_b32_e32 v130, s5, v1
	v_lshlrev_b64 v[2:3], 11, v[130:131]
	v_lshl_add_u64 v[2:3], v[88:89], 0, v[2:3]
	global_store_short v[2:3], v4, off sc1
	v_add_f32_e32 v2, v8, v24
	v_readlane_b32 s5, v252, 21
	v_mul_f32_e32 v2, v97, v2
	v_cvt_pk_bf16_f32 v4, v2, s0
	v_or_b32_e32 v130, s5, v1
	v_lshlrev_b64 v[2:3], 11, v[130:131]
	v_lshl_add_u64 v[2:3], v[88:89], 0, v[2:3]
	global_store_short v[2:3], v4, off sc1
	v_add_f32_e32 v2, v9, v25
	v_mul_f32_e32 v2, v99, v2
	v_cvt_pk_bf16_f32 v8, v2, s0
	ds_read_b128 v[2:5], v94 offset:448
	v_readlane_b32 s5, v252, 22
	s_nop 1
	v_or_b32_e32 v130, s5, v1
	v_lshlrev_b64 v[6:7], 11, v[130:131]
	v_lshl_add_u64 v[6:7], v[88:89], 0, v[6:7]
	v_readlane_b32 s5, v252, 23
	global_store_short v[6:7], v8, off sc1
	ds_read_b128 v[6:9], v94 offset:480
	s_waitcnt lgkmcnt(1)
	v_add_f32_e32 v2, v10, v2
	v_or_b32_e32 v130, s5, v1
	v_mul_f32_e32 v2, v82, v2
	v_lshlrev_b64 v[18:19], 11, v[130:131]
	v_cvt_pk_bf16_f32 v2, v2, s0
	v_lshl_add_u64 v[18:19], v[88:89], 0, v[18:19]
	global_store_short v[18:19], v2, off sc1
	v_add_f32_e32 v2, v11, v3
	v_readlane_b32 s5, v252, 24
	v_mul_f32_e32 v2, v84, v2
	v_cvt_pk_bf16_f32 v10, v2, s0
	v_or_b32_e32 v130, s5, v1
	v_lshlrev_b64 v[2:3], 11, v[130:131]
	v_lshl_add_u64 v[2:3], v[88:89], 0, v[2:3]
	global_store_short v[2:3], v10, off sc1
	v_add_f32_e32 v2, v12, v4
	v_readlane_b32 s5, v252, 25
	v_mul_f32_e32 v2, v85, v2
	v_cvt_pk_bf16_f32 v4, v2, s0
	v_or_b32_e32 v130, s5, v1
	v_lshlrev_b64 v[2:3], 11, v[130:131]
	v_lshl_add_u64 v[2:3], v[88:89], 0, v[2:3]
	global_store_short v[2:3], v4, off sc1
	v_add_f32_e32 v2, v13, v5
	v_readlane_b32 s5, v252, 26
	v_mul_f32_e32 v2, v101, v2
	v_cvt_pk_bf16_f32 v4, v2, s0
	v_or_b32_e32 v130, s5, v1
	v_lshlrev_b64 v[2:3], 11, v[130:131]
	v_lshl_add_u64 v[2:3], v[88:89], 0, v[2:3]
	global_store_short v[2:3], v4, off sc1
	s_waitcnt lgkmcnt(0)
	v_add_f32_e32 v2, v14, v6
	v_readlane_b32 s5, v252, 27
	v_mul_f32_e32 v2, v107, v2
	v_cvt_pk_bf16_f32 v4, v2, s0
	v_or_b32_e32 v130, s5, v1
	v_lshlrev_b64 v[2:3], 11, v[130:131]
	v_lshl_add_u64 v[2:3], v[88:89], 0, v[2:3]
	global_store_short v[2:3], v4, off sc1
	v_add_f32_e32 v2, v15, v7
	v_readlane_b32 s5, v252, 28
	v_mul_f32_e32 v2, v108, v2
	v_cvt_pk_bf16_f32 v4, v2, s0
	v_or_b32_e32 v130, s5, v1
	v_lshlrev_b64 v[2:3], 11, v[130:131]
	v_lshl_add_u64 v[2:3], v[88:89], 0, v[2:3]
	global_store_short v[2:3], v4, off sc1
	v_add_f32_e32 v2, v16, v8
	v_readlane_b32 s5, v252, 29
	v_mul_f32_e32 v2, v109, v2
	v_cvt_pk_bf16_f32 v4, v2, s0
	v_or_b32_e32 v130, s5, v1
	v_lshlrev_b64 v[2:3], 11, v[130:131]
	v_lshl_add_u64 v[2:3], v[88:89], 0, v[2:3]
	global_store_short v[2:3], v4, off sc1
	v_add_f32_e32 v2, v17, v9
	v_readlane_b32 s5, v252, 30
	v_mul_f32_e32 v2, v113, v2
	v_cvt_pk_bf16_f32 v4, v2, s0
	v_or_b32_e32 v130, s5, v1
	v_lshlrev_b64 v[2:3], 11, v[130:131]
	v_lshl_add_u64 v[2:3], v[88:89], 0, v[2:3]
	global_store_short v[2:3], v4, off sc1
	s_barrier
	s_cbranch_vccz .LBB0_314
	v_readlane_b32 s6, v253, 48
	v_mov_b32_e32 v1, v242
	v_readlane_b32 s7, v253, 49
	s_andn2_b64 vcc, exec, s[6:7]
	v_readfirstlane_b32 s5, v1
	s_cbranch_vccnz .LBB0_313
	s_load_dwordx8 s[44:51], s[0:1], 0x38
	v_mov_b32_e32 v2, 2
	v_lshlrev_b32_sdwa v130, v2, v1 dst_sel:DWORD dst_unused:UNUSED_PAD src0_sel:DWORD src1_sel:BYTE_0
	v_readlane_b32 s8, v254, 39
	v_readlane_b32 s9, v254, 40
	s_waitcnt lgkmcnt(0)
	v_lshl_add_u64 v[2:3], s[44:45], 0, v[130:131]
	v_lshl_add_u64 v[4:5], v[2:3], 0, s[62:63]
	global_load_dword v42, v[4:5], off
	v_lshl_add_u64 v[4:5], v[2:3], 0, s[8:9]
	v_readlane_b32 s8, v254, 41
	v_readlane_b32 s9, v254, 42
	global_load_dword v43, v[4:5], off
	s_ashr_i32 s6, s5, 6
	v_lshl_add_u64 v[4:5], v[2:3], 0, s[8:9]
	v_readlane_b32 s8, v254, 43
	v_readlane_b32 s9, v254, 44
	global_load_dword v45, v[4:5], off
	v_mov_b32_e32 v10, s46
	v_lshl_add_u64 v[4:5], v[2:3], 0, s[8:9]
	v_readlane_b32 s8, v254, 45
	v_readlane_b32 s9, v254, 46
	global_load_dword v47, v[4:5], off
	v_mov_b32_e32 v11, s47
	v_lshl_add_u64 v[4:5], v[2:3], 0, s[8:9]
	v_readlane_b32 s8, v254, 47
	v_readlane_b32 s9, v254, 48
	global_load_dword v49, v[4:5], off
	v_readlane_b32 s57, v253, 32
	v_lshl_add_u64 v[4:5], v[2:3], 0, s[8:9]
	v_readlane_b32 s8, v254, 49
	v_readlane_b32 s9, v254, 50
	global_load_dword v51, v[4:5], off
	s_mov_b32 s58, s2
	v_lshl_add_u64 v[4:5], v[2:3], 0, s[8:9]
	v_readlane_b32 s8, v254, 51
	v_readlane_b32 s9, v254, 52
	global_load_dword v53, v[4:5], off
	s_waitcnt vmcnt(5)
	v_mov_b32_e32 v44, v43
	v_lshl_add_u64 v[4:5], v[2:3], 0, s[8:9]
	v_readlane_b32 s8, v254, 53
	v_readlane_b32 s9, v254, 54
	global_load_dword v55, v[4:5], off
	s_waitcnt vmcnt(5)
	v_mov_b32_e32 v46, v45
	v_lshl_add_u64 v[4:5], v[2:3], 0, s[8:9]
	v_readlane_b32 s8, v254, 55
	v_readlane_b32 s9, v254, 56
	global_load_dword v57, v[4:5], off
	s_waitcnt vmcnt(5)
	v_mov_b32_e32 v48, v47
	v_lshl_add_u64 v[4:5], v[2:3], 0, s[8:9]
	v_readlane_b32 s8, v254, 57
	v_readlane_b32 s9, v254, 58
	global_load_dword v59, v[4:5], off
	s_waitcnt vmcnt(5)
	v_mov_b32_e32 v50, v49
	v_lshl_add_u64 v[4:5], v[2:3], 0, s[8:9]
	v_readlane_b32 s8, v254, 59
	v_readlane_b32 s9, v254, 60
	global_load_dword v61, v[4:5], off
	s_waitcnt vmcnt(5)
	v_mov_b32_e32 v52, v51
	v_lshl_add_u64 v[4:5], v[2:3], 0, s[8:9]
	v_readlane_b32 s8, v254, 61
	v_readlane_b32 s9, v254, 62
	global_load_dword v63, v[4:5], off
	s_waitcnt vmcnt(5)
	v_mov_b32_e32 v54, v53
	v_lshl_add_u64 v[4:5], v[2:3], 0, s[8:9]
	v_readlane_b32 s8, v254, 63
	v_readlane_b32 s9, v255, 0
	global_load_dword v65, v[4:5], off
	s_waitcnt vmcnt(5)
	v_mov_b32_e32 v56, v55
	v_lshl_add_u64 v[4:5], v[2:3], 0, s[8:9]
	v_readlane_b32 s8, v255, 1
	v_readlane_b32 s9, v255, 2
	global_load_dword v67, v[4:5], off
	s_waitcnt vmcnt(5)
	v_mov_b32_e32 v58, v57
	v_lshl_add_u64 v[4:5], v[2:3], 0, s[8:9]
	v_readlane_b32 s8, v255, 3
	v_readlane_b32 s9, v255, 4
	global_load_dword v69, v[4:5], off
	s_waitcnt vmcnt(5)
	v_mov_b32_e32 v60, v59
	v_lshl_add_u64 v[4:5], v[2:3], 0, s[8:9]
	v_readlane_b32 s8, v255, 5
	v_readlane_b32 s9, v255, 6
	global_load_dword v71, v[4:5], off
	s_waitcnt vmcnt(5)
	v_mov_b32_e32 v62, v61
	v_lshl_add_u64 v[4:5], v[2:3], 0, s[8:9]
	v_readlane_b32 s8, v255, 7
	v_readlane_b32 s9, v255, 8
	global_load_dword v73, v[4:5], off
	s_waitcnt vmcnt(5)
	v_mov_b32_e32 v64, v63
	v_lshl_add_u64 v[4:5], v[2:3], 0, s[8:9]
	v_readlane_b32 s8, v255, 9
	v_readlane_b32 s9, v255, 10
	global_load_dword v75, v[4:5], off
	s_waitcnt vmcnt(5)
	v_mov_b32_e32 v66, v65
	v_lshl_add_u64 v[4:5], v[2:3], 0, s[8:9]
	v_readlane_b32 s8, v255, 11
	v_readlane_b32 s9, v255, 12
	global_load_dword v77, v[4:5], off
	s_waitcnt vmcnt(5)
	v_mov_b32_e32 v68, v67
	v_lshl_add_u64 v[4:5], v[2:3], 0, s[8:9]
	v_readlane_b32 s8, v255, 13
	v_readlane_b32 s9, v255, 14
	global_load_dword v79, v[4:5], off
	s_waitcnt vmcnt(5)
	v_mov_b32_e32 v70, v69
	v_lshl_add_u64 v[4:5], v[2:3], 0, s[8:9]
	v_readlane_b32 s8, v255, 15
	v_readlane_b32 s9, v255, 16
	global_load_dword v81, v[4:5], off
	s_waitcnt vmcnt(5)
	v_mov_b32_e32 v72, v71
	v_lshl_add_u64 v[4:5], v[2:3], 0, s[8:9]
	v_readlane_b32 s8, v255, 17
	v_readlane_b32 s9, v255, 18
	global_load_dword v83, v[4:5], off
	s_waitcnt vmcnt(5)
	v_mov_b32_e32 v74, v73
	v_lshl_add_u64 v[4:5], v[2:3], 0, s[8:9]
	v_readlane_b32 s8, v255, 19
	v_readlane_b32 s9, v255, 20
	global_load_dword v85, v[4:5], off
	s_waitcnt vmcnt(5)
	v_mov_b32_e32 v76, v75
	v_lshl_add_u64 v[4:5], v[2:3], 0, s[8:9]
	v_readlane_b32 s8, v255, 21
	v_readlane_b32 s9, v255, 22
	global_load_dword v87, v[4:5], off
	s_waitcnt vmcnt(5)
	v_mov_b32_e32 v78, v77
	v_lshl_add_u64 v[4:5], v[2:3], 0, s[8:9]
	v_readlane_b32 s8, v254, 37
	v_readlane_b32 s9, v254, 38
	global_load_dword v89, v[4:5], off
	s_waitcnt vmcnt(5)
	v_mov_b32_e32 v80, v79
	v_lshl_add_u64 v[4:5], v[2:3], 0, s[8:9]
	v_readlane_b32 s8, v254, 35
	v_readlane_b32 s9, v254, 36
	global_load_dword v91, v[4:5], off
	s_waitcnt vmcnt(5)
	v_mov_b32_e32 v82, v81
	v_lshl_add_u64 v[4:5], v[2:3], 0, s[8:9]
	v_readlane_b32 s8, v255, 23
	v_readlane_b32 s9, v255, 24
	global_load_dword v93, v[4:5], off
	s_waitcnt vmcnt(5)
	v_mov_b32_e32 v84, v83
	v_lshl_add_u64 v[4:5], v[2:3], 0, s[8:9]
	global_load_dword v95, v[4:5], off
	v_lshl_add_u64 v[4:5], v[2:3], 0, s[68:69]
	s_lshl_b64 s[8:9], s[84:85], 2
	global_load_dword v97, v[4:5], off
	v_lshl_add_u64 v[4:5], v[2:3], 0, s[94:95]
	v_lshl_add_u64 v[2:3], v[2:3], 0, s[88:89]
	s_add_u32 s10, s48, s8
	global_load_dword v99, v[4:5], off
	global_load_dword v101, v[2:3], off
	s_addc_u32 s11, s49, s9
	v_lshlrev_b32_e32 v2, 2, v1
	v_and_b32_e32 v12, 0xfc, v2
	s_add_u32 s8, s50, s8
	v_lshlrev_b32_e32 v6, 2, v12
	s_addc_u32 s9, s51, s9
	s_min_i32 s5, s6, 5
	global_load_dwordx4 v[2:5], v6, s[10:11]
	s_addk_i32 s5, 0x58
	v_readlane_b32 s10, v250, 29
	s_add_i32 s7, s5, s10
	v_lshlrev_b32_e32 v130, 1, v12
	s_max_i32 s7, s7, 0
	v_readlane_b32 s11, v250, 30
	s_min_i32 s40, s6, 13
	v_lshl_add_u64 v[102:103], s[80:81], 0, v[130:131]
	s_add_i32 s7, s7, s11
	s_addk_i32 s40, 0x50
	global_load_dwordx4 v[6:9], v6, s[8:9]
	v_mad_u64_u32 v[12:13], s[8:9], s7, v238, v[102:103]
	s_add_i32 s7, s40, s10
	s_max_i32 s7, s7, 0
	s_min_i32 s41, s6, 21
	s_add_i32 s7, s7, s11
	s_addk_i32 s41, 0x48
	global_load_dwordx2 v[106:107], v[12:13], off offset:1536
	global_load_dwordx2 v[104:105], v[12:13], off offset:1024
	v_mad_u64_u32 v[12:13], s[8:9], s7, v238, v[102:103]
	s_add_i32 s7, s41, s10
	s_max_i32 s7, s7, 0
	s_min_i32 s44, s6, 29
	s_add_i32 s7, s7, s11
	s_add_i32 s44, s44, 64
	global_load_dwordx2 v[112:113], v[12:13], off offset:1536
	global_load_dwordx2 v[110:111], v[12:13], off offset:1024
	v_mad_u64_u32 v[12:13], s[8:9], s7, v238, v[102:103]
	s_add_i32 s7, s44, s10
	s_max_i32 s7, s7, 0
	s_min_i32 s45, s6, 37
	s_add_i32 s7, s7, s11
	s_add_i32 s45, s45, 56
	global_load_dwordx2 v[116:117], v[12:13], off offset:1536
	global_load_dwordx2 v[114:115], v[12:13], off offset:1024
	v_mad_u64_u32 v[12:13], s[8:9], s7, v238, v[102:103]
	s_add_i32 s7, s45, s10
	s_max_i32 s7, s7, 0
	s_min_i32 s46, s6, 45
	s_add_i32 s7, s7, s11
	s_add_i32 s46, s46, 48
	global_load_dwordx2 v[120:121], v[12:13], off offset:1536
	global_load_dwordx2 v[118:119], v[12:13], off offset:1024
	v_mad_u64_u32 v[12:13], s[8:9], s7, v238, v[102:103]
	s_add_i32 s7, s46, s10
	s_max_i32 s7, s7, 0
	s_min_i32 s47, s6, 53
	s_add_i32 s7, s7, s11
	s_add_i32 s47, s47, 40
	global_load_dwordx2 v[124:125], v[12:13], off offset:1536
	global_load_dwordx2 v[122:123], v[12:13], off offset:1024
	v_mad_u64_u32 v[12:13], s[8:9], s7, v238, v[102:103]
	s_add_i32 s7, s47, s10
	s_max_i32 s7, s7, 0
	s_min_i32 s48, s6, 61
	s_add_i32 s7, s7, s11
	s_add_i32 s48, s48, 32
	global_load_dwordx2 v[128:129], v[12:13], off offset:1536
	global_load_dwordx2 v[126:127], v[12:13], off offset:1024
	v_mad_u64_u32 v[12:13], s[8:9], s7, v238, v[102:103]
	s_add_i32 s7, s48, s10
	s_max_i32 s7, s7, 0
	s_min_i32 s49, s6, 0x45
	s_add_i32 s7, s7, s11
	s_add_i32 s49, s49, 24
	global_load_dwordx2 v[134:135], v[12:13], off offset:1536
	global_load_dwordx2 v[132:133], v[12:13], off offset:1024
	v_mad_u64_u32 v[12:13], s[8:9], s7, v238, v[102:103]
	s_add_i32 s7, s49, s10
	s_max_i32 s7, s7, 0
	s_min_i32 s50, s6, 0x4d
	s_add_i32 s7, s7, s11
	s_add_i32 s50, s50, 16
	global_load_dwordx2 v[138:139], v[12:13], off offset:1536
	global_load_dwordx2 v[136:137], v[12:13], off offset:1024
	v_mad_u64_u32 v[12:13], s[8:9], s7, v238, v[102:103]
	s_add_i32 s7, s50, s10
	s_max_i32 s7, s7, 0
	s_min_i32 s51, s6, 0x55
	s_add_i32 s7, s7, s11
	s_add_i32 s51, s51, 8
	global_load_dwordx2 v[142:143], v[12:13], off offset:1536
	global_load_dwordx2 v[140:141], v[12:13], off offset:1024
	v_mad_u64_u32 v[12:13], s[8:9], s7, v238, v[102:103]
	s_add_i32 s7, s51, s10
	s_min_i32 s56, s6, 0x5d
	s_max_i32 s7, s7, 0
	s_add_i32 s6, s56, s10
	s_add_i32 s7, s7, s11
	s_max_i32 s6, s6, 0
	global_load_dwordx2 v[146:147], v[12:13], off offset:1536
	global_load_dwordx2 v[144:145], v[12:13], off offset:1024
	v_mad_u64_u32 v[12:13], s[8:9], s7, v238, v[102:103]
	s_add_i32 s6, s6, s11
	global_load_dwordx2 v[150:151], v[12:13], off offset:1536
	global_load_dwordx2 v[148:149], v[12:13], off offset:1024
	v_mad_u64_u32 v[12:13], s[6:7], s6, v238, v[102:103]
	global_load_dwordx2 v[154:155], v[12:13], off offset:1536
	global_load_dwordx2 v[152:153], v[12:13], off offset:1024
	v_or_b32_sdwa v12, v1, s84 dst_sel:DWORD dst_unused:UNUSED_PAD src0_sel:BYTE_0 src1_sel:DWORD
	v_ashrrev_i32_e32 v13, 31, v12
	v_lshl_add_u64 v[10:11], v[12:13], 2, v[10:11]
	global_load_dword v108, v[10:11], off
	s_waitcnt vmcnt(35)
	v_mov_b32_e32 v86, v85
	s_waitcnt vmcnt(34)
	v_mov_b32_e32 v88, v87
	s_waitcnt vmcnt(33)
	v_mov_b32_e32 v90, v89
	s_waitcnt vmcnt(32)
	v_mov_b32_e32 v92, v91
	s_waitcnt vmcnt(31)
	v_mov_b32_e32 v94, v93
	s_waitcnt vmcnt(30)
	v_mov_b32_e32 v96, v95
	s_waitcnt vmcnt(29)
	v_mov_b32_e32 v98, v97
	s_waitcnt vmcnt(28)
	v_mov_b32_e32 v100, v99
	s_branch .LBB0_289
.LBB0_288:
	s_add_i32 s59, s58, 0xffffff80
	s_cmpk_lt_i32 s59, 0x180
	s_cselect_b32 s7, s58, s59
	s_lshl_b32 s7, s7, 6
	s_and_b32 s8, s7, 0xfc0
	s_sub_i32 s10, s8, 30
	s_add_i32 s8, s10, s56
	s_and_b32 s7, s7, 0xfffff000
	s_max_i32 s8, s8, 0
	s_add_i32 s8, s8, s7
	v_and_b32_e32 v14, 0xff, v10
	v_mad_i64_i32 v[10:11], s[8:9], s8, v238, v[102:103]
	s_add_i32 s8, s10, s51
	s_max_i32 s8, s8, 0
	s_add_i32 s8, s8, s7
	v_mad_i64_i32 v[12:13], s[8:9], s8, v238, v[102:103]
	s_add_i32 s8, s10, s50
	s_max_i32 s8, s8, 0
	s_add_i32 s8, s8, s7
	s_waitcnt lgkmcnt(0)
	s_barrier
	global_load_dwordx2 v[152:153], v[10:11], off offset:1024
	global_load_dwordx2 v[154:155], v[10:11], off offset:1536
	global_load_dwordx2 v[148:149], v[12:13], off offset:1024
	global_load_dwordx2 v[150:151], v[12:13], off offset:1536
	v_mad_i64_i32 v[10:11], s[8:9], s8, v238, v[102:103]
	s_add_i32 s8, s10, s49
	s_max_i32 s8, s8, 0
	s_add_i32 s8, s8, s7
	v_mad_i64_i32 v[12:13], s[8:9], s8, v238, v[102:103]
	s_add_i32 s8, s10, s48
	s_max_i32 s8, s8, 0
	s_add_i32 s8, s8, s7
	global_load_dwordx2 v[144:145], v[10:11], off offset:1024
	global_load_dwordx2 v[146:147], v[10:11], off offset:1536
	global_load_dwordx2 v[140:141], v[12:13], off offset:1024
	global_load_dwordx2 v[142:143], v[12:13], off offset:1536
	v_mad_i64_i32 v[10:11], s[8:9], s8, v238, v[102:103]
	s_add_i32 s8, s10, s47
	s_max_i32 s8, s8, 0
	s_add_i32 s8, s8, s7
	v_mad_i64_i32 v[12:13], s[8:9], s8, v238, v[102:103]
	s_add_i32 s8, s10, s46
	s_max_i32 s8, s8, 0
	s_add_i32 s8, s8, s7
	global_load_dwordx2 v[136:137], v[10:11], off offset:1024
	global_load_dwordx2 v[138:139], v[10:11], off offset:1536
	global_load_dwordx2 v[132:133], v[12:13], off offset:1024
	global_load_dwordx2 v[134:135], v[12:13], off offset:1536
	v_mad_i64_i32 v[10:11], s[8:9], s8, v238, v[102:103]
	s_add_i32 s8, s10, s45
	s_max_i32 s8, s8, 0
	s_add_i32 s8, s8, s7
	v_mad_i64_i32 v[12:13], s[8:9], s8, v238, v[102:103]
	s_add_i32 s8, s10, s44
	s_max_i32 s8, s8, 0
	s_add_i32 s8, s8, s7
	global_load_dwordx2 v[126:127], v[10:11], off offset:1024
	global_load_dwordx2 v[128:129], v[10:11], off offset:1536
	global_load_dwordx2 v[122:123], v[12:13], off offset:1024
	global_load_dwordx2 v[124:125], v[12:13], off offset:1536
	v_mad_i64_i32 v[10:11], s[8:9], s8, v238, v[102:103]
	s_add_i32 s8, s10, s41
	s_max_i32 s8, s8, 0
	s_add_i32 s8, s8, s7
	v_mad_i64_i32 v[12:13], s[8:9], s8, v238, v[102:103]
	s_add_i32 s8, s10, s40
	s_max_i32 s8, s8, 0
	s_add_i32 s8, s8, s7
	global_load_dwordx2 v[118:119], v[10:11], off offset:1024
	global_load_dwordx2 v[120:121], v[10:11], off offset:1536
	global_load_dwordx2 v[114:115], v[12:13], off offset:1024
	global_load_dwordx2 v[116:117], v[12:13], off offset:1536
	v_mad_i64_i32 v[10:11], s[8:9], s8, v238, v[102:103]
	s_add_i32 s10, s10, s5
	s_lshl_b32 s6, s6, 7
	s_max_i32 s8, s10, 0
	s_and_b32 s6, s6, 0xffff8000
	s_add_i32 s8, s8, s7
	s_add_i32 s6, s6, 0
	v_mad_i64_i32 v[12:13], s[8:9], s8, v238, v[102:103]
	v_lshl_add_u32 v163, v14, 2, s6
	global_load_dwordx2 v[110:111], v[10:11], off offset:1024
	global_load_dwordx2 v[112:113], v[10:11], off offset:1536
	global_load_dwordx2 v[104:105], v[12:13], off offset:1024
	global_load_dwordx2 v[106:107], v[12:13], off offset:1536
	ds_read2st64_b32 v[26:27], v163 offset1:4
	ds_read2st64_b32 v[28:29], v163 offset0:8 offset1:12
	ds_read2st64_b32 v[30:31], v163 offset0:16 offset1:20
	ds_read2st64_b32 v[32:33], v163 offset0:24 offset1:28
	ds_read2st64_b32 v[160:161], v163 offset0:32 offset1:36
	ds_read2st64_b32 v[158:159], v163 offset0:40 offset1:44
	ds_read2st64_b32 v[156:157], v163 offset0:48 offset1:52
	ds_read2st64_b32 v[40:41], v163 offset0:56 offset1:60
	ds_read2st64_b32 v[38:39], v163 offset0:64 offset1:68
	ds_read2st64_b32 v[36:37], v163 offset0:72 offset1:76
	ds_read2st64_b32 v[34:35], v163 offset0:80 offset1:84
	ds_read2st64_b32 v[24:25], v163 offset0:88 offset1:92
	ds_read2st64_b32 v[22:23], v163 offset0:96 offset1:100
	ds_read2st64_b32 v[20:21], v163 offset0:104 offset1:108
	ds_read2st64_b32 v[10:11], v163 offset0:120 offset1:124
	ds_read2st64_b32 v[18:19], v163 offset0:112 offset1:116
	ds_read2st64_b32 v[12:13], v163 offset0:128 offset1:132
	ds_read2st64_b32 v[14:15], v163 offset0:136 offset1:140
	ds_read2st64_b32 v[16:17], v163 offset0:144 offset1:148
	s_waitcnt vmcnt(51) lgkmcnt(4)
	v_mul_f32_e32 v109, v101, v10
	v_mul_f32_e32 v165, v42, v27
	s_waitcnt vmcnt(24)
	v_mov_b32_e32 v164, v108
	v_pk_fma_f32 v[26:27], v[42:43], v[26:27], v[108:109]
	v_pk_fma_f32 v[164:165], v[44:45], v[28:29], v[164:165]
	v_pk_fma_f32 v[26:27], v[46:47], v[28:29], v[26:27]
	v_pk_fma_f32 v[164:165], v[48:49], v[30:31], v[164:165]
	v_pk_fma_f32 v[26:27], v[50:51], v[30:31], v[26:27]
	v_pk_fma_f32 v[164:165], v[52:53], v[32:33], v[164:165]
	v_pk_fma_f32 v[26:27], v[54:55], v[32:33], v[26:27]
	v_pk_fma_f32 v[164:165], v[56:57], v[160:161], v[164:165]
	v_pk_fma_f32 v[26:27], v[58:59], v[160:161], v[26:27]
	v_pk_fma_f32 v[164:165], v[60:61], v[158:159], v[164:165]
	v_pk_fma_f32 v[26:27], v[62:63], v[158:159], v[26:27]
	v_pk_fma_f32 v[164:165], v[64:65], v[156:157], v[164:165]
	v_pk_fma_f32 v[26:27], v[66:67], v[156:157], v[26:27]
	v_pk_fma_f32 v[164:165], v[68:69], v[40:41], v[164:165]
	v_pk_fma_f32 v[26:27], v[70:71], v[40:41], v[26:27]
	v_pk_fma_f32 v[164:165], v[72:73], v[38:39], v[164:165]
	v_pk_fma_f32 v[26:27], v[74:75], v[38:39], v[26:27]
	v_pk_fma_f32 v[164:165], v[76:77], v[36:37], v[164:165]
	v_pk_fma_f32 v[26:27], v[78:79], v[36:37], v[26:27]
	v_pk_fma_f32 v[164:165], v[80:81], v[34:35], v[164:165]
	v_pk_fma_f32 v[26:27], v[82:83], v[34:35], v[26:27]
	v_pk_fma_f32 v[164:165], v[84:85], v[24:25], v[164:165]
	v_pk_fma_f32 v[26:27], v[86:87], v[24:25], v[26:27]
	v_pk_fma_f32 v[164:165], v[88:89], v[22:23], v[164:165]
	v_pk_fma_f32 v[26:27], v[90:91], v[22:23], v[26:27]
	v_pk_fma_f32 v[164:165], v[92:93], v[20:21], v[164:165]
	v_pk_fma_f32 v[26:27], v[94:95], v[20:21], v[26:27]
	s_waitcnt lgkmcnt(3)
	v_pk_fma_f32 v[164:165], v[96:97], v[18:19], v[164:165]
	v_pk_fma_f32 v[26:27], v[98:99], v[18:19], v[26:27]
	v_pk_fma_f32 v[166:167], v[100:101], v[10:11], v[164:165]
	v_add_f32_e32 v164, v26, v27
	v_mul_f32_e32 v27, v42, v29
	v_mov_b32_e32 v26, v108
	v_pk_fma_f32 v[26:27], v[44:45], v[30:31], v[26:27]
	v_add_f32_e32 v165, v166, v167
	v_pk_fma_f32 v[26:27], v[48:49], v[32:33], v[26:27]
	s_waitcnt lgkmcnt(2)
	v_mul_f32_e32 v109, v101, v12
	v_pk_fma_f32 v[26:27], v[52:53], v[160:161], v[26:27]
	v_pk_fma_f32 v[28:29], v[42:43], v[28:29], v[108:109]
	v_pk_fma_f32 v[26:27], v[56:57], v[158:159], v[26:27]
	v_pk_fma_f32 v[28:29], v[46:47], v[30:31], v[28:29]
	v_pk_fma_f32 v[26:27], v[60:61], v[156:157], v[26:27]
	v_pk_fma_f32 v[28:29], v[50:51], v[32:33], v[28:29]
	v_pk_fma_f32 v[26:27], v[64:65], v[40:41], v[26:27]
	v_pk_fma_f32 v[28:29], v[54:55], v[160:161], v[28:29]
	v_pk_fma_f32 v[26:27], v[68:69], v[38:39], v[26:27]
	v_pk_fma_f32 v[28:29], v[58:59], v[158:159], v[28:29]
	v_pk_fma_f32 v[26:27], v[72:73], v[36:37], v[26:27]
	v_pk_fma_f32 v[28:29], v[62:63], v[156:157], v[28:29]
	v_pk_fma_f32 v[26:27], v[76:77], v[34:35], v[26:27]
	v_pk_fma_f32 v[28:29], v[66:67], v[40:41], v[28:29]
	v_pk_fma_f32 v[26:27], v[80:81], v[24:25], v[26:27]
	v_pk_fma_f32 v[28:29], v[70:71], v[38:39], v[28:29]
	v_pk_fma_f32 v[26:27], v[84:85], v[22:23], v[26:27]
	v_pk_fma_f32 v[28:29], v[74:75], v[36:37], v[28:29]
	v_pk_fma_f32 v[26:27], v[88:89], v[20:21], v[26:27]
	v_pk_fma_f32 v[28:29], v[78:79], v[34:35], v[28:29]
	v_pk_fma_f32 v[26:27], v[92:93], v[18:19], v[26:27]
	v_pk_fma_f32 v[28:29], v[82:83], v[24:25], v[28:29]
	v_pk_fma_f32 v[26:27], v[96:97], v[10:11], v[26:27]
	v_pk_fma_f32 v[28:29], v[86:87], v[22:23], v[28:29]
	v_pk_fma_f32 v[26:27], v[100:101], v[12:13], v[26:27]
	v_pk_fma_f32 v[28:29], v[90:91], v[20:21], v[28:29]
	v_add_f32_e32 v167, v26, v27
	v_mul_f32_e32 v27, v42, v31
	v_mov_b32_e32 v26, v108
	v_pk_fma_f32 v[26:27], v[44:45], v[32:33], v[26:27]
	v_pk_fma_f32 v[28:29], v[94:95], v[18:19], v[28:29]
	v_pk_fma_f32 v[26:27], v[48:49], v[160:161], v[26:27]
	v_pk_fma_f32 v[28:29], v[98:99], v[10:11], v[28:29]
	v_pk_fma_f32 v[26:27], v[52:53], v[158:159], v[26:27]
	s_waitcnt lgkmcnt(1)
	v_mul_f32_e32 v109, v101, v14
	v_pk_fma_f32 v[26:27], v[56:57], v[156:157], v[26:27]
	v_add_f32_e32 v166, v28, v29
	v_pk_fma_f32 v[26:27], v[60:61], v[40:41], v[26:27]
	v_pk_fma_f32 v[28:29], v[42:43], v[30:31], v[108:109]
	v_pk_fma_f32 v[26:27], v[64:65], v[38:39], v[26:27]
	v_pk_fma_f32 v[28:29], v[46:47], v[32:33], v[28:29]
	v_pk_fma_f32 v[26:27], v[68:69], v[36:37], v[26:27]
	v_pk_fma_f32 v[28:29], v[50:51], v[160:161], v[28:29]
	v_pk_fma_f32 v[26:27], v[72:73], v[34:35], v[26:27]
	v_pk_fma_f32 v[28:29], v[54:55], v[158:159], v[28:29]
	v_pk_fma_f32 v[26:27], v[76:77], v[24:25], v[26:27]
	v_pk_fma_f32 v[28:29], v[58:59], v[156:157], v[28:29]
	v_pk_fma_f32 v[26:27], v[80:81], v[22:23], v[26:27]
	v_pk_fma_f32 v[28:29], v[62:63], v[40:41], v[28:29]
	v_pk_fma_f32 v[26:27], v[84:85], v[20:21], v[26:27]
	v_pk_fma_f32 v[28:29], v[66:67], v[38:39], v[28:29]
	v_pk_fma_f32 v[26:27], v[88:89], v[18:19], v[26:27]
	v_pk_fma_f32 v[28:29], v[70:71], v[36:37], v[28:29]
	v_pk_fma_f32 v[26:27], v[92:93], v[10:11], v[26:27]
	v_pk_fma_f32 v[28:29], v[74:75], v[34:35], v[28:29]
	v_pk_fma_f32 v[26:27], v[96:97], v[12:13], v[26:27]
	v_pk_fma_f32 v[28:29], v[78:79], v[24:25], v[28:29]
	v_pk_fma_f32 v[26:27], v[100:101], v[14:15], v[26:27]
	v_pk_fma_f32 v[28:29], v[82:83], v[22:23], v[28:29]
	v_add_f32_e32 v169, v26, v27
	v_mul_f32_e32 v27, v42, v33
	v_mov_b32_e32 v26, v108
	v_pk_fma_f32 v[26:27], v[44:45], v[160:161], v[26:27]
	v_pk_fma_f32 v[28:29], v[86:87], v[20:21], v[28:29]
	v_pk_fma_f32 v[26:27], v[48:49], v[158:159], v[26:27]
	v_pk_fma_f32 v[28:29], v[90:91], v[18:19], v[28:29]
	v_pk_fma_f32 v[26:27], v[52:53], v[156:157], v[26:27]
	v_pk_fma_f32 v[28:29], v[94:95], v[10:11], v[28:29]
	v_pk_fma_f32 v[26:27], v[56:57], v[40:41], v[26:27]
	v_pk_fma_f32 v[28:29], v[98:99], v[12:13], v[28:29]
	v_pk_fma_f32 v[26:27], v[60:61], v[38:39], v[26:27]
	s_waitcnt lgkmcnt(0)
	v_mul_f32_e32 v109, v101, v16
	v_pk_fma_f32 v[26:27], v[64:65], v[36:37], v[26:27]
	v_add_f32_e32 v168, v28, v29
	v_pk_fma_f32 v[26:27], v[68:69], v[34:35], v[26:27]
	v_pk_fma_f32 v[28:29], v[42:43], v[32:33], v[108:109]
	v_pk_fma_f32 v[26:27], v[72:73], v[24:25], v[26:27]
	v_pk_fma_f32 v[28:29], v[46:47], v[160:161], v[28:29]
	v_pk_fma_f32 v[26:27], v[76:77], v[22:23], v[26:27]
	v_pk_fma_f32 v[28:29], v[50:51], v[158:159], v[28:29]
	v_pk_fma_f32 v[26:27], v[80:81], v[20:21], v[26:27]
	v_pk_fma_f32 v[28:29], v[54:55], v[156:157], v[28:29]
	v_pk_fma_f32 v[26:27], v[84:85], v[18:19], v[26:27]
	v_pk_fma_f32 v[28:29], v[58:59], v[40:41], v[28:29]
	v_pk_fma_f32 v[26:27], v[88:89], v[10:11], v[26:27]
	v_mul_f32_e32 v173, v42, v161
	v_pk_fma_f32 v[26:27], v[92:93], v[12:13], v[26:27]
	v_pk_fma_f32 v[28:29], v[62:63], v[38:39], v[28:29]
	v_pk_fma_f32 v[26:27], v[96:97], v[14:15], v[26:27]
	v_pk_fma_f32 v[28:29], v[66:67], v[36:37], v[28:29]
	v_pk_fma_f32 v[30:31], v[100:101], v[16:17], v[26:27]
	ds_read2st64_b32 v[26:27], v163 offset0:152 offset1:156
	v_pk_fma_f32 v[28:29], v[70:71], v[34:35], v[28:29]
	v_add_f32_e32 v171, v30, v31
	v_pk_fma_f32 v[28:29], v[74:75], v[24:25], v[28:29]
	v_mov_b32_e32 v172, v108
	s_waitcnt lgkmcnt(0)
	v_mul_f32_e32 v109, v101, v26
	v_pk_fma_f32 v[160:161], v[42:43], v[160:161], v[108:109]
	v_pk_fma_f32 v[28:29], v[78:79], v[22:23], v[28:29]
	v_pk_fma_f32 v[160:161], v[46:47], v[158:159], v[160:161]
	v_pk_fma_f32 v[28:29], v[82:83], v[20:21], v[28:29]
	v_pk_fma_f32 v[160:161], v[50:51], v[156:157], v[160:161]
	v_pk_fma_f32 v[28:29], v[86:87], v[18:19], v[28:29]
	v_pk_fma_f32 v[160:161], v[54:55], v[40:41], v[160:161]
	v_pk_fma_f32 v[28:29], v[90:91], v[10:11], v[28:29]
	v_pk_fma_f32 v[160:161], v[58:59], v[38:39], v[160:161]
	v_pk_fma_f32 v[28:29], v[94:95], v[12:13], v[28:29]
	v_pk_fma_f32 v[160:161], v[62:63], v[36:37], v[160:161]
	v_pk_fma_f32 v[28:29], v[98:99], v[14:15], v[28:29]
	v_pk_fma_f32 v[160:161], v[66:67], v[34:35], v[160:161]
	v_add_f32_e32 v170, v28, v29
	v_pk_fma_f32 v[160:161], v[70:71], v[24:25], v[160:161]
	ds_read2st64_b32 v[28:29], v163 offset0:160 offset1:164
	ds_read2st64_b32 v[30:31], v163 offset0:168 offset1:172
	ds_read2st64_b32 v[32:33], v163 offset0:176 offset1:180
	v_pk_fma_f32 v[160:161], v[74:75], v[22:23], v[160:161]
	v_pk_fma_f32 v[172:173], v[44:45], v[158:159], v[172:173]
	v_pk_fma_f32 v[160:161], v[78:79], v[20:21], v[160:161]
	s_waitcnt lgkmcnt(2)
	v_mul_f32_e32 v109, v101, v28
	v_pk_fma_f32 v[160:161], v[82:83], v[18:19], v[160:161]
	v_pk_fma_f32 v[172:173], v[48:49], v[156:157], v[172:173]
	v_pk_fma_f32 v[160:161], v[86:87], v[10:11], v[160:161]
	v_pk_fma_f32 v[172:173], v[52:53], v[40:41], v[172:173]
	v_pk_fma_f32 v[160:161], v[90:91], v[12:13], v[160:161]
	v_pk_fma_f32 v[172:173], v[56:57], v[38:39], v[172:173]
	v_pk_fma_f32 v[160:161], v[94:95], v[14:15], v[160:161]
	v_pk_fma_f32 v[172:173], v[60:61], v[36:37], v[172:173]
	v_pk_fma_f32 v[160:161], v[98:99], v[16:17], v[160:161]
	v_pk_fma_f32 v[172:173], v[64:65], v[34:35], v[172:173]
	v_add_f32_e32 v174, v160, v161
	v_mul_f32_e32 v161, v42, v159
	v_pk_fma_f32 v[158:159], v[42:43], v[158:159], v[108:109]
	v_mov_b32_e32 v160, v108
	v_pk_fma_f32 v[158:159], v[46:47], v[156:157], v[158:159]
	s_waitcnt lgkmcnt(1)
	v_mul_f32_e32 v109, v101, v30
	v_pk_fma_f32 v[158:159], v[50:51], v[40:41], v[158:159]
	v_pk_fma_f32 v[160:161], v[44:45], v[156:157], v[160:161]
	v_pk_fma_f32 v[158:159], v[54:55], v[38:39], v[158:159]
	v_pk_fma_f32 v[160:161], v[48:49], v[40:41], v[160:161]
	v_pk_fma_f32 v[158:159], v[58:59], v[36:37], v[158:159]
	v_pk_fma_f32 v[172:173], v[68:69], v[24:25], v[172:173]
	v_pk_fma_f32 v[158:159], v[62:63], v[34:35], v[158:159]
	v_pk_fma_f32 v[172:173], v[72:73], v[22:23], v[172:173]
	v_pk_fma_f32 v[158:159], v[66:67], v[24:25], v[158:159]
	v_pk_fma_f32 v[172:173], v[76:77], v[20:21], v[172:173]
	v_pk_fma_f32 v[158:159], v[70:71], v[22:23], v[158:159]
	v_pk_fma_f32 v[172:173], v[80:81], v[18:19], v[172:173]
	v_pk_fma_f32 v[158:159], v[74:75], v[20:21], v[158:159]
	v_pk_fma_f32 v[172:173], v[84:85], v[10:11], v[172:173]
	v_pk_fma_f32 v[158:159], v[78:79], v[18:19], v[158:159]
	v_pk_fma_f32 v[172:173], v[88:89], v[12:13], v[172:173]
	v_pk_fma_f32 v[158:159], v[82:83], v[10:11], v[158:159]
	v_pk_fma_f32 v[172:173], v[92:93], v[14:15], v[172:173]
	v_pk_fma_f32 v[158:159], v[86:87], v[12:13], v[158:159]
	v_pk_fma_f32 v[172:173], v[96:97], v[16:17], v[172:173]
	v_pk_fma_f32 v[158:159], v[90:91], v[14:15], v[158:159]
	v_pk_fma_f32 v[160:161], v[52:53], v[38:39], v[160:161]
	v_pk_fma_f32 v[158:159], v[94:95], v[16:17], v[158:159]
	v_pk_fma_f32 v[172:173], v[100:101], v[26:27], v[172:173]
	v_pk_fma_f32 v[158:159], v[98:99], v[26:27], v[158:159]
	v_pk_fma_f32 v[160:161], v[56:57], v[36:37], v[160:161]
	v_add_f32_e32 v176, v158, v159
	v_mul_f32_e32 v159, v42, v157
	v_pk_fma_f32 v[156:157], v[42:43], v[156:157], v[108:109]
	v_mov_b32_e32 v158, v108
	v_pk_fma_f32 v[156:157], v[46:47], v[40:41], v[156:157]
	s_waitcnt lgkmcnt(0)
	v_mul_f32_e32 v109, v101, v32
	v_pk_fma_f32 v[156:157], v[50:51], v[38:39], v[156:157]
	v_pk_fma_f32 v[158:159], v[44:45], v[40:41], v[158:159]
	v_pk_fma_f32 v[156:157], v[54:55], v[36:37], v[156:157]
	v_pk_fma_f32 v[158:159], v[48:49], v[38:39], v[158:159]
	v_pk_fma_f32 v[156:157], v[58:59], v[34:35], v[156:157]
	v_pk_fma_f32 v[158:159], v[52:53], v[36:37], v[158:159]
	v_pk_fma_f32 v[156:157], v[62:63], v[24:25], v[156:157]
	v_pk_fma_f32 v[158:159], v[56:57], v[34:35], v[158:159]
	v_pk_fma_f32 v[156:157], v[66:67], v[22:23], v[156:157]
	v_add_f32_e32 v175, v172, v173
	v_pk_fma_f32 v[156:157], v[70:71], v[20:21], v[156:157]
	v_pk_fma_f32 v[160:161], v[60:61], v[34:35], v[160:161]
	v_pk_fma_f32 v[156:157], v[74:75], v[18:19], v[156:157]
	v_pk_fma_f32 v[158:159], v[60:61], v[24:25], v[158:159]
	v_pk_fma_f32 v[156:157], v[78:79], v[10:11], v[156:157]
	v_mul_f32_e32 v173, v42, v39
	v_pk_fma_f32 v[156:157], v[82:83], v[12:13], v[156:157]
	v_pk_fma_f32 v[160:161], v[64:65], v[24:25], v[160:161]
	v_pk_fma_f32 v[156:157], v[86:87], v[14:15], v[156:157]
	v_pk_fma_f32 v[158:159], v[64:65], v[22:23], v[158:159]
	v_pk_fma_f32 v[156:157], v[90:91], v[16:17], v[156:157]
	v_pk_fma_f32 v[160:161], v[68:69], v[22:23], v[160:161]
	v_pk_fma_f32 v[156:157], v[94:95], v[26:27], v[156:157]
	v_pk_fma_f32 v[158:159], v[68:69], v[20:21], v[158:159]
	v_pk_fma_f32 v[156:157], v[98:99], v[28:29], v[156:157]
	v_pk_fma_f32 v[160:161], v[72:73], v[20:21], v[160:161]
	v_add_f32_e32 v178, v156, v157
	v_mul_f32_e32 v157, v42, v41
	v_pk_fma_f32 v[40:41], v[42:43], v[40:41], v[108:109]
	v_mov_b32_e32 v156, v108
	v_pk_fma_f32 v[40:41], v[46:47], v[38:39], v[40:41]
	v_pk_fma_f32 v[156:157], v[44:45], v[38:39], v[156:157]
	v_pk_fma_f32 v[40:41], v[50:51], v[36:37], v[40:41]
	v_pk_fma_f32 v[156:157], v[48:49], v[36:37], v[156:157]
	v_pk_fma_f32 v[40:41], v[54:55], v[34:35], v[40:41]
	v_pk_fma_f32 v[156:157], v[52:53], v[34:35], v[156:157]
	v_pk_fma_f32 v[40:41], v[58:59], v[24:25], v[40:41]
	v_pk_fma_f32 v[156:157], v[56:57], v[24:25], v[156:157]
	v_pk_fma_f32 v[40:41], v[62:63], v[22:23], v[40:41]
	v_pk_fma_f32 v[156:157], v[60:61], v[22:23], v[156:157]
	v_pk_fma_f32 v[40:41], v[66:67], v[20:21], v[40:41]
	v_pk_fma_f32 v[156:157], v[64:65], v[20:21], v[156:157]
	v_pk_fma_f32 v[40:41], v[70:71], v[18:19], v[40:41]
	v_pk_fma_f32 v[156:157], v[68:69], v[18:19], v[156:157]
	v_pk_fma_f32 v[40:41], v[74:75], v[10:11], v[40:41]
	v_pk_fma_f32 v[158:159], v[72:73], v[18:19], v[158:159]
	v_pk_fma_f32 v[40:41], v[78:79], v[12:13], v[40:41]
	v_pk_fma_f32 v[156:157], v[72:73], v[10:11], v[156:157]
	v_pk_fma_f32 v[40:41], v[82:83], v[14:15], v[40:41]
	v_pk_fma_f32 v[160:161], v[76:77], v[18:19], v[160:161]
	v_pk_fma_f32 v[40:41], v[86:87], v[16:17], v[40:41]
	v_pk_fma_f32 v[158:159], v[76:77], v[10:11], v[158:159]
	v_pk_fma_f32 v[40:41], v[90:91], v[26:27], v[40:41]
	v_pk_fma_f32 v[156:157], v[76:77], v[12:13], v[156:157]
	v_pk_fma_f32 v[40:41], v[94:95], v[28:29], v[40:41]
	v_pk_fma_f32 v[160:161], v[80:81], v[10:11], v[160:161]
	v_pk_fma_f32 v[40:41], v[98:99], v[30:31], v[40:41]
	v_pk_fma_f32 v[158:159], v[80:81], v[12:13], v[158:159]
	v_add_f32_e32 v180, v40, v41
	ds_read2st64_b32 v[40:41], v163 offset0:184 offset1:188
	v_pk_fma_f32 v[156:157], v[80:81], v[14:15], v[156:157]
	v_pk_fma_f32 v[160:161], v[84:85], v[12:13], v[160:161]
	v_pk_fma_f32 v[158:159], v[84:85], v[14:15], v[158:159]
	v_pk_fma_f32 v[156:157], v[84:85], v[16:17], v[156:157]
	s_waitcnt lgkmcnt(0)
	v_mul_f32_e32 v109, v101, v40
	v_pk_fma_f32 v[38:39], v[42:43], v[38:39], v[108:109]
	v_pk_fma_f32 v[160:161], v[88:89], v[14:15], v[160:161]
	v_pk_fma_f32 v[38:39], v[46:47], v[36:37], v[38:39]
	v_pk_fma_f32 v[158:159], v[88:89], v[16:17], v[158:159]
	v_pk_fma_f32 v[38:39], v[50:51], v[34:35], v[38:39]
	v_pk_fma_f32 v[156:157], v[88:89], v[26:27], v[156:157]
	v_pk_fma_f32 v[38:39], v[54:55], v[24:25], v[38:39]
	v_pk_fma_f32 v[160:161], v[92:93], v[16:17], v[160:161]
	v_pk_fma_f32 v[38:39], v[58:59], v[22:23], v[38:39]
	v_pk_fma_f32 v[158:159], v[92:93], v[26:27], v[158:159]
	v_pk_fma_f32 v[38:39], v[62:63], v[20:21], v[38:39]
	v_pk_fma_f32 v[156:157], v[92:93], v[28:29], v[156:157]
	v_pk_fma_f32 v[38:39], v[66:67], v[18:19], v[38:39]
	v_pk_fma_f32 v[160:161], v[96:97], v[26:27], v[160:161]
	v_pk_fma_f32 v[38:39], v[70:71], v[10:11], v[38:39]
	v_pk_fma_f32 v[158:159], v[96:97], v[28:29], v[158:159]
	v_pk_fma_f32 v[38:39], v[74:75], v[12:13], v[38:39]
	v_pk_fma_f32 v[156:157], v[96:97], v[30:31], v[156:157]
	v_pk_fma_f32 v[38:39], v[78:79], v[14:15], v[38:39]
	v_pk_fma_f32 v[160:161], v[100:101], v[28:29], v[160:161]
	v_pk_fma_f32 v[158:159], v[100:101], v[30:31], v[158:159]
	v_pk_fma_f32 v[156:157], v[100:101], v[32:33], v[156:157]
	v_pk_fma_f32 v[38:39], v[82:83], v[16:17], v[38:39]
	v_add_f32_e32 v177, v160, v161
	v_add_f32_e32 v179, v158, v159
	v_add_f32_e32 v181, v156, v157
	ds_read2st64_b32 v[156:157], v163 offset0:192 offset1:196
	ds_read2st64_b32 v[158:159], v163 offset0:200 offset1:204
	ds_read2st64_b32 v[160:161], v163 offset0:208 offset1:212
	v_pk_fma_f32 v[38:39], v[86:87], v[26:27], v[38:39]
	v_mov_b32_e32 v172, v108
	v_pk_fma_f32 v[38:39], v[90:91], v[28:29], v[38:39]
	s_waitcnt lgkmcnt(2)
	v_mul_f32_e32 v109, v101, v156
	v_pk_fma_f32 v[38:39], v[94:95], v[30:31], v[38:39]
	v_pk_fma_f32 v[172:173], v[44:45], v[36:37], v[172:173]
	v_pk_fma_f32 v[38:39], v[98:99], v[32:33], v[38:39]
	v_pk_fma_f32 v[172:173], v[48:49], v[34:35], v[172:173]
	v_add_f32_e32 v182, v38, v39
	v_mul_f32_e32 v39, v42, v37
	v_pk_fma_f32 v[36:37], v[42:43], v[36:37], v[108:109]
	v_mov_b32_e32 v38, v108
	v_pk_fma_f32 v[36:37], v[46:47], v[34:35], v[36:37]
	s_waitcnt lgkmcnt(1)
	v_mul_f32_e32 v109, v101, v158
	v_pk_fma_f32 v[36:37], v[50:51], v[24:25], v[36:37]
	v_pk_fma_f32 v[38:39], v[44:45], v[34:35], v[38:39]
	v_pk_fma_f32 v[36:37], v[54:55], v[22:23], v[36:37]
	v_pk_fma_f32 v[172:173], v[52:53], v[24:25], v[172:173]
	v_pk_fma_f32 v[36:37], v[58:59], v[20:21], v[36:37]
	v_pk_fma_f32 v[38:39], v[48:49], v[24:25], v[38:39]
	v_pk_fma_f32 v[36:37], v[62:63], v[18:19], v[36:37]
	v_pk_fma_f32 v[172:173], v[56:57], v[22:23], v[172:173]
	v_pk_fma_f32 v[36:37], v[66:67], v[10:11], v[36:37]
	v_pk_fma_f32 v[172:173], v[60:61], v[20:21], v[172:173]
	v_pk_fma_f32 v[36:37], v[70:71], v[12:13], v[36:37]
	v_pk_fma_f32 v[172:173], v[64:65], v[18:19], v[172:173]
	v_pk_fma_f32 v[36:37], v[74:75], v[14:15], v[36:37]
	v_pk_fma_f32 v[172:173], v[68:69], v[10:11], v[172:173]
	v_pk_fma_f32 v[36:37], v[78:79], v[16:17], v[36:37]
	v_pk_fma_f32 v[172:173], v[72:73], v[12:13], v[172:173]
	v_pk_fma_f32 v[36:37], v[82:83], v[26:27], v[36:37]
	v_pk_fma_f32 v[172:173], v[76:77], v[14:15], v[172:173]
	v_pk_fma_f32 v[36:37], v[86:87], v[28:29], v[36:37]
	v_pk_fma_f32 v[172:173], v[80:81], v[16:17], v[172:173]
	v_pk_fma_f32 v[36:37], v[90:91], v[30:31], v[36:37]
	v_pk_fma_f32 v[172:173], v[84:85], v[26:27], v[172:173]
	v_pk_fma_f32 v[36:37], v[94:95], v[32:33], v[36:37]
	v_pk_fma_f32 v[172:173], v[88:89], v[28:29], v[172:173]
	v_pk_fma_f32 v[36:37], v[98:99], v[40:41], v[36:37]
	v_pk_fma_f32 v[172:173], v[92:93], v[30:31], v[172:173]
	v_add_f32_e32 v184, v36, v37
	v_mul_f32_e32 v37, v42, v35
	v_pk_fma_f32 v[34:35], v[42:43], v[34:35], v[108:109]
	v_mov_b32_e32 v36, v108
	v_pk_fma_f32 v[34:35], v[46:47], v[24:25], v[34:35]
	s_waitcnt lgkmcnt(0)
	v_mul_f32_e32 v109, v101, v160
	v_pk_fma_f32 v[34:35], v[50:51], v[22:23], v[34:35]
	v_pk_fma_f32 v[36:37], v[44:45], v[24:25], v[36:37]
	v_pk_fma_f32 v[34:35], v[54:55], v[20:21], v[34:35]
	v_pk_fma_f32 v[36:37], v[48:49], v[22:23], v[36:37]
	v_pk_fma_f32 v[34:35], v[58:59], v[18:19], v[34:35]
	v_pk_fma_f32 v[172:173], v[96:97], v[32:33], v[172:173]
	v_pk_fma_f32 v[34:35], v[62:63], v[10:11], v[34:35]
	v_pk_fma_f32 v[38:39], v[52:53], v[22:23], v[38:39]
	v_pk_fma_f32 v[34:35], v[66:67], v[12:13], v[34:35]
	v_pk_fma_f32 v[36:37], v[52:53], v[20:21], v[36:37]
	v_pk_fma_f32 v[34:35], v[70:71], v[14:15], v[34:35]
	v_pk_fma_f32 v[172:173], v[100:101], v[40:41], v[172:173]
	v_pk_fma_f32 v[34:35], v[74:75], v[16:17], v[34:35]
	v_pk_fma_f32 v[38:39], v[56:57], v[20:21], v[38:39]
	v_pk_fma_f32 v[34:35], v[78:79], v[26:27], v[34:35]
	v_pk_fma_f32 v[36:37], v[56:57], v[18:19], v[36:37]
	v_pk_fma_f32 v[34:35], v[82:83], v[28:29], v[34:35]
	v_add_f32_e32 v183, v172, v173
	v_pk_fma_f32 v[34:35], v[86:87], v[30:31], v[34:35]
	v_pk_fma_f32 v[38:39], v[60:61], v[18:19], v[38:39]
	v_pk_fma_f32 v[34:35], v[90:91], v[32:33], v[34:35]
	v_pk_fma_f32 v[36:37], v[60:61], v[10:11], v[36:37]
	v_pk_fma_f32 v[34:35], v[94:95], v[40:41], v[34:35]
	v_mul_f32_e32 v173, v42, v23
	v_pk_fma_f32 v[34:35], v[98:99], v[156:157], v[34:35]
	v_pk_fma_f32 v[38:39], v[64:65], v[10:11], v[38:39]
	v_add_f32_e32 v186, v34, v35
	v_mul_f32_e32 v35, v42, v25
	v_pk_fma_f32 v[24:25], v[42:43], v[24:25], v[108:109]
	v_mov_b32_e32 v34, v108
	v_pk_fma_f32 v[24:25], v[46:47], v[22:23], v[24:25]
	v_pk_fma_f32 v[34:35], v[44:45], v[22:23], v[34:35]
	v_pk_fma_f32 v[24:25], v[50:51], v[20:21], v[24:25]
	v_pk_fma_f32 v[34:35], v[48:49], v[20:21], v[34:35]
	v_pk_fma_f32 v[24:25], v[54:55], v[18:19], v[24:25]
	v_pk_fma_f32 v[34:35], v[52:53], v[18:19], v[34:35]
	v_pk_fma_f32 v[24:25], v[58:59], v[10:11], v[24:25]
	v_pk_fma_f32 v[34:35], v[56:57], v[10:11], v[34:35]
	v_pk_fma_f32 v[24:25], v[62:63], v[12:13], v[24:25]
	v_pk_fma_f32 v[34:35], v[60:61], v[12:13], v[34:35]
	v_pk_fma_f32 v[24:25], v[66:67], v[14:15], v[24:25]
	v_pk_fma_f32 v[36:37], v[64:65], v[12:13], v[36:37]
	v_pk_fma_f32 v[24:25], v[70:71], v[16:17], v[24:25]
	v_pk_fma_f32 v[34:35], v[64:65], v[14:15], v[34:35]
	v_pk_fma_f32 v[24:25], v[74:75], v[26:27], v[24:25]
	v_pk_fma_f32 v[38:39], v[68:69], v[12:13], v[38:39]
	v_pk_fma_f32 v[24:25], v[78:79], v[28:29], v[24:25]
	v_pk_fma_f32 v[36:37], v[68:69], v[14:15], v[36:37]
	v_pk_fma_f32 v[24:25], v[82:83], v[30:31], v[24:25]
	v_pk_fma_f32 v[34:35], v[68:69], v[16:17], v[34:35]
	v_pk_fma_f32 v[24:25], v[86:87], v[32:33], v[24:25]
	v_pk_fma_f32 v[38:39], v[72:73], v[14:15], v[38:39]
	v_pk_fma_f32 v[24:25], v[90:91], v[40:41], v[24:25]
	v_pk_fma_f32 v[36:37], v[72:73], v[16:17], v[36:37]
	v_pk_fma_f32 v[24:25], v[94:95], v[156:157], v[24:25]
	v_pk_fma_f32 v[34:35], v[72:73], v[26:27], v[34:35]
	v_pk_fma_f32 v[24:25], v[98:99], v[158:159], v[24:25]
	v_pk_fma_f32 v[38:39], v[76:77], v[16:17], v[38:39]
	v_add_f32_e32 v188, v24, v25
	ds_read2st64_b32 v[24:25], v163 offset0:216 offset1:220
	v_pk_fma_f32 v[36:37], v[76:77], v[26:27], v[36:37]
	v_pk_fma_f32 v[34:35], v[76:77], v[28:29], v[34:35]
	v_pk_fma_f32 v[38:39], v[80:81], v[26:27], v[38:39]
	v_pk_fma_f32 v[36:37], v[80:81], v[28:29], v[36:37]
	s_waitcnt lgkmcnt(0)
	v_mul_f32_e32 v109, v101, v24
	v_pk_fma_f32 v[22:23], v[42:43], v[22:23], v[108:109]
	v_pk_fma_f32 v[34:35], v[80:81], v[30:31], v[34:35]
	v_pk_fma_f32 v[22:23], v[46:47], v[20:21], v[22:23]
	v_pk_fma_f32 v[38:39], v[84:85], v[28:29], v[38:39]
	v_pk_fma_f32 v[22:23], v[50:51], v[18:19], v[22:23]
	v_pk_fma_f32 v[36:37], v[84:85], v[30:31], v[36:37]
	v_pk_fma_f32 v[22:23], v[54:55], v[10:11], v[22:23]
	v_pk_fma_f32 v[34:35], v[84:85], v[32:33], v[34:35]
	v_pk_fma_f32 v[22:23], v[58:59], v[12:13], v[22:23]
	v_pk_fma_f32 v[38:39], v[88:89], v[30:31], v[38:39]
	v_pk_fma_f32 v[22:23], v[62:63], v[14:15], v[22:23]
	v_pk_fma_f32 v[36:37], v[88:89], v[32:33], v[36:37]
	v_pk_fma_f32 v[22:23], v[66:67], v[16:17], v[22:23]
	v_pk_fma_f32 v[34:35], v[88:89], v[40:41], v[34:35]
	v_pk_fma_f32 v[22:23], v[70:71], v[26:27], v[22:23]
	v_pk_fma_f32 v[38:39], v[92:93], v[32:33], v[38:39]
	v_pk_fma_f32 v[36:37], v[92:93], v[40:41], v[36:37]
	v_pk_fma_f32 v[34:35], v[92:93], v[156:157], v[34:35]
	v_pk_fma_f32 v[22:23], v[74:75], v[28:29], v[22:23]
	v_pk_fma_f32 v[38:39], v[96:97], v[40:41], v[38:39]
	v_pk_fma_f32 v[36:37], v[96:97], v[156:157], v[36:37]
	v_pk_fma_f32 v[34:35], v[96:97], v[158:159], v[34:35]
	v_pk_fma_f32 v[22:23], v[78:79], v[30:31], v[22:23]
	v_pk_fma_f32 v[38:39], v[100:101], v[156:157], v[38:39]
	v_pk_fma_f32 v[36:37], v[100:101], v[158:159], v[36:37]
	v_pk_fma_f32 v[34:35], v[100:101], v[160:161], v[34:35]
	v_pk_fma_f32 v[22:23], v[82:83], v[32:33], v[22:23]
	v_add_f32_e32 v185, v38, v39
	v_add_f32_e32 v187, v36, v37
	v_add_f32_e32 v189, v34, v35
	ds_read2st64_b32 v[34:35], v163 offset0:224 offset1:228
	ds_read2st64_b32 v[36:37], v163 offset0:232 offset1:236
	ds_read2st64_b32 v[38:39], v163 offset0:240 offset1:244
	v_pk_fma_f32 v[22:23], v[86:87], v[40:41], v[22:23]
	v_mov_b32_e32 v172, v108
	v_pk_fma_f32 v[22:23], v[90:91], v[156:157], v[22:23]
	s_waitcnt lgkmcnt(2)
	v_mul_f32_e32 v109, v101, v34
	v_pk_fma_f32 v[22:23], v[94:95], v[158:159], v[22:23]
	v_pk_fma_f32 v[172:173], v[44:45], v[20:21], v[172:173]
	v_pk_fma_f32 v[22:23], v[98:99], v[160:161], v[22:23]
	v_pk_fma_f32 v[172:173], v[48:49], v[18:19], v[172:173]
	v_add_f32_e32 v190, v22, v23
	v_mul_f32_e32 v23, v42, v21
	v_pk_fma_f32 v[20:21], v[42:43], v[20:21], v[108:109]
	v_pk_fma_f32 v[172:173], v[52:53], v[10:11], v[172:173]
	v_pk_fma_f32 v[20:21], v[46:47], v[18:19], v[20:21]
	v_pk_fma_f32 v[172:173], v[56:57], v[12:13], v[172:173]
	v_pk_fma_f32 v[20:21], v[50:51], v[10:11], v[20:21]
	v_pk_fma_f32 v[172:173], v[60:61], v[14:15], v[172:173]
	v_pk_fma_f32 v[20:21], v[54:55], v[12:13], v[20:21]
	v_pk_fma_f32 v[172:173], v[64:65], v[16:17], v[172:173]
	v_pk_fma_f32 v[20:21], v[58:59], v[14:15], v[20:21]
	v_pk_fma_f32 v[172:173], v[68:69], v[26:27], v[172:173]
	v_pk_fma_f32 v[20:21], v[62:63], v[16:17], v[20:21]
	v_pk_fma_f32 v[172:173], v[72:73], v[28:29], v[172:173]
	v_pk_fma_f32 v[20:21], v[66:67], v[26:27], v[20:21]
	v_pk_fma_f32 v[172:173], v[76:77], v[30:31], v[172:173]
	v_pk_fma_f32 v[20:21], v[70:71], v[28:29], v[20:21]
	v_pk_fma_f32 v[172:173], v[80:81], v[32:33], v[172:173]
	v_pk_fma_f32 v[20:21], v[74:75], v[30:31], v[20:21]
	v_pk_fma_f32 v[172:173], v[84:85], v[40:41], v[172:173]
	v_pk_fma_f32 v[20:21], v[78:79], v[32:33], v[20:21]
	v_pk_fma_f32 v[172:173], v[88:89], v[156:157], v[172:173]
	v_pk_fma_f32 v[20:21], v[82:83], v[40:41], v[20:21]
	v_pk_fma_f32 v[172:173], v[92:93], v[158:159], v[172:173]
	v_pk_fma_f32 v[20:21], v[86:87], v[156:157], v[20:21]
	v_pk_fma_f32 v[172:173], v[96:97], v[160:161], v[172:173]
	v_pk_fma_f32 v[20:21], v[90:91], v[158:159], v[20:21]
	v_pk_fma_f32 v[172:173], v[100:101], v[24:25], v[172:173]
	v_pk_fma_f32 v[20:21], v[94:95], v[160:161], v[20:21]
	v_mov_b32_e32 v22, v108
	v_pk_fma_f32 v[20:21], v[98:99], v[24:25], v[20:21]
	s_waitcnt lgkmcnt(1)
	v_mul_f32_e32 v109, v101, v36
	v_add_f32_e32 v172, v172, v173
	v_pk_fma_f32 v[22:23], v[44:45], v[18:19], v[22:23]
	v_add_f32_e32 v173, v20, v21
	v_mul_f32_e32 v21, v42, v19
	v_pk_fma_f32 v[18:19], v[42:43], v[18:19], v[108:109]
	v_pk_fma_f32 v[22:23], v[48:49], v[10:11], v[22:23]
	v_pk_fma_f32 v[18:19], v[46:47], v[10:11], v[18:19]
	v_pk_fma_f32 v[22:23], v[52:53], v[12:13], v[22:23]
	v_pk_fma_f32 v[18:19], v[50:51], v[12:13], v[18:19]
	v_pk_fma_f32 v[22:23], v[56:57], v[14:15], v[22:23]
	v_pk_fma_f32 v[18:19], v[54:55], v[14:15], v[18:19]
	v_pk_fma_f32 v[22:23], v[60:61], v[16:17], v[22:23]
	v_pk_fma_f32 v[18:19], v[58:59], v[16:17], v[18:19]
	v_pk_fma_f32 v[22:23], v[64:65], v[26:27], v[22:23]
	v_pk_fma_f32 v[18:19], v[62:63], v[26:27], v[18:19]
	v_pk_fma_f32 v[22:23], v[68:69], v[28:29], v[22:23]
	v_pk_fma_f32 v[18:19], v[66:67], v[28:29], v[18:19]
	v_pk_fma_f32 v[22:23], v[72:73], v[30:31], v[22:23]
	v_pk_fma_f32 v[18:19], v[70:71], v[30:31], v[18:19]
	v_pk_fma_f32 v[22:23], v[76:77], v[32:33], v[22:23]
	v_pk_fma_f32 v[18:19], v[74:75], v[32:33], v[18:19]
	v_pk_fma_f32 v[22:23], v[80:81], v[40:41], v[22:23]
	v_pk_fma_f32 v[18:19], v[78:79], v[40:41], v[18:19]
	v_pk_fma_f32 v[22:23], v[84:85], v[156:157], v[22:23]
	v_pk_fma_f32 v[18:19], v[82:83], v[156:157], v[18:19]
	v_pk_fma_f32 v[22:23], v[88:89], v[158:159], v[22:23]
	v_pk_fma_f32 v[18:19], v[86:87], v[158:159], v[18:19]
	v_pk_fma_f32 v[22:23], v[92:93], v[160:161], v[22:23]
	v_pk_fma_f32 v[18:19], v[90:91], v[160:161], v[18:19]
	v_pk_fma_f32 v[22:23], v[96:97], v[24:25], v[22:23]
	v_pk_fma_f32 v[18:19], v[94:95], v[24:25], v[18:19]
	v_pk_fma_f32 v[22:23], v[100:101], v[34:35], v[22:23]
	v_pk_fma_f32 v[18:19], v[98:99], v[34:35], v[18:19]
	v_add_f32_e32 v22, v22, v23
	v_mov_b32_e32 v20, v108
	v_add_f32_e32 v23, v18, v19
	s_waitcnt lgkmcnt(0)
	v_mul_f32_e32 v109, v101, v38
	v_mul_f32_e32 v19, v42, v11
	v_mov_b32_e32 v18, v108
	v_pk_fma_f32 v[20:21], v[44:45], v[10:11], v[20:21]
	v_pk_fma_f32 v[10:11], v[42:43], v[10:11], v[108:109]
	v_pk_fma_f32 v[18:19], v[44:45], v[12:13], v[18:19]
	v_pk_fma_f32 v[20:21], v[48:49], v[12:13], v[20:21]
	v_pk_fma_f32 v[10:11], v[46:47], v[12:13], v[10:11]
	v_pk_fma_f32 v[12:13], v[48:49], v[14:15], v[18:19]
	v_pk_fma_f32 v[20:21], v[52:53], v[14:15], v[20:21]
	v_pk_fma_f32 v[10:11], v[50:51], v[14:15], v[10:11]
	v_pk_fma_f32 v[12:13], v[52:53], v[16:17], v[12:13]
	v_pk_fma_f32 v[20:21], v[56:57], v[16:17], v[20:21]
	v_pk_fma_f32 v[10:11], v[54:55], v[16:17], v[10:11]
	v_pk_fma_f32 v[12:13], v[56:57], v[26:27], v[12:13]
	v_pk_fma_f32 v[20:21], v[60:61], v[26:27], v[20:21]
	v_pk_fma_f32 v[10:11], v[58:59], v[26:27], v[10:11]
	v_pk_fma_f32 v[12:13], v[60:61], v[28:29], v[12:13]
	v_pk_fma_f32 v[20:21], v[64:65], v[28:29], v[20:21]
	v_pk_fma_f32 v[10:11], v[62:63], v[28:29], v[10:11]
	v_pk_fma_f32 v[12:13], v[64:65], v[30:31], v[12:13]
	v_pk_fma_f32 v[20:21], v[68:69], v[30:31], v[20:21]
	v_pk_fma_f32 v[10:11], v[66:67], v[30:31], v[10:11]
	v_pk_fma_f32 v[12:13], v[68:69], v[32:33], v[12:13]
	v_pk_fma_f32 v[20:21], v[72:73], v[32:33], v[20:21]
	v_pk_fma_f32 v[10:11], v[70:71], v[32:33], v[10:11]
	v_pk_fma_f32 v[12:13], v[72:73], v[40:41], v[12:13]
	v_pk_fma_f32 v[20:21], v[76:77], v[40:41], v[20:21]
	v_pk_fma_f32 v[10:11], v[74:75], v[40:41], v[10:11]
	v_pk_fma_f32 v[12:13], v[76:77], v[156:157], v[12:13]
	v_pk_fma_f32 v[20:21], v[80:81], v[156:157], v[20:21]
	v_pk_fma_f32 v[10:11], v[78:79], v[156:157], v[10:11]
	v_pk_fma_f32 v[12:13], v[80:81], v[158:159], v[12:13]
	v_pk_fma_f32 v[20:21], v[84:85], v[158:159], v[20:21]
	v_pk_fma_f32 v[10:11], v[82:83], v[158:159], v[10:11]
	v_pk_fma_f32 v[12:13], v[84:85], v[160:161], v[12:13]
	v_pk_fma_f32 v[20:21], v[88:89], v[160:161], v[20:21]
	v_pk_fma_f32 v[10:11], v[86:87], v[160:161], v[10:11]
	v_pk_fma_f32 v[12:13], v[88:89], v[24:25], v[12:13]
	v_pk_fma_f32 v[20:21], v[92:93], v[24:25], v[20:21]
	v_pk_fma_f32 v[10:11], v[90:91], v[24:25], v[10:11]
	v_pk_fma_f32 v[12:13], v[92:93], v[34:35], v[12:13]
	s_lshl_b32 s6, s28, 10
	v_pk_fma_f32 v[20:21], v[96:97], v[34:35], v[20:21]
	v_pk_fma_f32 v[10:11], v[94:95], v[34:35], v[10:11]
	v_pk_fma_f32 v[12:13], v[96:97], v[36:37], v[12:13]
	s_add_i32 s6, s6, 0
	v_pk_fma_f32 v[20:21], v[100:101], v[36:37], v[20:21]
	v_pk_fma_f32 v[10:11], v[98:99], v[36:37], v[10:11]
	v_pk_fma_f32 v[12:13], v[100:101], v[38:39], v[12:13]
	v_add_u32_e32 v109, s6, v162
	v_add_f32_e32 v20, v20, v21
	v_add_f32_e32 v10, v10, v11
	v_add_f32_e32 v11, v12, v13
	s_barrier
	ds_write2st64_b32 v163, v164, v165 offset1:4
	ds_write2st64_b32 v163, v166, v167 offset0:8 offset1:12
	ds_write2st64_b32 v163, v168, v169 offset0:16 offset1:20
	ds_write2st64_b32 v163, v170, v171 offset0:24 offset1:28
	ds_write2st64_b32 v163, v174, v175 offset0:32 offset1:36
	ds_write2st64_b32 v163, v176, v177 offset0:40 offset1:44
	ds_write2st64_b32 v163, v178, v179 offset0:48 offset1:52
	ds_write2st64_b32 v163, v180, v181 offset0:56 offset1:60
	ds_write2st64_b32 v163, v182, v183 offset0:64 offset1:68
	ds_write2st64_b32 v163, v184, v185 offset0:72 offset1:76
	ds_write2st64_b32 v163, v186, v187 offset0:80 offset1:84
	ds_write2st64_b32 v163, v188, v189 offset0:88 offset1:92
	ds_write2st64_b32 v163, v190, v172 offset0:96 offset1:100
	ds_write2st64_b32 v163, v173, v22 offset0:104 offset1:108
	ds_write2st64_b32 v163, v23, v20 offset0:112 offset1:116
	ds_write2st64_b32 v163, v10, v11 offset0:120 offset1:124
	s_waitcnt lgkmcnt(0)
	s_barrier
	ds_read_b128 v[38:41], v109
	ds_read_b128 v[34:37], v109 offset:8192
	ds_read_b128 v[30:33], v109 offset:16384
	ds_read_b128 v[26:29], v109 offset:24576
	ds_read_b128 v[22:25], v109 offset:32768
	ds_read_b128 v[18:21], v109 offset:40960
	s_waitcnt lgkmcnt(5)
	v_mov_b32_e32 v10, v39
	v_mov_b32_e32 v11, v40
	v_mov_b32_e32 v12, v38
	v_mov_b32_e32 v13, v41
	v_pk_add_f32 v[10:11], v[10:11], v[12:13]
	s_waitcnt lgkmcnt(4)
	v_mov_b32_e32 v12, v34
	v_add_f32_e32 v160, v10, v11
	v_mov_b32_e32 v10, v35
	v_mov_b32_e32 v11, v36
	v_mov_b32_e32 v13, v37
	v_pk_add_f32 v[10:11], v[10:11], v[12:13]
	s_waitcnt lgkmcnt(3)
	v_mov_b32_e32 v12, v30
	v_add_f32_e32 v161, v10, v11
	v_mov_b32_e32 v10, v31
	v_mov_b32_e32 v11, v32
	v_mov_b32_e32 v13, v33
	v_pk_add_f32 v[10:11], v[10:11], v[12:13]
	s_waitcnt lgkmcnt(2)
	v_mov_b32_e32 v12, v26
	v_add_f32_e32 v162, v10, v11
	v_mov_b32_e32 v10, v27
	v_mov_b32_e32 v11, v28
	v_mov_b32_e32 v13, v29
	v_pk_add_f32 v[10:11], v[10:11], v[12:13]
	s_waitcnt lgkmcnt(1)
	v_mov_b32_e32 v12, v22
	v_add_f32_e32 v163, v10, v11
	v_mov_b32_e32 v10, v23
	v_mov_b32_e32 v11, v24
	v_mov_b32_e32 v13, v25
	v_pk_add_f32 v[10:11], v[10:11], v[12:13]
	s_waitcnt lgkmcnt(0)
	v_mov_b32_e32 v12, v18
	v_add_f32_e32 v164, v10, v11
	v_mov_b32_e32 v10, v19
	v_mov_b32_e32 v11, v20
	ds_read_b128 v[14:17], v109 offset:49152
	v_mov_b32_e32 v13, v21
	v_pk_add_f32 v[10:11], v[10:11], v[12:13]
	s_add_i32 s28, s57, s28
	v_add_f32_e32 v165, v10, v11
	ds_read_b128 v[10:13], v109 offset:57344
	s_waitcnt lgkmcnt(1)
	v_mov_b32_e32 v156, v15
	v_mov_b32_e32 v157, v16
	v_mov_b32_e32 v158, v14
	v_mov_b32_e32 v159, v17
	v_pk_add_f32 v[156:157], v[156:157], v[158:159]
	s_waitcnt lgkmcnt(0)
	v_mov_b32_e32 v158, v10
	v_add_f32_e32 v109, v156, v157
	v_mov_b32_e32 v156, v11
	v_mov_b32_e32 v157, v12
	v_mov_b32_e32 v159, v13
	v_pk_add_f32 v[156:157], v[156:157], v[158:159]
	v_add_f32_dpp v158, v161, v161 quad_perm:[1,0,3,2] row_mask:0xf bank_mask:0xf bound_ctrl:1
	v_add_f32_e32 v156, v156, v157
	v_add_f32_dpp v157, v160, v160 quad_perm:[1,0,3,2] row_mask:0xf bank_mask:0xf bound_ctrl:1
	v_add_f32_dpp v160, v163, v163 quad_perm:[1,0,3,2] row_mask:0xf bank_mask:0xf bound_ctrl:1
	v_add_f32_dpp v158, v158, v158 quad_perm:[2,3,0,1] row_mask:0xf bank_mask:0xf bound_ctrl:1
	v_add_f32_dpp v157, v157, v157 quad_perm:[2,3,0,1] row_mask:0xf bank_mask:0xf bound_ctrl:1
	v_add_f32_dpp v159, v162, v162 quad_perm:[1,0,3,2] row_mask:0xf bank_mask:0xf bound_ctrl:1
	s_nop 0
	v_add_f32_dpp v157, v157, v157 row_half_mirror row_mask:0xf bank_mask:0xf bound_ctrl:1
	v_add_f32_dpp v158, v158, v158 row_half_mirror row_mask:0xf bank_mask:0xf bound_ctrl:1
	v_add_f32_dpp v159, v159, v159 quad_perm:[2,3,0,1] row_mask:0xf bank_mask:0xf bound_ctrl:1
	v_add_f32_dpp v157, v157, v157 row_mirror row_mask:0xf bank_mask:0xf bound_ctrl:1
	v_add_f32_dpp v158, v158, v158 row_mirror row_mask:0xf bank_mask:0xf bound_ctrl:1
	v_add_f32_dpp v159, v159, v159 row_half_mirror row_mask:0xf bank_mask:0xf bound_ctrl:1
	v_add_f32_dpp v157, v157, v157 row_bcast:15 row_mask:0xa bank_mask:0xf
	v_add_f32_dpp v160, v160, v160 quad_perm:[2,3,0,1] row_mask:0xf bank_mask:0xf bound_ctrl:1
	v_add_f32_dpp v159, v159, v159 row_mirror row_mask:0xf bank_mask:0xf bound_ctrl:1
	v_add_f32_dpp v158, v158, v158 row_bcast:15 row_mask:0xa bank_mask:0xf
	v_add_f32_dpp v161, v164, v164 quad_perm:[1,0,3,2] row_mask:0xf bank_mask:0xf bound_ctrl:1
	v_add_f32_dpp v160, v160, v160 row_half_mirror row_mask:0xf bank_mask:0xf bound_ctrl:1
	v_add_f32_dpp v159, v159, v159 row_bcast:15 row_mask:0xa bank_mask:0xf
	v_add_f32_dpp v161, v161, v161 quad_perm:[2,3,0,1] row_mask:0xf bank_mask:0xf bound_ctrl:1
	v_add_f32_dpp v160, v160, v160 row_mirror row_mask:0xf bank_mask:0xf bound_ctrl:1
	v_add_f32_dpp v162, v165, v165 quad_perm:[1,0,3,2] row_mask:0xf bank_mask:0xf bound_ctrl:1
	v_add_f32_dpp v161, v161, v161 row_half_mirror row_mask:0xf bank_mask:0xf bound_ctrl:1
	v_add_f32_dpp v160, v160, v160 row_bcast:15 row_mask:0xa bank_mask:0xf
	v_add_f32_dpp v162, v162, v162 quad_perm:[2,3,0,1] row_mask:0xf bank_mask:0xf bound_ctrl:1
	v_add_f32_dpp v161, v161, v161 row_mirror row_mask:0xf bank_mask:0xf bound_ctrl:1
	v_add_f32_dpp v109, v109, v109 quad_perm:[1,0,3,2] row_mask:0xf bank_mask:0xf bound_ctrl:1
	v_add_f32_dpp v162, v162, v162 row_half_mirror row_mask:0xf bank_mask:0xf bound_ctrl:1
	v_add_f32_dpp v161, v161, v161 row_bcast:15 row_mask:0xa bank_mask:0xf
	v_add_f32_dpp v109, v109, v109 quad_perm:[2,3,0,1] row_mask:0xf bank_mask:0xf bound_ctrl:1
	v_add_f32_dpp v162, v162, v162 row_mirror row_mask:0xf bank_mask:0xf bound_ctrl:1
	v_add_f32_dpp v156, v156, v156 quad_perm:[1,0,3,2] row_mask:0xf bank_mask:0xf bound_ctrl:1
	v_add_f32_dpp v109, v109, v109 row_half_mirror row_mask:0xf bank_mask:0xf bound_ctrl:1
	v_add_f32_dpp v162, v162, v162 row_bcast:15 row_mask:0xa bank_mask:0xf
	v_add_f32_dpp v156, v156, v156 quad_perm:[2,3,0,1] row_mask:0xf bank_mask:0xf bound_ctrl:1
	v_add_f32_dpp v109, v109, v109 row_mirror row_mask:0xf bank_mask:0xf bound_ctrl:1
	s_nop 0
	v_add_f32_dpp v156, v156, v156 row_half_mirror row_mask:0xf bank_mask:0xf bound_ctrl:1
	s_nop 0
	v_add_f32_dpp v109, v109, v109 row_bcast:15 row_mask:0xa bank_mask:0xf
	v_add_f32_dpp v156, v156, v156 row_mirror row_mask:0xf bank_mask:0xf bound_ctrl:1
	s_nop 1
	v_add_f32_dpp v156, v156, v156 row_bcast:15 row_mask:0xa bank_mask:0xf
	s_nop 1
	v_add_f32_dpp v157, v157, v157 row_bcast:31 row_mask:0xc bank_mask:0xf
	s_nop 0
	v_readlane_b32 s6, v157, 63
	s_nop 0
	v_add_f32_dpp v158, v158, v158 row_bcast:31 row_mask:0xc bank_mask:0xf
	v_fma_f32 v39, s6, v239, v39
	v_fma_f32 v38, s6, v239, v38
	v_add_f32_dpp v159, v159, v159 row_bcast:31 row_mask:0xc bank_mask:0xf
	v_fma_f32 v41, s6, v239, v41
	v_fmac_f32_e32 v40, s6, v239
	v_add_f32_dpp v160, v160, v160 row_bcast:31 row_mask:0xc bank_mask:0xf
	v_readlane_b32 s7, v158, 63
	v_readlane_b32 s8, v159, 63
	v_add_f32_dpp v161, v161, v161 row_bcast:31 row_mask:0xc bank_mask:0xf
	v_pk_mul_f32 v[158:159], v[38:39], v[38:39]
	v_readlane_b32 s9, v160, 63
	v_add_f32_dpp v162, v162, v162 row_bcast:31 row_mask:0xc bank_mask:0xf
	v_readlane_b32 s10, v161, 63
	v_fma_f32 v35, s7, v239, v35
	v_add_f32_dpp v109, v109, v109 row_bcast:31 row_mask:0xc bank_mask:0xf
	v_fma_f32 v34, s7, v239, v34
	v_fma_f32 v37, s7, v239, v37
	v_add_f32_dpp v156, v156, v156 row_bcast:31 row_mask:0xc bank_mask:0xf
	v_fmac_f32_e32 v36, s7, v239
	v_readlane_b32 s60, v156, 63
	v_pk_mul_f32 v[156:157], v[40:41], v[40:41]
	v_readlane_b32 s29, v109, 63
	v_pk_mov_b32 v[160:161], v[158:159], v[156:157] op_sel:[1,0]
	v_mov_b32_e32 v159, v157
	v_pk_add_f32 v[156:157], v[160:161], v[158:159]
	v_pk_mul_f32 v[158:159], v[34:35], v[34:35]
	v_add_f32_e32 v109, v156, v157
	v_pk_mul_f32 v[156:157], v[36:37], v[36:37]
	v_fma_f32 v31, s8, v239, v31
	v_pk_mov_b32 v[160:161], v[158:159], v[156:157] op_sel:[1,0]
	v_mov_b32_e32 v159, v157
	v_pk_add_f32 v[156:157], v[160:161], v[158:159]
	v_fma_f32 v30, s8, v239, v30
	v_fma_f32 v33, s8, v239, v33
	v_fmac_f32_e32 v32, s8, v239
	v_readlane_b32 s11, v162, 63
	v_add_f32_e32 v162, v156, v157
	v_pk_mul_f32 v[156:157], v[32:33], v[32:33]
	v_pk_mul_f32 v[158:159], v[30:31], v[30:31]
	v_fma_f32 v27, s9, v239, v27
	v_pk_mov_b32 v[160:161], v[158:159], v[156:157] op_sel:[1,0]
	v_mov_b32_e32 v159, v157
	v_pk_add_f32 v[156:157], v[160:161], v[158:159]
	v_fma_f32 v26, s9, v239, v26
	v_fma_f32 v29, s9, v239, v29
	v_fmac_f32_e32 v28, s9, v239
	v_add_f32_e32 v163, v156, v157
	v_pk_mul_f32 v[156:157], v[28:29], v[28:29]
	v_pk_mul_f32 v[158:159], v[26:27], v[26:27]
	v_fma_f32 v23, s10, v239, v23
	v_pk_mov_b32 v[160:161], v[158:159], v[156:157] op_sel:[1,0]
	v_mov_b32_e32 v159, v157
	v_pk_add_f32 v[156:157], v[160:161], v[158:159]
	v_fma_f32 v22, s10, v239, v22
	v_fma_f32 v25, s10, v239, v25
	v_fmac_f32_e32 v24, s10, v239
	v_add_f32_e32 v164, v156, v157
	v_pk_mul_f32 v[156:157], v[24:25], v[24:25]
	v_pk_mul_f32 v[158:159], v[22:23], v[22:23]
	v_fma_f32 v19, s11, v239, v19
	v_pk_mov_b32 v[160:161], v[158:159], v[156:157] op_sel:[1,0]
	v_mov_b32_e32 v159, v157
	v_pk_add_f32 v[156:157], v[160:161], v[158:159]
	v_fma_f32 v18, s11, v239, v18
	v_fma_f32 v21, s11, v239, v21
	v_fmac_f32_e32 v20, s11, v239
	v_add_f32_e32 v165, v156, v157
	v_pk_mul_f32 v[156:157], v[20:21], v[20:21]
	v_pk_mul_f32 v[158:159], v[18:19], v[18:19]
	v_fma_f32 v15, s29, v239, v15
	v_pk_mov_b32 v[160:161], v[158:159], v[156:157] op_sel:[1,0]
	v_mov_b32_e32 v159, v157
	v_pk_add_f32 v[156:157], v[160:161], v[158:159]
	v_fma_f32 v14, s29, v239, v14
	v_fma_f32 v17, s29, v239, v17
	v_fmac_f32_e32 v16, s29, v239
	v_add_f32_e32 v166, v156, v157
	v_pk_mul_f32 v[156:157], v[16:17], v[16:17]
	v_pk_mul_f32 v[158:159], v[14:15], v[14:15]
	v_fma_f32 v11, s60, v239, v11
	v_pk_mov_b32 v[160:161], v[158:159], v[156:157] op_sel:[1,0]
	v_mov_b32_e32 v159, v157
	v_pk_add_f32 v[156:157], v[160:161], v[158:159]
	v_fma_f32 v10, s60, v239, v10
	v_fma_f32 v13, s60, v239, v13
	v_fmac_f32_e32 v12, s60, v239
	v_add_f32_e32 v167, v156, v157
	v_pk_mul_f32 v[156:157], v[12:13], v[12:13]
	v_pk_mul_f32 v[158:159], v[10:11], v[10:11]
	v_add_f32_dpp v109, v109, v109 quad_perm:[1,0,3,2] row_mask:0xf bank_mask:0xf bound_ctrl:1
	v_pk_mov_b32 v[160:161], v[158:159], v[156:157] op_sel:[1,0]
	v_mov_b32_e32 v159, v157
	v_pk_add_f32 v[156:157], v[160:161], v[158:159]
	v_add_f32_dpp v109, v109, v109 quad_perm:[2,3,0,1] row_mask:0xf bank_mask:0xf bound_ctrl:1
	v_add_f32_e32 v156, v156, v157
	v_add_f32_dpp v157, v162, v162 quad_perm:[1,0,3,2] row_mask:0xf bank_mask:0xf bound_ctrl:1
	v_add_f32_dpp v109, v109, v109 row_half_mirror row_mask:0xf bank_mask:0xf bound_ctrl:1
	v_add_f32_dpp v158, v163, v163 quad_perm:[1,0,3,2] row_mask:0xf bank_mask:0xf bound_ctrl:1
	v_add_f32_dpp v157, v157, v157 quad_perm:[2,3,0,1] row_mask:0xf bank_mask:0xf bound_ctrl:1
	v_add_f32_dpp v109, v109, v109 row_mirror row_mask:0xf bank_mask:0xf bound_ctrl:1
	s_nop 0
	v_add_f32_dpp v157, v157, v157 row_half_mirror row_mask:0xf bank_mask:0xf bound_ctrl:1
	v_add_f32_dpp v158, v158, v158 quad_perm:[2,3,0,1] row_mask:0xf bank_mask:0xf bound_ctrl:1
	v_add_f32_dpp v109, v109, v109 row_bcast:15 row_mask:0xa bank_mask:0xf
	v_add_f32_dpp v157, v157, v157 row_mirror row_mask:0xf bank_mask:0xf bound_ctrl:1
	v_add_f32_dpp v159, v164, v164 quad_perm:[1,0,3,2] row_mask:0xf bank_mask:0xf bound_ctrl:1
	v_add_f32_dpp v158, v158, v158 row_half_mirror row_mask:0xf bank_mask:0xf bound_ctrl:1
	v_add_f32_dpp v157, v157, v157 row_bcast:15 row_mask:0xa bank_mask:0xf
	v_add_f32_dpp v159, v159, v159 quad_perm:[2,3,0,1] row_mask:0xf bank_mask:0xf bound_ctrl:1
	v_add_f32_dpp v158, v158, v158 row_mirror row_mask:0xf bank_mask:0xf bound_ctrl:1
	v_add_f32_dpp v160, v165, v165 quad_perm:[1,0,3,2] row_mask:0xf bank_mask:0xf bound_ctrl:1
	v_add_f32_dpp v159, v159, v159 row_half_mirror row_mask:0xf bank_mask:0xf bound_ctrl:1
	v_add_f32_dpp v158, v158, v158 row_bcast:15 row_mask:0xa bank_mask:0xf
	v_add_f32_dpp v160, v160, v160 quad_perm:[2,3,0,1] row_mask:0xf bank_mask:0xf bound_ctrl:1
	v_add_f32_dpp v159, v159, v159 row_mirror row_mask:0xf bank_mask:0xf bound_ctrl:1
	v_add_f32_dpp v161, v166, v166 quad_perm:[1,0,3,2] row_mask:0xf bank_mask:0xf bound_ctrl:1
	v_add_f32_dpp v160, v160, v160 row_half_mirror row_mask:0xf bank_mask:0xf bound_ctrl:1
	v_add_f32_dpp v159, v159, v159 row_bcast:15 row_mask:0xa bank_mask:0xf
	v_add_f32_dpp v161, v161, v161 quad_perm:[2,3,0,1] row_mask:0xf bank_mask:0xf bound_ctrl:1
	v_add_f32_dpp v160, v160, v160 row_mirror row_mask:0xf bank_mask:0xf bound_ctrl:1
	v_add_f32_dpp v162, v167, v167 quad_perm:[1,0,3,2] row_mask:0xf bank_mask:0xf bound_ctrl:1
	v_add_f32_dpp v161, v161, v161 row_half_mirror row_mask:0xf bank_mask:0xf bound_ctrl:1
	v_add_f32_dpp v160, v160, v160 row_bcast:15 row_mask:0xa bank_mask:0xf
	v_add_f32_dpp v162, v162, v162 quad_perm:[2,3,0,1] row_mask:0xf bank_mask:0xf bound_ctrl:1
	v_add_f32_dpp v161, v161, v161 row_mirror row_mask:0xf bank_mask:0xf bound_ctrl:1
	v_add_f32_dpp v156, v156, v156 quad_perm:[1,0,3,2] row_mask:0xf bank_mask:0xf bound_ctrl:1
	v_add_f32_dpp v162, v162, v162 row_half_mirror row_mask:0xf bank_mask:0xf bound_ctrl:1
	v_add_f32_dpp v161, v161, v161 row_bcast:15 row_mask:0xa bank_mask:0xf
	v_add_f32_dpp v156, v156, v156 quad_perm:[2,3,0,1] row_mask:0xf bank_mask:0xf bound_ctrl:1
	v_add_f32_dpp v162, v162, v162 row_mirror row_mask:0xf bank_mask:0xf bound_ctrl:1
	s_nop 0
	v_add_f32_dpp v156, v156, v156 row_half_mirror row_mask:0xf bank_mask:0xf bound_ctrl:1
	s_ashr_i32 s29, s28, 31
	v_add_f32_dpp v162, v162, v162 row_bcast:15 row_mask:0xa bank_mask:0xf
	v_add_f32_dpp v156, v156, v156 row_mirror row_mask:0xf bank_mask:0xf bound_ctrl:1
	s_lshl_b64 s[8:9], s[28:29], 11
	s_add_u32 s8, s76, s8
	v_add_f32_dpp v156, v156, v156 row_bcast:15 row_mask:0xa bank_mask:0xf
	s_addc_u32 s9, s77, s9
	s_nop 0
	v_add_f32_dpp v109, v109, v109 row_bcast:31 row_mask:0xc bank_mask:0xf
	s_nop 0
	v_readlane_b32 s6, v109, 63
	s_nop 0
	v_add_f32_dpp v157, v157, v157 row_bcast:31 row_mask:0xc bank_mask:0xf
	v_fma_f32 v109, s6, v235, v225
	v_readlane_b32 s10, v157, 63
	v_add_f32_dpp v158, v158, v158 row_bcast:31 row_mask:0xc bank_mask:0xf
	s_nop 0
	v_readlane_b32 s11, v158, 63
	s_nop 0
	v_add_f32_dpp v159, v159, v159 row_bcast:31 row_mask:0xc bank_mask:0xf
	s_nop 0
	v_readlane_b32 s65, v159, 63
	s_nop 0
	v_add_f32_dpp v160, v160, v160 row_bcast:31 row_mask:0xc bank_mask:0xf
	s_nop 0
	v_readlane_b32 s61, v160, 63
	s_nop 0
	v_add_f32_dpp v161, v161, v161 row_bcast:31 row_mask:0xc bank_mask:0xf
	s_nop 0
	v_readlane_b32 s60, v161, 63
	s_nop 0
	v_add_f32_dpp v162, v162, v162 row_bcast:31 row_mask:0xc bank_mask:0xf
	v_mov_b32_e32 v163, v131
	v_readlane_b32 s7, v162, 63
	s_nop 0
	v_mov_b32_dpp v163, v156 row_bcast:31 row_mask:0xc bank_mask:0xf
	v_add_f32_e32 v163, v156, v163
	v_rsq_f32_e32 v156, v109
	v_readlane_b32 s6, v163, 63
	v_pk_mul_f32 v[38:39], v[38:39], v[156:157] op_sel_hi:[1,0]
	s_nop 0
	v_pk_fma_f32 v[38:39], v[2:3], v[38:39], v[6:7]
	v_pk_mul_f32 v[40:41], v[40:41], v[156:157] op_sel_hi:[1,0]
	v_mul_f32_e32 v109, 0xbfb8aa3b, v38
	v_exp_f32_e32 v109, v109
	v_mul_f32_e32 v156, 0xbfb8aa3b, v39
	v_exp_f32_e32 v157, v156
	v_pk_fma_f32 v[40:41], v[4:5], v[40:41], v[8:9]
	v_add_f32_e32 v109, 1.0, v109
	v_rcp_f32_e32 v156, v109
	v_add_f32_e32 v109, 1.0, v157
	v_mul_f32_e32 v157, 0xbfb8aa3b, v40
	v_exp_f32_e32 v158, v157
	v_mul_f32_e32 v157, 0xbfb8aa3b, v41
	v_exp_f32_e32 v159, v157
	v_rcp_f32_e32 v157, v109
	v_add_f32_e32 v109, 1.0, v158
	v_rcp_f32_e32 v158, v109
	v_add_f32_e32 v109, 1.0, v159
	v_rcp_f32_e32 v159, v109
	v_pk_mul_f32 v[38:39], v[38:39], v[156:157]
	v_lshlrev_b32_e32 v109, 3, v130
	v_cvt_pk_bf16_f32 v38, v38, v39
	v_pk_mul_f32 v[40:41], v[40:41], v[158:159]
	v_cvt_pk_bf16_f32 v39, v40, v41
	v_fma_f32 v40, s10, v235, v225
	v_rsq_f32_e32 v40, v40
	global_store_dwordx2 v109, v[38:39], s[8:9] offset:512 sc1
	s_add_i32 s8, s28, 8
	s_ashr_i32 s9, s8, 31
	v_pk_mul_f32 v[36:37], v[36:37], v[40:41] op_sel_hi:[1,0]
	v_pk_mul_f32 v[34:35], v[34:35], v[40:41] op_sel_hi:[1,0]
	v_pk_fma_f32 v[36:37], v[4:5], v[36:37], v[8:9]
	v_pk_fma_f32 v[34:35], v[2:3], v[34:35], v[6:7]
	v_mul_f32_e32 v130, 0xbfb8aa3b, v36
	v_pk_mul_f32 v[40:41], v[34:35], s[96:97] op_sel_hi:[1,0]
	v_exp_f32_e32 v130, v130
	v_mul_f32_e32 v156, 0xbfb8aa3b, v37
	v_exp_f32_e32 v40, v40
	v_exp_f32_e32 v41, v41
	v_exp_f32_e32 v157, v156
	v_add_f32_e32 v130, 1.0, v130
	v_pk_add_f32 v[40:41], v[40:41], 1.0 op_sel_hi:[1,0]
	v_rcp_f32_e32 v156, v130
	v_add_f32_e32 v130, 1.0, v157
	v_rcp_f32_e32 v40, v40
	v_rcp_f32_e32 v41, v41
	v_rcp_f32_e32 v157, v130
	s_lshl_b64 s[8:9], s[8:9], 11
	s_add_u32 s8, s76, s8
	v_pk_mul_f32 v[34:35], v[34:35], v[40:41]
	v_pk_mul_f32 v[36:37], v[36:37], v[156:157]
	v_cvt_pk_bf16_f32 v34, v34, v35
	v_cvt_pk_bf16_f32 v35, v36, v37
	v_fma_f32 v36, s11, v235, v225
	v_rsq_f32_e32 v36, v36
	s_addc_u32 s9, s77, s9
	global_store_dwordx2 v109, v[34:35], s[8:9] offset:512 sc1
	s_add_i32 s8, s28, 16
	v_pk_mul_f32 v[30:31], v[30:31], v[36:37] op_sel_hi:[1,0]
	v_pk_mul_f32 v[32:33], v[32:33], v[36:37] op_sel_hi:[1,0]
	v_pk_fma_f32 v[30:31], v[2:3], v[30:31], v[6:7]
	v_pk_fma_f32 v[32:33], v[4:5], v[32:33], v[8:9]
	v_pk_mul_f32 v[36:37], v[30:31], s[96:97] op_sel_hi:[1,0]
	v_pk_mul_f32 v[38:39], v[32:33], s[96:97] op_sel_hi:[1,0]
	v_exp_f32_e32 v36, v36
	v_exp_f32_e32 v37, v37
	v_exp_f32_e32 v38, v38
	v_exp_f32_e32 v39, v39
	v_pk_add_f32 v[36:37], v[36:37], 1.0 op_sel_hi:[1,0]
	v_pk_add_f32 v[38:39], v[38:39], 1.0 op_sel_hi:[1,0]
	v_rcp_f32_e32 v36, v36
	v_rcp_f32_e32 v37, v37
	v_rcp_f32_e32 v38, v38
	v_rcp_f32_e32 v39, v39
	s_ashr_i32 s9, s8, 31
	v_pk_mul_f32 v[30:31], v[30:31], v[36:37]
	s_lshl_b64 s[8:9], s[8:9], 11
	v_pk_mul_f32 v[32:33], v[32:33], v[38:39]
	v_cvt_pk_bf16_f32 v30, v30, v31
	v_cvt_pk_bf16_f32 v31, v32, v33
	v_fma_f32 v32, s65, v235, v225
	v_rsq_f32_e32 v32, v32
	s_add_u32 s8, s76, s8
	s_addc_u32 s9, s77, s9
	global_store_dwordx2 v109, v[30:31], s[8:9] offset:512 sc1
	v_pk_mul_f32 v[26:27], v[26:27], v[32:33] op_sel_hi:[1,0]
	v_pk_mul_f32 v[28:29], v[28:29], v[32:33] op_sel_hi:[1,0]
	v_pk_fma_f32 v[26:27], v[2:3], v[26:27], v[6:7]
	v_pk_fma_f32 v[28:29], v[4:5], v[28:29], v[8:9]
	v_pk_mul_f32 v[32:33], v[26:27], s[96:97] op_sel_hi:[1,0]
	v_pk_mul_f32 v[34:35], v[28:29], s[96:97] op_sel_hi:[1,0]
	v_exp_f32_e32 v32, v32
	v_exp_f32_e32 v33, v33
	v_exp_f32_e32 v34, v34
	v_exp_f32_e32 v35, v35
	v_pk_add_f32 v[32:33], v[32:33], 1.0 op_sel_hi:[1,0]
	v_pk_add_f32 v[34:35], v[34:35], 1.0 op_sel_hi:[1,0]
	v_rcp_f32_e32 v32, v32
	v_rcp_f32_e32 v33, v33
	v_rcp_f32_e32 v34, v34
	v_rcp_f32_e32 v35, v35
	s_add_i32 s8, s28, 24
	v_pk_mul_f32 v[26:27], v[26:27], v[32:33]
	s_ashr_i32 s9, s8, 31
	v_pk_mul_f32 v[28:29], v[28:29], v[34:35]
	v_cvt_pk_bf16_f32 v26, v26, v27
	v_cvt_pk_bf16_f32 v27, v28, v29
	v_fma_f32 v28, s61, v235, v225
	v_rsq_f32_e32 v28, v28
	s_lshl_b64 s[8:9], s[8:9], 11
	s_add_u32 s8, s76, s8
	s_addc_u32 s9, s77, s9
	v_pk_mul_f32 v[22:23], v[22:23], v[28:29] op_sel_hi:[1,0]
	v_pk_mul_f32 v[24:25], v[24:25], v[28:29] op_sel_hi:[1,0]
	v_pk_fma_f32 v[22:23], v[2:3], v[22:23], v[6:7]
	v_pk_fma_f32 v[24:25], v[4:5], v[24:25], v[8:9]
	v_pk_mul_f32 v[28:29], v[22:23], s[96:97] op_sel_hi:[1,0]
	v_pk_mul_f32 v[30:31], v[24:25], s[96:97] op_sel_hi:[1,0]
	v_exp_f32_e32 v28, v28
	v_exp_f32_e32 v29, v29
	v_exp_f32_e32 v30, v30
	v_exp_f32_e32 v31, v31
	v_pk_add_f32 v[28:29], v[28:29], 1.0 op_sel_hi:[1,0]
	v_pk_add_f32 v[30:31], v[30:31], 1.0 op_sel_hi:[1,0]
	v_rcp_f32_e32 v28, v28
	v_rcp_f32_e32 v29, v29
	v_rcp_f32_e32 v30, v30
	v_rcp_f32_e32 v31, v31
	global_store_dwordx2 v109, v[26:27], s[8:9] offset:512 sc1
	v_pk_mul_f32 v[22:23], v[22:23], v[28:29]
	s_add_i32 s8, s28, 32
	v_pk_mul_f32 v[24:25], v[24:25], v[30:31]
	v_cvt_pk_bf16_f32 v22, v22, v23
	v_cvt_pk_bf16_f32 v23, v24, v25
	v_fma_f32 v24, s60, v235, v225
	v_rsq_f32_e32 v24, v24
	s_ashr_i32 s9, s8, 31
	s_lshl_b64 s[8:9], s[8:9], 11
	s_add_u32 s8, s76, s8
	v_pk_mul_f32 v[18:19], v[18:19], v[24:25] op_sel_hi:[1,0]
	v_pk_mul_f32 v[20:21], v[20:21], v[24:25] op_sel_hi:[1,0]
	v_pk_fma_f32 v[18:19], v[2:3], v[18:19], v[6:7]
	v_pk_fma_f32 v[20:21], v[4:5], v[20:21], v[8:9]
	v_pk_mul_f32 v[24:25], v[18:19], s[96:97] op_sel_hi:[1,0]
	v_pk_mul_f32 v[26:27], v[20:21], s[96:97] op_sel_hi:[1,0]
	v_exp_f32_e32 v24, v24
	v_exp_f32_e32 v25, v25
	v_exp_f32_e32 v26, v26
	v_exp_f32_e32 v27, v27
	v_pk_add_f32 v[24:25], v[24:25], 1.0 op_sel_hi:[1,0]
	v_pk_add_f32 v[26:27], v[26:27], 1.0 op_sel_hi:[1,0]
	v_rcp_f32_e32 v24, v24
	v_rcp_f32_e32 v25, v25
	v_rcp_f32_e32 v26, v26
	v_rcp_f32_e32 v27, v27
	s_addc_u32 s9, s77, s9
	v_pk_mul_f32 v[18:19], v[18:19], v[24:25]
	global_store_dwordx2 v109, v[22:23], s[8:9] offset:512 sc1
	v_pk_mul_f32 v[20:21], v[20:21], v[26:27]
	v_cvt_pk_bf16_f32 v18, v18, v19
	v_cvt_pk_bf16_f32 v19, v20, v21
	v_fma_f32 v20, s7, v235, v225
	v_rsq_f32_e32 v20, v20
	s_add_i32 s8, s28, 40
	s_ashr_i32 s9, s8, 31
	s_lshl_b64 s[8:9], s[8:9], 11
	v_pk_mul_f32 v[14:15], v[14:15], v[20:21] op_sel_hi:[1,0]
	v_pk_mul_f32 v[16:17], v[16:17], v[20:21] op_sel_hi:[1,0]
	v_pk_fma_f32 v[14:15], v[2:3], v[14:15], v[6:7]
	v_pk_fma_f32 v[16:17], v[4:5], v[16:17], v[8:9]
	v_pk_mul_f32 v[20:21], v[14:15], s[96:97] op_sel_hi:[1,0]
	v_pk_mul_f32 v[22:23], v[16:17], s[96:97] op_sel_hi:[1,0]
	v_exp_f32_e32 v20, v20
	v_exp_f32_e32 v21, v21
	v_exp_f32_e32 v22, v22
	v_exp_f32_e32 v23, v23
	v_pk_add_f32 v[20:21], v[20:21], 1.0 op_sel_hi:[1,0]
	v_pk_add_f32 v[22:23], v[22:23], 1.0 op_sel_hi:[1,0]
	v_rcp_f32_e32 v20, v20
	v_rcp_f32_e32 v21, v21
	v_rcp_f32_e32 v22, v22
	v_rcp_f32_e32 v23, v23
	s_add_u32 s8, s76, s8
	v_pk_mul_f32 v[14:15], v[14:15], v[20:21]
	s_addc_u32 s9, s77, s9
	v_pk_mul_f32 v[16:17], v[16:17], v[22:23]
	v_cvt_pk_bf16_f32 v14, v14, v15
	v_cvt_pk_bf16_f32 v15, v16, v17
	v_fma_f32 v16, s6, v235, v225
	v_rsq_f32_e32 v16, v16
	global_store_dwordx2 v109, v[18:19], s[8:9] offset:512 sc1
	s_add_i32 s8, s28, 48
	s_ashr_i32 s9, s8, 31
	v_pk_mul_f32 v[10:11], v[10:11], v[16:17] op_sel_hi:[1,0]
	v_pk_mul_f32 v[12:13], v[12:13], v[16:17] op_sel_hi:[1,0]
	v_pk_fma_f32 v[10:11], v[2:3], v[10:11], v[6:7]
	v_pk_fma_f32 v[12:13], v[4:5], v[12:13], v[8:9]
	v_pk_mul_f32 v[16:17], v[10:11], s[96:97] op_sel_hi:[1,0]
	v_pk_mul_f32 v[18:19], v[12:13], s[96:97] op_sel_hi:[1,0]
	v_exp_f32_e32 v16, v16
	v_exp_f32_e32 v17, v17
	v_exp_f32_e32 v18, v18
	v_exp_f32_e32 v19, v19
	s_lshl_b64 s[6:7], s[8:9], 11
	s_add_u32 s6, s76, s6
	s_addc_u32 s7, s77, s7
	v_pk_add_f32 v[16:17], v[16:17], 1.0 op_sel_hi:[1,0]
	v_pk_add_f32 v[18:19], v[18:19], 1.0 op_sel_hi:[1,0]
	v_rcp_f32_e32 v16, v16
	v_rcp_f32_e32 v17, v17
	v_rcp_f32_e32 v18, v18
	v_rcp_f32_e32 v19, v19
	global_store_dwordx2 v109, v[14:15], s[6:7] offset:512 sc1
	s_add_i32 s6, s28, 56
	s_ashr_i32 s7, s6, 31
	s_lshl_b64 s[6:7], s[6:7], 11
	s_add_u32 s6, s76, s6
	v_pk_mul_f32 v[10:11], v[10:11], v[16:17]
	v_pk_mul_f32 v[12:13], v[12:13], v[18:19]
	s_addc_u32 s7, s77, s7
	s_addk_i32 s58, 0x80
	s_addk_i32 s57, 0x2000
	v_cvt_pk_bf16_f32 v10, v10, v11
	v_cvt_pk_bf16_f32 v11, v12, v13
	s_cmpk_gt_i32 s59, 0x17f
	global_store_dwordx2 v109, v[10:11], s[6:7] offset:512 sc1
	s_barrier
	s_cbranch_scc1 .LBB0_313

.LBB0_314:
	s_andn2_b64 vcc, exec, s[28:29]
	s_cbranch_vccnz .LBB0_316
	v_mov_b32_e32 v1, v242
	s_mov_b32 s73, s11
	v_readfirstlane_b32 s5, v1
	s_ashr_i32 s65, s5, 6
	v_add_u32_e32 v6, s66, v1
	s_lshl_b32 s6, s65, 4
	v_readlane_b32 s66, v250, 31
	s_add_i32 s6, s6, s66
	s_mul_i32 s8, s6, 0x1800
	s_mul_hi_i32 s7, s6, 0x1800
	s_add_u32 s28, s80, s8
	s_addc_u32 s29, s81, s7
	s_mov_b64 s[8:9], s[28:29]
	v_and_b32_e32 v200, 63, v242
	v_lshlrev_b32_e32 v200, 4, v200
	s_nop 0
	global_load_dwordx4 v[204:207], v200, s[8:9]
	s_add_u32 s8, s8, 0x1800
	s_addc_u32 s9, s9, 0
	s_nop 0
	global_load_dwordx4 v[204:207], v200, s[8:9]
	s_add_u32 s8, s8, 0x1800
	s_addc_u32 s9, s9, 0
	s_nop 0
	global_load_dwordx4 v[204:207], v200, s[8:9]
	s_add_u32 s8, s8, 0x1800
	s_addc_u32 s9, s9, 0
	s_nop 0
	global_load_dwordx4 v[204:207], v200, s[8:9]
	s_add_u32 s8, s8, 0x1800
	s_addc_u32 s9, s9, 0
	s_nop 0
	global_load_dwordx4 v[204:207], v200, s[8:9]
	s_add_u32 s8, s8, 0x1800
	s_addc_u32 s9, s9, 0
	s_nop 0
	global_load_dwordx4 v[204:207], v200, s[8:9]
	s_add_u32 s8, s8, 0x1800
	s_addc_u32 s9, s9, 0
	s_nop 0
	global_load_dwordx4 v[204:207], v200, s[8:9]
	s_add_u32 s8, s8, 0x1800
	s_addc_u32 s9, s9, 0
	s_nop 0
	global_load_dwordx4 v[204:207], v200, s[8:9]
	s_add_u32 s8, s8, 0x1800
	s_addc_u32 s9, s9, 0
	s_nop 0
	global_load_dwordx4 v[204:207], v200, s[8:9]
	s_add_u32 s8, s8, 0x1800
	s_addc_u32 s9, s9, 0
	s_nop 0
	global_load_dwordx4 v[204:207], v200, s[8:9]
	s_add_u32 s8, s8, 0x1800
	s_addc_u32 s9, s9, 0
	s_nop 0
	global_load_dwordx4 v[204:207], v200, s[8:9]
	s_add_u32 s8, s8, 0x1800
	s_addc_u32 s9, s9, 0
	s_nop 0
	global_load_dwordx4 v[204:207], v200, s[8:9]
	s_add_u32 s8, s8, 0x1800
	s_addc_u32 s9, s9, 0
	s_nop 0
	global_load_dwordx4 v[204:207], v200, s[8:9]
	s_add_u32 s8, s8, 0x1800
	s_addc_u32 s9, s9, 0
	s_nop 0
	global_load_dwordx4 v[204:207], v200, s[8:9]
	s_add_u32 s8, s8, 0x1800
	s_addc_u32 s9, s9, 0
	s_nop 0
	global_load_dwordx4 v[204:207], v200, s[8:9]
	s_add_u32 s8, s8, 0x1800
	s_addc_u32 s9, s9, 0
	s_nop 0
	global_load_dwordx4 v[204:207], v200, s[8:9]
	s_or_b32 s7, s6, 1
	s_mul_hi_i32 s8, s7, 0x1800
	s_mulk_i32 s7, 0x1800
	v_and_b32_e32 v74, 63, v1
	s_add_u32 s40, s80, s7
	s_addc_u32 s41, s81, s8
	v_lshlrev_b32_e32 v44, 1, v74
	global_load_ushort v9, v44, s[40:41] offset:512
	global_load_ushort v20, v44, s[40:41] offset:640
	global_load_ushort v26, v44, s[40:41] offset:768
	global_load_ushort v30, v44, s[40:41] offset:896
	global_load_ushort v8, v44, s[28:29] offset:512
	global_load_ushort v21, v44, s[28:29] offset:640
	global_load_ushort v27, v44, s[28:29] offset:768
	global_load_ushort v31, v44, s[28:29] offset:896
	s_or_b32 s7, s6, 2
	s_mul_hi_i32 s9, s7, 0x1800
	s_mulk_i32 s7, 0x1800
	s_add_u32 s8, s80, s7
	s_addc_u32 s9, s81, s9
	s_or_b32 s7, s6, 3
	s_mul_hi_i32 s11, s7, 0x1800
	s_mulk_i32 s7, 0x1800
	s_add_u32 s10, s80, s7
	s_addc_u32 s11, s81, s11
	global_load_ushort v18, v44, s[10:11] offset:512
	global_load_ushort v19, v44, s[10:11] offset:640
	global_load_ushort v22, v44, s[10:11] offset:768
	global_load_ushort v32, v44, s[10:11] offset:896
	global_load_ushort v23, v44, s[8:9] offset:512
	global_load_ushort v28, v44, s[8:9] offset:640
	global_load_ushort v29, v44, s[8:9] offset:768
	global_load_ushort v33, v44, s[8:9] offset:896
	s_mov_b32 s8, 0xbf3a00e3
	v_mov_b64_e32 v[24:25], s[8:9]
	s_mov_b64 s[10:11], s[68:69]
	s_mov_b64 s[68:69], s[12:13]
	s_mov_b32 s12, 0x3f07dc22
	s_mov_b32 s14, 0x3f35f0e3
	s_mov_b32 s16, 0xbe11a98e
	s_mov_b32 s18, 0x3e027906
	s_or_b32 s7, s6, 4
	s_mul_hi_i32 s8, s7, 0x1800
	s_mulk_i32 s7, 0x1800
	s_add_u32 s28, s80, s7
	s_addc_u32 s29, s81, s8
	s_or_b32 s7, s6, 5
	s_mul_hi_i32 s8, s7, 0x1800
	s_mulk_i32 s7, 0x1800
	s_add_u32 s40, s80, s7
	s_addc_u32 s41, s81, s8
	s_or_b32 s7, s6, 6
	s_mul_hi_i32 s8, s7, 0x1800
	s_mulk_i32 s7, 0x1800
	s_add_u32 s58, s80, s7
	s_addc_u32 s59, s81, s8
	s_or_b32 s7, s6, 7
	s_mul_hi_i32 s8, s7, 0x1800
	s_mulk_i32 s7, 0x1800
	s_add_u32 s60, s80, s7
	s_addc_u32 s61, s81, s8
	s_or_b32 s7, s6, 8
	s_mul_hi_i32 s8, s7, 0x1800
	s_mulk_i32 s7, 0x1800
	v_or_b32_e32 v2, s84, v74
	s_add_u32 s46, s80, s7
	v_ashrrev_i32_e32 v3, 31, v2
	s_addc_u32 s47, s81, s8
	s_or_b32 s7, s6, 9
	v_lshlrev_b64 v[4:5], 2, v[2:3]
	s_mul_hi_i32 s8, s7, 0x1800
	s_mulk_i32 s7, 0x1800
	v_lshl_add_u64 v[2:3], s[52:53], 0, v[4:5]
	v_lshl_add_u64 v[4:5], s[54:55], 0, v[4:5]
	s_add_u32 s54, s80, s7
	s_addc_u32 s55, s81, s8
	s_or_b32 s7, s6, 10
	s_mul_hi_i32 s8, s7, 0x1800
	s_mulk_i32 s7, 0x1800
	s_add_u32 s48, s80, s7
	s_addc_u32 s49, s81, s8
	s_or_b32 s7, s6, 11
	s_mul_hi_i32 s8, s7, 0x1800
	s_mulk_i32 s7, 0x1800
	s_add_u32 s56, s80, s7
	s_addc_u32 s57, s81, s8
	s_or_b32 s7, s6, 12
	v_ashrrev_i32_e32 v7, 31, v6
	s_mul_hi_i32 s8, s7, 0x1800
	s_mulk_i32 s7, 0x1800
	v_lshl_add_u64 v[6:7], v[6:7], 2, s[42:43]
	s_add_u32 s42, s80, s7
	s_addc_u32 s43, s81, s8
	s_or_b32 s7, s6, 13
	s_waitcnt vmcnt(15)
	v_lshlrev_b32_e32 v9, 16, v9
	v_mul_f32_e32 v13, v9, v9
	v_mul_f32_e32 v13, 0xbf38aa3b, v13
	v_exp_f32_e32 v13, v13
	s_waitcnt vmcnt(11)
	v_lshlrev_b32_e32 v8, 16, v8
	v_mul_f32_e32 v11, v8, v8
	v_mul_f32_e32 v11, 0xbf38aa3b, v11
	v_fma_f32 v10, |v8|, s92, 1.0
	v_exp_f32_e32 v12, v11
	v_fma_f32 v11, |v9|, s92, 1.0
	v_rcp_f32_e32 v10, v10
	v_rcp_f32_e32 v11, v11
	v_cmp_gt_f32_e32 vcc, 0, v9
	s_mul_hi_i32 s8, s7, 0x1800
	s_mulk_i32 s7, 0x1800
	v_pk_fma_f32 v[14:15], v[10:11], s[12:13], v[24:25] op_sel_hi:[1,0,0]
	s_add_u32 s50, s80, s7
	v_pk_fma_f32 v[14:15], v[10:11], v[14:15], s[14:15] op_sel_hi:[1,1,0]
	s_addc_u32 s51, s81, s8
	v_pk_fma_f32 v[14:15], v[10:11], v[14:15], s[16:17] op_sel_hi:[1,1,0]
	s_or_b32 s7, s6, 14
	v_pk_fma_f32 v[14:15], v[10:11], v[14:15], s[18:19] op_sel_hi:[1,1,0]
	s_mul_hi_i32 s8, s7, 0x1800
	v_pk_mul_f32 v[10:11], v[10:11], v[14:15]
	s_mulk_i32 s7, 0x1800
	v_pk_mul_f32 v[10:11], v[12:13], v[10:11]
	s_add_u32 s44, s80, s7
	v_pk_mul_f32 v[12:13], v[10:11], v[8:9]
	v_pk_fma_f32 v[10:11], v[10:11], v[8:9], v[8:9] neg_lo:[1,0,0] neg_hi:[1,0,0]
	s_addc_u32 s45, s81, s8
	v_cndmask_b32_e32 v17, v11, v13, vcc
	v_cmp_gt_f32_e32 vcc, 0, v8
	s_waitcnt vmcnt(3)
	v_lshlrev_b32_e32 v8, 16, v23
	v_fma_f32 v9, |v8|, s92, 1.0
	v_mul_f32_e32 v11, v8, v8
	v_cndmask_b32_e32 v16, v10, v12, vcc
	v_rcp_f32_e32 v10, v9
	v_mul_f32_e32 v11, 0xbf38aa3b, v11
	v_lshlrev_b32_e32 v9, 16, v18
	v_exp_f32_e32 v12, v11
	v_fma_f32 v11, |v9|, s92, 1.0
	v_rcp_f32_e32 v11, v11
	v_mul_f32_e32 v13, v9, v9
	v_mul_f32_e32 v13, 0xbf38aa3b, v13
	v_exp_f32_e32 v13, v13
	v_pk_fma_f32 v[14:15], v[10:11], s[12:13], v[24:25] op_sel_hi:[1,0,0]
	v_cmp_gt_f32_e32 vcc, 0, v9
	v_pk_fma_f32 v[14:15], v[10:11], v[14:15], s[14:15] op_sel_hi:[1,1,0]
	s_or_b32 s6, s6, 15
	v_pk_fma_f32 v[14:15], v[10:11], v[14:15], s[16:17] op_sel_hi:[1,1,0]
	s_mul_hi_i32 s7, s6, 0x1800
	v_pk_fma_f32 v[14:15], v[10:11], v[14:15], s[18:19] op_sel_hi:[1,1,0]
	s_mulk_i32 s6, 0x1800
	v_pk_mul_f32 v[10:11], v[10:11], v[14:15]
	s_add_u32 s52, s80, s6
	v_pk_mul_f32 v[10:11], v[12:13], v[10:11]
	s_addc_u32 s53, s81, s7
	v_pk_mul_f32 v[12:13], v[10:11], v[8:9]
	v_pk_fma_f32 v[10:11], v[10:11], v[8:9], v[8:9] neg_lo:[1,0,0] neg_hi:[1,0,0]
	s_mov_b32 s8, 0x3b800000
	v_cndmask_b32_e32 v9, v11, v13, vcc
	v_cmp_gt_f32_e32 vcc, 0, v8
	s_ashr_i32 s5, s5, 7
	v_lshlrev_b32_e32 v130, 4, v74
	v_cndmask_b32_e32 v8, v10, v12, vcc
	s_waitcnt vmcnt(2)
	v_lshlrev_b32_e32 v10, 16, v28
	v_fma_f32 v11, |v10|, s92, 1.0
	v_rcp_f32_e32 v12, v11
	v_lshlrev_b32_e32 v11, 16, v19
	v_fma_f32 v13, |v11|, s92, 1.0
	v_rcp_f32_e32 v13, v13
	v_mul_f32_e32 v14, v10, v10
	v_mul_f32_e32 v15, v11, v11
	v_mul_f32_e32 v14, 0xbf38aa3b, v14
	v_pk_fma_f32 v[18:19], v[12:13], s[12:13], v[24:25] op_sel_hi:[1,0,0]
	v_mul_f32_e32 v15, 0xbf38aa3b, v15
	v_exp_f32_e32 v14, v14
	v_pk_fma_f32 v[18:19], v[12:13], v[18:19], s[14:15] op_sel_hi:[1,1,0]
	v_exp_f32_e32 v15, v15
	v_pk_fma_f32 v[18:19], v[12:13], v[18:19], s[16:17] op_sel_hi:[1,1,0]
	v_cmp_gt_f32_e32 vcc, 0, v11
	v_pk_fma_f32 v[18:19], v[12:13], v[18:19], s[18:19] op_sel_hi:[1,1,0]
	s_nop 0
	v_pk_mul_f32 v[12:13], v[12:13], v[18:19]
	v_pk_mul_f32 v[12:13], v[14:15], v[12:13]
	v_pk_mul_f32 v[14:15], v[12:13], v[10:11]
	v_pk_fma_f32 v[12:13], v[12:13], v[10:11], v[10:11] neg_lo:[1,0,0] neg_hi:[1,0,0]
	v_lshlrev_b32_e32 v11, 16, v20
	v_cndmask_b32_e32 v13, v13, v15, vcc
	v_cmp_gt_f32_e32 vcc, 0, v10
	v_lshlrev_b32_e32 v10, 16, v21
	v_mul_f32_e32 v15, v10, v10
	v_mul_f32_e32 v15, 0xbf38aa3b, v15
	v_cndmask_b32_e32 v12, v12, v14, vcc
	v_fma_f32 v14, |v10|, s92, 1.0
	v_exp_f32_e32 v18, v15
	v_fma_f32 v15, |v11|, s92, 1.0
	v_rcp_f32_e32 v14, v14
	v_rcp_f32_e32 v15, v15
	v_mul_f32_e32 v19, v11, v11
	v_mul_f32_e32 v19, 0xbf38aa3b, v19
	v_exp_f32_e32 v19, v19
	v_pk_fma_f32 v[20:21], v[14:15], s[12:13], v[24:25] op_sel_hi:[1,0,0]
	v_cmp_gt_f32_e32 vcc, 0, v11
	v_pk_fma_f32 v[20:21], v[14:15], v[20:21], s[14:15] op_sel_hi:[1,1,0]
	s_nop 0
	v_pk_fma_f32 v[20:21], v[14:15], v[20:21], s[16:17] op_sel_hi:[1,1,0]
	s_nop 0
	v_pk_fma_f32 v[20:21], v[14:15], v[20:21], s[18:19] op_sel_hi:[1,1,0]
	v_pk_mul_f32 v[14:15], v[14:15], v[20:21]
	v_pk_mul_f32 v[14:15], v[18:19], v[14:15]
	v_pk_mul_f32 v[18:19], v[14:15], v[10:11]
	v_pk_fma_f32 v[14:15], v[14:15], v[10:11], v[10:11] neg_lo:[1,0,0] neg_hi:[1,0,0]
	v_lshlrev_b32_e32 v11, 16, v22
	v_cndmask_b32_e32 v19, v15, v19, vcc
	v_cmp_gt_f32_e32 vcc, 0, v10
	s_waitcnt vmcnt(1)
	v_lshlrev_b32_e32 v10, 16, v29
	v_fma_f32 v15, |v11|, s92, 1.0
	v_cndmask_b32_e32 v18, v14, v18, vcc
	v_fma_f32 v14, |v10|, s92, 1.0
	v_rcp_f32_e32 v14, v14
	v_rcp_f32_e32 v15, v15
	v_mul_f32_e32 v20, v10, v10
	v_mul_f32_e32 v21, v11, v11
	v_mul_f32_e32 v20, 0xbf38aa3b, v20
	v_pk_fma_f32 v[22:23], v[14:15], s[12:13], v[24:25] op_sel_hi:[1,0,0]
	v_mul_f32_e32 v21, 0xbf38aa3b, v21
	v_exp_f32_e32 v20, v20
	v_pk_fma_f32 v[22:23], v[14:15], v[22:23], s[14:15] op_sel_hi:[1,1,0]
	v_exp_f32_e32 v21, v21
	v_pk_fma_f32 v[22:23], v[14:15], v[22:23], s[16:17] op_sel_hi:[1,1,0]
	v_cmp_gt_f32_e32 vcc, 0, v11
	v_pk_fma_f32 v[22:23], v[14:15], v[22:23], s[18:19] op_sel_hi:[1,1,0]
	s_nop 0
	v_pk_mul_f32 v[14:15], v[14:15], v[22:23]
	v_pk_mul_f32 v[14:15], v[20:21], v[14:15]
	v_pk_mul_f32 v[20:21], v[14:15], v[10:11]
	v_pk_fma_f32 v[14:15], v[14:15], v[10:11], v[10:11] neg_lo:[1,0,0] neg_hi:[1,0,0]
	v_lshlrev_b32_e32 v11, 16, v26
	v_cndmask_b32_e32 v21, v15, v21, vcc
	v_cmp_gt_f32_e32 vcc, 0, v10
	v_lshlrev_b32_e32 v10, 16, v27
	v_mul_f32_e32 v15, v10, v10
	v_mul_f32_e32 v15, 0xbf38aa3b, v15
	v_cndmask_b32_e32 v20, v14, v20, vcc
	v_fma_f32 v14, |v10|, s92, 1.0
	v_exp_f32_e32 v22, v15
	v_fma_f32 v15, |v11|, s92, 1.0
	v_rcp_f32_e32 v14, v14
	v_rcp_f32_e32 v15, v15
	v_mul_f32_e32 v23, v11, v11
	v_mul_f32_e32 v23, 0xbf38aa3b, v23
	v_exp_f32_e32 v23, v23
	v_pk_fma_f32 v[26:27], v[14:15], s[12:13], v[24:25] op_sel_hi:[1,0,0]
	v_cmp_gt_f32_e32 vcc, 0, v11
	v_pk_fma_f32 v[26:27], v[14:15], v[26:27], s[14:15] op_sel_hi:[1,1,0]
	s_nop 0
	v_pk_fma_f32 v[26:27], v[14:15], v[26:27], s[16:17] op_sel_hi:[1,1,0]
	s_nop 0
	v_pk_fma_f32 v[26:27], v[14:15], v[26:27], s[18:19] op_sel_hi:[1,1,0]
	v_pk_mul_f32 v[14:15], v[14:15], v[26:27]
	v_pk_mul_f32 v[14:15], v[22:23], v[14:15]
	v_pk_mul_f32 v[22:23], v[14:15], v[10:11]
	v_pk_fma_f32 v[14:15], v[14:15], v[10:11], v[10:11] neg_lo:[1,0,0] neg_hi:[1,0,0]
	v_lshlrev_b32_e32 v11, 16, v32
	v_cndmask_b32_e32 v29, v15, v23, vcc
	v_cmp_gt_f32_e32 vcc, 0, v10
	s_waitcnt vmcnt(0)
	v_lshlrev_b32_e32 v10, 16, v33
	v_fma_f32 v15, |v11|, s92, 1.0
	v_cndmask_b32_e32 v28, v14, v22, vcc
	v_fma_f32 v14, |v10|, s92, 1.0
	v_rcp_f32_e32 v14, v14
	v_rcp_f32_e32 v15, v15
	v_mul_f32_e32 v22, v10, v10
	v_mul_f32_e32 v23, v11, v11
	v_mul_f32_e32 v22, 0xbf38aa3b, v22
	v_pk_fma_f32 v[26:27], v[14:15], s[12:13], v[24:25] op_sel_hi:[1,0,0]
	v_mul_f32_e32 v23, 0xbf38aa3b, v23
	v_exp_f32_e32 v22, v22
	v_pk_fma_f32 v[26:27], v[14:15], v[26:27], s[14:15] op_sel_hi:[1,1,0]
	v_exp_f32_e32 v23, v23
	v_pk_fma_f32 v[26:27], v[14:15], v[26:27], s[16:17] op_sel_hi:[1,1,0]
	v_cmp_gt_f32_e32 vcc, 0, v11
	v_pk_fma_f32 v[26:27], v[14:15], v[26:27], s[18:19] op_sel_hi:[1,1,0]
	v_mov_b32_e32 v32, v19
	v_pk_mul_f32 v[14:15], v[14:15], v[26:27]
	v_pk_mul_f32 v[14:15], v[22:23], v[14:15]
	v_pk_mul_f32 v[22:23], v[14:15], v[10:11]
	v_pk_fma_f32 v[14:15], v[14:15], v[10:11], v[10:11] neg_lo:[1,0,0] neg_hi:[1,0,0]
	v_lshlrev_b32_e32 v11, 16, v30
	v_cndmask_b32_e32 v23, v15, v23, vcc
	v_cmp_gt_f32_e32 vcc, 0, v10
	v_lshlrev_b32_e32 v10, 16, v31
	v_mul_f32_e32 v15, v10, v10
	v_mul_f32_e32 v15, 0xbf38aa3b, v15
	v_cndmask_b32_e32 v22, v14, v22, vcc
	v_fma_f32 v14, |v10|, s92, 1.0
	v_exp_f32_e32 v26, v15
	v_fma_f32 v15, |v11|, s92, 1.0
	v_rcp_f32_e32 v14, v14
	v_rcp_f32_e32 v15, v15
	v_mul_f32_e32 v27, v11, v11
	v_mul_f32_e32 v27, 0xbf38aa3b, v27
	v_exp_f32_e32 v27, v27
	v_pk_fma_f32 v[30:31], v[14:15], s[12:13], v[24:25] op_sel_hi:[1,0,0]
	v_cmp_gt_f32_e32 vcc, 0, v11
	v_pk_fma_f32 v[30:31], v[14:15], v[30:31], s[14:15] op_sel_hi:[1,1,0]
	s_nop 0
	v_pk_fma_f32 v[30:31], v[14:15], v[30:31], s[16:17] op_sel_hi:[1,1,0]
	s_nop 0
	v_pk_fma_f32 v[30:31], v[14:15], v[30:31], s[18:19] op_sel_hi:[1,1,0]
	v_pk_mul_f32 v[14:15], v[14:15], v[30:31]
	v_pk_mul_f32 v[14:15], v[26:27], v[14:15]
	v_pk_mul_f32 v[26:27], v[14:15], v[10:11]
	v_pk_fma_f32 v[14:15], v[14:15], v[10:11], v[10:11] neg_lo:[1,0,0] neg_hi:[1,0,0]
	v_mov_b32_e32 v11, v20
	v_cndmask_b32_e32 v31, v15, v27, vcc
	v_cmp_gt_f32_e32 vcc, 0, v10
	v_mov_b32_e32 v10, v8
	v_mov_b32_e32 v15, v22
	v_cndmask_b32_e32 v30, v14, v26, vcc
	v_mov_b32_e32 v14, v12
	v_pk_add_f32 v[10:11], v[10:11], v[14:15]
	v_mov_b32_e32 v14, v9
	v_add_f32_e32 v10, v10, v11
	v_mov_b32_e32 v15, v21
	s_nop 0
	v_add_f32_dpp v10, v10, v10 quad_perm:[1,0,3,2] row_mask:0xf bank_mask:0xf bound_ctrl:1
	v_mov_b32_e32 v26, v13
	v_mov_b32_e32 v27, v23
	v_add_f32_dpp v10, v10, v10 quad_perm:[2,3,0,1] row_mask:0xf bank_mask:0xf bound_ctrl:1
	v_pk_add_f32 v[14:15], v[14:15], v[26:27]
	v_mov_b64_e32 v[26:27], s[8:9]
	v_add_f32_dpp v10, v10, v10 row_half_mirror row_mask:0xf bank_mask:0xf bound_ctrl:1
	v_mov_b32_e32 v33, v31
	s_mov_b32 s8, 0x3e027906
	v_add_f32_dpp v10, v10, v10 row_mirror row_mask:0xf bank_mask:0xf bound_ctrl:1
	s_nop 1
	v_add_f32_dpp v10, v10, v10 row_bcast:15 row_mask:0xa bank_mask:0xf
	s_nop 1
	v_add_f32_dpp v10, v10, v10 row_bcast:31 row_mask:0xc bank_mask:0xf
	v_add_f32_e32 v11, v14, v15
	v_readlane_b32 s6, v10, 63
	s_nop 0
	v_add_f32_dpp v11, v11, v11 quad_perm:[1,0,3,2] row_mask:0xf bank_mask:0xf bound_ctrl:1
	s_xor_b32 s6, s6, 0x80000000
	s_nop 0
	v_add_f32_dpp v11, v11, v11 quad_perm:[2,3,0,1] row_mask:0xf bank_mask:0xf bound_ctrl:1
	s_nop 1
	v_add_f32_dpp v11, v11, v11 row_half_mirror row_mask:0xf bank_mask:0xf bound_ctrl:1
	s_nop 1
	v_add_f32_dpp v11, v11, v11 row_mirror row_mask:0xf bank_mask:0xf bound_ctrl:1
	s_nop 1
	v_add_f32_dpp v11, v11, v11 row_bcast:15 row_mask:0xa bank_mask:0xf
	s_nop 1
	v_add_f32_dpp v11, v11, v11 row_bcast:31 row_mask:0xc bank_mask:0xf
	s_nop 0
	v_readlane_b32 s7, v11, 63
	s_xor_b32 s7, s7, 0x80000000
	s_nop 0
	v_pk_fma_f32 v[10:11], s[6:7], v[26:27], v[8:9] op_sel_hi:[1,0,1]
	v_pk_fma_f32 v[14:15], s[6:7], v[26:27], v[12:13] op_sel_hi:[1,0,1]
	v_pk_fma_f32 v[12:13], s[6:7], v[26:27], v[20:21] op_sel_hi:[1,0,1]
	v_pk_fma_f32 v[8:9], s[6:7], v[26:27], v[22:23] op_sel_hi:[1,0,1]
	v_mov_b32_e32 v20, v16
	v_mov_b32_e32 v21, v28
	v_mov_b32_e32 v22, v18
	v_mov_b32_e32 v23, v30
	v_pk_add_f32 v[20:21], v[20:21], v[22:23]
	v_mov_b32_e32 v22, v17
	v_add_f32_e32 v20, v20, v21
	v_mov_b32_e32 v23, v29
	s_nop 0
	v_add_f32_dpp v20, v20, v20 quad_perm:[1,0,3,2] row_mask:0xf bank_mask:0xf bound_ctrl:1
	v_pk_add_f32 v[22:23], v[22:23], v[32:33]
	s_nop 0
	v_add_f32_dpp v20, v20, v20 quad_perm:[2,3,0,1] row_mask:0xf bank_mask:0xf bound_ctrl:1
	s_nop 1
	v_add_f32_dpp v20, v20, v20 row_half_mirror row_mask:0xf bank_mask:0xf bound_ctrl:1
	s_nop 1
	v_add_f32_dpp v20, v20, v20 row_mirror row_mask:0xf bank_mask:0xf bound_ctrl:1
	s_nop 1
	v_add_f32_dpp v20, v20, v20 row_bcast:15 row_mask:0xa bank_mask:0xf
	s_nop 1
	v_add_f32_dpp v20, v20, v20 row_bcast:31 row_mask:0xc bank_mask:0xf
	v_add_f32_e32 v21, v22, v23
	v_readlane_b32 s6, v20, 63
	s_nop 0
	v_add_f32_dpp v21, v21, v21 quad_perm:[1,0,3,2] row_mask:0xf bank_mask:0xf bound_ctrl:1
	s_xor_b32 s6, s6, 0x80000000
	s_nop 0
	v_add_f32_dpp v21, v21, v21 quad_perm:[2,3,0,1] row_mask:0xf bank_mask:0xf bound_ctrl:1
	s_nop 1
	v_add_f32_dpp v21, v21, v21 row_half_mirror row_mask:0xf bank_mask:0xf bound_ctrl:1
	s_nop 1
	v_add_f32_dpp v21, v21, v21 row_mirror row_mask:0xf bank_mask:0xf bound_ctrl:1
	s_nop 1
	v_add_f32_dpp v21, v21, v21 row_bcast:15 row_mask:0xa bank_mask:0xf
	s_nop 1
	v_add_f32_dpp v21, v21, v21 row_bcast:31 row_mask:0xc bank_mask:0xf
	s_nop 0
	v_readlane_b32 s7, v21, 63
	s_xor_b32 s7, s7, 0x80000000
	s_nop 0
	v_pk_fma_f32 v[22:23], s[6:7], v[26:27], v[16:17] op_sel_hi:[1,0,1]
	v_pk_fma_f32 v[20:21], s[6:7], v[26:27], v[18:19] op_sel_hi:[1,0,1]
	v_pk_fma_f32 v[18:19], s[6:7], v[26:27], v[28:29] op_sel_hi:[1,0,1]
	v_pk_fma_f32 v[16:17], s[6:7], v[26:27], v[30:31] op_sel_hi:[1,0,1]
	global_load_ushort v28, v44, s[60:61] offset:512
	global_load_ushort v38, v44, s[60:61] offset:640
	global_load_ushort v42, v44, s[60:61] offset:768
	global_load_ushort v45, v44, s[60:61] offset:896
	global_load_ushort v30, v44, s[58:59] offset:512
	global_load_ushort v39, v44, s[58:59] offset:640
	global_load_ushort v43, v44, s[58:59] offset:768
	global_load_ushort v48, v44, s[58:59] offset:896
	s_waitcnt vmcnt(7)
	v_lshlrev_b32_e32 v29, 16, v28
	v_fma_f32 v31, |v29|, s92, 1.0
	v_rcp_f32_e32 v31, v31
	v_mul_f32_e32 v33, v29, v29
	s_waitcnt vmcnt(3)
	v_lshlrev_b32_e32 v28, 16, v30
	v_fma_f32 v30, |v28|, s92, 1.0
	v_rcp_f32_e32 v30, v30
	v_mul_f32_e32 v32, v28, v28
	v_mul_f32_e32 v32, 0xbf38aa3b, v32
	v_mul_f32_e32 v33, 0xbf38aa3b, v33
	v_pk_fma_f32 v[34:35], v[30:31], s[12:13], v[24:25] op_sel_hi:[1,0,0]
	v_exp_f32_e32 v32, v32
	v_pk_fma_f32 v[34:35], v[30:31], v[34:35], s[14:15] op_sel_hi:[1,1,0]
	v_exp_f32_e32 v33, v33
	v_pk_fma_f32 v[34:35], v[30:31], v[34:35], s[16:17] op_sel_hi:[1,1,0]
	v_cmp_gt_f32_e32 vcc, 0, v29
	v_pk_fma_f32 v[34:35], v[30:31], v[34:35], s[18:19] op_sel_hi:[1,1,0]
	s_nop 0
	v_pk_mul_f32 v[30:31], v[30:31], v[34:35]
	v_pk_mul_f32 v[30:31], v[32:33], v[30:31]
	v_pk_mul_f32 v[32:33], v[30:31], v[28:29]
	v_pk_fma_f32 v[30:31], v[30:31], v[28:29], v[28:29] neg_lo:[1,0,0] neg_hi:[1,0,0]
	s_nop 0
	v_cndmask_b32_e32 v29, v31, v33, vcc
	v_cmp_gt_f32_e32 vcc, 0, v28
	s_nop 1
	v_cndmask_b32_e32 v28, v30, v32, vcc
	global_load_ushort v30, v44, s[40:41] offset:512
	global_load_ushort v40, v44, s[40:41] offset:640
	global_load_ushort v46, v44, s[40:41] offset:768
	global_load_ushort v50, v44, s[40:41] offset:896
	global_load_ushort v32, v44, s[28:29] offset:512
	global_load_ushort v41, v44, s[28:29] offset:640
	global_load_ushort v47, v44, s[28:29] offset:768
	global_load_ushort v51, v44, s[28:29] offset:896
	s_movk_i32 s40, 0x110
	s_movk_i32 s41, 0x3000
	s_waitcnt vmcnt(7)
	v_lshlrev_b32_e32 v31, 16, v30
	v_mul_f32_e32 v35, v31, v31
	v_mul_f32_e32 v35, 0xbf38aa3b, v35
	v_exp_f32_e32 v35, v35
	s_waitcnt vmcnt(3)
	v_lshlrev_b32_e32 v30, 16, v32
	v_mul_f32_e32 v33, v30, v30
	v_mul_f32_e32 v33, 0xbf38aa3b, v33
	v_fma_f32 v32, |v30|, s92, 1.0
	v_exp_f32_e32 v34, v33
	v_fma_f32 v33, |v31|, s92, 1.0
	v_rcp_f32_e32 v32, v32
	v_rcp_f32_e32 v33, v33
	v_cmp_gt_f32_e32 vcc, 0, v31
	v_pk_fma_f32 v[36:37], v[32:33], s[12:13], v[24:25] op_sel_hi:[1,0,0]
	s_nop 0
	v_pk_fma_f32 v[36:37], v[32:33], v[36:37], s[14:15] op_sel_hi:[1,1,0]
	s_nop 0
	v_pk_fma_f32 v[36:37], v[32:33], v[36:37], s[16:17] op_sel_hi:[1,1,0]
	s_nop 0
	v_pk_fma_f32 v[36:37], v[32:33], v[36:37], s[18:19] op_sel_hi:[1,1,0]
	v_pk_mul_f32 v[32:33], v[32:33], v[36:37]
	v_pk_mul_f32 v[32:33], v[34:35], v[32:33]
	v_pk_mul_f32 v[34:35], v[32:33], v[30:31]
	v_pk_fma_f32 v[32:33], v[32:33], v[30:31], v[30:31] neg_lo:[1,0,0] neg_hi:[1,0,0]
	v_lshlrev_b32_e32 v31, 16, v38
	v_cndmask_b32_e32 v37, v33, v35, vcc
	v_cmp_gt_f32_e32 vcc, 0, v30
	v_lshlrev_b32_e32 v30, 16, v39
	v_fma_f32 v33, |v31|, s92, 1.0
	v_cndmask_b32_e32 v36, v32, v34, vcc
	v_fma_f32 v32, |v30|, s92, 1.0
	v_rcp_f32_e32 v32, v32
	v_rcp_f32_e32 v33, v33
	v_mul_f32_e32 v34, v30, v30
	v_mul_f32_e32 v35, v31, v31
	v_mul_f32_e32 v34, 0xbf38aa3b, v34
	v_pk_fma_f32 v[38:39], v[32:33], s[12:13], v[24:25] op_sel_hi:[1,0,0]
	v_mul_f32_e32 v35, 0xbf38aa3b, v35
	v_exp_f32_e32 v34, v34
	v_pk_fma_f32 v[38:39], v[32:33], v[38:39], s[14:15] op_sel_hi:[1,1,0]
	v_exp_f32_e32 v35, v35
	v_pk_fma_f32 v[38:39], v[32:33], v[38:39], s[16:17] op_sel_hi:[1,1,0]
	v_cmp_gt_f32_e32 vcc, 0, v31
	v_pk_fma_f32 v[38:39], v[32:33], v[38:39], s[18:19] op_sel_hi:[1,1,0]
	s_nop 0
	v_pk_mul_f32 v[32:33], v[32:33], v[38:39]
	v_pk_mul_f32 v[32:33], v[34:35], v[32:33]
	v_pk_mul_f32 v[34:35], v[32:33], v[30:31]
	v_pk_fma_f32 v[32:33], v[32:33], v[30:31], v[30:31] neg_lo:[1,0,0] neg_hi:[1,0,0]
	s_nop 0
	v_cndmask_b32_e32 v31, v33, v35, vcc
	v_cmp_gt_f32_e32 vcc, 0, v30
	v_lshlrev_b32_e32 v33, 16, v40
	v_mul_f32_e32 v39, v33, v33
	v_cndmask_b32_e32 v30, v32, v34, vcc
	s_waitcnt vmcnt(2)
	v_lshlrev_b32_e32 v32, 16, v41
	v_mul_f32_e32 v35, v32, v32
	v_mul_f32_e32 v35, 0xbf38aa3b, v35
	v_fma_f32 v34, |v32|, s92, 1.0
	v_exp_f32_e32 v38, v35
	v_fma_f32 v35, |v33|, s92, 1.0
	v_rcp_f32_e32 v34, v34
	v_rcp_f32_e32 v35, v35
	v_mul_f32_e32 v39, 0xbf38aa3b, v39
	v_exp_f32_e32 v39, v39
	v_cmp_gt_f32_e32 vcc, 0, v33
	v_pk_fma_f32 v[40:41], v[34:35], s[12:13], v[24:25] op_sel_hi:[1,0,0]
	s_nop 0
	v_pk_fma_f32 v[40:41], v[34:35], v[40:41], s[14:15] op_sel_hi:[1,1,0]
	s_nop 0
	v_pk_fma_f32 v[40:41], v[34:35], v[40:41], s[16:17] op_sel_hi:[1,1,0]
	s_nop 0
	v_pk_fma_f32 v[40:41], v[34:35], v[40:41], s[18:19] op_sel_hi:[1,1,0]
	v_pk_mul_f32 v[34:35], v[34:35], v[40:41]
	v_pk_mul_f32 v[34:35], v[38:39], v[34:35]
	v_pk_mul_f32 v[38:39], v[34:35], v[32:33]
	v_pk_fma_f32 v[34:35], v[34:35], v[32:33], v[32:33] neg_lo:[1,0,0] neg_hi:[1,0,0]
	v_lshlrev_b32_e32 v33, 16, v42
	v_cndmask_b32_e32 v39, v35, v39, vcc
	v_cmp_gt_f32_e32 vcc, 0, v32
	v_lshlrev_b32_e32 v32, 16, v43
	v_fma_f32 v35, |v33|, s92, 1.0
	v_cndmask_b32_e32 v38, v34, v38, vcc
	v_fma_f32 v34, |v32|, s92, 1.0
	v_rcp_f32_e32 v34, v34
	v_rcp_f32_e32 v35, v35
	v_mul_f32_e32 v40, v32, v32
	v_mul_f32_e32 v41, v33, v33
	v_mul_f32_e32 v40, 0xbf38aa3b, v40
	v_pk_fma_f32 v[42:43], v[34:35], s[12:13], v[24:25] op_sel_hi:[1,0,0]
	v_mul_f32_e32 v41, 0xbf38aa3b, v41
	v_exp_f32_e32 v40, v40
	v_pk_fma_f32 v[42:43], v[34:35], v[42:43], s[14:15] op_sel_hi:[1,1,0]
	v_exp_f32_e32 v41, v41
	v_pk_fma_f32 v[42:43], v[34:35], v[42:43], s[16:17] op_sel_hi:[1,1,0]
	v_cmp_gt_f32_e32 vcc, 0, v33
	v_pk_fma_f32 v[42:43], v[34:35], v[42:43], s[18:19] op_sel_hi:[1,1,0]
	s_nop 0
	v_pk_mul_f32 v[34:35], v[34:35], v[42:43]
	v_pk_mul_f32 v[34:35], v[40:41], v[34:35]
	v_pk_mul_f32 v[40:41], v[34:35], v[32:33]
	v_pk_fma_f32 v[34:35], v[34:35], v[32:33], v[32:33] neg_lo:[1,0,0] neg_hi:[1,0,0]
	v_lshlrev_b32_e32 v33, 16, v46
	v_cndmask_b32_e32 v41, v35, v41, vcc
	v_cmp_gt_f32_e32 vcc, 0, v32
	s_waitcnt vmcnt(1)
	v_lshlrev_b32_e32 v32, 16, v47
	v_mul_f32_e32 v35, v32, v32
	v_mul_f32_e32 v35, 0xbf38aa3b, v35
	v_cndmask_b32_e32 v40, v34, v40, vcc
	v_fma_f32 v34, |v32|, s92, 1.0
	v_exp_f32_e32 v42, v35
	v_fma_f32 v35, |v33|, s92, 1.0
	v_rcp_f32_e32 v34, v34
	v_rcp_f32_e32 v35, v35
	v_mul_f32_e32 v43, v33, v33
	v_mul_f32_e32 v43, 0xbf38aa3b, v43
	v_exp_f32_e32 v43, v43
	v_pk_fma_f32 v[46:47], v[34:35], s[12:13], v[24:25] op_sel_hi:[1,0,0]
	v_cmp_gt_f32_e32 vcc, 0, v33
	v_pk_fma_f32 v[46:47], v[34:35], v[46:47], s[14:15] op_sel_hi:[1,1,0]
	s_nop 0
	v_pk_fma_f32 v[46:47], v[34:35], v[46:47], s[16:17] op_sel_hi:[1,1,0]
	s_nop 0
	v_pk_fma_f32 v[46:47], v[34:35], v[46:47], s[18:19] op_sel_hi:[1,1,0]
	v_pk_mul_f32 v[34:35], v[34:35], v[46:47]
	v_pk_mul_f32 v[34:35], v[42:43], v[34:35]
	v_pk_mul_f32 v[42:43], v[34:35], v[32:33]
	v_pk_fma_f32 v[34:35], v[34:35], v[32:33], v[32:33] neg_lo:[1,0,0] neg_hi:[1,0,0]
	v_lshlrev_b32_e32 v33, 16, v45
	v_cndmask_b32_e32 v47, v35, v43, vcc
	v_cmp_gt_f32_e32 vcc, 0, v32
	v_lshlrev_b32_e32 v32, 16, v48
	v_fma_f32 v35, |v33|, s92, 1.0
	v_cndmask_b32_e32 v46, v34, v42, vcc
	v_fma_f32 v34, |v32|, s92, 1.0
	v_rcp_f32_e32 v34, v34
	v_rcp_f32_e32 v35, v35
	v_mul_f32_e32 v42, v32, v32
	v_mul_f32_e32 v43, v33, v33
	v_mul_f32_e32 v42, 0xbf38aa3b, v42
	v_pk_fma_f32 v[48:49], v[34:35], s[12:13], v[24:25] op_sel_hi:[1,0,0]
	v_mul_f32_e32 v43, 0xbf38aa3b, v43
	v_exp_f32_e32 v42, v42
	v_pk_fma_f32 v[48:49], v[34:35], v[48:49], s[14:15] op_sel_hi:[1,1,0]
	v_exp_f32_e32 v43, v43
	v_pk_fma_f32 v[48:49], v[34:35], v[48:49], s[16:17] op_sel_hi:[1,1,0]
	v_cmp_gt_f32_e32 vcc, 0, v33
	v_pk_fma_f32 v[48:49], v[34:35], v[48:49], s[18:19] op_sel_hi:[1,1,0]
	s_nop 0
	v_pk_mul_f32 v[34:35], v[34:35], v[48:49]
	v_pk_mul_f32 v[34:35], v[42:43], v[34:35]
	v_pk_mul_f32 v[42:43], v[34:35], v[32:33]
	v_pk_fma_f32 v[34:35], v[34:35], v[32:33], v[32:33] neg_lo:[1,0,0] neg_hi:[1,0,0]
	v_lshlrev_b32_e32 v33, 16, v50
	v_cndmask_b32_e32 v43, v35, v43, vcc
	v_cmp_gt_f32_e32 vcc, 0, v32
	s_waitcnt vmcnt(0)
	v_lshlrev_b32_e32 v32, 16, v51
	v_mul_f32_e32 v35, v32, v32
	v_mul_f32_e32 v35, 0xbf38aa3b, v35
	v_cndmask_b32_e32 v42, v34, v42, vcc
	v_fma_f32 v34, |v32|, s92, 1.0
	v_exp_f32_e32 v48, v35
	v_fma_f32 v35, |v33|, s92, 1.0
	v_rcp_f32_e32 v34, v34
	v_rcp_f32_e32 v35, v35
	v_mul_f32_e32 v45, v33, v33
	v_mul_f32_e32 v45, 0xbf38aa3b, v45
	v_exp_f32_e32 v49, v45
	v_pk_fma_f32 v[50:51], v[34:35], s[12:13], v[24:25] op_sel_hi:[1,0,0]
	v_cmp_gt_f32_e32 vcc, 0, v33
	v_pk_fma_f32 v[50:51], v[34:35], v[50:51], s[14:15] op_sel_hi:[1,1,0]
	s_nop 0
	v_pk_fma_f32 v[50:51], v[34:35], v[50:51], s[16:17] op_sel_hi:[1,1,0]
	s_nop 0
	v_pk_fma_f32 v[50:51], v[34:35], v[50:51], s[18:19] op_sel_hi:[1,1,0]
	v_pk_mul_f32 v[34:35], v[34:35], v[50:51]
	v_mov_b32_e32 v50, v31
	v_pk_mul_f32 v[34:35], v[48:49], v[34:35]
	v_mov_b32_e32 v51, v43
	v_pk_mul_f32 v[48:49], v[34:35], v[32:33]
	v_pk_fma_f32 v[34:35], v[34:35], v[32:33], v[32:33] neg_lo:[1,0,0] neg_hi:[1,0,0]
	v_mov_b32_e32 v33, v40
	v_cndmask_b32_e32 v49, v35, v49, vcc
	v_cmp_gt_f32_e32 vcc, 0, v32
	v_mov_b32_e32 v32, v28
	v_mov_b32_e32 v35, v42
	v_cndmask_b32_e32 v48, v34, v48, vcc
	v_mov_b32_e32 v34, v30
	v_pk_add_f32 v[32:33], v[32:33], v[34:35]
	v_mov_b32_e32 v34, v29
	v_add_f32_e32 v32, v32, v33
	v_mov_b32_e32 v35, v41
	s_nop 0
	v_add_f32_dpp v32, v32, v32 quad_perm:[1,0,3,2] row_mask:0xf bank_mask:0xf bound_ctrl:1
	v_pk_add_f32 v[34:35], v[34:35], v[50:51]
	v_mov_b32_e32 v50, v39
	v_add_f32_dpp v32, v32, v32 quad_perm:[2,3,0,1] row_mask:0xf bank_mask:0xf bound_ctrl:1
	v_mov_b32_e32 v51, v49
	s_nop 0
	v_add_f32_dpp v32, v32, v32 row_half_mirror row_mask:0xf bank_mask:0xf bound_ctrl:1
	s_nop 1
	v_add_f32_dpp v32, v32, v32 row_mirror row_mask:0xf bank_mask:0xf bound_ctrl:1
	s_nop 1
	v_add_f32_dpp v32, v32, v32 row_bcast:15 row_mask:0xa bank_mask:0xf
	s_nop 1
	v_add_f32_dpp v32, v32, v32 row_bcast:31 row_mask:0xc bank_mask:0xf
	v_add_f32_e32 v33, v34, v35
	v_readlane_b32 s6, v32, 63
	s_nop 0
	v_add_f32_dpp v33, v33, v33 quad_perm:[1,0,3,2] row_mask:0xf bank_mask:0xf bound_ctrl:1
	s_xor_b32 s6, s6, 0x80000000
	s_nop 0
	v_add_f32_dpp v33, v33, v33 quad_perm:[2,3,0,1] row_mask:0xf bank_mask:0xf bound_ctrl:1
	s_nop 1
	v_add_f32_dpp v33, v33, v33 row_half_mirror row_mask:0xf bank_mask:0xf bound_ctrl:1
	s_nop 1
	v_add_f32_dpp v33, v33, v33 row_mirror row_mask:0xf bank_mask:0xf bound_ctrl:1
	s_nop 1
	v_add_f32_dpp v33, v33, v33 row_bcast:15 row_mask:0xa bank_mask:0xf
	s_nop 1
	v_add_f32_dpp v33, v33, v33 row_bcast:31 row_mask:0xc bank_mask:0xf
	s_nop 0
	v_readlane_b32 s7, v33, 63
	s_xor_b32 s7, s7, 0x80000000
	s_nop 0
	v_pk_fma_f32 v[34:35], s[6:7], v[26:27], v[28:29] op_sel_hi:[1,0,1]
	v_pk_fma_f32 v[32:33], s[6:7], v[26:27], v[30:31] op_sel_hi:[1,0,1]
	v_pk_fma_f32 v[30:31], s[6:7], v[26:27], v[40:41] op_sel_hi:[1,0,1]
	v_pk_fma_f32 v[28:29], s[6:7], v[26:27], v[42:43] op_sel_hi:[1,0,1]
	v_mov_b32_e32 v40, v36
	v_mov_b32_e32 v41, v46
	v_mov_b32_e32 v42, v38
	v_mov_b32_e32 v43, v48
	v_pk_add_f32 v[40:41], v[40:41], v[42:43]
	v_mov_b32_e32 v42, v37
	v_add_f32_e32 v40, v40, v41
	v_mov_b32_e32 v43, v47
	s_nop 0
	v_add_f32_dpp v40, v40, v40 quad_perm:[1,0,3,2] row_mask:0xf bank_mask:0xf bound_ctrl:1
	v_pk_add_f32 v[42:43], v[42:43], v[50:51]
	s_nop 0
	v_add_f32_dpp v40, v40, v40 quad_perm:[2,3,0,1] row_mask:0xf bank_mask:0xf bound_ctrl:1
	s_nop 1
	v_add_f32_dpp v40, v40, v40 row_half_mirror row_mask:0xf bank_mask:0xf bound_ctrl:1
	s_nop 1
	v_add_f32_dpp v40, v40, v40 row_mirror row_mask:0xf bank_mask:0xf bound_ctrl:1
	s_nop 1
	v_add_f32_dpp v40, v40, v40 row_bcast:15 row_mask:0xa bank_mask:0xf
	s_nop 1
	v_add_f32_dpp v40, v40, v40 row_bcast:31 row_mask:0xc bank_mask:0xf
	v_add_f32_e32 v41, v42, v43
	v_readlane_b32 s6, v40, 63
	s_nop 0
	v_add_f32_dpp v41, v41, v41 quad_perm:[1,0,3,2] row_mask:0xf bank_mask:0xf bound_ctrl:1
	s_xor_b32 s6, s6, 0x80000000
	s_nop 0
	v_add_f32_dpp v41, v41, v41 quad_perm:[2,3,0,1] row_mask:0xf bank_mask:0xf bound_ctrl:1
	s_nop 1
	v_add_f32_dpp v41, v41, v41 row_half_mirror row_mask:0xf bank_mask:0xf bound_ctrl:1
	s_nop 1
	v_add_f32_dpp v41, v41, v41 row_mirror row_mask:0xf bank_mask:0xf bound_ctrl:1
	s_nop 1
	v_add_f32_dpp v41, v41, v41 row_bcast:15 row_mask:0xa bank_mask:0xf
	s_nop 1
	v_add_f32_dpp v41, v41, v41 row_bcast:31 row_mask:0xc bank_mask:0xf
	s_nop 0
	v_readlane_b32 s7, v41, 63
	s_xor_b32 s7, s7, 0x80000000
	s_nop 0
	v_pk_fma_f32 v[40:41], s[6:7], v[26:27], v[38:39] op_sel_hi:[1,0,1]
	v_pk_fma_f32 v[38:39], s[6:7], v[26:27], v[46:47] op_sel_hi:[1,0,1]
	global_load_ushort v52, v44, s[54:55] offset:512
	global_load_ushort v56, v44, s[54:55] offset:640
	global_load_ushort v77, v44, s[54:55] offset:768
	global_load_ushort v82, v44, s[54:55] offset:896
	global_load_ushort v53, v44, s[46:47] offset:512
	global_load_ushort v57, v44, s[46:47] offset:640
	global_load_ushort v78, v44, s[46:47] offset:768
	global_load_ushort v83, v44, s[46:47] offset:896
	global_load_ushort v45, v44, s[56:57] offset:512
	global_load_ushort v54, v44, s[56:57] offset:640
	global_load_ushort v58, v44, s[56:57] offset:768
	global_load_ushort v80, v44, s[56:57] offset:896
	global_load_ushort v46, v44, s[48:49] offset:512
	global_load_ushort v55, v44, s[48:49] offset:640
	global_load_ushort v59, v44, s[48:49] offset:768
	global_load_ushort v81, v44, s[48:49] offset:896
	global_load_ushort v66, v44, s[50:51] offset:512
	global_load_ushort v68, v44, s[50:51] offset:640
	global_load_ushort v72, v44, s[50:51] offset:768
	global_load_ushort v64, v44, s[50:51] offset:896
	global_load_ushort v67, v44, s[42:43] offset:512
	global_load_ushort v69, v44, s[42:43] offset:640
	global_load_ushort v73, v44, s[42:43] offset:768
	global_load_ushort v65, v44, s[42:43] offset:896
	global_load_ushort v60, v44, s[52:53] offset:512
	global_load_ushort v62, v44, s[52:53] offset:640
	global_load_ushort v75, v44, s[52:53] offset:768
	global_load_ushort v70, v44, s[52:53] offset:896
	global_load_ushort v61, v44, s[44:45] offset:512
	global_load_ushort v63, v44, s[44:45] offset:640
	global_load_ushort v76, v44, s[44:45] offset:768
	global_load_ushort v71, v44, s[44:45] offset:896
	v_pk_fma_f32 v[42:43], s[6:7], v[26:27], v[36:37] op_sel_hi:[1,0,1]
	v_pk_fma_f32 v[36:37], s[6:7], v[26:27], v[48:49] op_sel_hi:[1,0,1]
	s_movk_i32 s46, 0x2000
	s_waitcnt vmcnt(23)
	v_lshlrev_b32_e32 v45, 16, v45
	v_fma_f32 v47, |v45|, s92, 1.0
	v_rcp_f32_e32 v47, v47
	v_mul_f32_e32 v49, v45, v45
	s_waitcnt vmcnt(19)
	v_lshlrev_b32_e32 v44, 16, v46
	v_fma_f32 v46, |v44|, s92, 1.0
	v_rcp_f32_e32 v46, v46
	v_mul_f32_e32 v48, v44, v44
	v_mul_f32_e32 v48, 0xbf38aa3b, v48
	v_mul_f32_e32 v49, 0xbf38aa3b, v49
	v_pk_fma_f32 v[50:51], v[46:47], s[12:13], v[24:25] op_sel_hi:[1,0,0]
	v_exp_f32_e32 v48, v48
	v_pk_fma_f32 v[50:51], v[46:47], v[50:51], s[14:15] op_sel_hi:[1,1,0]
	v_exp_f32_e32 v49, v49
	v_pk_fma_f32 v[50:51], v[46:47], v[50:51], s[16:17] op_sel_hi:[1,1,0]
	v_cmp_gt_f32_e32 vcc, 0, v45
	v_pk_fma_f32 v[50:51], v[46:47], v[50:51], s[18:19] op_sel_hi:[1,1,0]
	s_waitcnt vmcnt(1)
	v_lshlrev_b32_e32 v76, 16, v76
	v_pk_mul_f32 v[46:47], v[46:47], v[50:51]
	v_pk_mul_f32 v[46:47], v[48:49], v[46:47]
	v_pk_mul_f32 v[48:49], v[46:47], v[44:45]
	v_pk_fma_f32 v[46:47], v[46:47], v[44:45], v[44:45] neg_lo:[1,0,0] neg_hi:[1,0,0]
	s_nop 0
	v_cndmask_b32_e32 v45, v47, v49, vcc
	v_cmp_gt_f32_e32 vcc, 0, v44
	v_lshlrev_b32_e32 v47, 16, v52
	v_mul_f32_e32 v51, v47, v47
	v_cndmask_b32_e32 v44, v46, v48, vcc
	v_lshlrev_b32_e32 v46, 16, v53
	v_mul_f32_e32 v49, v46, v46
	v_mul_f32_e32 v49, 0xbf38aa3b, v49
	v_fma_f32 v48, |v46|, s92, 1.0
	v_exp_f32_e32 v50, v49
	v_fma_f32 v49, |v47|, s92, 1.0
	v_rcp_f32_e32 v48, v48
	v_rcp_f32_e32 v49, v49
	v_mul_f32_e32 v51, 0xbf38aa3b, v51
	v_exp_f32_e32 v51, v51
	v_cmp_gt_f32_e32 vcc, 0, v47
	v_pk_fma_f32 v[52:53], v[48:49], s[12:13], v[24:25] op_sel_hi:[1,0,0]
	s_nop 0
	v_pk_fma_f32 v[52:53], v[48:49], v[52:53], s[14:15] op_sel_hi:[1,1,0]
	s_nop 0
	v_pk_fma_f32 v[52:53], v[48:49], v[52:53], s[16:17] op_sel_hi:[1,1,0]
	s_nop 0
	v_pk_fma_f32 v[52:53], v[48:49], v[52:53], s[18:19] op_sel_hi:[1,1,0]
	v_pk_mul_f32 v[48:49], v[48:49], v[52:53]
	v_pk_mul_f32 v[48:49], v[50:51], v[48:49]
	v_pk_mul_f32 v[50:51], v[48:49], v[46:47]
	v_pk_fma_f32 v[48:49], v[48:49], v[46:47], v[46:47] neg_lo:[1,0,0] neg_hi:[1,0,0]
	v_lshlrev_b32_e32 v47, 16, v54
	v_cndmask_b32_e32 v53, v49, v51, vcc
	v_cmp_gt_f32_e32 vcc, 0, v46
	v_lshlrev_b32_e32 v46, 16, v55
	v_fma_f32 v49, |v47|, s92, 1.0
	v_cndmask_b32_e32 v52, v48, v50, vcc
	v_fma_f32 v48, |v46|, s92, 1.0
	v_rcp_f32_e32 v48, v48
	v_rcp_f32_e32 v49, v49
	v_mul_f32_e32 v50, v46, v46
	v_mul_f32_e32 v51, v47, v47
	v_mul_f32_e32 v50, 0xbf38aa3b, v50
	v_pk_fma_f32 v[54:55], v[48:49], s[12:13], v[24:25] op_sel_hi:[1,0,0]
	v_mul_f32_e32 v51, 0xbf38aa3b, v51
	v_exp_f32_e32 v50, v50
	v_pk_fma_f32 v[54:55], v[48:49], v[54:55], s[14:15] op_sel_hi:[1,1,0]
	v_exp_f32_e32 v51, v51
	v_pk_fma_f32 v[54:55], v[48:49], v[54:55], s[16:17] op_sel_hi:[1,1,0]
	v_cmp_gt_f32_e32 vcc, 0, v47
	v_pk_fma_f32 v[54:55], v[48:49], v[54:55], s[18:19] op_sel_hi:[1,1,0]
	s_nop 0
	v_pk_mul_f32 v[48:49], v[48:49], v[54:55]
	v_pk_mul_f32 v[48:49], v[50:51], v[48:49]
	v_pk_mul_f32 v[50:51], v[48:49], v[46:47]
	v_pk_fma_f32 v[48:49], v[48:49], v[46:47], v[46:47] neg_lo:[1,0,0] neg_hi:[1,0,0]
	v_lshlrev_b32_e32 v47, 16, v56
	v_cndmask_b32_e32 v49, v49, v51, vcc
	v_cmp_gt_f32_e32 vcc, 0, v46
	v_lshlrev_b32_e32 v46, 16, v57
	v_mul_f32_e32 v51, v46, v46
	v_mul_f32_e32 v51, 0xbf38aa3b, v51
	v_cndmask_b32_e32 v48, v48, v50, vcc
	v_fma_f32 v50, |v46|, s92, 1.0
	v_exp_f32_e32 v54, v51
	v_fma_f32 v51, |v47|, s92, 1.0
	v_rcp_f32_e32 v50, v50
	v_rcp_f32_e32 v51, v51
	v_mul_f32_e32 v55, v47, v47
	v_mul_f32_e32 v55, 0xbf38aa3b, v55
	v_exp_f32_e32 v55, v55
	v_pk_fma_f32 v[56:57], v[50:51], s[12:13], v[24:25] op_sel_hi:[1,0,0]
	v_cmp_gt_f32_e32 vcc, 0, v47
	v_pk_fma_f32 v[56:57], v[50:51], v[56:57], s[14:15] op_sel_hi:[1,1,0]
	s_nop 0
	v_pk_fma_f32 v[56:57], v[50:51], v[56:57], s[16:17] op_sel_hi:[1,1,0]
	s_nop 0
	v_pk_fma_f32 v[56:57], v[50:51], v[56:57], s[18:19] op_sel_hi:[1,1,0]
	v_pk_mul_f32 v[50:51], v[50:51], v[56:57]
	v_pk_mul_f32 v[50:51], v[54:55], v[50:51]
	v_pk_mul_f32 v[54:55], v[50:51], v[46:47]
	v_pk_fma_f32 v[50:51], v[50:51], v[46:47], v[46:47] neg_lo:[1,0,0] neg_hi:[1,0,0]
	v_lshlrev_b32_e32 v47, 16, v58
	v_cndmask_b32_e32 v55, v51, v55, vcc
	v_cmp_gt_f32_e32 vcc, 0, v46
	v_lshlrev_b32_e32 v46, 16, v59
	v_fma_f32 v51, |v47|, s92, 1.0
	v_cndmask_b32_e32 v54, v50, v54, vcc
	v_fma_f32 v50, |v46|, s92, 1.0
	v_rcp_f32_e32 v50, v50
	v_rcp_f32_e32 v51, v51
	v_mul_f32_e32 v56, v46, v46
	v_mul_f32_e32 v57, v47, v47
	v_mul_f32_e32 v56, 0xbf38aa3b, v56
	v_pk_fma_f32 v[58:59], v[50:51], s[12:13], v[24:25] op_sel_hi:[1,0,0]
	v_mul_f32_e32 v57, 0xbf38aa3b, v57
	v_exp_f32_e32 v56, v56
	v_pk_fma_f32 v[58:59], v[50:51], v[58:59], s[14:15] op_sel_hi:[1,1,0]
	v_exp_f32_e32 v57, v57
	v_pk_fma_f32 v[58:59], v[50:51], v[58:59], s[16:17] op_sel_hi:[1,1,0]
	v_cmp_gt_f32_e32 vcc, 0, v47
	v_pk_fma_f32 v[58:59], v[50:51], v[58:59], s[18:19] op_sel_hi:[1,1,0]
	s_nop 0
	v_pk_mul_f32 v[50:51], v[50:51], v[58:59]
	v_pk_mul_f32 v[50:51], v[56:57], v[50:51]
	v_pk_mul_f32 v[56:57], v[50:51], v[46:47]
	v_pk_fma_f32 v[50:51], v[50:51], v[46:47], v[46:47] neg_lo:[1,0,0] neg_hi:[1,0,0]
	v_lshlrev_b32_e32 v47, 16, v77
	v_cndmask_b32_e32 v57, v51, v57, vcc
	v_cmp_gt_f32_e32 vcc, 0, v46
	v_lshlrev_b32_e32 v46, 16, v78
	v_mul_f32_e32 v51, v46, v46
	v_mul_f32_e32 v51, 0xbf38aa3b, v51
	v_cndmask_b32_e32 v56, v50, v56, vcc
	v_fma_f32 v50, |v46|, s92, 1.0
	v_exp_f32_e32 v58, v51
	v_fma_f32 v51, |v47|, s92, 1.0
	v_rcp_f32_e32 v50, v50
	v_rcp_f32_e32 v51, v51
	v_mul_f32_e32 v59, v47, v47
	v_mul_f32_e32 v59, 0xbf38aa3b, v59
	v_exp_f32_e32 v59, v59
	v_pk_fma_f32 v[78:79], v[50:51], s[12:13], v[24:25] op_sel_hi:[1,0,0]
	v_cmp_gt_f32_e32 vcc, 0, v47
	v_pk_fma_f32 v[78:79], v[50:51], v[78:79], s[14:15] op_sel_hi:[1,1,0]
	s_nop 0
	v_pk_fma_f32 v[78:79], v[50:51], v[78:79], s[16:17] op_sel_hi:[1,1,0]
	s_nop 0
	v_pk_fma_f32 v[78:79], v[50:51], v[78:79], s[18:19] op_sel_hi:[1,1,0]
	v_pk_mul_f32 v[50:51], v[50:51], v[78:79]
	v_pk_mul_f32 v[50:51], v[58:59], v[50:51]
	v_pk_mul_f32 v[58:59], v[50:51], v[46:47]
	v_pk_fma_f32 v[50:51], v[50:51], v[46:47], v[46:47] neg_lo:[1,0,0] neg_hi:[1,0,0]
	v_lshlrev_b32_e32 v47, 16, v80
	v_cndmask_b32_e32 v79, v51, v59, vcc
	v_cmp_gt_f32_e32 vcc, 0, v46
	v_lshlrev_b32_e32 v46, 16, v81
	v_fma_f32 v51, |v47|, s92, 1.0
	v_cndmask_b32_e32 v78, v50, v58, vcc
	v_fma_f32 v50, |v46|, s92, 1.0
	v_rcp_f32_e32 v50, v50
	v_rcp_f32_e32 v51, v51
	v_mul_f32_e32 v58, v46, v46
	v_mul_f32_e32 v59, v47, v47
	v_mul_f32_e32 v58, 0xbf38aa3b, v58
	v_pk_fma_f32 v[80:81], v[50:51], s[12:13], v[24:25] op_sel_hi:[1,0,0]
	v_mul_f32_e32 v59, 0xbf38aa3b, v59
	v_exp_f32_e32 v58, v58
	v_pk_fma_f32 v[80:81], v[50:51], v[80:81], s[14:15] op_sel_hi:[1,1,0]
	v_exp_f32_e32 v59, v59
	v_pk_fma_f32 v[80:81], v[50:51], v[80:81], s[16:17] op_sel_hi:[1,1,0]
	v_cmp_gt_f32_e32 vcc, 0, v47
	v_pk_fma_f32 v[80:81], v[50:51], v[80:81], s[18:19] op_sel_hi:[1,1,0]
	s_nop 0
	v_pk_mul_f32 v[50:51], v[50:51], v[80:81]
	v_pk_mul_f32 v[50:51], v[58:59], v[50:51]
	v_pk_mul_f32 v[58:59], v[50:51], v[46:47]
	v_pk_fma_f32 v[50:51], v[50:51], v[46:47], v[46:47] neg_lo:[1,0,0] neg_hi:[1,0,0]
	v_lshlrev_b32_e32 v47, 16, v82
	v_cndmask_b32_e32 v59, v51, v59, vcc
	v_cmp_gt_f32_e32 vcc, 0, v46
	v_lshlrev_b32_e32 v46, 16, v83
	v_mul_f32_e32 v51, v46, v46
	v_mul_f32_e32 v51, 0xbf38aa3b, v51
	v_cndmask_b32_e32 v58, v50, v58, vcc
	v_fma_f32 v50, |v46|, s92, 1.0
	v_exp_f32_e32 v80, v51
	v_fma_f32 v51, |v47|, s92, 1.0
	v_rcp_f32_e32 v50, v50
	v_rcp_f32_e32 v51, v51
	v_mul_f32_e32 v77, v47, v47
	v_mul_f32_e32 v77, 0xbf38aa3b, v77
	v_exp_f32_e32 v81, v77
	v_pk_fma_f32 v[82:83], v[50:51], s[12:13], v[24:25] op_sel_hi:[1,0,0]
	v_cmp_gt_f32_e32 vcc, 0, v47
	v_pk_fma_f32 v[82:83], v[50:51], v[82:83], s[14:15] op_sel_hi:[1,1,0]
	s_nop 0
	v_pk_fma_f32 v[82:83], v[50:51], v[82:83], s[16:17] op_sel_hi:[1,1,0]
	s_nop 0
	v_pk_fma_f32 v[82:83], v[50:51], v[82:83], s[18:19] op_sel_hi:[1,1,0]
	v_pk_mul_f32 v[50:51], v[50:51], v[82:83]
	v_mov_b32_e32 v82, v49
	v_pk_mul_f32 v[50:51], v[80:81], v[50:51]
	v_mov_b32_e32 v83, v59
	v_pk_mul_f32 v[80:81], v[50:51], v[46:47]
	v_pk_fma_f32 v[50:51], v[50:51], v[46:47], v[46:47] neg_lo:[1,0,0] neg_hi:[1,0,0]
	v_mov_b32_e32 v47, v56
	v_cndmask_b32_e32 v81, v51, v81, vcc
	v_cmp_gt_f32_e32 vcc, 0, v46
	v_mov_b32_e32 v46, v44
	v_mov_b32_e32 v51, v58
	v_cndmask_b32_e32 v80, v50, v80, vcc
	v_mov_b32_e32 v50, v48
	v_pk_add_f32 v[46:47], v[46:47], v[50:51]
	v_mov_b32_e32 v50, v45
	v_add_f32_e32 v46, v46, v47
	v_mov_b32_e32 v51, v57
	s_nop 0
	v_add_f32_dpp v46, v46, v46 quad_perm:[1,0,3,2] row_mask:0xf bank_mask:0xf bound_ctrl:1
	v_pk_add_f32 v[50:51], v[50:51], v[82:83]
	v_mov_b32_e32 v82, v55
	v_add_f32_dpp v46, v46, v46 quad_perm:[2,3,0,1] row_mask:0xf bank_mask:0xf bound_ctrl:1
	v_mov_b32_e32 v83, v81
	s_nop 0
	v_add_f32_dpp v46, v46, v46 row_half_mirror row_mask:0xf bank_mask:0xf bound_ctrl:1
	s_nop 1
	v_add_f32_dpp v46, v46, v46 row_mirror row_mask:0xf bank_mask:0xf bound_ctrl:1
	s_nop 1
	v_add_f32_dpp v46, v46, v46 row_bcast:15 row_mask:0xa bank_mask:0xf
	s_nop 1
	v_add_f32_dpp v46, v46, v46 row_bcast:31 row_mask:0xc bank_mask:0xf
	v_add_f32_e32 v47, v50, v51
	v_readlane_b32 s6, v46, 63
	s_nop 0
	v_add_f32_dpp v47, v47, v47 quad_perm:[1,0,3,2] row_mask:0xf bank_mask:0xf bound_ctrl:1
	s_xor_b32 s6, s6, 0x80000000
	s_nop 0
	v_add_f32_dpp v47, v47, v47 quad_perm:[2,3,0,1] row_mask:0xf bank_mask:0xf bound_ctrl:1
	s_nop 1
	v_add_f32_dpp v47, v47, v47 row_half_mirror row_mask:0xf bank_mask:0xf bound_ctrl:1
	s_nop 1
	v_add_f32_dpp v47, v47, v47 row_mirror row_mask:0xf bank_mask:0xf bound_ctrl:1
	s_nop 1
	v_add_f32_dpp v47, v47, v47 row_bcast:15 row_mask:0xa bank_mask:0xf
	s_nop 1
	v_add_f32_dpp v47, v47, v47 row_bcast:31 row_mask:0xc bank_mask:0xf
	s_nop 0
	v_readlane_b32 s7, v47, 63
	s_xor_b32 s7, s7, 0x80000000
	s_nop 0
	v_pk_fma_f32 v[46:47], s[6:7], v[26:27], v[44:45] op_sel_hi:[1,0,1]
	v_pk_fma_f32 v[50:51], s[6:7], v[26:27], v[48:49] op_sel_hi:[1,0,1]
	v_pk_fma_f32 v[48:49], s[6:7], v[26:27], v[56:57] op_sel_hi:[1,0,1]
	v_pk_fma_f32 v[44:45], s[6:7], v[26:27], v[58:59] op_sel_hi:[1,0,1]
	v_mov_b32_e32 v56, v52
	v_mov_b32_e32 v57, v78
	v_mov_b32_e32 v58, v54
	v_mov_b32_e32 v59, v80
	v_pk_add_f32 v[56:57], v[56:57], v[58:59]
	v_mov_b32_e32 v58, v53
	v_add_f32_e32 v56, v56, v57
	v_mov_b32_e32 v59, v79
	s_nop 0
	v_add_f32_dpp v56, v56, v56 quad_perm:[1,0,3,2] row_mask:0xf bank_mask:0xf bound_ctrl:1
	v_pk_add_f32 v[58:59], v[58:59], v[82:83]
	s_nop 0
	v_add_f32_dpp v56, v56, v56 quad_perm:[2,3,0,1] row_mask:0xf bank_mask:0xf bound_ctrl:1
	s_nop 1
	v_add_f32_dpp v56, v56, v56 row_half_mirror row_mask:0xf bank_mask:0xf bound_ctrl:1
	s_nop 1
	v_add_f32_dpp v56, v56, v56 row_mirror row_mask:0xf bank_mask:0xf bound_ctrl:1
	s_nop 1
	v_add_f32_dpp v56, v56, v56 row_bcast:15 row_mask:0xa bank_mask:0xf
	s_nop 1
	v_add_f32_dpp v56, v56, v56 row_bcast:31 row_mask:0xc bank_mask:0xf
	v_add_f32_e32 v57, v58, v59
	v_readlane_b32 s6, v56, 63
	s_nop 0
	v_add_f32_dpp v57, v57, v57 quad_perm:[1,0,3,2] row_mask:0xf bank_mask:0xf bound_ctrl:1
	s_xor_b32 s6, s6, 0x80000000
	s_nop 0
	v_add_f32_dpp v57, v57, v57 quad_perm:[2,3,0,1] row_mask:0xf bank_mask:0xf bound_ctrl:1
	s_nop 1
	v_add_f32_dpp v57, v57, v57 row_half_mirror row_mask:0xf bank_mask:0xf bound_ctrl:1
	s_nop 1
	v_add_f32_dpp v57, v57, v57 row_mirror row_mask:0xf bank_mask:0xf bound_ctrl:1
	s_nop 1
	v_add_f32_dpp v57, v57, v57 row_bcast:15 row_mask:0xa bank_mask:0xf
	s_nop 1
	v_add_f32_dpp v57, v57, v57 row_bcast:31 row_mask:0xc bank_mask:0xf
	s_nop 0
	v_readlane_b32 s7, v57, 63
	s_xor_b32 s7, s7, 0x80000000
	s_nop 0
	v_pk_fma_f32 v[56:57], s[6:7], v[26:27], v[54:55] op_sel_hi:[1,0,1]
	v_pk_fma_f32 v[54:55], s[6:7], v[26:27], v[78:79] op_sel_hi:[1,0,1]
	v_lshlrev_b32_e32 v79, 16, v60
	v_lshlrev_b32_e32 v78, 16, v61
	v_fma_f32 v60, |v78|, s92, 1.0
	v_fma_f32 v61, |v79|, s92, 1.0
	v_rcp_f32_e32 v60, v60
	v_rcp_f32_e32 v61, v61
	v_mul_f32_e32 v77, v78, v78
	v_mul_f32_e32 v77, 0xbf38aa3b, v77
	v_pk_fma_f32 v[58:59], s[6:7], v[26:27], v[52:53] op_sel_hi:[1,0,1]
	v_pk_fma_f32 v[52:53], s[6:7], v[26:27], v[80:81] op_sel_hi:[1,0,1]
	v_exp_f32_e32 v80, v77
	v_mul_f32_e32 v77, v79, v79
	v_pk_fma_f32 v[82:83], v[60:61], s[12:13], v[24:25] op_sel_hi:[1,0,0]
	v_mul_f32_e32 v77, 0xbf38aa3b, v77
	v_pk_fma_f32 v[82:83], v[60:61], v[82:83], s[14:15] op_sel_hi:[1,1,0]
	v_exp_f32_e32 v81, v77
	v_pk_fma_f32 v[82:83], v[60:61], v[82:83], s[16:17] op_sel_hi:[1,1,0]
	v_cmp_gt_f32_e32 vcc, 0, v79
	v_pk_fma_f32 v[82:83], v[60:61], v[82:83], s[18:19] op_sel_hi:[1,1,0]
	s_mov_b32 s6, 0xbe11a98e
	v_pk_mul_f32 v[60:61], v[60:61], v[82:83]
	v_pk_mul_f32 v[60:61], v[80:81], v[60:61]
	v_pk_mul_f32 v[80:81], v[60:61], v[78:79]
	v_pk_fma_f32 v[60:61], v[60:61], v[78:79], v[78:79] neg_lo:[1,0,0] neg_hi:[1,0,0]
	v_lshlrev_b32_e32 v79, 16, v66
	v_cndmask_b32_e32 v61, v61, v81, vcc
	v_cmp_gt_f32_e32 vcc, 0, v78
	v_lshlrev_b32_e32 v78, 16, v67
	v_mul_f32_e32 v67, v78, v78
	v_mul_f32_e32 v67, 0xbf38aa3b, v67
	v_cndmask_b32_e32 v60, v60, v80, vcc
	v_fma_f32 v66, |v78|, s92, 1.0
	v_exp_f32_e32 v80, v67
	v_fma_f32 v67, |v79|, s92, 1.0
	v_rcp_f32_e32 v66, v66
	v_rcp_f32_e32 v67, v67
	v_mul_f32_e32 v77, v79, v79
	v_mul_f32_e32 v77, 0xbf38aa3b, v77
	v_exp_f32_e32 v81, v77
	v_pk_fma_f32 v[82:83], v[66:67], s[12:13], v[24:25] op_sel_hi:[1,0,0]
	v_cmp_gt_f32_e32 vcc, 0, v79
	v_pk_fma_f32 v[82:83], v[66:67], v[82:83], s[14:15] op_sel_hi:[1,1,0]
	s_nop 0
	v_pk_fma_f32 v[82:83], v[66:67], v[82:83], s[16:17] op_sel_hi:[1,1,0]
	s_nop 0
	v_pk_fma_f32 v[82:83], v[66:67], v[82:83], s[18:19] op_sel_hi:[1,1,0]
	v_pk_mul_f32 v[66:67], v[66:67], v[82:83]
	v_pk_mul_f32 v[66:67], v[80:81], v[66:67]
	v_pk_mul_f32 v[80:81], v[66:67], v[78:79]
	v_pk_fma_f32 v[66:67], v[66:67], v[78:79], v[78:79] neg_lo:[1,0,0] neg_hi:[1,0,0]
	v_lshlrev_b32_e32 v79, 16, v62
	v_cndmask_b32_e32 v67, v67, v81, vcc
	v_cmp_gt_f32_e32 vcc, 0, v78
	v_lshlrev_b32_e32 v78, 16, v63
	v_fma_f32 v62, |v78|, s92, 1.0
	v_fma_f32 v63, |v79|, s92, 1.0
	v_rcp_f32_e32 v62, v62
	v_rcp_f32_e32 v63, v63
	v_mul_f32_e32 v77, v78, v78
	v_mul_f32_e32 v77, 0xbf38aa3b, v77
	v_cndmask_b32_e32 v66, v66, v80, vcc
	v_exp_f32_e32 v80, v77
	v_mul_f32_e32 v77, v79, v79
	v_pk_fma_f32 v[82:83], v[62:63], s[12:13], v[24:25] op_sel_hi:[1,0,0]
	v_mul_f32_e32 v77, 0xbf38aa3b, v77
	v_pk_fma_f32 v[82:83], v[62:63], v[82:83], s[14:15] op_sel_hi:[1,1,0]
	v_exp_f32_e32 v81, v77
	v_pk_fma_f32 v[82:83], v[62:63], v[82:83], s[16:17] op_sel_hi:[1,1,0]
	v_cmp_gt_f32_e32 vcc, 0, v79
	v_pk_fma_f32 v[82:83], v[62:63], v[82:83], s[18:19] op_sel_hi:[1,1,0]
	s_nop 0
	v_pk_mul_f32 v[62:63], v[62:63], v[82:83]
	v_pk_mul_f32 v[62:63], v[80:81], v[62:63]
	v_pk_mul_f32 v[80:81], v[62:63], v[78:79]
	v_pk_fma_f32 v[62:63], v[62:63], v[78:79], v[78:79] neg_lo:[1,0,0] neg_hi:[1,0,0]
	v_lshlrev_b32_e32 v79, 16, v68
	v_cndmask_b32_e32 v63, v63, v81, vcc
	v_cmp_gt_f32_e32 vcc, 0, v78
	v_lshlrev_b32_e32 v78, 16, v69
	v_mul_f32_e32 v69, v78, v78
	v_mul_f32_e32 v69, 0xbf38aa3b, v69
	v_cndmask_b32_e32 v62, v62, v80, vcc
	v_fma_f32 v68, |v78|, s92, 1.0
	v_exp_f32_e32 v80, v69
	v_fma_f32 v69, |v79|, s92, 1.0
	v_rcp_f32_e32 v68, v68
	v_rcp_f32_e32 v69, v69
	v_mul_f32_e32 v77, v79, v79
	v_mul_f32_e32 v77, 0xbf38aa3b, v77
	v_exp_f32_e32 v81, v77
	v_pk_fma_f32 v[82:83], v[68:69], s[12:13], v[24:25] op_sel_hi:[1,0,0]
	v_cmp_gt_f32_e32 vcc, 0, v79
	v_pk_fma_f32 v[82:83], v[68:69], v[82:83], s[14:15] op_sel_hi:[1,1,0]
	v_lshlrev_b32_e32 v77, 16, v75
	v_pk_fma_f32 v[82:83], v[68:69], v[82:83], s[16:17] op_sel_hi:[1,1,0]
	v_fma_f32 v75, |v76|, s92, 1.0
	v_pk_fma_f32 v[82:83], v[68:69], v[82:83], s[18:19] op_sel_hi:[1,1,0]
	v_pk_mul_f32 v[68:69], v[68:69], v[82:83]
	v_pk_mul_f32 v[68:69], v[80:81], v[68:69]
	v_pk_mul_f32 v[80:81], v[68:69], v[78:79]
	v_pk_fma_f32 v[68:69], v[68:69], v[78:79], v[78:79] neg_lo:[1,0,0] neg_hi:[1,0,0]
	s_nop 0
	v_cndmask_b32_e32 v69, v69, v81, vcc
	v_cmp_gt_f32_e32 vcc, 0, v78
	v_rcp_f32_e32 v78, v75
	v_fma_f32 v75, |v77|, s92, 1.0
	v_rcp_f32_e32 v79, v75
	v_mul_f32_e32 v75, v76, v76
	v_mul_f32_e32 v75, 0xbf38aa3b, v75
	v_cndmask_b32_e32 v68, v68, v80, vcc
	v_exp_f32_e32 v80, v75
	v_mul_f32_e32 v75, v77, v77
	v_pk_fma_f32 v[82:83], v[78:79], s[12:13], v[24:25] op_sel_hi:[1,0,0]
	v_mul_f32_e32 v75, 0xbf38aa3b, v75
	v_pk_fma_f32 v[82:83], v[78:79], v[82:83], s[14:15] op_sel_hi:[1,1,0]
	v_exp_f32_e32 v81, v75
	v_pk_fma_f32 v[82:83], v[78:79], v[82:83], s[16:17] op_sel_hi:[1,1,0]
	v_cmp_gt_f32_e32 vcc, 0, v77
	v_pk_fma_f32 v[82:83], v[78:79], v[82:83], s[18:19] op_sel_hi:[1,1,0]
	s_nop 0
	v_pk_mul_f32 v[78:79], v[78:79], v[82:83]
	v_pk_mul_f32 v[78:79], v[80:81], v[78:79]
	v_pk_mul_f32 v[80:81], v[78:79], v[76:77]
	v_pk_fma_f32 v[78:79], v[78:79], v[76:77], v[76:77] neg_lo:[1,0,0] neg_hi:[1,0,0]
	s_nop 0
	v_cndmask_b32_e32 v77, v79, v81, vcc
	v_cmp_gt_f32_e32 vcc, 0, v76
	v_lshlrev_b32_e32 v79, 16, v72
	v_mul_f32_e32 v75, v79, v79
	v_cndmask_b32_e32 v76, v78, v80, vcc
	v_lshlrev_b32_e32 v78, 16, v73
	v_mul_f32_e32 v73, v78, v78
	v_mul_f32_e32 v73, 0xbf38aa3b, v73
	v_fma_f32 v72, |v78|, s92, 1.0
	v_exp_f32_e32 v80, v73
	v_fma_f32 v73, |v79|, s92, 1.0
	v_rcp_f32_e32 v72, v72
	v_rcp_f32_e32 v73, v73
	v_mul_f32_e32 v75, 0xbf38aa3b, v75
	v_exp_f32_e32 v81, v75
	v_cmp_gt_f32_e32 vcc, 0, v79
	v_pk_fma_f32 v[82:83], v[72:73], s[12:13], v[24:25] op_sel_hi:[1,0,0]
	s_nop 0
	v_pk_fma_f32 v[82:83], v[72:73], v[82:83], s[14:15] op_sel_hi:[1,1,0]
	s_nop 0
	v_pk_fma_f32 v[82:83], v[72:73], v[82:83], s[16:17] op_sel_hi:[1,1,0]
	s_nop 0
	v_pk_fma_f32 v[82:83], v[72:73], v[82:83], s[18:19] op_sel_hi:[1,1,0]
	v_pk_mul_f32 v[72:73], v[72:73], v[82:83]
	v_pk_mul_f32 v[72:73], v[80:81], v[72:73]
	v_pk_mul_f32 v[80:81], v[72:73], v[78:79]
	v_pk_fma_f32 v[72:73], v[72:73], v[78:79], v[78:79] neg_lo:[1,0,0] neg_hi:[1,0,0]
	v_lshlrev_b32_e32 v79, 16, v70
	v_cndmask_b32_e32 v73, v73, v81, vcc
	v_cmp_gt_f32_e32 vcc, 0, v78
	s_waitcnt vmcnt(0)
	v_lshlrev_b32_e32 v78, 16, v71
	v_fma_f32 v70, |v78|, s92, 1.0
	v_fma_f32 v71, |v79|, s92, 1.0
	v_rcp_f32_e32 v70, v70
	v_rcp_f32_e32 v71, v71
	v_mul_f32_e32 v75, v78, v78
	v_mul_f32_e32 v75, 0xbf38aa3b, v75
	v_cndmask_b32_e32 v72, v72, v80, vcc
	v_exp_f32_e32 v80, v75
	v_mul_f32_e32 v75, v79, v79
	v_pk_fma_f32 v[82:83], v[70:71], s[12:13], v[24:25] op_sel_hi:[1,0,0]
	v_mul_f32_e32 v75, 0xbf38aa3b, v75
	v_pk_fma_f32 v[82:83], v[70:71], v[82:83], s[14:15] op_sel_hi:[1,1,0]
	v_exp_f32_e32 v81, v75
	v_pk_fma_f32 v[82:83], v[70:71], v[82:83], s[16:17] op_sel_hi:[1,1,0]
	v_cmp_gt_f32_e32 vcc, 0, v79
	v_pk_fma_f32 v[82:83], v[70:71], v[82:83], s[18:19] op_sel_hi:[1,1,0]
	s_nop 0
	v_pk_mul_f32 v[70:71], v[70:71], v[82:83]
	v_pk_mul_f32 v[70:71], v[80:81], v[70:71]
	v_pk_mul_f32 v[80:81], v[70:71], v[78:79]
	v_pk_fma_f32 v[70:71], v[70:71], v[78:79], v[78:79] neg_lo:[1,0,0] neg_hi:[1,0,0]
	v_lshlrev_b32_e32 v79, 16, v64
	v_cndmask_b32_e32 v71, v71, v81, vcc
	v_cmp_gt_f32_e32 vcc, 0, v78
	v_lshlrev_b32_e32 v78, 16, v65
	v_mul_f32_e32 v65, v78, v78
	v_mul_f32_e32 v65, 0xbf38aa3b, v65
	v_cndmask_b32_e32 v70, v70, v80, vcc
	v_fma_f32 v64, |v78|, s92, 1.0
	v_exp_f32_e32 v80, v65
	v_fma_f32 v65, |v79|, s92, 1.0
	v_rcp_f32_e32 v64, v64
	v_rcp_f32_e32 v65, v65
	v_mul_f32_e32 v75, v79, v79
	v_mul_f32_e32 v75, 0xbf38aa3b, v75
	v_exp_f32_e32 v81, v75
	v_pk_fma_f32 v[24:25], v[64:65], s[12:13], v[24:25] op_sel_hi:[1,0,0]
	v_cmp_gt_f32_e32 vcc, 0, v79
	v_pk_fma_f32 v[24:25], v[64:65], v[24:25], s[14:15] op_sel_hi:[1,1,0]
	v_mov_b32_e32 v75, v131
	v_pk_fma_f32 v[24:25], v[64:65], v[24:25], s[6:7] op_sel_hi:[1,1,0]
	s_mov_b64 s[12:13], s[68:69]
	v_pk_fma_f32 v[24:25], v[64:65], v[24:25], s[8:9] op_sel_hi:[1,1,0]
	s_mov_b64 s[68:69], s[10:11]
	v_pk_mul_f32 v[24:25], v[64:65], v[24:25]
	v_pk_mul_f32 v[24:25], v[80:81], v[24:25]
	v_mov_b32_e32 v80, v63
	v_pk_mul_f32 v[64:65], v[24:25], v[78:79]
	v_pk_fma_f32 v[24:25], v[24:25], v[78:79], v[78:79] neg_lo:[1,0,0] neg_hi:[1,0,0]
	v_mov_b32_e32 v81, v71
	v_cndmask_b32_e32 v79, v25, v65, vcc
	v_cmp_gt_f32_e32 vcc, 0, v78
	v_mov_b32_e32 v25, v76
	v_mov_b32_e32 v65, v70
	v_cndmask_b32_e32 v78, v24, v64, vcc
	v_mov_b32_e32 v24, v60
	v_mov_b32_e32 v64, v62
	v_pk_add_f32 v[24:25], v[24:25], v[64:65]
	v_mov_b32_e32 v64, v61
	v_add_f32_e32 v24, v24, v25
	v_mov_b32_e32 v65, v77
	s_nop 0
	v_add_f32_dpp v24, v24, v24 quad_perm:[1,0,3,2] row_mask:0xf bank_mask:0xf bound_ctrl:1
	v_pk_add_f32 v[64:65], v[64:65], v[80:81]
	v_mov_b32_e32 v80, v69
	v_add_f32_dpp v24, v24, v24 quad_perm:[2,3,0,1] row_mask:0xf bank_mask:0xf bound_ctrl:1
	v_mov_b32_e32 v81, v79
	s_nop 0
	v_add_f32_dpp v24, v24, v24 row_half_mirror row_mask:0xf bank_mask:0xf bound_ctrl:1
	s_nop 1
	v_add_f32_dpp v24, v24, v24 row_mirror row_mask:0xf bank_mask:0xf bound_ctrl:1
	s_nop 1
	v_add_f32_dpp v24, v24, v24 row_bcast:15 row_mask:0xa bank_mask:0xf
	s_nop 1
	v_add_f32_dpp v24, v24, v24 row_bcast:31 row_mask:0xc bank_mask:0xf
	v_add_f32_e32 v25, v64, v65
	v_readlane_b32 s6, v24, 63
	s_nop 0
	v_add_f32_dpp v25, v25, v25 quad_perm:[1,0,3,2] row_mask:0xf bank_mask:0xf bound_ctrl:1
	s_xor_b32 s6, s6, 0x80000000
	s_nop 0
	v_add_f32_dpp v25, v25, v25 quad_perm:[2,3,0,1] row_mask:0xf bank_mask:0xf bound_ctrl:1
	s_nop 1
	v_add_f32_dpp v25, v25, v25 row_half_mirror row_mask:0xf bank_mask:0xf bound_ctrl:1
	s_nop 1
	v_add_f32_dpp v25, v25, v25 row_mirror row_mask:0xf bank_mask:0xf bound_ctrl:1
	s_nop 1
	v_add_f32_dpp v25, v25, v25 row_bcast:15 row_mask:0xa bank_mask:0xf
	s_nop 1
	v_add_f32_dpp v25, v25, v25 row_bcast:31 row_mask:0xc bank_mask:0xf
	s_nop 0
	v_readlane_b32 s7, v25, 63
	s_xor_b32 s7, s7, 0x80000000
	s_nop 0
	v_pk_fma_f32 v[64:65], s[6:7], v[26:27], v[60:61] op_sel_hi:[1,0,1]
	v_pk_fma_f32 v[60:61], s[6:7], v[26:27], v[76:77] op_sel_hi:[1,0,1]
	v_pk_fma_f32 v[24:25], s[6:7], v[26:27], v[70:71] op_sel_hi:[1,0,1]
	v_mov_b32_e32 v70, v66
	v_mov_b32_e32 v71, v72
	v_mov_b32_e32 v76, v68
	v_mov_b32_e32 v77, v78
	v_pk_add_f32 v[70:71], v[70:71], v[76:77]
	v_mov_b32_e32 v76, v67
	v_add_f32_e32 v70, v70, v71
	v_mov_b32_e32 v77, v73
	s_nop 0
	v_add_f32_dpp v70, v70, v70 quad_perm:[1,0,3,2] row_mask:0xf bank_mask:0xf bound_ctrl:1
	v_pk_add_f32 v[76:77], v[76:77], v[80:81]
	v_pk_fma_f32 v[62:63], s[6:7], v[26:27], v[62:63] op_sel_hi:[1,0,1]
	v_add_f32_dpp v70, v70, v70 quad_perm:[2,3,0,1] row_mask:0xf bank_mask:0xf bound_ctrl:1
	s_nop 1
	v_add_f32_dpp v70, v70, v70 row_half_mirror row_mask:0xf bank_mask:0xf bound_ctrl:1
	s_nop 1
	v_add_f32_dpp v70, v70, v70 row_mirror row_mask:0xf bank_mask:0xf bound_ctrl:1
	s_nop 1
	v_add_f32_dpp v70, v70, v70 row_bcast:15 row_mask:0xa bank_mask:0xf
	s_nop 1
	v_add_f32_dpp v70, v70, v70 row_bcast:31 row_mask:0xc bank_mask:0xf
	v_add_f32_e32 v71, v76, v77
	v_readlane_b32 s6, v70, 63
	s_xor_b32 s6, s6, 0x80000000
	v_add_f32_dpp v71, v71, v71 quad_perm:[1,0,3,2] row_mask:0xf bank_mask:0xf bound_ctrl:1
	v_mov_b32_e32 v76, v20
	v_mov_b32_e32 v77, v16
	v_add_f32_dpp v71, v71, v71 quad_perm:[2,3,0,1] row_mask:0xf bank_mask:0xf bound_ctrl:1
	v_pk_mul_f32 v[76:77], v[76:77], v[76:77]
	s_nop 0
	v_add_f32_dpp v71, v71, v71 row_half_mirror row_mask:0xf bank_mask:0xf bound_ctrl:1
	s_nop 1
	v_add_f32_dpp v71, v71, v71 row_mirror row_mask:0xf bank_mask:0xf bound_ctrl:1
	s_nop 1
	v_mov_b32_dpp v75, v71 row_bcast:15 row_mask:0xa bank_mask:0xf
	v_add_f32_e32 v71, v71, v75
	v_mov_b32_e32 v75, v131
	s_nop 1
	v_mov_b32_dpp v75, v71 row_bcast:31 row_mask:0xc bank_mask:0xf
	v_add_f32_e32 v71, v71, v75
	s_nop 0
	v_readlane_b32 s7, v71, 63
	s_xor_b32 s7, s7, 0x80000000
	s_nop 0
	v_pk_fma_f32 v[70:71], s[6:7], v[26:27], v[66:67] op_sel_hi:[1,0,1]
	v_pk_fma_f32 v[66:67], s[6:7], v[26:27], v[72:73] op_sel_hi:[1,0,1]
	v_mov_b32_e32 v72, v22
	v_mov_b32_e32 v73, v18
	v_pk_fma_f32 v[72:73], v[72:73], v[72:73], v[76:77]
	v_pk_fma_f32 v[68:69], s[6:7], v[26:27], v[68:69] op_sel_hi:[1,0,1]
	v_add_f32_e32 v72, v72, v73
	v_pk_fma_f32 v[26:27], s[6:7], v[26:27], v[78:79] op_sel_hi:[1,0,1]
	s_nop 0
	v_add_f32_dpp v72, v72, v72 quad_perm:[1,0,3,2] row_mask:0xf bank_mask:0xf bound_ctrl:1
	s_lshl_b32 s6, s65, 5
	s_add_i32 s7, s5, s73
	v_add_f32_dpp v72, v72, v72 quad_perm:[2,3,0,1] row_mask:0xf bank_mask:0xf bound_ctrl:1
	s_mul_hi_i32 s8, s7, 0x5000
	s_mulk_i32 s7, 0x5000
	v_add_f32_dpp v72, v72, v72 row_half_mirror row_mask:0xf bank_mask:0xf bound_ctrl:1
	s_lshl_b32 s5, s5, 9
	s_add_i32 s9, s6, 0
	v_add_f32_dpp v72, v72, v72 row_mirror row_mask:0xf bank_mask:0xf bound_ctrl:1
	v_mov_b32_e32 v76, v21
	v_mov_b32_e32 v77, v17
	v_add_f32_dpp v72, v72, v72 row_bcast:15 row_mask:0xa bank_mask:0xf
	s_add_u32 s28, s34, s7
	v_pk_mul_f32 v[76:77], v[76:77], v[76:77]
	v_add_f32_dpp v72, v72, v72 row_bcast:31 row_mask:0xc bank_mask:0xf
	v_mov_b32_e32 v73, v19
	v_readlane_b32 s7, v72, 63
	v_mov_b32_e32 v72, v23
	v_pk_fma_f32 v[72:73], v[72:73], v[72:73], v[76:77]
	v_mov_b32_e32 v76, v14
	v_add_f32_e32 v72, v72, v73
	v_mov_b32_e32 v77, v8
	s_nop 0
	v_add_f32_dpp v72, v72, v72 quad_perm:[1,0,3,2] row_mask:0xf bank_mask:0xf bound_ctrl:1
	v_fma_f32 v79, s7, v235, v225
	v_pk_mul_f32 v[76:77], v[76:77], v[76:77]
	v_add_f32_dpp v72, v72, v72 quad_perm:[2,3,0,1] row_mask:0xf bank_mask:0xf bound_ctrl:1
	s_addc_u32 s29, s64, s8
	v_readlane_b32 s8, v253, 54
	v_add_f32_dpp v72, v72, v72 row_half_mirror row_mask:0xf bank_mask:0xf bound_ctrl:1
	v_mov_b32_e32 v75, s9
	s_add_i32 s5, s8, s5
	v_add_f32_dpp v72, v72, v72 row_mirror row_mask:0xf bank_mask:0xf bound_ctrl:1
	s_nop 1
	v_add_f32_dpp v72, v72, v72 row_bcast:15 row_mask:0xa bank_mask:0xf
	s_nop 1
	v_add_f32_dpp v72, v72, v72 row_bcast:31 row_mask:0xc bank_mask:0xf
	v_mov_b32_e32 v73, v12
	v_readlane_b32 s7, v72, 63
	v_mov_b32_e32 v72, v10
	v_pk_fma_f32 v[72:73], v[72:73], v[72:73], v[76:77]
	v_mov_b32_e32 v76, v15
	v_add_f32_e32 v72, v72, v73
	v_mov_b32_e32 v77, v9
	s_nop 0
	v_add_f32_dpp v72, v72, v72 quad_perm:[1,0,3,2] row_mask:0xf bank_mask:0xf bound_ctrl:1
	v_fma_f32 v81, s7, v235, v225
	v_pk_mul_f32 v[76:77], v[76:77], v[76:77]
	v_add_f32_dpp v72, v72, v72 quad_perm:[2,3,0,1] row_mask:0xf bank_mask:0xf bound_ctrl:1
	s_nop 1
	v_add_f32_dpp v72, v72, v72 row_half_mirror row_mask:0xf bank_mask:0xf bound_ctrl:1
	s_nop 1
	v_add_f32_dpp v72, v72, v72 row_mirror row_mask:0xf bank_mask:0xf bound_ctrl:1
	s_nop 1
	v_add_f32_dpp v72, v72, v72 row_bcast:15 row_mask:0xa bank_mask:0xf
	s_nop 1
	v_add_f32_dpp v72, v72, v72 row_bcast:31 row_mask:0xc bank_mask:0xf
	v_mov_b32_e32 v73, v13
	v_readlane_b32 s7, v72, 63
	v_mov_b32_e32 v72, v11
	v_pk_fma_f32 v[72:73], v[72:73], v[72:73], v[76:77]
	v_mov_b32_e32 v76, v40
	v_add_f32_e32 v72, v72, v73
	v_mov_b32_e32 v77, v36
	s_nop 0
	v_add_f32_dpp v72, v72, v72 quad_perm:[1,0,3,2] row_mask:0xf bank_mask:0xf bound_ctrl:1
	v_fma_f32 v83, s7, v235, v225
	v_pk_mul_f32 v[76:77], v[76:77], v[76:77]
	v_add_f32_dpp v72, v72, v72 quad_perm:[2,3,0,1] row_mask:0xf bank_mask:0xf bound_ctrl:1
	s_nop 1
	v_add_f32_dpp v72, v72, v72 row_half_mirror row_mask:0xf bank_mask:0xf bound_ctrl:1
	s_nop 1
	v_add_f32_dpp v72, v72, v72 row_mirror row_mask:0xf bank_mask:0xf bound_ctrl:1
	s_nop 1
	v_add_f32_dpp v72, v72, v72 row_bcast:15 row_mask:0xa bank_mask:0xf
	s_nop 1
	v_add_f32_dpp v72, v72, v72 row_bcast:31 row_mask:0xc bank_mask:0xf
	v_mov_b32_e32 v73, v38
	v_readlane_b32 s7, v72, 63
	v_mov_b32_e32 v72, v42
	v_pk_fma_f32 v[72:73], v[72:73], v[72:73], v[76:77]
	v_mov_b32_e32 v76, v41
	v_add_f32_e32 v72, v72, v73
	v_mov_b32_e32 v77, v37
	s_nop 0
	v_add_f32_dpp v72, v72, v72 quad_perm:[1,0,3,2] row_mask:0xf bank_mask:0xf bound_ctrl:1
	v_fma_f32 v85, s7, v235, v225
	v_pk_mul_f32 v[76:77], v[76:77], v[76:77]
	v_add_f32_dpp v72, v72, v72 quad_perm:[2,3,0,1] row_mask:0xf bank_mask:0xf bound_ctrl:1
	s_nop 1
	v_add_f32_dpp v72, v72, v72 row_half_mirror row_mask:0xf bank_mask:0xf bound_ctrl:1
	s_nop 1
	v_add_f32_dpp v72, v72, v72 row_mirror row_mask:0xf bank_mask:0xf bound_ctrl:1
	s_nop 1
	v_add_f32_dpp v72, v72, v72 row_bcast:15 row_mask:0xa bank_mask:0xf
	s_nop 1
	v_add_f32_dpp v72, v72, v72 row_bcast:31 row_mask:0xc bank_mask:0xf
	v_mov_b32_e32 v73, v39
	v_readlane_b32 s7, v72, 63
	v_mov_b32_e32 v72, v43
	v_pk_fma_f32 v[72:73], v[72:73], v[72:73], v[76:77]
	v_mov_b32_e32 v76, v32
	v_add_f32_e32 v72, v72, v73
	v_mov_b32_e32 v77, v28
	s_nop 0
	v_add_f32_dpp v72, v72, v72 quad_perm:[1,0,3,2] row_mask:0xf bank_mask:0xf bound_ctrl:1
	v_fma_f32 v87, s7, v235, v225
	v_pk_mul_f32 v[76:77], v[76:77], v[76:77]
	v_add_f32_dpp v72, v72, v72 quad_perm:[2,3,0,1] row_mask:0xf bank_mask:0xf bound_ctrl:1
	s_nop 1
	v_add_f32_dpp v72, v72, v72 row_half_mirror row_mask:0xf bank_mask:0xf bound_ctrl:1
	s_nop 1
	v_add_f32_dpp v72, v72, v72 row_mirror row_mask:0xf bank_mask:0xf bound_ctrl:1
	s_nop 1
	v_add_f32_dpp v72, v72, v72 row_bcast:15 row_mask:0xa bank_mask:0xf
	s_nop 1
	v_add_f32_dpp v72, v72, v72 row_bcast:31 row_mask:0xc bank_mask:0xf
	v_mov_b32_e32 v73, v30
	v_readlane_b32 s7, v72, 63
	v_mov_b32_e32 v72, v34
	v_pk_fma_f32 v[72:73], v[72:73], v[72:73], v[76:77]
	v_mov_b32_e32 v76, v33
	v_add_f32_e32 v72, v72, v73
	v_mov_b32_e32 v77, v29
	s_nop 0
	v_add_f32_dpp v72, v72, v72 quad_perm:[1,0,3,2] row_mask:0xf bank_mask:0xf bound_ctrl:1
	v_fma_f32 v88, s7, v235, v225
	v_pk_mul_f32 v[76:77], v[76:77], v[76:77]
	v_add_f32_dpp v72, v72, v72 quad_perm:[2,3,0,1] row_mask:0xf bank_mask:0xf bound_ctrl:1
	s_nop 1
	v_add_f32_dpp v72, v72, v72 row_half_mirror row_mask:0xf bank_mask:0xf bound_ctrl:1
	s_nop 1
	v_add_f32_dpp v72, v72, v72 row_mirror row_mask:0xf bank_mask:0xf bound_ctrl:1
	s_nop 1
	v_add_f32_dpp v72, v72, v72 row_bcast:15 row_mask:0xa bank_mask:0xf
	s_nop 1
	v_add_f32_dpp v72, v72, v72 row_bcast:31 row_mask:0xc bank_mask:0xf
	v_mov_b32_e32 v73, v31
	v_readlane_b32 s7, v72, 63
	v_mov_b32_e32 v72, v35
	v_pk_fma_f32 v[72:73], v[72:73], v[72:73], v[76:77]
	v_mov_b32_e32 v76, v56
	v_add_f32_e32 v72, v72, v73
	v_mov_b32_e32 v77, v52
	s_nop 0
	v_add_f32_dpp v72, v72, v72 quad_perm:[1,0,3,2] row_mask:0xf bank_mask:0xf bound_ctrl:1
	v_fma_f32 v89, s7, v235, v225
	v_pk_mul_f32 v[76:77], v[76:77], v[76:77]
	v_add_f32_dpp v72, v72, v72 quad_perm:[2,3,0,1] row_mask:0xf bank_mask:0xf bound_ctrl:1
	s_nop 1
	v_add_f32_dpp v72, v72, v72 row_half_mirror row_mask:0xf bank_mask:0xf bound_ctrl:1
	s_nop 1
	v_add_f32_dpp v72, v72, v72 row_mirror row_mask:0xf bank_mask:0xf bound_ctrl:1
	s_nop 1
	v_add_f32_dpp v72, v72, v72 row_bcast:15 row_mask:0xa bank_mask:0xf
	s_nop 1
	v_add_f32_dpp v72, v72, v72 row_bcast:31 row_mask:0xc bank_mask:0xf
	v_mov_b32_e32 v73, v54
	v_readlane_b32 s7, v72, 63
	v_mov_b32_e32 v72, v58
	v_pk_fma_f32 v[72:73], v[72:73], v[72:73], v[76:77]
	v_mov_b32_e32 v76, v57
	v_add_f32_e32 v72, v72, v73
	v_mov_b32_e32 v77, v53
	s_nop 0
	v_add_f32_dpp v72, v72, v72 quad_perm:[1,0,3,2] row_mask:0xf bank_mask:0xf bound_ctrl:1
	v_fma_f32 v90, s7, v235, v225
	v_pk_mul_f32 v[76:77], v[76:77], v[76:77]
	v_add_f32_dpp v72, v72, v72 quad_perm:[2,3,0,1] row_mask:0xf bank_mask:0xf bound_ctrl:1
	s_nop 1
	v_add_f32_dpp v72, v72, v72 row_half_mirror row_mask:0xf bank_mask:0xf bound_ctrl:1
	s_nop 1
	v_add_f32_dpp v72, v72, v72 row_mirror row_mask:0xf bank_mask:0xf bound_ctrl:1
	s_nop 1
	v_add_f32_dpp v72, v72, v72 row_bcast:15 row_mask:0xa bank_mask:0xf
	s_nop 1
	v_add_f32_dpp v72, v72, v72 row_bcast:31 row_mask:0xc bank_mask:0xf
	v_mov_b32_e32 v73, v55
	v_readlane_b32 s7, v72, 63
	v_mov_b32_e32 v72, v59
	v_pk_fma_f32 v[72:73], v[72:73], v[72:73], v[76:77]
	v_mov_b32_e32 v76, v50
	v_add_f32_e32 v72, v72, v73
	v_mov_b32_e32 v77, v44
	s_nop 0
	v_add_f32_dpp v72, v72, v72 quad_perm:[1,0,3,2] row_mask:0xf bank_mask:0xf bound_ctrl:1
	v_fma_f32 v92, s7, v235, v225
	v_pk_mul_f32 v[76:77], v[76:77], v[76:77]
	v_add_f32_dpp v72, v72, v72 quad_perm:[2,3,0,1] row_mask:0xf bank_mask:0xf bound_ctrl:1
	s_nop 1
	v_add_f32_dpp v72, v72, v72 row_half_mirror row_mask:0xf bank_mask:0xf bound_ctrl:1
	s_nop 1
	v_add_f32_dpp v72, v72, v72 row_mirror row_mask:0xf bank_mask:0xf bound_ctrl:1
	s_nop 1
	v_add_f32_dpp v72, v72, v72 row_bcast:15 row_mask:0xa bank_mask:0xf
	s_nop 1
	v_add_f32_dpp v72, v72, v72 row_bcast:31 row_mask:0xc bank_mask:0xf
	v_mov_b32_e32 v73, v48
	v_readlane_b32 s7, v72, 63
	v_mov_b32_e32 v72, v46
	v_pk_fma_f32 v[72:73], v[72:73], v[72:73], v[76:77]
	v_mov_b32_e32 v76, v51
	v_add_f32_e32 v72, v72, v73
	v_mov_b32_e32 v77, v45
	s_nop 0
	v_add_f32_dpp v72, v72, v72 quad_perm:[1,0,3,2] row_mask:0xf bank_mask:0xf bound_ctrl:1
	v_fma_f32 v93, s7, v235, v225
	v_pk_mul_f32 v[76:77], v[76:77], v[76:77]
	v_add_f32_dpp v72, v72, v72 quad_perm:[2,3,0,1] row_mask:0xf bank_mask:0xf bound_ctrl:1
	s_nop 1
	v_add_f32_dpp v72, v72, v72 row_half_mirror row_mask:0xf bank_mask:0xf bound_ctrl:1
	s_nop 1
	v_add_f32_dpp v72, v72, v72 row_mirror row_mask:0xf bank_mask:0xf bound_ctrl:1
	s_nop 1
	v_add_f32_dpp v72, v72, v72 row_bcast:15 row_mask:0xa bank_mask:0xf
	s_nop 1
	v_add_f32_dpp v72, v72, v72 row_bcast:31 row_mask:0xc bank_mask:0xf
	v_mov_b32_e32 v73, v49
	v_readlane_b32 s7, v72, 63
	v_mov_b32_e32 v72, v47
	v_pk_fma_f32 v[72:73], v[72:73], v[72:73], v[76:77]
	v_mov_b32_e32 v76, v68
	v_add_f32_e32 v72, v72, v73
	v_mov_b32_e32 v77, v26
	s_nop 0
	v_add_f32_dpp v72, v72, v72 quad_perm:[1,0,3,2] row_mask:0xf bank_mask:0xf bound_ctrl:1
	v_fma_f32 v94, s7, v235, v225
	v_pk_mul_f32 v[76:77], v[76:77], v[76:77]
	v_add_f32_dpp v72, v72, v72 quad_perm:[2,3,0,1] row_mask:0xf bank_mask:0xf bound_ctrl:1
	s_nop 1
	v_add_f32_dpp v72, v72, v72 row_half_mirror row_mask:0xf bank_mask:0xf bound_ctrl:1
	s_nop 1
	v_add_f32_dpp v72, v72, v72 row_mirror row_mask:0xf bank_mask:0xf bound_ctrl:1
	s_nop 1
	v_add_f32_dpp v72, v72, v72 row_bcast:15 row_mask:0xa bank_mask:0xf
	s_nop 1
	v_add_f32_dpp v72, v72, v72 row_bcast:31 row_mask:0xc bank_mask:0xf
	v_mov_b32_e32 v73, v66
	v_readlane_b32 s7, v72, 63
	v_mov_b32_e32 v72, v70
	v_pk_fma_f32 v[72:73], v[72:73], v[72:73], v[76:77]
	v_mov_b32_e32 v76, v69
	v_add_f32_e32 v72, v72, v73
	v_mov_b32_e32 v77, v27
	s_nop 0
	v_add_f32_dpp v72, v72, v72 quad_perm:[1,0,3,2] row_mask:0xf bank_mask:0xf bound_ctrl:1
	v_fma_f32 v95, s7, v235, v225
	v_pk_mul_f32 v[76:77], v[76:77], v[76:77]
	v_add_f32_dpp v72, v72, v72 quad_perm:[2,3,0,1] row_mask:0xf bank_mask:0xf bound_ctrl:1
	s_nop 1
	v_add_f32_dpp v72, v72, v72 row_half_mirror row_mask:0xf bank_mask:0xf bound_ctrl:1
	s_nop 1
	v_add_f32_dpp v72, v72, v72 row_mirror row_mask:0xf bank_mask:0xf bound_ctrl:1
	s_nop 1
	v_add_f32_dpp v72, v72, v72 row_bcast:15 row_mask:0xa bank_mask:0xf
	s_nop 1
	v_add_f32_dpp v72, v72, v72 row_bcast:31 row_mask:0xc bank_mask:0xf
	v_mov_b32_e32 v73, v67
	v_readlane_b32 s7, v72, 63
	v_mov_b32_e32 v72, v71
	v_pk_fma_f32 v[72:73], v[72:73], v[72:73], v[76:77]
	v_mov_b32_e32 v76, v62
	v_add_f32_e32 v72, v72, v73
	v_mov_b32_e32 v77, v24
	s_nop 0
	v_add_f32_dpp v72, v72, v72 quad_perm:[1,0,3,2] row_mask:0xf bank_mask:0xf bound_ctrl:1
	v_fma_f32 v96, s7, v235, v225
	v_pk_mul_f32 v[76:77], v[76:77], v[76:77]
	v_add_f32_dpp v72, v72, v72 quad_perm:[2,3,0,1] row_mask:0xf bank_mask:0xf bound_ctrl:1
	s_nop 1
	v_add_f32_dpp v72, v72, v72 row_half_mirror row_mask:0xf bank_mask:0xf bound_ctrl:1
	s_nop 1
	v_add_f32_dpp v72, v72, v72 row_mirror row_mask:0xf bank_mask:0xf bound_ctrl:1
	s_nop 1
	v_add_f32_dpp v72, v72, v72 row_bcast:15 row_mask:0xa bank_mask:0xf
	s_nop 1
	v_add_f32_dpp v72, v72, v72 row_bcast:31 row_mask:0xc bank_mask:0xf
	v_mov_b32_e32 v73, v60
	v_readlane_b32 s7, v72, 63
	v_mov_b32_e32 v72, v64
	v_pk_fma_f32 v[72:73], v[72:73], v[72:73], v[76:77]
	v_mov_b32_e32 v76, v63
	v_add_f32_e32 v72, v72, v73
	v_mov_b32_e32 v77, v25
	s_nop 0
	v_add_f32_dpp v72, v72, v72 quad_perm:[1,0,3,2] row_mask:0xf bank_mask:0xf bound_ctrl:1
	v_fma_f32 v97, s7, v235, v225
	v_pk_mul_f32 v[76:77], v[76:77], v[76:77]
	v_add_f32_dpp v72, v72, v72 quad_perm:[2,3,0,1] row_mask:0xf bank_mask:0xf bound_ctrl:1
	s_nop 1
	v_add_f32_dpp v72, v72, v72 row_half_mirror row_mask:0xf bank_mask:0xf bound_ctrl:1
	s_nop 1
	v_add_f32_dpp v72, v72, v72 row_mirror row_mask:0xf bank_mask:0xf bound_ctrl:1
	s_nop 1
	v_add_f32_dpp v72, v72, v72 row_bcast:15 row_mask:0xa bank_mask:0xf
	s_nop 1
	v_add_f32_dpp v72, v72, v72 row_bcast:31 row_mask:0xc bank_mask:0xf
	v_mov_b32_e32 v73, v61
	v_readlane_b32 s7, v72, 63
	v_mov_b32_e32 v72, v65
	v_pk_fma_f32 v[72:73], v[72:73], v[72:73], v[76:77]
	v_fma_f32 v98, s7, v235, v225
	v_add_f32_e32 v72, v72, v73
	v_lshl_add_u32 v77, v1, 2, s8
	s_nop 0
	v_add_f32_dpp v72, v72, v72 quad_perm:[1,0,3,2] row_mask:0xf bank_mask:0xf bound_ctrl:1
	s_nop 1
	v_add_f32_dpp v72, v72, v72 quad_perm:[2,3,0,1] row_mask:0xf bank_mask:0xf bound_ctrl:1
	s_nop 1
	v_add_f32_dpp v72, v72, v72 row_half_mirror row_mask:0xf bank_mask:0xf bound_ctrl:1
	s_nop 1
	v_add_f32_dpp v72, v72, v72 row_mirror row_mask:0xf bank_mask:0xf bound_ctrl:1
	s_nop 1
	v_add_f32_dpp v72, v72, v72 row_bcast:15 row_mask:0xa bank_mask:0xf
	s_nop 1
	v_add_f32_dpp v72, v72, v72 row_bcast:31 row_mask:0xc bank_mask:0xf
	s_nop 0
	v_readlane_b32 s7, v72, 63
	global_load_dword v7, v[6:7], off
	s_nop 0
	global_load_dword v6, v[4:5], off
	global_load_dword v72, v[2:3], off
	global_load_dword v76, v[2:3], off offset:256
	global_load_dword v78, v[4:5], off offset:256
	global_load_dword v80, v[4:5], off offset:512
	global_load_dword v82, v[2:3], off offset:512
	global_load_dword v84, v[2:3], off offset:768
	global_load_dword v86, v[4:5], off offset:768
	v_rsq_f32_e32 v2, v79
	v_rsq_f32_e32 v3, v81
	v_rsq_f32_e32 v4, v83
	v_rsq_f32_e32 v5, v85
	v_fma_f32 v73, s7, v235, v225
	v_pk_mul_f32 v[22:23], v[22:23], v[2:3]
	v_pk_mul_f32 v[20:21], v[20:21], v[2:3]
	v_pk_mul_f32 v[10:11], v[10:11], v[4:5]
	v_pk_mul_f32 v[14:15], v[14:15], v[4:5]
	v_pk_mul_f32 v[18:19], v[18:19], v[2:3]
	v_pk_mul_f32 v[12:13], v[12:13], v[4:5]
	v_pk_mul_f32 v[2:3], v[16:17], v[2:3]
	v_pk_mul_f32 v[4:5], v[8:9], v[4:5]
	v_rsq_f32_e32 v8, v87
	v_rsq_f32_e32 v9, v88
	v_rsq_f32_e32 v16, v89
	v_rsq_f32_e32 v17, v90
	s_waitcnt vmcnt(8)
	ds_write_b32 v77, v7
	v_mad_u32_u24 v7, v74, s40, v75
	s_waitcnt vmcnt(6)
	v_pk_fma_f32 v[10:11], v[72:73], v[10:11], v[6:7] op_sel_hi:[0,1,0]
	v_pk_fma_f32 v[22:23], v[72:73], v[22:23], v[6:7] op_sel_hi:[0,1,0]
	s_waitcnt vmcnt(4)
	v_pk_fma_f32 v[14:15], v[76:77], v[14:15], v[78:79] op_sel_hi:[0,1,0]
	v_pk_fma_f32 v[20:21], v[76:77], v[20:21], v[78:79] op_sel_hi:[0,1,0]
	s_waitcnt vmcnt(2)
	v_pk_fma_f32 v[12:13], v[82:83], v[12:13], v[80:81] op_sel_hi:[0,1,0]
	v_pk_fma_f32 v[18:19], v[82:83], v[18:19], v[80:81] op_sel_hi:[0,1,0]
	s_waitcnt vmcnt(0)
	v_pk_fma_f32 v[88:89], v[84:85], v[4:5], v[86:87] op_sel_hi:[0,1,0]
	v_pk_fma_f32 v[90:91], v[84:85], v[2:3], v[86:87] op_sel_hi:[0,1,0]
	v_pk_mul_f32 v[2:3], v[42:43], v[8:9]
	v_pk_mul_f32 v[4:5], v[34:35], v[16:17]
	v_pk_fma_f32 v[2:3], v[72:73], v[2:3], v[6:7] op_sel_hi:[0,1,0]
	v_pk_fma_f32 v[4:5], v[72:73], v[4:5], v[6:7] op_sel_hi:[0,1,0]
	v_cvt_pk_bf16_f32 v5, v4, v5
	v_cvt_pk_bf16_f32 v4, v2, v3
	v_cvt_pk_bf16_f32 v3, v10, v11
	v_cvt_pk_bf16_f32 v2, v22, v23
	ds_write_b128 v7, v[2:5]
	v_pk_mul_f32 v[2:3], v[40:41], v[8:9]
	v_pk_mul_f32 v[4:5], v[32:33], v[16:17]
	v_pk_fma_f32 v[2:3], v[76:77], v[2:3], v[78:79] op_sel_hi:[0,1,0]
	v_pk_fma_f32 v[4:5], v[76:77], v[4:5], v[78:79] op_sel_hi:[0,1,0]
	v_cvt_pk_bf16_f32 v5, v4, v5
	v_cvt_pk_bf16_f32 v4, v2, v3
	v_cvt_pk_bf16_f32 v3, v14, v15
	v_cvt_pk_bf16_f32 v2, v20, v21
	ds_write_b128 v7, v[2:5] offset:17408
	v_pk_mul_f32 v[2:3], v[38:39], v[8:9]
	v_pk_mul_f32 v[4:5], v[30:31], v[16:17]
	v_pk_fma_f32 v[2:3], v[82:83], v[2:3], v[80:81] op_sel_hi:[0,1,0]
	v_pk_fma_f32 v[4:5], v[82:83], v[4:5], v[80:81] op_sel_hi:[0,1,0]
	v_cvt_pk_bf16_f32 v5, v4, v5
	v_cvt_pk_bf16_f32 v4, v2, v3
	v_cvt_pk_bf16_f32 v3, v12, v13
	v_cvt_pk_bf16_f32 v2, v18, v19
	ds_write_b128 v7, v[2:5] offset:34816
	v_pk_mul_f32 v[2:3], v[36:37], v[8:9]
	v_rsq_f32_e32 v8, v92
	v_rsq_f32_e32 v9, v93
	v_rsq_f32_e32 v10, v94
	v_rsq_f32_e32 v11, v95
	v_pk_mul_f32 v[4:5], v[28:29], v[16:17]
	v_pk_fma_f32 v[2:3], v[84:85], v[2:3], v[86:87] op_sel_hi:[0,1,0]
	v_pk_fma_f32 v[4:5], v[84:85], v[4:5], v[86:87] op_sel_hi:[0,1,0]
	v_cvt_pk_bf16_f32 v5, v4, v5
	v_cvt_pk_bf16_f32 v4, v2, v3
	v_cvt_pk_bf16_f32 v3, v88, v89
	v_cvt_pk_bf16_f32 v2, v90, v91
	ds_write_b128 v7, v[2:5] offset:52224
	v_pk_mul_f32 v[2:3], v[58:59], v[8:9]
	v_pk_mul_f32 v[4:5], v[46:47], v[10:11]
	v_pk_fma_f32 v[14:15], v[72:73], v[2:3], v[6:7] op_sel_hi:[0,1,0]
	v_pk_fma_f32 v[12:13], v[72:73], v[4:5], v[6:7] op_sel_hi:[0,1,0]
	v_pk_mul_f32 v[2:3], v[56:57], v[8:9]
	v_pk_mul_f32 v[4:5], v[50:51], v[10:11]
	v_pk_fma_f32 v[18:19], v[76:77], v[2:3], v[78:79] op_sel_hi:[0,1,0]
	v_pk_fma_f32 v[16:17], v[76:77], v[4:5], v[78:79] op_sel_hi:[0,1,0]
	v_pk_mul_f32 v[2:3], v[54:55], v[8:9]
	v_pk_mul_f32 v[4:5], v[48:49], v[10:11]
	v_pk_fma_f32 v[22:23], v[82:83], v[2:3], v[80:81] op_sel_hi:[0,1,0]
	v_pk_fma_f32 v[20:21], v[82:83], v[4:5], v[80:81] op_sel_hi:[0,1,0]
	v_pk_mul_f32 v[2:3], v[52:53], v[8:9]
	v_pk_mul_f32 v[4:5], v[44:45], v[10:11]
	v_rsq_f32_e32 v8, v96
	v_rsq_f32_e32 v9, v97
	v_rsq_f32_e32 v10, v98
	v_rsq_f32_e32 v11, v73
	v_pk_fma_f32 v[28:29], v[84:85], v[4:5], v[86:87] op_sel_hi:[0,1,0]
	v_pk_fma_f32 v[30:31], v[84:85], v[2:3], v[86:87] op_sel_hi:[0,1,0]
	v_pk_mul_f32 v[2:3], v[70:71], v[8:9]
	v_pk_mul_f32 v[4:5], v[64:65], v[10:11]
	v_pk_fma_f32 v[2:3], v[72:73], v[2:3], v[6:7] op_sel_hi:[0,1,0]
	v_pk_fma_f32 v[4:5], v[72:73], v[4:5], v[6:7] op_sel_hi:[0,1,0]
	v_cvt_pk_bf16_f32 v5, v4, v5
	v_cvt_pk_bf16_f32 v4, v2, v3
	v_cvt_pk_bf16_f32 v3, v12, v13
	v_cvt_pk_bf16_f32 v2, v14, v15
	ds_write_b128 v7, v[2:5] offset:16
	v_pk_mul_f32 v[2:3], v[68:69], v[8:9]
	v_pk_mul_f32 v[4:5], v[62:63], v[10:11]
	v_pk_fma_f32 v[2:3], v[76:77], v[2:3], v[78:79] op_sel_hi:[0,1,0]
	v_pk_fma_f32 v[4:5], v[76:77], v[4:5], v[78:79] op_sel_hi:[0,1,0]
	v_cvt_pk_bf16_f32 v5, v4, v5
	v_cvt_pk_bf16_f32 v4, v2, v3
	v_cvt_pk_bf16_f32 v3, v16, v17
	v_cvt_pk_bf16_f32 v2, v18, v19
	ds_write_b128 v7, v[2:5] offset:17424
	v_pk_mul_f32 v[2:3], v[66:67], v[8:9]
	v_pk_mul_f32 v[4:5], v[60:61], v[10:11]
	v_pk_fma_f32 v[2:3], v[82:83], v[2:3], v[80:81] op_sel_hi:[0,1,0]
	v_pk_fma_f32 v[4:5], v[82:83], v[4:5], v[80:81] op_sel_hi:[0,1,0]
	v_cvt_pk_bf16_f32 v5, v4, v5
	v_cvt_pk_bf16_f32 v4, v2, v3
	v_cvt_pk_bf16_f32 v3, v20, v21
	v_cvt_pk_bf16_f32 v2, v22, v23
	ds_write_b128 v7, v[2:5] offset:34832
	v_pk_mul_f32 v[2:3], v[26:27], v[8:9]
	v_pk_mul_f32 v[4:5], v[24:25], v[10:11]
	v_pk_fma_f32 v[2:3], v[84:85], v[2:3], v[86:87] op_sel_hi:[0,1,0]
	v_pk_fma_f32 v[4:5], v[84:85], v[4:5], v[86:87] op_sel_hi:[0,1,0]
	v_cvt_pk_bf16_f32 v5, v4, v5
	v_cvt_pk_bf16_f32 v4, v2, v3
	v_cvt_pk_bf16_f32 v3, v28, v29
	v_cvt_pk_bf16_f32 v2, v30, v31
	v_lshl_add_u64 v[8:9], s[28:29], 0, v[130:131]
	v_and_or_b32 v6, v1, 31, s6
	v_bfe_u32 v73, v1, 5, 1
	ds_write_b128 v7, v[2:5] offset:52240
	v_add_co_u32_e32 v70, vcc, s90, v8
	v_lshlrev_b32_e32 v1, 2, v73
	v_ashrrev_i32_e32 v7, 31, v6
	v_addc_co_u32_e32 v71, vcc, 0, v9, vcc
	v_or_b32_e32 v72, s66, v1
	v_lshlrev_b64 v[74:75], 1, v[6:7]
	v_add_co_u32_e32 v82, vcc, s46, v8
	v_lshl_add_u64 v[26:27], s[80:81], 0, v[74:75]
	v_mul_lo_u32 v10, v72, s87
	v_mov_b32_e32 v11, v131
	v_addc_co_u32_e32 v83, vcc, 0, v9, vcc
	v_lshl_add_u64 v[10:11], v[26:27], 0, v[10:11]
	v_add_co_u32_e32 v94, vcc, s90, v10
	s_mov_b32 s6, 0xc000
	s_nop 0
	v_addc_co_u32_e32 v95, vcc, 0, v11, vcc
	v_add_co_u32_e32 v28, vcc, s41, v10
	v_or_b32_e32 v7, s33, v1
	s_nop 0
	v_addc_co_u32_e32 v29, vcc, 0, v11, vcc
	v_add_co_u32_e32 v76, vcc, s97, v10
	s_waitcnt lgkmcnt(0)
	s_nop 0
	v_addc_co_u32_e32 v77, vcc, 0, v11, vcc
	v_add_co_u32_e32 v78, vcc, s6, v10
	s_mov_b32 s6, 0xd000
	s_nop 0
	v_addc_co_u32_e32 v79, vcc, 0, v11, vcc
	v_add_co_u32_e32 v80, vcc, s6, v10
	s_mov_b32 s6, 0xf000
	s_nop 0
	v_addc_co_u32_e32 v81, vcc, 0, v11, vcc
	v_add_co_u32_e32 v84, vcc, s6, v10
	s_mov_b32 s6, 0x10000
	s_nop 0
	v_addc_co_u32_e32 v85, vcc, 0, v11, vcc
	v_add_co_u32_e32 v86, vcc, s6, v10
	s_mov_b32 s6, 0x18000
	s_nop 0
	v_addc_co_u32_e32 v87, vcc, 0, v11, vcc
	v_add_co_u32_e32 v88, vcc, s6, v10
	s_mov_b32 s6, 0x19000
	s_nop 0
	v_addc_co_u32_e32 v89, vcc, 0, v11, vcc
	v_add_co_u32_e32 v90, vcc, s6, v10
	s_mov_b32 s6, 0x1b000
	s_nop 0
	v_addc_co_u32_e32 v91, vcc, 0, v11, vcc
	v_add_co_u32_e32 v92, vcc, s6, v10
	s_mov_b32 s6, 0x1c000
	s_nop 0
	v_addc_co_u32_e32 v93, vcc, 0, v11, vcc
	v_add_co_u32_e32 v54, vcc, s6, v10
	s_mov_b32 s6, 0x24000
	s_nop 0
	v_addc_co_u32_e32 v55, vcc, 0, v11, vcc
	v_add_co_u32_e32 v56, vcc, s6, v10
	s_mov_b32 s6, 0x25000
	s_nop 0
	v_addc_co_u32_e32 v57, vcc, 0, v11, vcc
	v_add_co_u32_e32 v58, vcc, s6, v10
	s_mov_b32 s6, 0x27000
	s_nop 0
	v_addc_co_u32_e32 v59, vcc, 0, v11, vcc
	v_add_co_u32_e32 v60, vcc, s6, v10
	s_mov_b32 s6, 0x28000
	s_nop 0
	v_addc_co_u32_e32 v61, vcc, 0, v11, vcc
	v_add_co_u32_e32 v62, vcc, s6, v10
	v_mul_lo_u32 v10, v7, s87
	s_nop 0
	v_addc_co_u32_e32 v63, vcc, 0, v11, vcc
	v_mov_b32_e32 v11, v131
	v_lshl_add_u64 v[10:11], v[26:27], 0, v[10:11]
	s_mov_b32 s6, 0x6030000
	v_add_co_u32_e32 v64, vcc, s6, v10
	s_mov_b32 s6, 0x6031000
	s_nop 0
	v_addc_co_u32_e32 v65, vcc, 0, v11, vcc
	v_add_co_u32_e32 v66, vcc, s6, v10
	s_mov_b32 s6, 0x6033000
	s_nop 0
	v_addc_co_u32_e32 v67, vcc, 0, v11, vcc
	v_add_co_u32_e32 v68, vcc, s6, v10
	s_mov_b32 s6, 0x6034000
	s_nop 0
	v_addc_co_u32_e32 v69, vcc, 0, v11, vcc
	v_add_co_u32_e32 v38, vcc, s6, v10
	s_mov_b32 s6, 0x603c000
	s_nop 0
	v_addc_co_u32_e32 v39, vcc, 0, v11, vcc
	v_add_co_u32_e32 v40, vcc, s6, v10
	s_mov_b32 s6, 0x603d000
	s_nop 0
	v_addc_co_u32_e32 v41, vcc, 0, v11, vcc
	v_add_co_u32_e32 v42, vcc, s6, v10
	s_mov_b32 s6, 0x603f000
	s_nop 0
	v_addc_co_u32_e32 v43, vcc, 0, v11, vcc
	v_add_co_u32_e32 v44, vcc, s6, v10
	s_mov_b32 s6, 0x6040000
	s_nop 0
	v_addc_co_u32_e32 v45, vcc, 0, v11, vcc
	v_add_co_u32_e32 v46, vcc, s6, v10
	s_mov_b32 s6, 0x6048000
	s_nop 0
	v_addc_co_u32_e32 v47, vcc, 0, v11, vcc
	v_add_co_u32_e32 v48, vcc, s6, v10
	s_mov_b32 s6, 0x6049000
	s_nop 0
	v_addc_co_u32_e32 v49, vcc, 0, v11, vcc
	v_add_co_u32_e32 v50, vcc, s6, v10
	s_mov_b32 s6, 0x604b000
	s_nop 0
	v_addc_co_u32_e32 v51, vcc, 0, v11, vcc
	v_add_co_u32_e32 v52, vcc, s6, v10
	s_mov_b32 s6, 0x604c000
	s_nop 0
	v_addc_co_u32_e32 v53, vcc, 0, v11, vcc
	v_add_co_u32_e32 v12, vcc, s6, v10
	s_mov_b32 s6, 0x6054000
	s_nop 0
	v_addc_co_u32_e32 v13, vcc, 0, v11, vcc
	v_add_co_u32_e32 v14, vcc, s6, v10
	s_mov_b32 s6, 0x6055000
	s_nop 0
	v_addc_co_u32_e32 v15, vcc, 0, v11, vcc
	v_add_co_u32_e32 v16, vcc, s6, v10
	s_mov_b32 s6, 0x6057000
	s_nop 0
	v_addc_co_u32_e32 v17, vcc, 0, v11, vcc
	v_add_co_u32_e32 v34, vcc, s6, v10
	s_mov_b32 s6, 0x6058000
	s_nop 0
	v_addc_co_u32_e32 v35, vcc, 0, v11, vcc
	v_add_co_u32_e32 v36, vcc, s6, v10
	v_mad_u64_u32 v[26:27], s[6:7], v72, s87, v[26:27]
	s_barrier
	global_load_dwordx4 v[2:5], v130, s[28:29]
	global_load_dwordx4 v[30:33], v130, s[28:29] offset:1024
	global_load_dwordx4 v[22:25], v130, s[28:29] offset:2048
	global_load_dwordx4 v[18:21], v130, s[28:29] offset:3072
	global_load_ushort v96, v[26:27], off
	global_load_ushort v7, v[28:29], off
	s_nop 0
	global_load_dwordx4 v[26:29], v[70:71], off offset:1024
	v_addc_co_u32_e32 v37, vcc, 0, v11, vcc
	global_load_ushort v94, v[94:95], off offset:2048
	s_mov_b32 s6, 0x6060000
	v_mul_lo_u32 v6, v6, s40
	s_waitcnt vmcnt(3)
	v_lshlrev_b32_e32 v96, 16, v96
	v_fma_f32 v97, |v96|, s92, 1.0
	v_rcp_f32_e32 v97, v97
	v_mul_f32_e32 v99, v96, v96
	v_mul_f32_e32 v99, 0xbf38aa3b, v99
	v_exp_f32_e32 v99, v99
	v_fmamk_f32 v98, v97, 0x3f07dc22, v236
	v_fmaak_f32 v98, v97, v98, 0x3f35f0e3
	v_fmaak_f32 v98, v97, v98, 0xbe11a98e
	s_waitcnt vmcnt(0)
	v_lshlrev_b32_e32 v94, 16, v94
	v_fmaak_f32 v98, v97, v98, 0x3e027906
	v_fma_f32 v95, |v94|, s92, 1.0
	v_mul_f32_e32 v97, v97, v98
	v_rcp_f32_e32 v95, v95
	v_mul_f32_e32 v97, v99, v97
	v_mul_f32_e32 v98, v97, v96
	v_fma_f32 v97, -v97, v96, v96
	v_cmp_gt_f32_e32 vcc, 0, v96
	v_fmamk_f32 v96, v95, 0x3f07dc22, v236
	v_fmaak_f32 v96, v95, v96, 0x3f35f0e3
	v_cndmask_b32_e32 v130, v97, v98, vcc
	v_mul_f32_e32 v97, v94, v94
	v_mul_f32_e32 v97, 0xbf38aa3b, v97
	v_exp_f32_e32 v97, v97
	v_fmaak_f32 v96, v95, v96, 0xbe11a98e
	v_fmaak_f32 v96, v95, v96, 0x3e027906
	v_mul_f32_e32 v95, v95, v96
	v_mul_f32_e32 v95, v97, v95
	v_lshlrev_b32_e32 v7, 16, v7
	v_mul_f32_e32 v96, v95, v94
	v_fma_f32 v95, -v95, v94, v94
	v_cmp_gt_f32_e32 vcc, 0, v94
	v_fma_f32 v94, |v7|, s92, 1.0
	v_rcp_f32_e32 v94, v94
	v_cndmask_b32_e32 v167, v95, v96, vcc
	v_mul_f32_e32 v96, v7, v7
	v_mul_f32_e32 v96, 0xbf38aa3b, v96
	v_fmamk_f32 v95, v94, 0x3f07dc22, v236
	v_fmaak_f32 v95, v94, v95, 0x3f35f0e3
	v_exp_f32_e32 v96, v96
	v_fmaak_f32 v95, v94, v95, 0xbe11a98e
	v_fmaak_f32 v95, v94, v95, 0x3e027906
	v_mul_f32_e32 v94, v94, v95
	v_mul_f32_e32 v94, v96, v94
	v_mul_f32_e32 v95, v94, v7
	v_fma_f32 v94, -v94, v7, v7
	v_cmp_gt_f32_e32 vcc, 0, v7
	global_load_ushort v7, v[76:77], off offset:2048
	s_nop 0
	global_load_ushort v76, v[78:79], off
	global_load_ushort v77, v[80:81], off offset:2048
	s_nop 0
	global_load_ushort v78, v[84:85], off
	global_load_ushort v79, v[86:87], off offset:2048
	global_load_ushort v80, v[88:89], off
	global_load_ushort v81, v[90:91], off offset:2048
	s_nop 0
	global_load_ushort v84, v[92:93], off
	v_cndmask_b32_e32 v168, v94, v95, vcc
	s_waitcnt vmcnt(7)
	v_lshlrev_b32_e32 v7, 16, v7
	v_fma_f32 v85, |v7|, s92, 1.0
	v_rcp_f32_e32 v85, v85
	v_mul_f32_e32 v87, v7, v7
	v_mul_f32_e32 v87, 0xbf38aa3b, v87
	v_exp_f32_e32 v87, v87
	v_fmamk_f32 v86, v85, 0x3f07dc22, v236
	v_fmaak_f32 v86, v85, v86, 0x3f35f0e3
	v_fmaak_f32 v86, v85, v86, 0xbe11a98e
	v_fmaak_f32 v86, v85, v86, 0x3e027906
	v_mul_f32_e32 v85, v85, v86
	v_mul_f32_e32 v85, v87, v85
	v_mul_f32_e32 v86, v85, v7
	v_fma_f32 v85, -v85, v7, v7
	v_cmp_gt_f32_e32 vcc, 0, v7
	s_waitcnt vmcnt(6)
	v_lshlrev_b32_e32 v7, 16, v76
	v_fma_f32 v76, |v7|, s92, 1.0
	v_rcp_f32_e32 v76, v76
	v_cndmask_b32_e32 v169, v85, v86, vcc
	v_mul_f32_e32 v86, v7, v7
	v_mul_f32_e32 v86, 0xbf38aa3b, v86
	v_fmamk_f32 v85, v76, 0x3f07dc22, v236
	v_fmaak_f32 v85, v76, v85, 0x3f35f0e3
	v_exp_f32_e32 v86, v86
	v_fmaak_f32 v85, v76, v85, 0xbe11a98e
	v_fmaak_f32 v85, v76, v85, 0x3e027906
	v_mul_f32_e32 v76, v76, v85
	v_mul_f32_e32 v76, v86, v76
	v_mul_f32_e32 v85, v76, v7
	v_fma_f32 v76, -v76, v7, v7
	v_cmp_gt_f32_e32 vcc, 0, v7
	s_waitcnt vmcnt(5)
	v_lshlrev_b32_e32 v7, 16, v77
	v_cndmask_b32_e32 v170, v76, v85, vcc
	v_fma_f32 v76, |v7|, s92, 1.0
	v_rcp_f32_e32 v76, v76
	v_mul_f32_e32 v85, v7, v7
	v_mul_f32_e32 v85, 0xbf38aa3b, v85
	v_exp_f32_e32 v85, v85
	v_fmamk_f32 v77, v76, 0x3f07dc22, v236
	v_fmaak_f32 v77, v76, v77, 0x3f35f0e3
	v_fmaak_f32 v77, v76, v77, 0xbe11a98e
	v_fmaak_f32 v77, v76, v77, 0x3e027906
	v_mul_f32_e32 v76, v76, v77
	v_mul_f32_e32 v76, v85, v76
	v_mul_f32_e32 v77, v76, v7
	v_fma_f32 v76, -v76, v7, v7
	v_cmp_gt_f32_e32 vcc, 0, v7
	s_waitcnt vmcnt(4)
	v_lshlrev_b32_e32 v7, 16, v78
	v_mul_f32_e32 v78, v7, v7
	v_cndmask_b32_e32 v171, v76, v77, vcc
	v_fma_f32 v76, |v7|, s92, 1.0
	v_rcp_f32_e32 v76, v76
	v_mul_f32_e32 v78, 0xbf38aa3b, v78
	v_exp_f32_e32 v78, v78
	v_cmp_gt_f32_e32 vcc, 0, v7
	v_fmamk_f32 v77, v76, 0x3f07dc22, v236
	v_fmaak_f32 v77, v76, v77, 0x3f35f0e3
	v_fmaak_f32 v77, v76, v77, 0xbe11a98e
	v_fmaak_f32 v77, v76, v77, 0x3e027906
	v_mul_f32_e32 v76, v76, v77
	v_mul_f32_e32 v76, v78, v76
	v_mul_f32_e32 v77, v76, v7
	v_fma_f32 v76, -v76, v7, v7
	s_waitcnt vmcnt(3)
	v_lshlrev_b32_e32 v7, 16, v79
	v_cndmask_b32_e32 v172, v76, v77, vcc
	v_fma_f32 v76, |v7|, s92, 1.0
	v_rcp_f32_e32 v76, v76
	v_mul_f32_e32 v78, v7, v7
	v_mul_f32_e32 v78, 0xbf38aa3b, v78
	v_exp_f32_e32 v78, v78
	v_fmamk_f32 v77, v76, 0x3f07dc22, v236
	v_fmaak_f32 v77, v76, v77, 0x3f35f0e3
	v_fmaak_f32 v77, v76, v77, 0xbe11a98e
	v_fmaak_f32 v77, v76, v77, 0x3e027906
	v_mul_f32_e32 v76, v76, v77
	v_mul_f32_e32 v76, v78, v76
	v_mul_f32_e32 v77, v76, v7
	v_fma_f32 v76, -v76, v7, v7
	v_cmp_gt_f32_e32 vcc, 0, v7
	s_waitcnt vmcnt(2)
	v_lshlrev_b32_e32 v7, 16, v80
	v_mul_f32_e32 v78, v7, v7
	v_cndmask_b32_e32 v173, v76, v77, vcc
	v_fma_f32 v76, |v7|, s92, 1.0
	v_rcp_f32_e32 v76, v76
	v_mul_f32_e32 v78, 0xbf38aa3b, v78
	v_exp_f32_e32 v78, v78
	v_cmp_gt_f32_e32 vcc, 0, v7
	v_fmamk_f32 v77, v76, 0x3f07dc22, v236
	v_fmaak_f32 v77, v76, v77, 0x3f35f0e3
	v_fmaak_f32 v77, v76, v77, 0xbe11a98e
	v_fmaak_f32 v77, v76, v77, 0x3e027906
	v_mul_f32_e32 v76, v76, v77
	v_mul_f32_e32 v76, v78, v76
	v_mul_f32_e32 v77, v76, v7
	v_fma_f32 v76, -v76, v7, v7
	s_waitcnt vmcnt(1)
	v_lshlrev_b32_e32 v7, 16, v81
	v_cndmask_b32_e32 v174, v76, v77, vcc
	v_fma_f32 v76, |v7|, s92, 1.0
	v_rcp_f32_e32 v76, v76
	v_mul_f32_e32 v78, v7, v7
	v_mul_f32_e32 v78, 0xbf38aa3b, v78
	v_exp_f32_e32 v78, v78
	v_fmamk_f32 v77, v76, 0x3f07dc22, v236
	v_fmaak_f32 v77, v76, v77, 0x3f35f0e3
	v_fmaak_f32 v77, v76, v77, 0xbe11a98e
	v_fmaak_f32 v77, v76, v77, 0x3e027906
	v_mul_f32_e32 v76, v76, v77
	v_mul_f32_e32 v76, v78, v76
	v_mul_f32_e32 v77, v76, v7
	v_fma_f32 v76, -v76, v7, v7
	v_cmp_gt_f32_e32 vcc, 0, v7
	s_waitcnt vmcnt(0)
	v_lshlrev_b32_e32 v7, 16, v84
	v_mul_f32_e32 v78, v7, v7
	v_cndmask_b32_e32 v175, v76, v77, vcc
	v_fma_f32 v76, |v7|, s92, 1.0
	v_rcp_f32_e32 v76, v76
	v_mul_f32_e32 v78, 0xbf38aa3b, v78
	v_exp_f32_e32 v78, v78
	v_cmp_gt_f32_e32 vcc, 0, v7
	v_fmamk_f32 v77, v76, 0x3f07dc22, v236
	v_fmaak_f32 v77, v76, v77, 0x3f35f0e3
	v_fmaak_f32 v77, v76, v77, 0xbe11a98e
	v_fmaak_f32 v77, v76, v77, 0x3e027906
	v_mul_f32_e32 v76, v76, v77
	v_mul_f32_e32 v76, v78, v76
	v_mul_f32_e32 v77, v76, v7
	v_fma_f32 v76, -v76, v7, v7
	global_load_ushort v7, v[54:55], off offset:2048
	s_nop 0
	global_load_ushort v54, v[56:57], off
	global_load_ushort v55, v[58:59], off offset:2048
	s_nop 0
	global_load_ushort v56, v[60:61], off
	global_load_ushort v57, v[62:63], off offset:2048
	global_load_ushort v58, v[64:65], off
	global_load_ushort v59, v[66:67], off offset:2048
	s_nop 0
	global_load_ushort v60, v[68:69], off
	v_cndmask_b32_e32 v176, v76, v77, vcc
	v_lshl_add_u64 v[84:85], s[76:77], 0, v[74:75]
	s_waitcnt vmcnt(7)
	v_lshlrev_b32_e32 v7, 16, v7
	v_fma_f32 v61, |v7|, s92, 1.0
	v_rcp_f32_e32 v61, v61
	v_mul_f32_e32 v63, v7, v7
	v_mul_f32_e32 v63, 0xbf38aa3b, v63
	v_exp_f32_e32 v63, v63
	v_fmamk_f32 v62, v61, 0x3f07dc22, v236
	v_fmaak_f32 v62, v61, v62, 0x3f35f0e3
	v_fmaak_f32 v62, v61, v62, 0xbe11a98e
	v_fmaak_f32 v62, v61, v62, 0x3e027906
	v_mul_f32_e32 v61, v61, v62
	v_mul_f32_e32 v61, v63, v61
	v_mul_f32_e32 v62, v61, v7
	v_fma_f32 v61, -v61, v7, v7
	v_cmp_gt_f32_e32 vcc, 0, v7
	s_waitcnt vmcnt(6)
	v_lshlrev_b32_e32 v7, 16, v54
	v_fma_f32 v54, |v7|, s92, 1.0
	v_rcp_f32_e32 v54, v54
	v_cndmask_b32_e32 v177, v61, v62, vcc
	v_mul_f32_e32 v62, v7, v7
	v_mul_f32_e32 v62, 0xbf38aa3b, v62
	v_fmamk_f32 v61, v54, 0x3f07dc22, v236
	v_fmaak_f32 v61, v54, v61, 0x3f35f0e3
	v_exp_f32_e32 v62, v62
	v_fmaak_f32 v61, v54, v61, 0xbe11a98e
	v_fmaak_f32 v61, v54, v61, 0x3e027906
	v_mul_f32_e32 v54, v54, v61
	v_mul_f32_e32 v54, v62, v54
	v_mul_f32_e32 v61, v54, v7
	v_fma_f32 v54, -v54, v7, v7
	v_cmp_gt_f32_e32 vcc, 0, v7
	s_waitcnt vmcnt(5)
	v_lshlrev_b32_e32 v7, 16, v55
	v_cndmask_b32_e32 v178, v54, v61, vcc
	v_fma_f32 v54, |v7|, s92, 1.0
	v_rcp_f32_e32 v54, v54
	v_mul_f32_e32 v61, v7, v7
	v_mul_f32_e32 v61, 0xbf38aa3b, v61
	v_exp_f32_e32 v61, v61
	v_fmamk_f32 v55, v54, 0x3f07dc22, v236
	v_fmaak_f32 v55, v54, v55, 0x3f35f0e3
	v_fmaak_f32 v55, v54, v55, 0xbe11a98e
	v_fmaak_f32 v55, v54, v55, 0x3e027906
	v_mul_f32_e32 v54, v54, v55
	v_mul_f32_e32 v54, v61, v54
	v_mul_f32_e32 v55, v54, v7
	v_fma_f32 v54, -v54, v7, v7
	v_cmp_gt_f32_e32 vcc, 0, v7
	s_waitcnt vmcnt(4)
	v_lshlrev_b32_e32 v7, 16, v56
	v_mul_f32_e32 v56, v7, v7
	v_cndmask_b32_e32 v179, v54, v55, vcc
	v_fma_f32 v54, |v7|, s92, 1.0
	v_rcp_f32_e32 v54, v54
	v_mul_f32_e32 v56, 0xbf38aa3b, v56
	v_exp_f32_e32 v56, v56
	v_cmp_gt_f32_e32 vcc, 0, v7
	v_fmamk_f32 v55, v54, 0x3f07dc22, v236
	v_fmaak_f32 v55, v54, v55, 0x3f35f0e3
	v_fmaak_f32 v55, v54, v55, 0xbe11a98e
	v_fmaak_f32 v55, v54, v55, 0x3e027906
	v_mul_f32_e32 v54, v54, v55
	v_mul_f32_e32 v54, v56, v54
	v_mul_f32_e32 v55, v54, v7
	v_fma_f32 v54, -v54, v7, v7
	s_waitcnt vmcnt(3)
	v_lshlrev_b32_e32 v7, 16, v57
	v_cndmask_b32_e32 v180, v54, v55, vcc
	v_fma_f32 v54, |v7|, s92, 1.0
	v_rcp_f32_e32 v54, v54
	v_mul_f32_e32 v56, v7, v7
	v_mul_f32_e32 v56, 0xbf38aa3b, v56
	v_exp_f32_e32 v56, v56
	v_fmamk_f32 v55, v54, 0x3f07dc22, v236
	v_fmaak_f32 v55, v54, v55, 0x3f35f0e3
	v_fmaak_f32 v55, v54, v55, 0xbe11a98e
	v_fmaak_f32 v55, v54, v55, 0x3e027906
	v_mul_f32_e32 v54, v54, v55
	v_mul_f32_e32 v54, v56, v54
	v_mul_f32_e32 v55, v54, v7
	v_fma_f32 v54, -v54, v7, v7
	v_cmp_gt_f32_e32 vcc, 0, v7
	s_waitcnt vmcnt(2)
	v_lshlrev_b32_e32 v7, 16, v58
	v_mul_f32_e32 v56, v7, v7
	v_cndmask_b32_e32 v181, v54, v55, vcc
	v_add_co_u32_e32 v134, vcc, s6, v10
	s_mov_b32 s6, 0x6061000
	s_nop 0
	v_addc_co_u32_e32 v135, vcc, 0, v11, vcc
	v_add_co_u32_e32 v136, vcc, s6, v10
	s_mov_b32 s6, 0x6063000
	s_nop 0
	v_addc_co_u32_e32 v137, vcc, 0, v11, vcc
	v_add_co_u32_e32 v138, vcc, s6, v10
	s_mov_b32 s6, 0x6064000
	s_nop 0
	v_addc_co_u32_e32 v139, vcc, 0, v11, vcc
	v_add_co_u32_e32 v140, vcc, s6, v10
	s_mov_b32 s6, 0x606c000
	s_nop 0
	v_addc_co_u32_e32 v141, vcc, 0, v11, vcc
	v_add_co_u32_e32 v142, vcc, s6, v10
	s_mov_b32 s6, 0x606d000
	s_nop 0
	v_addc_co_u32_e32 v143, vcc, 0, v11, vcc
	v_add_co_u32_e32 v144, vcc, s6, v10
	s_mov_b32 s6, 0x606f000
	s_nop 0
	v_addc_co_u32_e32 v145, vcc, 0, v11, vcc
	v_add_co_u32_e32 v146, vcc, s6, v10
	s_mov_b32 s6, 0x6070000
	s_nop 0
	v_addc_co_u32_e32 v147, vcc, 0, v11, vcc
	v_add_co_u32_e32 v148, vcc, s6, v10
	s_mov_b32 s6, 0x6078000
	s_nop 0
	v_addc_co_u32_e32 v149, vcc, 0, v11, vcc
	v_add_co_u32_e32 v76, vcc, s6, v10
	s_mov_b32 s6, 0x6079000
	s_nop 0
	v_addc_co_u32_e32 v77, vcc, 0, v11, vcc
	v_add_co_u32_e32 v78, vcc, s6, v10
	s_mov_b32 s6, 0x607b000
	s_nop 0
	v_addc_co_u32_e32 v79, vcc, 0, v11, vcc
	v_add_co_u32_e32 v80, vcc, s6, v10
	s_mov_b32 s6, 0x607c000
	s_nop 0
	v_addc_co_u32_e32 v81, vcc, 0, v11, vcc
	v_fma_f32 v54, |v7|, s92, 1.0
	v_add_co_u32_e32 v122, vcc, s6, v10
	v_rcp_f32_e32 v54, v54
	s_nop 0
	v_addc_co_u32_e32 v123, vcc, 0, v11, vcc
	s_mov_b32 s6, 0x6084000
	v_add_co_u32_e32 v124, vcc, s6, v10
	s_mov_b32 s6, 0x6085000
	s_nop 0
	v_addc_co_u32_e32 v125, vcc, 0, v11, vcc
	v_add_co_u32_e32 v126, vcc, s6, v10
	v_fmamk_f32 v55, v54, 0x3f07dc22, v236
	v_mul_f32_e32 v56, 0xbf38aa3b, v56
	v_addc_co_u32_e32 v127, vcc, 0, v11, vcc
	s_mov_b32 s6, 0x6087000
	v_fmaak_f32 v55, v54, v55, 0x3f35f0e3
	v_exp_f32_e32 v56, v56
	v_add_co_u32_e32 v128, vcc, s6, v10
	v_fmaak_f32 v55, v54, v55, 0xbe11a98e
	s_nop 0
	v_addc_co_u32_e32 v129, vcc, 0, v11, vcc
	s_mov_b32 s6, 0x6088000
	v_fmaak_f32 v55, v54, v55, 0x3e027906
	v_add_co_u32_e32 v132, vcc, s6, v10
	v_mul_f32_e32 v54, v54, v55
	s_nop 0
	v_addc_co_u32_e32 v133, vcc, 0, v11, vcc
	v_mul_f32_e32 v54, v56, v54
	v_mul_f32_e32 v55, v54, v7
	v_fma_f32 v54, -v54, v7, v7
	v_cmp_gt_f32_e32 vcc, 0, v7
	s_waitcnt vmcnt(1)
	v_lshlrev_b32_e32 v7, 16, v59
	v_mul_f32_e32 v56, v7, v7
	v_cndmask_b32_e32 v151, v54, v55, vcc
	v_fma_f32 v54, |v7|, s92, 1.0
	v_rcp_f32_e32 v54, v54
	v_mul_f32_e32 v56, 0xbf38aa3b, v56
	v_exp_f32_e32 v56, v56
	v_cmp_gt_f32_e32 vcc, 0, v7
	v_fmamk_f32 v55, v54, 0x3f07dc22, v236
	v_fmaak_f32 v55, v54, v55, 0x3f35f0e3
	v_fmaak_f32 v55, v54, v55, 0xbe11a98e
	v_fmaak_f32 v55, v54, v55, 0x3e027906
	v_mul_f32_e32 v54, v54, v55
	v_mul_f32_e32 v54, v56, v54
	v_mul_f32_e32 v55, v54, v7
	v_fma_f32 v54, -v54, v7, v7
	s_waitcnt vmcnt(0)
	v_lshlrev_b32_e32 v7, 16, v60
	v_cndmask_b32_e32 v152, v54, v55, vcc
	v_fma_f32 v54, |v7|, s92, 1.0
	v_rcp_f32_e32 v54, v54
	v_mul_f32_e32 v56, v7, v7
	v_mul_f32_e32 v56, 0xbf38aa3b, v56
	v_exp_f32_e32 v56, v56
	v_fmamk_f32 v55, v54, 0x3f07dc22, v236
	v_fmaak_f32 v55, v54, v55, 0x3f35f0e3
	v_fmaak_f32 v55, v54, v55, 0xbe11a98e
	v_fmaak_f32 v55, v54, v55, 0x3e027906
	v_mul_f32_e32 v54, v54, v55
	v_mul_f32_e32 v54, v56, v54
	v_mul_f32_e32 v55, v54, v7
	v_fma_f32 v54, -v54, v7, v7
	v_cmp_gt_f32_e32 vcc, 0, v7
	global_load_ushort v7, v[38:39], off offset:2048
	s_nop 0
	global_load_ushort v38, v[40:41], off
	global_load_ushort v39, v[42:43], off offset:2048
	s_nop 0
	global_load_ushort v40, v[44:45], off
	global_load_ushort v41, v[46:47], off offset:2048
	global_load_ushort v42, v[48:49], off
	global_load_ushort v43, v[50:51], off offset:2048
	s_nop 0
	global_load_ushort v44, v[52:53], off
	v_cndmask_b32_e32 v153, v54, v55, vcc
	s_mov_b32 s6, 0x6090000
	s_waitcnt vmcnt(7)
	v_lshlrev_b32_e32 v7, 16, v7
	v_fma_f32 v45, |v7|, s92, 1.0
	v_rcp_f32_e32 v45, v45
	v_mul_f32_e32 v47, v7, v7
	v_mul_f32_e32 v47, 0xbf38aa3b, v47
	v_exp_f32_e32 v47, v47
	v_fmamk_f32 v46, v45, 0x3f07dc22, v236
	v_fmaak_f32 v46, v45, v46, 0x3f35f0e3
	v_fmaak_f32 v46, v45, v46, 0xbe11a98e
	v_fmaak_f32 v46, v45, v46, 0x3e027906
	v_mul_f32_e32 v45, v45, v46
	v_mul_f32_e32 v45, v47, v45
	v_mul_f32_e32 v46, v45, v7
	v_fma_f32 v45, -v45, v7, v7
	v_cmp_gt_f32_e32 vcc, 0, v7
	s_waitcnt vmcnt(6)
	v_lshlrev_b32_e32 v7, 16, v38
	v_fma_f32 v38, |v7|, s92, 1.0
	v_rcp_f32_e32 v38, v38
	v_cndmask_b32_e32 v154, v45, v46, vcc
	v_mul_f32_e32 v46, v7, v7
	v_mul_f32_e32 v46, 0xbf38aa3b, v46
	v_fmamk_f32 v45, v38, 0x3f07dc22, v236
	v_fmaak_f32 v45, v38, v45, 0x3f35f0e3
	v_exp_f32_e32 v46, v46
	v_fmaak_f32 v45, v38, v45, 0xbe11a98e
	v_fmaak_f32 v45, v38, v45, 0x3e027906
	v_mul_f32_e32 v38, v38, v45
	v_mul_f32_e32 v38, v46, v38
	v_mul_f32_e32 v45, v38, v7
	v_fma_f32 v38, -v38, v7, v7
	v_cmp_gt_f32_e32 vcc, 0, v7
	s_waitcnt vmcnt(5)
	v_lshlrev_b32_e32 v7, 16, v39
	v_cndmask_b32_e32 v155, v38, v45, vcc
	v_fma_f32 v38, |v7|, s92, 1.0
	v_rcp_f32_e32 v38, v38
	v_mul_f32_e32 v45, v7, v7
	v_mul_f32_e32 v45, 0xbf38aa3b, v45
	v_exp_f32_e32 v45, v45
	v_fmamk_f32 v39, v38, 0x3f07dc22, v236
	v_fmaak_f32 v39, v38, v39, 0x3f35f0e3
	v_fmaak_f32 v39, v38, v39, 0xbe11a98e
	v_fmaak_f32 v39, v38, v39, 0x3e027906
	v_mul_f32_e32 v38, v38, v39
	v_mul_f32_e32 v38, v45, v38
	v_mul_f32_e32 v39, v38, v7
	v_fma_f32 v38, -v38, v7, v7
	v_cmp_gt_f32_e32 vcc, 0, v7
	s_waitcnt vmcnt(4)
	v_lshlrev_b32_e32 v7, 16, v40
	v_mul_f32_e32 v40, v7, v7
	v_cndmask_b32_e32 v156, v38, v39, vcc
	v_fma_f32 v38, |v7|, s92, 1.0
	v_rcp_f32_e32 v38, v38
	v_mul_f32_e32 v40, 0xbf38aa3b, v40
	v_exp_f32_e32 v40, v40
	v_cmp_gt_f32_e32 vcc, 0, v7
	v_fmamk_f32 v39, v38, 0x3f07dc22, v236
	v_fmaak_f32 v39, v38, v39, 0x3f35f0e3
	v_fmaak_f32 v39, v38, v39, 0xbe11a98e
	v_fmaak_f32 v39, v38, v39, 0x3e027906
	v_mul_f32_e32 v38, v38, v39
	v_mul_f32_e32 v38, v40, v38
	v_mul_f32_e32 v39, v38, v7
	v_fma_f32 v38, -v38, v7, v7
	s_waitcnt vmcnt(3)
	v_lshlrev_b32_e32 v7, 16, v41
	v_cndmask_b32_e32 v157, v38, v39, vcc
	v_fma_f32 v38, |v7|, s92, 1.0
	v_rcp_f32_e32 v38, v38
	v_mul_f32_e32 v40, v7, v7
	v_mul_f32_e32 v40, 0xbf38aa3b, v40
	v_exp_f32_e32 v40, v40
	v_fmamk_f32 v39, v38, 0x3f07dc22, v236
	v_fmaak_f32 v39, v38, v39, 0x3f35f0e3
	v_fmaak_f32 v39, v38, v39, 0xbe11a98e
	v_fmaak_f32 v39, v38, v39, 0x3e027906
	v_mul_f32_e32 v38, v38, v39
	v_mul_f32_e32 v38, v40, v38
	v_mul_f32_e32 v39, v38, v7
	v_fma_f32 v38, -v38, v7, v7
	v_cmp_gt_f32_e32 vcc, 0, v7
	s_waitcnt vmcnt(2)
	v_lshlrev_b32_e32 v7, 16, v42
	v_mul_f32_e32 v40, v7, v7
	v_cndmask_b32_e32 v158, v38, v39, vcc
	v_fma_f32 v38, |v7|, s92, 1.0
	v_rcp_f32_e32 v38, v38
	v_mul_f32_e32 v40, 0xbf38aa3b, v40
	v_exp_f32_e32 v40, v40
	v_cmp_gt_f32_e32 vcc, 0, v7
	v_fmamk_f32 v39, v38, 0x3f07dc22, v236
	v_fmaak_f32 v39, v38, v39, 0x3f35f0e3
	v_fmaak_f32 v39, v38, v39, 0xbe11a98e
	v_fmaak_f32 v39, v38, v39, 0x3e027906
	v_mul_f32_e32 v38, v38, v39
	v_mul_f32_e32 v38, v40, v38
	v_mul_f32_e32 v39, v38, v7
	v_fma_f32 v38, -v38, v7, v7
	s_waitcnt vmcnt(1)
	v_lshlrev_b32_e32 v7, 16, v43
	v_cndmask_b32_e32 v159, v38, v39, vcc
	v_fma_f32 v38, |v7|, s92, 1.0
	v_rcp_f32_e32 v38, v38
	v_mul_f32_e32 v40, v7, v7
	v_mul_f32_e32 v40, 0xbf38aa3b, v40
	v_exp_f32_e32 v40, v40
	v_fmamk_f32 v39, v38, 0x3f07dc22, v236
	v_fmaak_f32 v39, v38, v39, 0x3f35f0e3
	v_fmaak_f32 v39, v38, v39, 0xbe11a98e
	v_fmaak_f32 v39, v38, v39, 0x3e027906
	v_mul_f32_e32 v38, v38, v39
	v_mul_f32_e32 v38, v40, v38
	v_mul_f32_e32 v39, v38, v7
	v_fma_f32 v38, -v38, v7, v7
	v_cmp_gt_f32_e32 vcc, 0, v7
	s_waitcnt vmcnt(0)
	v_lshlrev_b32_e32 v7, 16, v44
	v_mul_f32_e32 v40, v7, v7
	v_cndmask_b32_e32 v160, v38, v39, vcc
	v_fma_f32 v38, |v7|, s92, 1.0
	v_rcp_f32_e32 v38, v38
	v_mul_f32_e32 v40, 0xbf38aa3b, v40
	v_exp_f32_e32 v40, v40
	v_cmp_gt_f32_e32 vcc, 0, v7
	v_fmamk_f32 v39, v38, 0x3f07dc22, v236
	v_fmaak_f32 v39, v38, v39, 0x3f35f0e3
	v_fmaak_f32 v39, v38, v39, 0xbe11a98e
	v_fmaak_f32 v39, v38, v39, 0x3e027906
	v_mul_f32_e32 v38, v38, v39
	v_mul_f32_e32 v38, v40, v38
	v_mul_f32_e32 v39, v38, v7
	v_fma_f32 v38, -v38, v7, v7
	global_load_ushort v7, v[12:13], off offset:2048
	s_nop 0
	global_load_ushort v12, v[14:15], off
	global_load_ushort v13, v[16:17], off offset:2048
	s_nop 0
	global_load_ushort v14, v[34:35], off
	global_load_ushort v15, v[36:37], off offset:2048
	v_cndmask_b32_e32 v161, v38, v39, vcc
	s_waitcnt vmcnt(4)
	v_lshlrev_b32_e32 v7, 16, v7
	v_fma_f32 v16, |v7|, s92, 1.0
	v_rcp_f32_e32 v16, v16
	v_mul_f32_e32 v34, v7, v7
	v_mul_f32_e32 v34, 0xbf38aa3b, v34
	v_exp_f32_e32 v34, v34
	v_fmamk_f32 v17, v16, 0x3f07dc22, v236
	v_fmaak_f32 v17, v16, v17, 0x3f35f0e3
	v_fmaak_f32 v17, v16, v17, 0xbe11a98e
	v_fmaak_f32 v17, v16, v17, 0x3e027906
	v_mul_f32_e32 v16, v16, v17
	v_mul_f32_e32 v16, v34, v16
	v_mul_f32_e32 v17, v16, v7
	v_fma_f32 v16, -v16, v7, v7
	v_cmp_gt_f32_e32 vcc, 0, v7
	s_waitcnt vmcnt(3)
	v_lshlrev_b32_e32 v7, 16, v12
	v_fma_f32 v12, |v7|, s92, 1.0
	v_rcp_f32_e32 v12, v12
	v_cndmask_b32_e32 v162, v16, v17, vcc
	v_mul_f32_e32 v17, v7, v7
	v_mul_f32_e32 v17, 0xbf38aa3b, v17
	v_fmamk_f32 v16, v12, 0x3f07dc22, v236
	v_fmaak_f32 v16, v12, v16, 0x3f35f0e3
	v_exp_f32_e32 v17, v17
	v_fmaak_f32 v16, v12, v16, 0xbe11a98e
	v_fmaak_f32 v16, v12, v16, 0x3e027906
	v_mul_f32_e32 v12, v12, v16
	v_mul_f32_e32 v12, v17, v12
	v_mul_f32_e32 v16, v12, v7
	v_fma_f32 v12, -v12, v7, v7
	v_cmp_gt_f32_e32 vcc, 0, v7
	s_waitcnt vmcnt(2)
	v_lshlrev_b32_e32 v7, 16, v13
	v_cndmask_b32_e32 v163, v12, v16, vcc
	v_fma_f32 v12, |v7|, s92, 1.0
	v_rcp_f32_e32 v12, v12
	v_mul_f32_e32 v16, v7, v7
	v_mul_f32_e32 v16, 0xbf38aa3b, v16
	v_exp_f32_e32 v16, v16
	v_fmamk_f32 v13, v12, 0x3f07dc22, v236
	v_fmaak_f32 v13, v12, v13, 0x3f35f0e3
	v_fmaak_f32 v13, v12, v13, 0xbe11a98e
	v_fmaak_f32 v13, v12, v13, 0x3e027906
	v_mul_f32_e32 v12, v12, v13
	v_mul_f32_e32 v12, v16, v12
	v_mul_f32_e32 v13, v12, v7
	v_fma_f32 v12, -v12, v7, v7
	v_cmp_gt_f32_e32 vcc, 0, v7
	s_waitcnt vmcnt(1)
	v_lshlrev_b32_e32 v7, 16, v14
	v_mul_f32_e32 v14, v7, v7
	v_cndmask_b32_e32 v164, v12, v13, vcc
	v_fma_f32 v12, |v7|, s92, 1.0
	v_rcp_f32_e32 v12, v12
	v_mul_f32_e32 v14, 0xbf38aa3b, v14
	v_exp_f32_e32 v14, v14
	v_cmp_gt_f32_e32 vcc, 0, v7
	v_fmamk_f32 v13, v12, 0x3f07dc22, v236
	v_fmaak_f32 v13, v12, v13, 0x3f35f0e3
	v_fmaak_f32 v13, v12, v13, 0xbe11a98e
	v_fmaak_f32 v13, v12, v13, 0x3e027906
	v_mul_f32_e32 v12, v12, v13
	v_mul_f32_e32 v12, v14, v12
	v_mul_f32_e32 v13, v12, v7
	v_fma_f32 v12, -v12, v7, v7
	s_waitcnt vmcnt(0)
	v_lshlrev_b32_e32 v7, 16, v15
	v_cndmask_b32_e32 v165, v12, v13, vcc
	v_fma_f32 v12, |v7|, s92, 1.0
	v_rcp_f32_e32 v12, v12
	v_mul_f32_e32 v14, v7, v7
	v_mul_f32_e32 v14, 0xbf38aa3b, v14
	v_exp_f32_e32 v14, v14
	v_fmamk_f32 v13, v12, 0x3f07dc22, v236
	v_fmaak_f32 v13, v12, v13, 0x3f35f0e3
	v_fmaak_f32 v13, v12, v13, 0xbe11a98e
	v_fmaak_f32 v13, v12, v13, 0x3e027906
	v_mul_f32_e32 v12, v12, v13
	v_mul_f32_e32 v12, v14, v12
	v_mul_f32_e32 v13, v12, v7
	v_fma_f32 v12, -v12, v7, v7
	v_cmp_gt_f32_e32 vcc, 0, v7
	v_lshlrev_b32_e32 v7, 4, v73
	v_add3_u32 v34, 0, v6, v7
	v_cndmask_b32_e32 v166, v12, v13, vcc
	v_add_co_u32_e32 v88, vcc, s41, v8
	ds_read_b128 v[62:65], v34
	ds_read_b128 v[58:61], v34 offset:32
	ds_read_b128 v[54:57], v34 offset:64
	ds_read_b128 v[50:53], v34 offset:96
	v_addc_co_u32_e32 v89, vcc, 0, v9, vcc
	v_add_co_u32_e32 v86, vcc, s97, v8
	v_add_u32_e32 v150, s5, v7
	s_nop 0
	v_addc_co_u32_e32 v87, vcc, 0, v9, vcc
	v_add_co_u32_e32 v116, vcc, s6, v10
	s_mov_b32 s6, 0x6091000
	s_nop 0
	v_addc_co_u32_e32 v117, vcc, 0, v11, vcc
	v_add_co_u32_e32 v118, vcc, s6, v10
	s_mov_b32 s6, 0x6093000
	s_nop 0
	v_addc_co_u32_e32 v119, vcc, 0, v11, vcc
	v_add_co_u32_e32 v120, vcc, s6, v10
	s_mov_b32 s6, 0x6094000
	s_nop 0
	v_addc_co_u32_e32 v121, vcc, 0, v11, vcc
	v_add_co_u32_e32 v100, vcc, s6, v10
	s_mov_b32 s6, 0x609c000
	s_nop 0
	v_addc_co_u32_e32 v101, vcc, 0, v11, vcc
	v_add_co_u32_e32 v102, vcc, s6, v10
	s_mov_b32 s6, 0x609d000
	s_nop 0
	v_addc_co_u32_e32 v103, vcc, 0, v11, vcc
	v_add_co_u32_e32 v104, vcc, s6, v10
	s_mov_b32 s6, 0x609f000
	s_nop 0
	v_addc_co_u32_e32 v105, vcc, 0, v11, vcc
	v_add_co_u32_e32 v106, vcc, s6, v10
	s_mov_b32 s6, 0x60a0000
	s_nop 0
	v_addc_co_u32_e32 v107, vcc, 0, v11, vcc
	v_add_co_u32_e32 v108, vcc, s6, v10
	s_mov_b32 s6, 0x60a8000
	s_nop 0
	v_addc_co_u32_e32 v109, vcc, 0, v11, vcc
	v_add_co_u32_e32 v110, vcc, s6, v10
	s_mov_b32 s6, 0x60a9000
	s_nop 0
	v_addc_co_u32_e32 v111, vcc, 0, v11, vcc
	v_add_co_u32_e32 v112, vcc, s6, v10
	s_mov_b32 s6, 0x60ab000
	s_nop 0
	v_addc_co_u32_e32 v113, vcc, 0, v11, vcc
	v_add_co_u32_e32 v114, vcc, s6, v10
	s_mov_b32 s6, 0x60ac000
	s_nop 0
	v_addc_co_u32_e32 v115, vcc, 0, v11, vcc
	v_add_co_u32_e32 v90, vcc, s6, v10
	s_mov_b32 s6, 0x60b4000
	s_nop 0
	v_addc_co_u32_e32 v91, vcc, 0, v11, vcc
	v_add_co_u32_e32 v92, vcc, s6, v10
	s_mov_b32 s6, 0x60b5000
	s_nop 0
	v_addc_co_u32_e32 v93, vcc, 0, v11, vcc
	v_add_co_u32_e32 v94, vcc, s6, v10
	s_mov_b32 s6, 0x60b7000
	s_nop 0
	v_addc_co_u32_e32 v95, vcc, 0, v11, vcc
	v_add_co_u32_e32 v96, vcc, s6, v10
	s_mov_b32 s6, 0x60b8000
	s_nop 0
	v_addc_co_u32_e32 v97, vcc, 0, v11, vcc
	v_add_co_u32_e32 v98, vcc, s6, v10
	ds_read_b128 v[46:49], v34 offset:128
	ds_read_b128 v[42:45], v34 offset:160
	ds_read_b128 v[38:41], v34 offset:192
	ds_read_b128 v[34:37], v34 offset:224
	v_addc_co_u32_e32 v99, vcc, 0, v11, vcc
	s_waitcnt lgkmcnt(7)
	v_mfma_f32_32x32x16_bf16 v[2:17], v[2:5], v[62:65], 0
	global_load_dwordx4 v[66:69], v[82:83], off offset:-4096
	ds_read_b128 v[182:185], v150
	v_mov_b32_e32 v73, v131
	v_lshlrev_b64 v[72:73], 11, v[72:73]
	v_lshl_add_u64 v[72:73], v[84:85], 0, v[72:73]
	v_readlane_b32 s5, v252, 31
	s_waitcnt lgkmcnt(7)
	v_mfma_f32_32x32x16_bf16 v[2:17], v[30:33], v[58:61], v[2:17]
	ds_read_b128 v[30:33], v150 offset:32
	s_waitcnt lgkmcnt(1)
	s_nop 9
	v_add_f32_e32 v2, v2, v182
	v_mul_f32_e32 v2, v130, v2
	v_cvt_pk_bf16_f32 v2, v2, s0
	global_store_short v[72:73], v2, off sc1
	v_add_f32_e32 v2, v3, v183
	v_mul_f32_e32 v2, v167, v2
	v_cvt_pk_bf16_f32 v72, v2, s0
	v_or_b32_e32 v2, s5, v1
	v_lshlrev_b32_e32 v130, 11, v2
	v_lshl_add_u64 v[2:3], v[84:85], 0, v[130:131]
	global_store_short v[2:3], v72, off sc1
	v_add_f32_e32 v2, v4, v184
	v_mul_f32_e32 v2, v168, v2
	v_readlane_b32 s5, v252, 32
	v_cvt_pk_bf16_f32 v4, v2, s0
	s_nop 0
	v_or_b32_e32 v2, s5, v1
	v_lshlrev_b32_e32 v130, 11, v2
	v_lshl_add_u64 v[2:3], v[84:85], 0, v[130:131]
	global_store_short v[2:3], v4, off sc1
	v_add_f32_e32 v2, v5, v185
	v_mul_f32_e32 v2, v169, v2
	v_readlane_b32 s5, v252, 33
	v_cvt_pk_bf16_f32 v4, v2, s0
	s_nop 0
	v_or_b32_e32 v2, s5, v1
	v_lshlrev_b32_e32 v130, 11, v2
	v_lshl_add_u64 v[2:3], v[84:85], 0, v[130:131]
	global_store_short v[2:3], v4, off sc1
	s_waitcnt lgkmcnt(0)
	v_add_f32_e32 v2, v6, v30
	v_mul_f32_e32 v2, v170, v2
	v_readlane_b32 s5, v252, 34
	v_cvt_pk_bf16_f32 v4, v2, s0
	s_nop 0
	v_or_b32_e32 v2, s5, v1
	v_lshlrev_b32_e32 v130, 11, v2
	v_lshl_add_u64 v[2:3], v[84:85], 0, v[130:131]
	global_store_short v[2:3], v4, off sc1
	v_add_f32_e32 v2, v7, v31
	v_mul_f32_e32 v2, v171, v2
	v_readlane_b32 s5, v252, 35
	v_cvt_pk_bf16_f32 v4, v2, s0
	s_nop 0
	v_or_b32_e32 v2, s5, v1
	v_lshlrev_b32_e32 v130, 11, v2
	v_lshl_add_u64 v[2:3], v[84:85], 0, v[130:131]
	global_store_short v[2:3], v4, off sc1
	v_add_f32_e32 v2, v8, v32
	v_mul_f32_e32 v2, v172, v2
	v_readlane_b32 s5, v252, 36
	v_cvt_pk_bf16_f32 v4, v2, s0
	s_nop 0
	v_or_b32_e32 v2, s5, v1
	v_lshlrev_b32_e32 v130, 11, v2
	v_lshl_add_u64 v[2:3], v[84:85], 0, v[130:131]
	global_store_short v[2:3], v4, off sc1
	v_add_f32_e32 v2, v9, v33
	v_mul_f32_e32 v2, v173, v2
	v_cvt_pk_bf16_f32 v8, v2, s0
	ds_read_b128 v[2:5], v150 offset:64
	v_readlane_b32 s5, v252, 37
	s_nop 1
	v_or_b32_e32 v6, s5, v1
	v_lshlrev_b32_e32 v130, 11, v6
	v_lshl_add_u64 v[6:7], v[84:85], 0, v[130:131]
	v_readlane_b32 s5, v252, 38
	global_store_short v[6:7], v8, off sc1
	ds_read_b128 v[6:9], v150 offset:96
	s_waitcnt lgkmcnt(1)
	v_add_f32_e32 v2, v10, v2
	v_or_b32_e32 v10, s5, v1
	v_mul_f32_e32 v2, v174, v2
	v_lshlrev_b32_e32 v130, 11, v10
	v_cvt_pk_bf16_f32 v2, v2, s0
	v_lshl_add_u64 v[30:31], v[84:85], 0, v[130:131]
	global_store_short v[30:31], v2, off sc1
	v_add_f32_e32 v2, v11, v3
	v_mul_f32_e32 v2, v175, v2
	v_readlane_b32 s5, v252, 39
	v_cvt_pk_bf16_f32 v10, v2, s0
	s_nop 0
	v_or_b32_e32 v2, s5, v1
	v_lshlrev_b32_e32 v130, 11, v2
	v_lshl_add_u64 v[2:3], v[84:85], 0, v[130:131]
	global_store_short v[2:3], v10, off sc1
	v_add_f32_e32 v2, v12, v4
	v_mul_f32_e32 v2, v176, v2
	v_readlane_b32 s5, v252, 40
	v_cvt_pk_bf16_f32 v4, v2, s0
	s_nop 0
	v_or_b32_e32 v2, s5, v1
	v_lshlrev_b32_e32 v130, 11, v2
	v_lshl_add_u64 v[2:3], v[84:85], 0, v[130:131]
	global_store_short v[2:3], v4, off sc1
	v_add_f32_e32 v2, v13, v5
	v_mul_f32_e32 v2, v177, v2
	v_readlane_b32 s5, v252, 41
	v_cvt_pk_bf16_f32 v4, v2, s0
	s_nop 0
	v_or_b32_e32 v2, s5, v1
	v_lshlrev_b32_e32 v130, 11, v2
	v_lshl_add_u64 v[2:3], v[84:85], 0, v[130:131]
	global_store_short v[2:3], v4, off sc1
	s_waitcnt lgkmcnt(0)
	v_add_f32_e32 v2, v14, v6
	v_mul_f32_e32 v2, v178, v2
	v_readlane_b32 s5, v252, 42
	v_cvt_pk_bf16_f32 v4, v2, s0
	s_nop 0
	v_or_b32_e32 v2, s5, v1
	v_lshlrev_b32_e32 v130, 11, v2
	v_lshl_add_u64 v[2:3], v[84:85], 0, v[130:131]
	global_store_short v[2:3], v4, off sc1
	v_add_f32_e32 v2, v15, v7
	v_mul_f32_e32 v2, v179, v2
	v_readlane_b32 s5, v252, 43
	v_cvt_pk_bf16_f32 v4, v2, s0
	s_nop 0
	v_or_b32_e32 v2, s5, v1
	v_lshlrev_b32_e32 v130, 11, v2
	v_lshl_add_u64 v[2:3], v[84:85], 0, v[130:131]
	global_store_short v[2:3], v4, off sc1
	v_add_f32_e32 v2, v16, v8
	v_mul_f32_e32 v2, v180, v2
	v_readlane_b32 s5, v252, 44
	v_cvt_pk_bf16_f32 v4, v2, s0
	s_nop 0
	v_or_b32_e32 v2, s5, v1
	v_lshlrev_b32_e32 v130, 11, v2
	v_lshl_add_u64 v[2:3], v[84:85], 0, v[130:131]
	global_store_short v[2:3], v4, off sc1
	v_add_f32_e32 v2, v17, v9
	v_mul_f32_e32 v2, v181, v2
	v_readlane_b32 s5, v252, 45
	v_cvt_pk_bf16_f32 v4, v2, s0
	s_nop 0
	v_or_b32_e32 v2, s5, v1
	v_lshlrev_b32_e32 v130, 11, v2
	v_lshl_add_u64 v[2:3], v[84:85], 0, v[130:131]
	global_store_short v[2:3], v4, off sc1
	global_load_ushort v2, v[134:135], off
	global_load_ushort v3, v[136:137], off offset:2048
	global_load_ushort v4, v[138:139], off
	global_load_ushort v5, v[140:141], off offset:2048
	global_load_ushort v6, v[142:143], off
	global_load_ushort v7, v[144:145], off offset:2048
	global_load_ushort v8, v[146:147], off
	global_load_ushort v9, v[148:149], off offset:2048
	v_readlane_b32 s5, v252, 46
	s_waitcnt vmcnt(7)
	v_lshlrev_b32_e32 v2, 16, v2
	v_fma_f32 v10, |v2|, s92, 1.0
	v_rcp_f32_e32 v10, v10
	v_mul_f32_e32 v12, v2, v2
	v_mul_f32_e32 v12, 0xbf38aa3b, v12
	v_exp_f32_e32 v12, v12
	v_fmamk_f32 v11, v10, 0x3f07dc22, v236
	v_fmaak_f32 v11, v10, v11, 0x3f35f0e3
	v_fmaak_f32 v11, v10, v11, 0xbe11a98e
	v_fmaak_f32 v11, v10, v11, 0x3e027906
	v_mul_f32_e32 v10, v10, v11
	v_mul_f32_e32 v10, v12, v10
	v_mul_f32_e32 v11, v10, v2
	v_fma_f32 v10, -v10, v2, v2
	v_cmp_gt_f32_e32 vcc, 0, v2
	s_waitcnt vmcnt(6)
	v_lshlrev_b32_e32 v2, 16, v3
	v_fma_f32 v3, |v2|, s92, 1.0
	v_rcp_f32_e32 v3, v3
	v_cndmask_b32_e32 v134, v10, v11, vcc
	v_mul_f32_e32 v11, v2, v2
	v_mul_f32_e32 v11, 0xbf38aa3b, v11
	v_fmamk_f32 v10, v3, 0x3f07dc22, v236
	v_fmaak_f32 v10, v3, v10, 0x3f35f0e3
	v_exp_f32_e32 v11, v11
	v_fmaak_f32 v10, v3, v10, 0xbe11a98e
	v_fmaak_f32 v10, v3, v10, 0x3e027906
	v_mul_f32_e32 v3, v3, v10
	v_mul_f32_e32 v3, v11, v3
	v_mul_f32_e32 v10, v3, v2
	v_fma_f32 v3, -v3, v2, v2
	v_cmp_gt_f32_e32 vcc, 0, v2
	s_waitcnt vmcnt(5)
	v_lshlrev_b32_e32 v2, 16, v4
	v_cndmask_b32_e32 v135, v3, v10, vcc
	v_fma_f32 v3, |v2|, s92, 1.0
	v_rcp_f32_e32 v3, v3
	v_mul_f32_e32 v10, v2, v2
	v_mul_f32_e32 v10, 0xbf38aa3b, v10
	v_exp_f32_e32 v10, v10
	v_fmamk_f32 v4, v3, 0x3f07dc22, v236
	v_fmaak_f32 v4, v3, v4, 0x3f35f0e3
	v_fmaak_f32 v4, v3, v4, 0xbe11a98e
	v_fmaak_f32 v4, v3, v4, 0x3e027906
	v_mul_f32_e32 v3, v3, v4
	v_mul_f32_e32 v3, v10, v3
	v_mul_f32_e32 v4, v3, v2
	v_fma_f32 v3, -v3, v2, v2
	v_cmp_gt_f32_e32 vcc, 0, v2
	s_waitcnt vmcnt(4)
	v_lshlrev_b32_e32 v2, 16, v5
	v_mul_f32_e32 v5, v2, v2
	v_cndmask_b32_e32 v136, v3, v4, vcc
	v_fma_f32 v3, |v2|, s92, 1.0
	v_rcp_f32_e32 v3, v3
	v_mul_f32_e32 v5, 0xbf38aa3b, v5
	v_exp_f32_e32 v5, v5
	v_cmp_gt_f32_e32 vcc, 0, v2
	v_fmamk_f32 v4, v3, 0x3f07dc22, v236
	v_fmaak_f32 v4, v3, v4, 0x3f35f0e3
	v_fmaak_f32 v4, v3, v4, 0xbe11a98e
	v_fmaak_f32 v4, v3, v4, 0x3e027906
	v_mul_f32_e32 v3, v3, v4
	v_mul_f32_e32 v3, v5, v3
	v_mul_f32_e32 v4, v3, v2
	v_fma_f32 v3, -v3, v2, v2
	s_waitcnt vmcnt(3)
	v_lshlrev_b32_e32 v2, 16, v6
	v_cndmask_b32_e32 v137, v3, v4, vcc
	v_fma_f32 v3, |v2|, s92, 1.0
	v_rcp_f32_e32 v3, v3
	v_mul_f32_e32 v5, v2, v2
	v_mul_f32_e32 v5, 0xbf38aa3b, v5
	v_exp_f32_e32 v5, v5
	v_fmamk_f32 v4, v3, 0x3f07dc22, v236
	v_fmaak_f32 v4, v3, v4, 0x3f35f0e3
	v_fmaak_f32 v4, v3, v4, 0xbe11a98e
	v_fmaak_f32 v4, v3, v4, 0x3e027906
	v_mul_f32_e32 v3, v3, v4
	v_mul_f32_e32 v3, v5, v3
	v_mul_f32_e32 v4, v3, v2
	v_fma_f32 v3, -v3, v2, v2
	v_cmp_gt_f32_e32 vcc, 0, v2
	s_waitcnt vmcnt(2)
	v_lshlrev_b32_e32 v2, 16, v7
	v_mul_f32_e32 v5, v2, v2
	v_cndmask_b32_e32 v138, v3, v4, vcc
	v_fma_f32 v3, |v2|, s92, 1.0
	v_rcp_f32_e32 v3, v3
	v_mul_f32_e32 v5, 0xbf38aa3b, v5
	v_exp_f32_e32 v5, v5
	v_cmp_gt_f32_e32 vcc, 0, v2
	v_fmamk_f32 v4, v3, 0x3f07dc22, v236
	v_fmaak_f32 v4, v3, v4, 0x3f35f0e3
	v_fmaak_f32 v4, v3, v4, 0xbe11a98e
	v_fmaak_f32 v4, v3, v4, 0x3e027906
	v_mul_f32_e32 v3, v3, v4
	v_mul_f32_e32 v3, v5, v3
	v_mul_f32_e32 v4, v3, v2
	v_fma_f32 v3, -v3, v2, v2
	s_waitcnt vmcnt(1)
	v_lshlrev_b32_e32 v2, 16, v8
	v_cndmask_b32_e32 v139, v3, v4, vcc
	v_fma_f32 v3, |v2|, s92, 1.0
	v_rcp_f32_e32 v3, v3
	v_mul_f32_e32 v5, v2, v2
	v_mul_f32_e32 v5, 0xbf38aa3b, v5
	v_exp_f32_e32 v5, v5
	v_fmamk_f32 v4, v3, 0x3f07dc22, v236
	v_fmaak_f32 v4, v3, v4, 0x3f35f0e3
	v_fmaak_f32 v4, v3, v4, 0xbe11a98e
	v_fmaak_f32 v4, v3, v4, 0x3e027906
	v_mul_f32_e32 v3, v3, v4
	v_mul_f32_e32 v3, v5, v3
	v_mul_f32_e32 v4, v3, v2
	v_fma_f32 v3, -v3, v2, v2
	v_cmp_gt_f32_e32 vcc, 0, v2
	s_waitcnt vmcnt(0)
	v_lshlrev_b32_e32 v2, 16, v9
	v_mul_f32_e32 v5, v2, v2
	v_cndmask_b32_e32 v140, v3, v4, vcc
	v_fma_f32 v3, |v2|, s92, 1.0
	v_rcp_f32_e32 v3, v3
	v_mul_f32_e32 v5, 0xbf38aa3b, v5
	v_exp_f32_e32 v5, v5
	v_cmp_gt_f32_e32 vcc, 0, v2
	v_fmamk_f32 v4, v3, 0x3f07dc22, v236
	v_fmaak_f32 v4, v3, v4, 0x3f35f0e3
	v_fmaak_f32 v4, v3, v4, 0xbe11a98e
	v_fmaak_f32 v4, v3, v4, 0x3e027906
	v_mul_f32_e32 v3, v3, v4
	v_mul_f32_e32 v3, v5, v3
	v_mul_f32_e32 v4, v3, v2
	v_fma_f32 v3, -v3, v2, v2
	v_cndmask_b32_e32 v141, v3, v4, vcc
	global_load_ushort v2, v[76:77], off
	global_load_ushort v3, v[78:79], off offset:2048
	global_load_ushort v4, v[80:81], off
	global_load_ushort v5, v[122:123], off offset:2048
	global_load_ushort v6, v[124:125], off
	global_load_ushort v7, v[126:127], off offset:2048
	global_load_ushort v8, v[128:129], off
	global_load_ushort v30, v[132:133], off offset:2048
	s_waitcnt vmcnt(7)
	v_lshlrev_b32_e32 v2, 16, v2
	v_fma_f32 v9, |v2|, s92, 1.0
	v_rcp_f32_e32 v9, v9
	v_mul_f32_e32 v11, v2, v2
	v_mul_f32_e32 v11, 0xbf38aa3b, v11
	v_exp_f32_e32 v11, v11
	v_fmamk_f32 v10, v9, 0x3f07dc22, v236
	v_fmaak_f32 v10, v9, v10, 0x3f35f0e3
	v_fmaak_f32 v10, v9, v10, 0xbe11a98e
	v_fmaak_f32 v10, v9, v10, 0x3e027906
	v_mul_f32_e32 v9, v9, v10
	v_mul_f32_e32 v9, v11, v9
	v_mul_f32_e32 v10, v9, v2
	v_fma_f32 v9, -v9, v2, v2
	v_cmp_gt_f32_e32 vcc, 0, v2
	s_waitcnt vmcnt(6)
	v_lshlrev_b32_e32 v2, 16, v3
	v_fma_f32 v3, |v2|, s92, 1.0
	v_rcp_f32_e32 v3, v3
	v_cndmask_b32_e32 v122, v9, v10, vcc
	v_mul_f32_e32 v10, v2, v2
	v_mul_f32_e32 v10, 0xbf38aa3b, v10
	v_fmamk_f32 v9, v3, 0x3f07dc22, v236
	v_fmaak_f32 v9, v3, v9, 0x3f35f0e3
	v_exp_f32_e32 v10, v10
	v_fmaak_f32 v9, v3, v9, 0xbe11a98e
	v_fmaak_f32 v9, v3, v9, 0x3e027906
	v_mul_f32_e32 v3, v3, v9
	v_mul_f32_e32 v3, v10, v3
	v_mul_f32_e32 v9, v3, v2
	v_fma_f32 v3, -v3, v2, v2
	v_cmp_gt_f32_e32 vcc, 0, v2
	s_waitcnt vmcnt(5)
	v_lshlrev_b32_e32 v2, 16, v4
	s_waitcnt vmcnt(1)
	v_lshlrev_b32_e32 v31, 16, v8
	v_cndmask_b32_e32 v123, v3, v9, vcc
	v_fma_f32 v3, |v2|, s92, 1.0
	v_rcp_f32_e32 v3, v3
	v_mul_f32_e32 v9, v2, v2
	v_mul_f32_e32 v9, 0xbf38aa3b, v9
	v_exp_f32_e32 v9, v9
	v_fmamk_f32 v4, v3, 0x3f07dc22, v236
	v_fmaak_f32 v4, v3, v4, 0x3f35f0e3
	v_fmaak_f32 v4, v3, v4, 0xbe11a98e
	v_fmaak_f32 v4, v3, v4, 0x3e027906
	v_mul_f32_e32 v3, v3, v4
	v_mul_f32_e32 v3, v9, v3
	v_mul_f32_e32 v4, v3, v2
	v_fma_f32 v3, -v3, v2, v2
	v_cmp_gt_f32_e32 vcc, 0, v2
	v_lshlrev_b32_e32 v2, 16, v5
	v_mul_f32_e32 v5, v2, v2
	v_cndmask_b32_e32 v124, v3, v4, vcc
	v_fma_f32 v3, |v2|, s92, 1.0
	v_rcp_f32_e32 v3, v3
	v_mul_f32_e32 v5, 0xbf38aa3b, v5
	v_exp_f32_e32 v5, v5
	v_cmp_gt_f32_e32 vcc, 0, v2
	v_fmamk_f32 v4, v3, 0x3f07dc22, v236
	v_fmaak_f32 v4, v3, v4, 0x3f35f0e3
	v_fmaak_f32 v4, v3, v4, 0xbe11a98e
	v_fmaak_f32 v4, v3, v4, 0x3e027906
	v_mul_f32_e32 v3, v3, v4
	v_mul_f32_e32 v3, v5, v3
	v_mul_f32_e32 v4, v3, v2
	v_fma_f32 v3, -v3, v2, v2
	v_lshlrev_b32_e32 v2, 16, v6
	v_cndmask_b32_e32 v125, v3, v4, vcc
	v_fma_f32 v3, |v2|, s92, 1.0
	v_rcp_f32_e32 v3, v3
	v_mul_f32_e32 v5, v2, v2
	v_mul_f32_e32 v5, 0xbf38aa3b, v5
	v_exp_f32_e32 v5, v5
	v_fmamk_f32 v4, v3, 0x3f07dc22, v236
	v_fmaak_f32 v4, v3, v4, 0x3f35f0e3
	v_fmaak_f32 v4, v3, v4, 0xbe11a98e
	v_fmaak_f32 v4, v3, v4, 0x3e027906
	v_mul_f32_e32 v3, v3, v4
	v_mul_f32_e32 v3, v5, v3
	v_mul_f32_e32 v4, v3, v2
	v_fma_f32 v3, -v3, v2, v2
	v_cmp_gt_f32_e32 vcc, 0, v2
	v_lshlrev_b32_e32 v2, 16, v7
	v_mul_f32_e32 v5, v2, v2
	v_cndmask_b32_e32 v126, v3, v4, vcc
	v_fma_f32 v3, |v2|, s92, 1.0
	v_rcp_f32_e32 v3, v3
	v_mul_f32_e32 v5, 0xbf38aa3b, v5
	v_exp_f32_e32 v5, v5
	v_cmp_gt_f32_e32 vcc, 0, v2
	v_fmamk_f32 v4, v3, 0x3f07dc22, v236
	v_fmaak_f32 v4, v3, v4, 0x3f35f0e3
	v_fmaak_f32 v4, v3, v4, 0xbe11a98e
	v_fmaak_f32 v4, v3, v4, 0x3e027906
	v_mul_f32_e32 v3, v3, v4
	v_mul_f32_e32 v3, v5, v3
	v_mul_f32_e32 v4, v3, v2
	v_fma_f32 v3, -v3, v2, v2
	v_fma_f32 v2, |v31|, s92, 1.0
	v_cndmask_b32_e32 v127, v3, v4, vcc
	v_rcp_f32_e32 v32, v2
	v_mfma_f32_32x32x16_bf16 v[2:17], v[22:25], v[62:65], 0
	v_mul_f32_e32 v23, v31, v31
	v_mul_f32_e32 v23, 0xbf38aa3b, v23
	v_fmamk_f32 v22, v32, 0x3f07dc22, v236
	v_fmaak_f32 v22, v32, v22, 0x3f35f0e3
	v_exp_f32_e32 v23, v23
	v_fmaak_f32 v22, v32, v22, 0xbe11a98e
	v_fmaak_f32 v22, v32, v22, 0x3e027906
	v_mfma_f32_32x32x16_bf16 v[2:17], v[18:21], v[58:61], v[2:17]
	v_mul_f32_e32 v22, v32, v22
	v_mul_f32_e32 v22, v23, v22
	v_mul_f32_e32 v23, v22, v31
	v_fma_f32 v22, -v22, v31, v31
	v_cmp_gt_f32_e32 vcc, 0, v31
	s_nop 1
	v_cndmask_b32_e32 v128, v22, v23, vcc
	s_waitcnt vmcnt(0)
	v_lshlrev_b32_e32 v22, 16, v30
	v_fma_f32 v23, |v22|, s92, 1.0
	v_rcp_f32_e32 v23, v23
	v_mfma_f32_32x32x16_bf16 v[2:17], v[66:69], v[54:57], v[2:17]
	v_mul_f32_e32 v19, v22, v22
	v_mul_f32_e32 v19, 0xbf38aa3b, v19
	v_fmamk_f32 v18, v23, 0x3f07dc22, v236
	v_fmaak_f32 v18, v23, v18, 0x3f35f0e3
	v_exp_f32_e32 v19, v19
	v_fmaak_f32 v18, v23, v18, 0xbe11a98e
	v_fmaak_f32 v18, v23, v18, 0x3e027906
	v_mul_f32_e32 v18, v23, v18
	v_mul_f32_e32 v18, v19, v18
	v_mfma_f32_32x32x16_bf16 v[2:17], v[26:29], v[50:53], v[2:17]
	v_mul_f32_e32 v19, v18, v22
	v_fma_f32 v18, -v18, v22, v22
	v_cmp_gt_f32_e32 vcc, 0, v22
	s_nop 1
	v_cndmask_b32_e32 v129, v18, v19, vcc
	global_load_dwordx4 v[18:21], v[70:71], off offset:2048
	global_load_dwordx4 v[78:81], v[70:71], off offset:3072
	global_load_dwordx4 v[74:77], v[82:83], off
	s_nop 0
	global_load_dwordx4 v[70:73], v[82:83], off offset:1024
	global_load_dwordx4 v[66:69], v[82:83], off offset:2048
	global_load_dwordx4 v[30:33], v[82:83], off offset:3072
	ds_read_b128 v[22:25], v150 offset:128
	ds_read_b128 v[26:29], v150 offset:160
	s_waitcnt lgkmcnt(1)
	v_add_f32_e32 v2, v2, v22
	v_or_b32_e32 v22, s5, v1
	v_mul_f32_e32 v2, v151, v2
	v_lshlrev_b32_e32 v130, 11, v22
	v_cvt_pk_bf16_f32 v2, v2, s0
	v_lshl_add_u64 v[82:83], v[84:85], 0, v[130:131]
	global_store_short v[82:83], v2, off sc1
	v_add_f32_e32 v2, v3, v23
	v_mul_f32_e32 v2, v152, v2
	v_readlane_b32 s5, v252, 47
	v_cvt_pk_bf16_f32 v22, v2, s0
	s_nop 0
	v_or_b32_e32 v2, s5, v1
	v_lshlrev_b32_e32 v130, 11, v2
	v_lshl_add_u64 v[2:3], v[84:85], 0, v[130:131]
	global_store_short v[2:3], v22, off sc1
	v_add_f32_e32 v2, v4, v24
	v_mul_f32_e32 v2, v153, v2
	v_readlane_b32 s5, v252, 48
	v_cvt_pk_bf16_f32 v4, v2, s0
	s_nop 0
	v_or_b32_e32 v2, s5, v1
	v_lshlrev_b32_e32 v130, 11, v2
	v_lshl_add_u64 v[2:3], v[84:85], 0, v[130:131]
	global_store_short v[2:3], v4, off sc1
	v_add_f32_e32 v2, v5, v25
	v_mul_f32_e32 v2, v154, v2
	v_readlane_b32 s5, v252, 49
	v_cvt_pk_bf16_f32 v4, v2, s0
	s_nop 0
	v_or_b32_e32 v2, s5, v1
	v_lshlrev_b32_e32 v130, 11, v2
	v_lshl_add_u64 v[2:3], v[84:85], 0, v[130:131]
	global_store_short v[2:3], v4, off sc1
	s_waitcnt lgkmcnt(0)
	v_add_f32_e32 v2, v6, v26
	v_mul_f32_e32 v2, v155, v2
	v_readlane_b32 s5, v252, 50
	v_cvt_pk_bf16_f32 v4, v2, s0
	s_nop 0
	v_or_b32_e32 v2, s5, v1
	v_lshlrev_b32_e32 v130, 11, v2
	v_lshl_add_u64 v[2:3], v[84:85], 0, v[130:131]
	global_store_short v[2:3], v4, off sc1
	v_add_f32_e32 v2, v7, v27
	v_mul_f32_e32 v2, v156, v2
	v_readlane_b32 s5, v252, 51
	v_cvt_pk_bf16_f32 v4, v2, s0
	s_nop 0
	v_or_b32_e32 v2, s5, v1
	v_lshlrev_b32_e32 v130, 11, v2
	v_lshl_add_u64 v[2:3], v[84:85], 0, v[130:131]
	global_store_short v[2:3], v4, off sc1
	v_add_f32_e32 v2, v8, v28
	v_mul_f32_e32 v2, v157, v2
	v_readlane_b32 s5, v252, 52
	v_cvt_pk_bf16_f32 v4, v2, s0
	s_nop 0
	v_or_b32_e32 v2, s5, v1
	v_lshlrev_b32_e32 v130, 11, v2
	v_lshl_add_u64 v[2:3], v[84:85], 0, v[130:131]
	global_store_short v[2:3], v4, off sc1
	v_add_f32_e32 v2, v9, v29
	v_mul_f32_e32 v2, v158, v2
	v_cvt_pk_bf16_f32 v8, v2, s0
	ds_read_b128 v[2:5], v150 offset:192
	v_readlane_b32 s5, v252, 53
	s_nop 1
	v_or_b32_e32 v6, s5, v1
	v_lshlrev_b32_e32 v130, 11, v6
	v_lshl_add_u64 v[6:7], v[84:85], 0, v[130:131]
	v_readlane_b32 s5, v252, 54
	global_store_short v[6:7], v8, off sc1
	ds_read_b128 v[6:9], v150 offset:224
	s_waitcnt lgkmcnt(1)
	v_add_f32_e32 v2, v10, v2
	v_or_b32_e32 v10, s5, v1
	v_mul_f32_e32 v2, v159, v2
	v_lshlrev_b32_e32 v130, 11, v10
	v_cvt_pk_bf16_f32 v2, v2, s0
	v_lshl_add_u64 v[22:23], v[84:85], 0, v[130:131]
	global_store_short v[22:23], v2, off sc1
	v_add_f32_e32 v2, v11, v3
	v_mul_f32_e32 v2, v160, v2
	v_readlane_b32 s5, v252, 55
	v_cvt_pk_bf16_f32 v10, v2, s0
	s_nop 0
	v_or_b32_e32 v2, s5, v1
	v_lshlrev_b32_e32 v130, 11, v2
	v_lshl_add_u64 v[2:3], v[84:85], 0, v[130:131]
	global_store_short v[2:3], v10, off sc1
	v_add_f32_e32 v2, v12, v4
	v_mul_f32_e32 v2, v161, v2
	v_readlane_b32 s5, v252, 56
	v_cvt_pk_bf16_f32 v4, v2, s0
	s_nop 0
	v_or_b32_e32 v2, s5, v1
	v_lshlrev_b32_e32 v130, 11, v2
	v_lshl_add_u64 v[2:3], v[84:85], 0, v[130:131]
	global_store_short v[2:3], v4, off sc1
	v_add_f32_e32 v2, v13, v5
	v_mul_f32_e32 v2, v162, v2
	v_readlane_b32 s5, v252, 57
	v_cvt_pk_bf16_f32 v4, v2, s0
	s_nop 0
	v_or_b32_e32 v2, s5, v1
	v_lshlrev_b32_e32 v130, 11, v2
	v_lshl_add_u64 v[2:3], v[84:85], 0, v[130:131]
	global_store_short v[2:3], v4, off sc1
	s_waitcnt lgkmcnt(0)
	v_add_f32_e32 v2, v14, v6
	v_mul_f32_e32 v2, v163, v2
	v_readlane_b32 s5, v252, 58
	v_cvt_pk_bf16_f32 v4, v2, s0
	s_nop 0
	v_or_b32_e32 v2, s5, v1
	v_lshlrev_b32_e32 v130, 11, v2
	v_lshl_add_u64 v[2:3], v[84:85], 0, v[130:131]
	global_store_short v[2:3], v4, off sc1
	v_add_f32_e32 v2, v15, v7
	v_mul_f32_e32 v2, v164, v2
	v_readlane_b32 s5, v252, 59
	v_cvt_pk_bf16_f32 v4, v2, s0
	s_nop 0
	v_or_b32_e32 v2, s5, v1
	v_lshlrev_b32_e32 v130, 11, v2
	v_lshl_add_u64 v[2:3], v[84:85], 0, v[130:131]
	global_store_short v[2:3], v4, off sc1
	v_add_f32_e32 v2, v16, v8
	v_mul_f32_e32 v2, v165, v2
	v_readlane_b32 s5, v252, 60
	v_cvt_pk_bf16_f32 v4, v2, s0
	s_nop 0
	v_or_b32_e32 v2, s5, v1
	v_lshlrev_b32_e32 v130, 11, v2
	v_lshl_add_u64 v[2:3], v[84:85], 0, v[130:131]
	global_store_short v[2:3], v4, off sc1
	v_add_f32_e32 v2, v17, v9
	v_mul_f32_e32 v2, v166, v2
	v_readlane_b32 s5, v252, 61
	v_cvt_pk_bf16_f32 v4, v2, s0
	s_nop 0
	v_or_b32_e32 v2, s5, v1
	v_lshlrev_b32_e32 v130, 11, v2
	v_lshl_add_u64 v[2:3], v[84:85], 0, v[130:131]
	global_store_short v[2:3], v4, off sc1
	global_load_ushort v4, v[116:117], off
	global_load_ushort v3, v[118:119], off offset:2048
	global_load_ushort v2, v[120:121], off
	global_load_dwordx4 v[24:27], v[88:89], off offset:3072
	v_readlane_b32 s5, v252, 62
	s_waitcnt vmcnt(3)
	v_lshlrev_b32_e32 v4, 16, v4
	v_fma_f32 v5, |v4|, s92, 1.0
	v_rcp_f32_e32 v5, v5
	v_mul_f32_e32 v7, v4, v4
	v_mul_f32_e32 v7, 0xbf38aa3b, v7
	v_exp_f32_e32 v7, v7
	v_fmamk_f32 v6, v5, 0x3f07dc22, v236
	v_fmaak_f32 v6, v5, v6, 0x3f35f0e3
	v_fmaak_f32 v6, v5, v6, 0xbe11a98e
	v_fmaak_f32 v6, v5, v6, 0x3e027906
	v_mul_f32_e32 v5, v5, v6
	v_mul_f32_e32 v5, v7, v5
	s_waitcnt vmcnt(2)
	v_lshlrev_b32_e32 v3, 16, v3
	v_mul_f32_e32 v6, v5, v4
	v_fma_f32 v5, -v5, v4, v4
	v_cmp_gt_f32_e32 vcc, 0, v4
	v_fma_f32 v4, |v3|, s92, 1.0
	v_rcp_f32_e32 v4, v4
	v_cndmask_b32_e32 v28, v5, v6, vcc
	v_mul_f32_e32 v6, v3, v3
	v_mul_f32_e32 v6, 0xbf38aa3b, v6
	v_fmamk_f32 v5, v4, 0x3f07dc22, v236
	v_fmaak_f32 v5, v4, v5, 0x3f35f0e3
	v_exp_f32_e32 v6, v6
	v_fmaak_f32 v5, v4, v5, 0xbe11a98e
	v_fmaak_f32 v5, v4, v5, 0x3e027906
	v_mul_f32_e32 v4, v4, v5
	v_mul_f32_e32 v4, v6, v4
	s_waitcnt vmcnt(1)
	v_lshlrev_b32_e32 v2, 16, v2
	v_mul_f32_e32 v5, v4, v3
	v_fma_f32 v4, -v4, v3, v3
	v_cmp_gt_f32_e32 vcc, 0, v3
	v_fma_f32 v3, |v2|, s92, 1.0
	v_rcp_f32_e32 v3, v3
	v_cndmask_b32_e32 v29, v4, v5, vcc
	v_mul_f32_e32 v5, v2, v2
	v_mul_f32_e32 v5, 0xbf38aa3b, v5
	v_fmamk_f32 v4, v3, 0x3f07dc22, v236
	v_fmaak_f32 v4, v3, v4, 0x3f35f0e3
	v_exp_f32_e32 v5, v5
	v_fmaak_f32 v4, v3, v4, 0xbe11a98e
	v_fmaak_f32 v4, v3, v4, 0x3e027906
	v_mul_f32_e32 v3, v3, v4
	v_mul_f32_e32 v3, v5, v3
	v_mul_f32_e32 v4, v3, v2
	v_fma_f32 v3, -v3, v2, v2
	v_cmp_gt_f32_e32 vcc, 0, v2
	s_nop 1
	v_cndmask_b32_e32 v82, v3, v4, vcc
	global_load_ushort v2, v[100:101], off offset:2048
	global_load_ushort v3, v[102:103], off
	global_load_ushort v4, v[104:105], off offset:2048
	global_load_ushort v5, v[106:107], off
	global_load_ushort v6, v[108:109], off offset:2048
	global_load_ushort v7, v[110:111], off
	global_load_ushort v8, v[112:113], off offset:2048
	global_load_ushort v9, v[114:115], off
	s_waitcnt vmcnt(7)
	v_lshlrev_b32_e32 v2, 16, v2
	v_fma_f32 v10, |v2|, s92, 1.0
	v_rcp_f32_e32 v10, v10
	v_mul_f32_e32 v12, v2, v2
	v_mul_f32_e32 v12, 0xbf38aa3b, v12
	v_exp_f32_e32 v12, v12
	v_fmamk_f32 v11, v10, 0x3f07dc22, v236
	v_fmaak_f32 v11, v10, v11, 0x3f35f0e3
	v_fmaak_f32 v11, v10, v11, 0xbe11a98e
	v_fmaak_f32 v11, v10, v11, 0x3e027906
	v_mul_f32_e32 v10, v10, v11
	v_mul_f32_e32 v10, v12, v10
	v_mul_f32_e32 v11, v10, v2
	v_fma_f32 v10, -v10, v2, v2
	v_cmp_gt_f32_e32 vcc, 0, v2
	s_waitcnt vmcnt(6)
	v_lshlrev_b32_e32 v2, 16, v3
	v_fma_f32 v3, |v2|, s92, 1.0
	v_rcp_f32_e32 v3, v3
	v_cndmask_b32_e32 v83, v10, v11, vcc
	v_mul_f32_e32 v11, v2, v2
	v_mul_f32_e32 v11, 0xbf38aa3b, v11
	v_fmamk_f32 v10, v3, 0x3f07dc22, v236
	v_fmaak_f32 v10, v3, v10, 0x3f35f0e3
	v_exp_f32_e32 v11, v11
	v_fmaak_f32 v10, v3, v10, 0xbe11a98e
	v_fmaak_f32 v10, v3, v10, 0x3e027906
	v_mul_f32_e32 v3, v3, v10
	v_mul_f32_e32 v3, v11, v3
	v_mul_f32_e32 v10, v3, v2
	v_fma_f32 v3, -v3, v2, v2
	v_cmp_gt_f32_e32 vcc, 0, v2
	s_waitcnt vmcnt(5)
	v_lshlrev_b32_e32 v2, 16, v4
	v_cndmask_b32_e32 v100, v3, v10, vcc
	v_fma_f32 v3, |v2|, s92, 1.0
	v_rcp_f32_e32 v3, v3
	v_mul_f32_e32 v10, v2, v2
	v_mul_f32_e32 v10, 0xbf38aa3b, v10
	v_exp_f32_e32 v10, v10
	v_fmamk_f32 v4, v3, 0x3f07dc22, v236
	v_fmaak_f32 v4, v3, v4, 0x3f35f0e3
	v_fmaak_f32 v4, v3, v4, 0xbe11a98e
	v_fmaak_f32 v4, v3, v4, 0x3e027906
	v_mul_f32_e32 v3, v3, v4
	v_mul_f32_e32 v3, v10, v3
	v_mul_f32_e32 v4, v3, v2
	v_fma_f32 v3, -v3, v2, v2
	v_cmp_gt_f32_e32 vcc, 0, v2
	s_waitcnt vmcnt(4)
	v_lshlrev_b32_e32 v2, 16, v5
	v_mul_f32_e32 v5, v2, v2
	v_cndmask_b32_e32 v101, v3, v4, vcc
	v_fma_f32 v3, |v2|, s92, 1.0
	v_rcp_f32_e32 v3, v3
	v_mul_f32_e32 v5, 0xbf38aa3b, v5
	v_exp_f32_e32 v5, v5
	v_cmp_gt_f32_e32 vcc, 0, v2
	v_fmamk_f32 v4, v3, 0x3f07dc22, v236
	v_fmaak_f32 v4, v3, v4, 0x3f35f0e3
	v_fmaak_f32 v4, v3, v4, 0xbe11a98e
	v_fmaak_f32 v4, v3, v4, 0x3e027906
	v_mul_f32_e32 v3, v3, v4
	v_mul_f32_e32 v3, v5, v3
	v_mul_f32_e32 v4, v3, v2
	v_fma_f32 v3, -v3, v2, v2
	s_waitcnt vmcnt(3)
	v_lshlrev_b32_e32 v2, 16, v6
	v_cndmask_b32_e32 v102, v3, v4, vcc
	v_fma_f32 v3, |v2|, s92, 1.0
	v_rcp_f32_e32 v3, v3
	v_mul_f32_e32 v5, v2, v2
	v_mul_f32_e32 v5, 0xbf38aa3b, v5
	v_exp_f32_e32 v5, v5
	v_fmamk_f32 v4, v3, 0x3f07dc22, v236
	v_fmaak_f32 v4, v3, v4, 0x3f35f0e3
	v_fmaak_f32 v4, v3, v4, 0xbe11a98e
	v_fmaak_f32 v4, v3, v4, 0x3e027906
	v_mul_f32_e32 v3, v3, v4
	v_mul_f32_e32 v3, v5, v3
	v_mul_f32_e32 v4, v3, v2
	v_fma_f32 v3, -v3, v2, v2
	v_cmp_gt_f32_e32 vcc, 0, v2
	s_waitcnt vmcnt(2)
	v_lshlrev_b32_e32 v2, 16, v7
	v_mul_f32_e32 v5, v2, v2
	v_cndmask_b32_e32 v103, v3, v4, vcc
	v_fma_f32 v3, |v2|, s92, 1.0
	v_rcp_f32_e32 v3, v3
	v_mul_f32_e32 v5, 0xbf38aa3b, v5
	v_exp_f32_e32 v5, v5
	v_cmp_gt_f32_e32 vcc, 0, v2
	v_fmamk_f32 v4, v3, 0x3f07dc22, v236
	v_fmaak_f32 v4, v3, v4, 0x3f35f0e3
	v_fmaak_f32 v4, v3, v4, 0xbe11a98e
	v_fmaak_f32 v4, v3, v4, 0x3e027906
	v_mul_f32_e32 v3, v3, v4
	v_mul_f32_e32 v3, v5, v3
	v_mul_f32_e32 v4, v3, v2
	v_fma_f32 v3, -v3, v2, v2
	s_waitcnt vmcnt(1)
	v_lshlrev_b32_e32 v2, 16, v8
	v_cndmask_b32_e32 v104, v3, v4, vcc
	v_fma_f32 v3, |v2|, s92, 1.0
	v_rcp_f32_e32 v3, v3
	v_mul_f32_e32 v5, v2, v2
	v_mul_f32_e32 v5, 0xbf38aa3b, v5
	v_exp_f32_e32 v5, v5
	v_fmamk_f32 v4, v3, 0x3f07dc22, v236
	v_fmaak_f32 v4, v3, v4, 0x3f35f0e3
	v_fmaak_f32 v4, v3, v4, 0xbe11a98e
	v_fmaak_f32 v4, v3, v4, 0x3e027906
	v_mul_f32_e32 v3, v3, v4
	v_mul_f32_e32 v3, v5, v3
	v_mul_f32_e32 v4, v3, v2
	v_fma_f32 v3, -v3, v2, v2
	v_cmp_gt_f32_e32 vcc, 0, v2
	s_waitcnt vmcnt(0)
	v_lshlrev_b32_e32 v2, 16, v9
	v_mul_f32_e32 v5, v2, v2
	v_cndmask_b32_e32 v105, v3, v4, vcc
	v_fma_f32 v3, |v2|, s92, 1.0
	v_rcp_f32_e32 v3, v3
	v_mul_f32_e32 v5, 0xbf38aa3b, v5
	v_exp_f32_e32 v5, v5
	v_cmp_gt_f32_e32 vcc, 0, v2
	v_fmamk_f32 v4, v3, 0x3f07dc22, v236
	v_fmaak_f32 v4, v3, v4, 0x3f35f0e3
	v_fmaak_f32 v4, v3, v4, 0xbe11a98e
	v_fmaak_f32 v4, v3, v4, 0x3e027906
	v_mul_f32_e32 v3, v3, v4
	v_mul_f32_e32 v3, v5, v3
	v_mul_f32_e32 v4, v3, v2
	v_fma_f32 v3, -v3, v2, v2
	v_cndmask_b32_e32 v106, v3, v4, vcc
	global_load_ushort v2, v[90:91], off offset:2048
	global_load_ushort v3, v[92:93], off
	global_load_ushort v4, v[94:95], off offset:2048
	global_load_ushort v5, v[96:97], off
	global_load_ushort v6, v[98:99], off offset:2048
	s_waitcnt vmcnt(4)
	v_lshlrev_b32_e32 v2, 16, v2
	v_fma_f32 v7, |v2|, s92, 1.0
	v_rcp_f32_e32 v7, v7
	v_mul_f32_e32 v9, v2, v2
	v_mul_f32_e32 v9, 0xbf38aa3b, v9
	v_exp_f32_e32 v9, v9
	v_fmamk_f32 v8, v7, 0x3f07dc22, v236
	v_fmaak_f32 v8, v7, v8, 0x3f35f0e3
	v_fmaak_f32 v8, v7, v8, 0xbe11a98e
	v_fmaak_f32 v8, v7, v8, 0x3e027906
	v_mul_f32_e32 v7, v7, v8
	v_mul_f32_e32 v7, v9, v7
	v_mul_f32_e32 v8, v7, v2
	v_fma_f32 v7, -v7, v2, v2
	v_cmp_gt_f32_e32 vcc, 0, v2
	s_waitcnt vmcnt(3)
	v_lshlrev_b32_e32 v2, 16, v3
	v_fma_f32 v3, |v2|, s92, 1.0
	v_rcp_f32_e32 v3, v3
	v_cndmask_b32_e32 v107, v7, v8, vcc
	v_mul_f32_e32 v8, v2, v2
	v_mul_f32_e32 v8, 0xbf38aa3b, v8
	v_fmamk_f32 v7, v3, 0x3f07dc22, v236
	v_fmaak_f32 v7, v3, v7, 0x3f35f0e3
	v_exp_f32_e32 v8, v8
	v_fmaak_f32 v7, v3, v7, 0xbe11a98e
	v_fmaak_f32 v7, v3, v7, 0x3e027906
	v_mul_f32_e32 v3, v3, v7
	v_mul_f32_e32 v3, v8, v3
	v_mul_f32_e32 v7, v3, v2
	v_fma_f32 v3, -v3, v2, v2
	v_cmp_gt_f32_e32 vcc, 0, v2
	s_waitcnt vmcnt(2)
	v_lshlrev_b32_e32 v2, 16, v4
	v_mfma_f32_32x32x16_bf16 v[8:23], v[18:21], v[62:65], 0
	v_cndmask_b32_e32 v108, v3, v7, vcc
	v_fma_f32 v3, |v2|, s92, 1.0
	v_rcp_f32_e32 v3, v3
	v_mul_f32_e32 v7, v2, v2
	v_mul_f32_e32 v7, 0xbf38aa3b, v7
	v_exp_f32_e32 v7, v7
	v_fmamk_f32 v4, v3, 0x3f07dc22, v236
	v_fmaak_f32 v4, v3, v4, 0x3f35f0e3
	v_fmaak_f32 v4, v3, v4, 0xbe11a98e
	v_fmaak_f32 v4, v3, v4, 0x3e027906
	v_mul_f32_e32 v3, v3, v4
	v_mul_f32_e32 v3, v7, v3
	v_mul_f32_e32 v4, v3, v2
	v_fma_f32 v3, -v3, v2, v2
	v_cmp_gt_f32_e32 vcc, 0, v2
	s_waitcnt vmcnt(1)
	v_lshlrev_b32_e32 v2, 16, v5
	v_mul_f32_e32 v5, v2, v2
	v_cndmask_b32_e32 v109, v3, v4, vcc
	v_fma_f32 v3, |v2|, s92, 1.0
	v_rcp_f32_e32 v3, v3
	v_mul_f32_e32 v5, 0xbf38aa3b, v5
	v_exp_f32_e32 v5, v5
	v_cmp_gt_f32_e32 vcc, 0, v2
	v_fmamk_f32 v4, v3, 0x3f07dc22, v236
	v_fmaak_f32 v4, v3, v4, 0x3f35f0e3
	v_fmaak_f32 v4, v3, v4, 0xbe11a98e
	v_fmaak_f32 v4, v3, v4, 0x3e027906
	v_mul_f32_e32 v3, v3, v4
	v_mul_f32_e32 v3, v5, v3
	v_mul_f32_e32 v4, v3, v2
	v_fma_f32 v3, -v3, v2, v2
	s_waitcnt vmcnt(0)
	v_lshlrev_b32_e32 v2, 16, v6
	v_cndmask_b32_e32 v110, v3, v4, vcc
	v_fma_f32 v3, |v2|, s92, 1.0
	v_rcp_f32_e32 v3, v3
	v_mul_f32_e32 v5, v2, v2
	v_mul_f32_e32 v5, 0xbf38aa3b, v5
	v_mfma_f32_32x32x16_bf16 v[8:23], v[78:81], v[58:61], v[8:23]
	v_fmamk_f32 v4, v3, 0x3f07dc22, v236
	v_fmaak_f32 v4, v3, v4, 0x3f35f0e3
	v_exp_f32_e32 v5, v5
	v_fmaak_f32 v4, v3, v4, 0xbe11a98e
	v_fmaak_f32 v4, v3, v4, 0x3e027906
	v_mul_f32_e32 v3, v3, v4
	v_mul_f32_e32 v3, v5, v3
	v_mul_f32_e32 v4, v3, v2
	v_fma_f32 v3, -v3, v2, v2
	v_cmp_gt_f32_e32 vcc, 0, v2
	v_mfma_f32_32x32x16_bf16 v[8:23], v[74:77], v[54:57], v[8:23]
	s_nop 0
	v_cndmask_b32_e32 v111, v3, v4, vcc
	global_load_dwordx4 v[2:5], v[86:87], off offset:-4096
	v_mfma_f32_32x32x16_bf16 v[8:23], v[70:73], v[50:53], v[8:23]
	v_mfma_f32_32x32x16_bf16 v[8:23], v[66:69], v[46:49], v[8:23]
	global_load_dwordx4 v[66:69], v[88:89], off offset:1024
	global_load_dwordx4 v[70:73], v[88:89], off offset:2048
	global_load_dwordx4 v[74:77], v[86:87], off
	global_load_dwordx4 v[78:81], v[86:87], off offset:1024
	s_nop 0
	global_load_dwordx4 v[88:91], v[86:87], off offset:2048
	global_load_dwordx4 v[92:95], v[86:87], off offset:3072
	ds_read_b128 v[96:99], v150 offset:256
	v_mfma_f32_32x32x16_bf16 v[8:23], v[30:33], v[42:45], v[8:23]
	ds_read_b128 v[30:33], v150 offset:288
	s_waitcnt lgkmcnt(1)
	s_nop 9
	v_add_f32_e32 v6, v8, v96
	v_mul_f32_e32 v6, v134, v6
	v_cvt_pk_bf16_f32 v8, v6, s0
	v_or_b32_e32 v6, s5, v1
	v_lshlrev_b32_e32 v130, 11, v6
	v_lshl_add_u64 v[6:7], v[84:85], 0, v[130:131]
	global_store_short v[6:7], v8, off sc1
	v_add_f32_e32 v6, v9, v97
	v_mul_f32_e32 v6, v135, v6
	v_readlane_b32 s5, v252, 63
	v_cvt_pk_bf16_f32 v8, v6, s0
	s_nop 0
	v_or_b32_e32 v6, s5, v1
	v_lshlrev_b32_e32 v130, 11, v6
	v_lshl_add_u64 v[6:7], v[84:85], 0, v[130:131]
	global_store_short v[6:7], v8, off sc1
	v_add_f32_e32 v6, v10, v98
	v_mul_f32_e32 v6, v136, v6
	v_readlane_b32 s5, v253, 0
	v_cvt_pk_bf16_f32 v8, v6, s0
	s_nop 0
	v_or_b32_e32 v6, s5, v1
	v_lshlrev_b32_e32 v130, 11, v6
	v_lshl_add_u64 v[6:7], v[84:85], 0, v[130:131]
	global_store_short v[6:7], v8, off sc1
	v_add_f32_e32 v6, v11, v99
	v_mul_f32_e32 v6, v137, v6
	v_readlane_b32 s5, v253, 1
	v_cvt_pk_bf16_f32 v8, v6, s0
	ds_read_b128 v[96:99], v150 offset:352
	v_or_b32_e32 v6, s5, v1
	v_lshlrev_b32_e32 v130, 11, v6
	v_lshl_add_u64 v[6:7], v[84:85], 0, v[130:131]
	global_store_short v[6:7], v8, off sc1
	s_waitcnt lgkmcnt(1)
	v_add_f32_e32 v6, v12, v30
	v_mul_f32_e32 v6, v138, v6
	v_readlane_b32 s5, v253, 2
	v_cvt_pk_bf16_f32 v8, v6, s0
	s_nop 0
	v_or_b32_e32 v6, s5, v1
	v_lshlrev_b32_e32 v130, 11, v6
	v_lshl_add_u64 v[6:7], v[84:85], 0, v[130:131]
	global_store_short v[6:7], v8, off sc1
	v_add_f32_e32 v6, v13, v31
	v_mul_f32_e32 v6, v139, v6
	v_readlane_b32 s5, v253, 3
	v_cvt_pk_bf16_f32 v8, v6, s0
	s_nop 0
	v_or_b32_e32 v6, s5, v1
	v_lshlrev_b32_e32 v130, 11, v6
	v_lshl_add_u64 v[6:7], v[84:85], 0, v[130:131]
	global_store_short v[6:7], v8, off sc1
	v_add_f32_e32 v6, v14, v32
	v_mul_f32_e32 v6, v140, v6
	v_readlane_b32 s5, v253, 4
	v_cvt_pk_bf16_f32 v8, v6, s0
	s_nop 0
	v_or_b32_e32 v6, s5, v1
	v_lshlrev_b32_e32 v130, 11, v6
	v_lshl_add_u64 v[6:7], v[84:85], 0, v[130:131]
	global_store_short v[6:7], v8, off sc1
	v_add_f32_e32 v6, v15, v33
	ds_read_b128 v[30:33], v150 offset:320
	v_mul_f32_e32 v6, v141, v6
	v_readlane_b32 s5, v253, 5
	v_cvt_pk_bf16_f32 v8, v6, s0
	s_waitcnt lgkmcnt(0)
	v_add_f32_e32 v18, v18, v32
	v_or_b32_e32 v6, s5, v1
	v_lshlrev_b32_e32 v130, 11, v6
	v_lshl_add_u64 v[6:7], v[84:85], 0, v[130:131]
	global_store_short v[6:7], v8, off sc1
	v_add_f32_e32 v6, v16, v30
	v_mul_f32_e32 v6, v122, v6
	v_readlane_b32 s5, v253, 6
	v_cvt_pk_bf16_f32 v8, v6, s0
	v_mul_f32_e32 v18, v124, v18
	v_or_b32_e32 v6, s5, v1
	v_lshlrev_b32_e32 v130, 11, v6
	v_lshl_add_u64 v[6:7], v[84:85], 0, v[130:131]
	global_store_short v[6:7], v8, off sc1
	v_add_f32_e32 v6, v17, v31
	v_mul_f32_e32 v30, v123, v6
	s_waitcnt vmcnt(15)
	v_mfma_f32_32x32x16_bf16 v[2:17], v[2:5], v[62:65], 0
	v_readlane_b32 s5, v253, 7
	v_cvt_pk_bf16_f32 v62, v30, s0
	v_cvt_pk_bf16_f32 v18, v18, s0
	v_or_b32_e32 v30, s5, v1
	v_lshlrev_b32_e32 v130, 11, v30
	v_lshl_add_u64 v[30:31], v[84:85], 0, v[130:131]
	v_readlane_b32 s5, v253, 8
	s_waitcnt vmcnt(14)
	v_mfma_f32_32x32x16_bf16 v[2:17], v[66:69], v[58:61], v[2:17]
	global_store_short v[30:31], v62, off sc1
	v_or_b32_e32 v30, s5, v1
	v_lshlrev_b32_e32 v130, 11, v30
	v_lshl_add_u64 v[30:31], v[84:85], 0, v[130:131]
	global_store_short v[30:31], v18, off sc1
	v_add_f32_e32 v18, v19, v33
	v_mul_f32_e32 v18, v125, v18
	s_waitcnt vmcnt(15)
	v_mfma_f32_32x32x16_bf16 v[2:17], v[70:73], v[54:57], v[2:17]
	v_readlane_b32 s5, v253, 9
	v_cvt_pk_bf16_f32 v30, v18, s0
	s_nop 0
	v_or_b32_e32 v18, s5, v1
	v_lshlrev_b32_e32 v130, 11, v18
	v_lshl_add_u64 v[18:19], v[84:85], 0, v[130:131]
	global_store_short v[18:19], v30, off sc1
	v_mfma_f32_32x32x16_bf16 v[2:17], v[24:27], v[50:53], v[2:17]
	v_add_f32_e32 v18, v20, v96
	v_mul_f32_e32 v18, v126, v18
	v_readlane_b32 s5, v253, 10
	v_cvt_pk_bf16_f32 v20, v18, s0
	s_nop 0
	v_or_b32_e32 v18, s5, v1
	v_lshlrev_b32_e32 v130, 11, v18
	s_waitcnt vmcnt(15)
	v_mfma_f32_32x32x16_bf16 v[2:17], v[74:77], v[46:49], v[2:17]
	v_lshl_add_u64 v[18:19], v[84:85], 0, v[130:131]
	global_store_short v[18:19], v20, off sc1
	v_add_f32_e32 v18, v21, v97
	v_mul_f32_e32 v18, v127, v18
	v_readlane_b32 s5, v253, 11
	v_cvt_pk_bf16_f32 v20, v18, s0
	s_waitcnt vmcnt(15)
	v_mfma_f32_32x32x16_bf16 v[2:17], v[78:81], v[42:45], v[2:17]
	v_or_b32_e32 v18, s5, v1
	v_lshlrev_b32_e32 v130, 11, v18
	v_lshl_add_u64 v[18:19], v[84:85], 0, v[130:131]
	global_store_short v[18:19], v20, off sc1
	v_add_f32_e32 v18, v22, v98
	v_mul_f32_e32 v18, v128, v18
	v_readlane_b32 s5, v253, 12
	s_waitcnt vmcnt(15)
	v_mfma_f32_32x32x16_bf16 v[2:17], v[88:91], v[38:41], v[2:17]
	v_cvt_pk_bf16_f32 v20, v18, s0
	v_or_b32_e32 v18, s5, v1
	v_lshlrev_b32_e32 v130, 11, v18
	v_lshl_add_u64 v[18:19], v[84:85], 0, v[130:131]
	global_store_short v[18:19], v20, off sc1
	v_add_f32_e32 v18, v23, v99
	v_mul_f32_e32 v18, v129, v18
	v_readlane_b32 s5, v253, 13
	v_cvt_pk_bf16_f32 v20, v18, s0
	s_waitcnt vmcnt(15)
	v_mfma_f32_32x32x16_bf16 v[2:17], v[92:95], v[34:37], v[2:17]
	v_or_b32_e32 v18, s5, v1
	v_lshlrev_b32_e32 v130, 11, v18
	v_lshl_add_u64 v[18:19], v[84:85], 0, v[130:131]
	global_store_short v[18:19], v20, off sc1
	ds_read_b128 v[18:21], v150 offset:384
	ds_read_b128 v[22:25], v150 offset:416
	v_readlane_b32 s5, v253, 14
	s_waitcnt lgkmcnt(1)
	s_nop 3
	v_add_f32_e32 v2, v2, v18
	v_or_b32_e32 v18, s5, v1
	v_mul_f32_e32 v2, v28, v2
	v_lshlrev_b32_e32 v130, 11, v18
	v_cvt_pk_bf16_f32 v2, v2, s0
	v_lshl_add_u64 v[26:27], v[84:85], 0, v[130:131]
	global_store_short v[26:27], v2, off sc1
	v_add_f32_e32 v2, v3, v19
	v_mul_f32_e32 v2, v29, v2
	v_readlane_b32 s5, v253, 15
	v_cvt_pk_bf16_f32 v18, v2, s0
	s_nop 0
	v_or_b32_e32 v2, s5, v1
	v_lshlrev_b32_e32 v130, 11, v2
	v_lshl_add_u64 v[2:3], v[84:85], 0, v[130:131]
	global_store_short v[2:3], v18, off sc1
	v_add_f32_e32 v2, v4, v20
	v_mul_f32_e32 v2, v82, v2
	v_readlane_b32 s5, v253, 16
	v_cvt_pk_bf16_f32 v4, v2, s0
	s_nop 0
	v_or_b32_e32 v2, s5, v1
	v_lshlrev_b32_e32 v130, 11, v2
	v_lshl_add_u64 v[2:3], v[84:85], 0, v[130:131]
	global_store_short v[2:3], v4, off sc1
	v_add_f32_e32 v2, v5, v21
	v_mul_f32_e32 v2, v83, v2
	v_readlane_b32 s5, v253, 17
	v_cvt_pk_bf16_f32 v4, v2, s0
	s_nop 0
	v_or_b32_e32 v2, s5, v1
	v_lshlrev_b32_e32 v130, 11, v2
	v_lshl_add_u64 v[2:3], v[84:85], 0, v[130:131]
	global_store_short v[2:3], v4, off sc1
	s_waitcnt lgkmcnt(0)
	v_add_f32_e32 v2, v6, v22
	v_mul_f32_e32 v2, v100, v2
	v_readlane_b32 s5, v253, 18
	v_cvt_pk_bf16_f32 v4, v2, s0
	s_nop 0
	v_or_b32_e32 v2, s5, v1
	v_lshlrev_b32_e32 v130, 11, v2
	v_lshl_add_u64 v[2:3], v[84:85], 0, v[130:131]
	global_store_short v[2:3], v4, off sc1
	v_add_f32_e32 v2, v7, v23
	v_mul_f32_e32 v2, v101, v2
	v_readlane_b32 s5, v253, 19
	v_cvt_pk_bf16_f32 v4, v2, s0
	s_nop 0
	v_or_b32_e32 v2, s5, v1
	v_lshlrev_b32_e32 v130, 11, v2
	v_lshl_add_u64 v[2:3], v[84:85], 0, v[130:131]
	global_store_short v[2:3], v4, off sc1
	v_add_f32_e32 v2, v8, v24
	v_mul_f32_e32 v2, v102, v2
	v_readlane_b32 s5, v253, 20
	v_cvt_pk_bf16_f32 v4, v2, s0
	s_nop 0
	v_or_b32_e32 v2, s5, v1
	v_lshlrev_b32_e32 v130, 11, v2
	v_lshl_add_u64 v[2:3], v[84:85], 0, v[130:131]
	global_store_short v[2:3], v4, off sc1
	v_add_f32_e32 v2, v9, v25
	v_mul_f32_e32 v2, v103, v2
	v_cvt_pk_bf16_f32 v8, v2, s0
	ds_read_b128 v[2:5], v150 offset:448
	v_readlane_b32 s5, v253, 21
	s_nop 1
	v_or_b32_e32 v6, s5, v1
	v_lshlrev_b32_e32 v130, 11, v6
	v_lshl_add_u64 v[6:7], v[84:85], 0, v[130:131]
	v_readlane_b32 s5, v253, 22
	global_store_short v[6:7], v8, off sc1
	ds_read_b128 v[6:9], v150 offset:480
	s_waitcnt lgkmcnt(1)
	v_add_f32_e32 v2, v10, v2
	v_or_b32_e32 v10, s5, v1
	v_mul_f32_e32 v2, v104, v2
	v_lshlrev_b32_e32 v130, 11, v10
	v_cvt_pk_bf16_f32 v2, v2, s0
	v_lshl_add_u64 v[18:19], v[84:85], 0, v[130:131]
	global_store_short v[18:19], v2, off sc1
	v_add_f32_e32 v2, v11, v3
	v_mul_f32_e32 v2, v105, v2
	v_readlane_b32 s5, v253, 23
	v_cvt_pk_bf16_f32 v10, v2, s0
	s_nop 0
	v_or_b32_e32 v2, s5, v1
	v_lshlrev_b32_e32 v130, 11, v2
	v_lshl_add_u64 v[2:3], v[84:85], 0, v[130:131]
	global_store_short v[2:3], v10, off sc1
	v_add_f32_e32 v2, v12, v4
	v_mul_f32_e32 v2, v106, v2
	v_readlane_b32 s5, v253, 24
	v_cvt_pk_bf16_f32 v4, v2, s0
	s_nop 0
	v_or_b32_e32 v2, s5, v1
	v_lshlrev_b32_e32 v130, 11, v2
	v_lshl_add_u64 v[2:3], v[84:85], 0, v[130:131]
	global_store_short v[2:3], v4, off sc1
	v_add_f32_e32 v2, v13, v5
	v_mul_f32_e32 v2, v107, v2
	v_readlane_b32 s5, v253, 25
	v_cvt_pk_bf16_f32 v4, v2, s0
	s_nop 0
	v_or_b32_e32 v2, s5, v1
	v_lshlrev_b32_e32 v130, 11, v2
	v_lshl_add_u64 v[2:3], v[84:85], 0, v[130:131]
	global_store_short v[2:3], v4, off sc1
	s_waitcnt lgkmcnt(0)
	v_add_f32_e32 v2, v14, v6
	v_mul_f32_e32 v2, v108, v2
	v_readlane_b32 s5, v253, 26
	v_cvt_pk_bf16_f32 v4, v2, s0
	s_nop 0
	v_or_b32_e32 v2, s5, v1
	v_lshlrev_b32_e32 v130, 11, v2
	v_lshl_add_u64 v[2:3], v[84:85], 0, v[130:131]
	global_store_short v[2:3], v4, off sc1
	v_add_f32_e32 v2, v15, v7
	v_mul_f32_e32 v2, v109, v2
	v_readlane_b32 s5, v253, 27
	v_cvt_pk_bf16_f32 v4, v2, s0
	s_nop 0
	v_or_b32_e32 v2, s5, v1
	v_lshlrev_b32_e32 v130, 11, v2
	v_lshl_add_u64 v[2:3], v[84:85], 0, v[130:131]
	global_store_short v[2:3], v4, off sc1
	v_add_f32_e32 v2, v16, v8
	v_mul_f32_e32 v2, v110, v2
	v_readlane_b32 s5, v253, 28
	v_cvt_pk_bf16_f32 v4, v2, s0
	s_nop 0
	v_or_b32_e32 v2, s5, v1
	v_lshlrev_b32_e32 v130, 11, v2
	v_lshl_add_u64 v[2:3], v[84:85], 0, v[130:131]
	v_readlane_b32 s5, v253, 29
	global_store_short v[2:3], v4, off sc1
	v_add_f32_e32 v2, v17, v9
	v_or_b32_e32 v1, s5, v1
	v_mul_f32_e32 v2, v111, v2
	v_lshlrev_b32_e32 v130, 11, v1
	v_cvt_pk_bf16_f32 v4, v2, s0
	v_lshl_add_u64 v[2:3], v[84:85], 0, v[130:131]
	global_store_short v[2:3], v4, off sc1
	s_barrier

.LBB0_317:
	s_andn2_b64 vcc, exec, s[28:29]
	s_cbranch_vccnz .LBB0_345
	s_branch .LBB0_345
	s_waitcnt vmcnt(0)
	v_mov_b32_e32 v1, v242
	s_load_dwordx8 s[44:51], s[0:1], 0x38
	v_mov_b32_e32 v2, 2
	v_lshlrev_b32_sdwa v130, v2, v1 dst_sel:DWORD dst_unused:UNUSED_PAD src0_sel:DWORD src1_sel:BYTE_0
	v_readlane_b32 s8, v254, 39
	v_readlane_b32 s9, v254, 40
	s_waitcnt lgkmcnt(0)
	v_lshl_add_u64 v[2:3], s[44:45], 0, v[130:131]
	v_lshl_add_u64 v[4:5], v[2:3], 0, s[62:63]
	global_load_dword v42, v[4:5], off
	v_lshl_add_u64 v[4:5], v[2:3], 0, s[8:9]
	v_readlane_b32 s8, v254, 41
	v_readlane_b32 s9, v254, 42
	global_load_dword v43, v[4:5], off
	v_readfirstlane_b32 s5, v1
	v_lshl_add_u64 v[4:5], v[2:3], 0, s[8:9]
	v_readlane_b32 s8, v254, 43
	v_readlane_b32 s9, v254, 44
	global_load_dword v45, v[4:5], off
	s_ashr_i32 s6, s5, 6
	v_lshl_add_u64 v[4:5], v[2:3], 0, s[8:9]
	v_readlane_b32 s8, v254, 45
	v_readlane_b32 s9, v254, 46
	global_load_dword v47, v[4:5], off
	v_mov_b32_e32 v10, s46
	v_lshl_add_u64 v[4:5], v[2:3], 0, s[8:9]
	v_readlane_b32 s8, v254, 47
	v_readlane_b32 s9, v254, 48
	global_load_dword v49, v[4:5], off
	v_mov_b32_e32 v11, s47
	v_lshl_add_u64 v[4:5], v[2:3], 0, s[8:9]
	v_readlane_b32 s8, v254, 49
	v_readlane_b32 s9, v254, 50
	global_load_dword v51, v[4:5], off
	s_mov_b32 s16, s67
	v_lshl_add_u64 v[4:5], v[2:3], 0, s[8:9]
	v_readlane_b32 s8, v254, 51
	v_readlane_b32 s9, v254, 52
	global_load_dword v53, v[4:5], off
	s_mov_b32 s14, s72
	v_lshl_add_u64 v[4:5], v[2:3], 0, s[8:9]
	v_readlane_b32 s8, v254, 53
	v_readlane_b32 s9, v254, 54
	global_load_dword v55, v[4:5], off
	v_readlane_b32 s64, v253, 34
	v_lshl_add_u64 v[4:5], v[2:3], 0, s[8:9]
	v_readlane_b32 s8, v254, 55
	v_readlane_b32 s9, v254, 56
	global_load_dword v57, v[4:5], off
	s_nop 0
	v_lshl_add_u64 v[4:5], v[2:3], 0, s[8:9]
	v_readlane_b32 s8, v254, 57
	v_readlane_b32 s9, v254, 58
	global_load_dword v59, v[4:5], off
	s_nop 0
	v_lshl_add_u64 v[4:5], v[2:3], 0, s[8:9]
	v_readlane_b32 s8, v254, 59
	v_readlane_b32 s9, v254, 60
	global_load_dword v61, v[4:5], off
	s_nop 0
	v_lshl_add_u64 v[4:5], v[2:3], 0, s[8:9]
	v_readlane_b32 s8, v254, 61
	v_readlane_b32 s9, v254, 62
	global_load_dword v63, v[4:5], off
	s_nop 0
	v_lshl_add_u64 v[4:5], v[2:3], 0, s[8:9]
	v_readlane_b32 s8, v254, 63
	v_readlane_b32 s9, v255, 0
	global_load_dword v65, v[4:5], off
	s_nop 0
	v_lshl_add_u64 v[4:5], v[2:3], 0, s[8:9]
	v_readlane_b32 s8, v255, 1
	v_readlane_b32 s9, v255, 2
	global_load_dword v67, v[4:5], off
	s_nop 0
	v_lshl_add_u64 v[4:5], v[2:3], 0, s[8:9]
	v_readlane_b32 s8, v255, 3
	v_readlane_b32 s9, v255, 4
	global_load_dword v69, v[4:5], off
	s_nop 0
	v_lshl_add_u64 v[4:5], v[2:3], 0, s[8:9]
	v_readlane_b32 s8, v255, 5
	v_readlane_b32 s9, v255, 6
	global_load_dword v71, v[4:5], off
	s_nop 0
	v_lshl_add_u64 v[4:5], v[2:3], 0, s[8:9]
	v_readlane_b32 s8, v255, 7
	v_readlane_b32 s9, v255, 8
	global_load_dword v73, v[4:5], off
	s_nop 0
	v_lshl_add_u64 v[4:5], v[2:3], 0, s[8:9]
	v_readlane_b32 s8, v255, 9
	v_readlane_b32 s9, v255, 10
	global_load_dword v75, v[4:5], off
	s_nop 0
	v_lshl_add_u64 v[4:5], v[2:3], 0, s[8:9]
	v_readlane_b32 s8, v255, 11
	v_readlane_b32 s9, v255, 12
	global_load_dword v77, v[4:5], off
	s_nop 0
	v_lshl_add_u64 v[4:5], v[2:3], 0, s[8:9]
	v_readlane_b32 s8, v255, 13
	v_readlane_b32 s9, v255, 14
	global_load_dword v79, v[4:5], off
	s_nop 0
	v_lshl_add_u64 v[4:5], v[2:3], 0, s[8:9]
	v_readlane_b32 s8, v255, 15
	v_readlane_b32 s9, v255, 16
	global_load_dword v81, v[4:5], off
	s_nop 0
	v_lshl_add_u64 v[4:5], v[2:3], 0, s[8:9]
	v_readlane_b32 s8, v255, 17
	v_readlane_b32 s9, v255, 18
	global_load_dword v83, v[4:5], off
	s_nop 0
	v_lshl_add_u64 v[4:5], v[2:3], 0, s[8:9]
	v_readlane_b32 s8, v255, 19
	v_readlane_b32 s9, v255, 20
	global_load_dword v85, v[4:5], off
	s_nop 0
	v_lshl_add_u64 v[4:5], v[2:3], 0, s[8:9]
	v_readlane_b32 s8, v255, 21
	v_readlane_b32 s9, v255, 22
	global_load_dword v87, v[4:5], off
	s_nop 0
	v_lshl_add_u64 v[4:5], v[2:3], 0, s[8:9]
	v_readlane_b32 s8, v254, 37
	v_readlane_b32 s9, v254, 38
	global_load_dword v89, v[4:5], off
	s_nop 0
	v_lshl_add_u64 v[4:5], v[2:3], 0, s[8:9]
	v_readlane_b32 s8, v254, 35
	v_readlane_b32 s9, v254, 36
	global_load_dword v91, v[4:5], off
	s_nop 0
	v_lshl_add_u64 v[4:5], v[2:3], 0, s[8:9]
	global_load_dword v93, v[4:5], off
	v_lshl_add_u64 v[4:5], v[2:3], 0, s[58:59]
	global_load_dword v95, v[4:5], off
	v_lshl_add_u64 v[4:5], v[2:3], 0, s[68:69]
	s_lshl_b64 s[8:9], s[84:85], 2
	global_load_dword v97, v[4:5], off
	v_lshl_add_u64 v[4:5], v[2:3], 0, s[94:95]
	v_lshl_add_u64 v[2:3], v[2:3], 0, s[88:89]
	s_add_u32 s10, s48, s8
	global_load_dword v99, v[4:5], off
	global_load_dword v101, v[2:3], off
	s_addc_u32 s11, s49, s9
	v_lshlrev_b32_e32 v2, 2, v1
	v_and_b32_e32 v12, 0xfc, v2
	s_add_u32 s8, s50, s8
	v_lshlrev_b32_e32 v6, 2, v12
	s_addc_u32 s9, s51, s9
	s_min_i32 s5, s6, 5
	global_load_dwordx4 v[2:5], v6, s[10:11]
	s_addk_i32 s5, 0x58
	v_readlane_b32 s10, v250, 32
	s_add_i32 s7, s5, s10
	v_lshlrev_b32_e32 v130, 1, v12
	s_max_i32 s7, s7, 0
	v_readlane_b32 s11, v250, 33
	s_min_i32 s28, s6, 13
	v_lshl_add_u64 v[102:103], s[80:81], 0, v[130:131]
	s_add_i32 s7, s7, s11
	s_addk_i32 s28, 0x50
	global_load_dwordx4 v[6:9], v6, s[8:9]
	v_mad_i64_i32 v[12:13], s[8:9], s7, v238, v[102:103]
	s_add_i32 s7, s28, s10
	s_max_i32 s7, s7, 0
	s_min_i32 s29, s6, 21
	s_add_i32 s7, s7, s11
	s_addk_i32 s29, 0x48
	global_load_dwordx2 v[108:109], v[12:13], off offset:1536
	global_load_dwordx2 v[106:107], v[12:13], off offset:1024
	v_mad_i64_i32 v[12:13], s[8:9], s7, v238, v[102:103]
	s_add_i32 s7, s29, s10
	s_max_i32 s7, s7, 0
	s_min_i32 s34, s6, 29
	s_add_i32 s7, s7, s11
	s_add_i32 s34, s34, 64
	global_load_dwordx2 v[112:113], v[12:13], off offset:1536
	global_load_dwordx2 v[110:111], v[12:13], off offset:1024
	v_mad_i64_i32 v[12:13], s[8:9], s7, v238, v[102:103]
	s_add_i32 s7, s34, s10
	s_max_i32 s7, s7, 0
	s_min_i32 s40, s6, 37
	s_add_i32 s7, s7, s11
	s_add_i32 s40, s40, 56
	global_load_dwordx2 v[116:117], v[12:13], off offset:1536
	global_load_dwordx2 v[114:115], v[12:13], off offset:1024
	v_mad_i64_i32 v[12:13], s[8:9], s7, v238, v[102:103]
	s_add_i32 s7, s40, s10
	s_max_i32 s7, s7, 0
	s_min_i32 s41, s6, 45
	s_add_i32 s7, s7, s11
	s_add_i32 s41, s41, 48
	global_load_dwordx2 v[120:121], v[12:13], off offset:1536
	global_load_dwordx2 v[118:119], v[12:13], off offset:1024
	v_mad_i64_i32 v[12:13], s[8:9], s7, v238, v[102:103]
	s_add_i32 s7, s41, s10
	s_max_i32 s7, s7, 0
	s_min_i32 s58, s6, 53
	s_add_i32 s7, s7, s11
	s_add_i32 s58, s58, 40
	global_load_dwordx2 v[124:125], v[12:13], off offset:1536
	global_load_dwordx2 v[122:123], v[12:13], off offset:1024
	v_mad_i64_i32 v[12:13], s[8:9], s7, v238, v[102:103]
	s_add_i32 s7, s58, s10
	s_max_i32 s7, s7, 0
	s_min_i32 s59, s6, 61
	s_add_i32 s7, s7, s11
	s_add_i32 s59, s59, 32
	global_load_dwordx2 v[128:129], v[12:13], off offset:1536
	global_load_dwordx2 v[126:127], v[12:13], off offset:1024
	v_mad_i64_i32 v[12:13], s[8:9], s7, v238, v[102:103]
	s_add_i32 s7, s59, s10
	s_max_i32 s7, s7, 0
	s_min_i32 s60, s6, 0x45
	s_add_i32 s7, s7, s11
	s_add_i32 s60, s60, 24
	global_load_dwordx2 v[134:135], v[12:13], off offset:1536
	global_load_dwordx2 v[132:133], v[12:13], off offset:1024
	v_mad_i64_i32 v[12:13], s[8:9], s7, v238, v[102:103]
	s_add_i32 s7, s60, s10
	s_max_i32 s7, s7, 0
	s_min_i32 s61, s6, 0x4d
	s_add_i32 s7, s7, s11
	s_add_i32 s61, s61, 16
	global_load_dwordx2 v[138:139], v[12:13], off offset:1536
	global_load_dwordx2 v[136:137], v[12:13], off offset:1024
	v_mad_i64_i32 v[12:13], s[8:9], s7, v238, v[102:103]
	s_add_i32 s7, s61, s10
	s_max_i32 s7, s7, 0
	s_min_i32 s62, s6, 0x55
	s_add_i32 s7, s7, s11
	s_add_i32 s62, s62, 8
	global_load_dwordx2 v[142:143], v[12:13], off offset:1536
	global_load_dwordx2 v[140:141], v[12:13], off offset:1024
	v_mad_i64_i32 v[12:13], s[8:9], s7, v238, v[102:103]
	s_add_i32 s7, s62, s10
	s_min_i32 s63, s6, 0x5d
	s_max_i32 s7, s7, 0
	s_add_i32 s6, s63, s10
	s_add_i32 s7, s7, s11
	s_max_i32 s6, s6, 0
	global_load_dwordx2 v[146:147], v[12:13], off offset:1536
	global_load_dwordx2 v[144:145], v[12:13], off offset:1024
	v_mad_i64_i32 v[12:13], s[8:9], s7, v238, v[102:103]
	s_add_i32 s6, s6, s11
	global_load_dwordx2 v[150:151], v[12:13], off offset:1536
	global_load_dwordx2 v[148:149], v[12:13], off offset:1024
	v_mad_i64_i32 v[12:13], s[6:7], s6, v238, v[102:103]
	global_load_dwordx2 v[154:155], v[12:13], off offset:1536
	global_load_dwordx2 v[152:153], v[12:13], off offset:1024
	v_or_b32_sdwa v12, v1, s84 dst_sel:DWORD dst_unused:UNUSED_PAD src0_sel:BYTE_0 src1_sel:DWORD
	v_ashrrev_i32_e32 v13, 31, v12
	v_lshl_add_u64 v[10:11], v[12:13], 2, v[10:11]
	global_load_dword v104, v[10:11], off
	s_waitcnt vmcnt(38)
	v_mov_b32_e32 v44, v43
	v_mov_b32_e32 v46, v45
	v_mov_b32_e32 v48, v47
	v_mov_b32_e32 v50, v49
	v_mov_b32_e32 v52, v51
	v_mov_b32_e32 v54, v53
	v_mov_b32_e32 v56, v55
	v_mov_b32_e32 v58, v57
	v_mov_b32_e32 v60, v59
	v_mov_b32_e32 v62, v61
	v_mov_b32_e32 v64, v63
	v_mov_b32_e32 v66, v65
	v_mov_b32_e32 v68, v67
	v_mov_b32_e32 v70, v69
	v_mov_b32_e32 v72, v71
	v_mov_b32_e32 v74, v73
	v_mov_b32_e32 v76, v75
	v_mov_b32_e32 v78, v77
	v_mov_b32_e32 v80, v79
	s_waitcnt vmcnt(37)
	v_mov_b32_e32 v82, v81
	s_waitcnt vmcnt(36)
	v_mov_b32_e32 v84, v83
	s_waitcnt vmcnt(35)
	v_mov_b32_e32 v86, v85
	s_waitcnt vmcnt(34)
	v_mov_b32_e32 v88, v87
	s_waitcnt vmcnt(33)
	v_mov_b32_e32 v90, v89
	s_waitcnt vmcnt(32)
	v_mov_b32_e32 v92, v91
	s_waitcnt vmcnt(31)
	v_mov_b32_e32 v94, v93
	s_waitcnt vmcnt(30)
	v_mov_b32_e32 v96, v95
	s_waitcnt vmcnt(29)
	v_mov_b32_e32 v98, v97
	s_waitcnt vmcnt(28)
	v_mov_b32_e32 v100, v99
	v_readlane_b32 s6, v253, 33
	s_branch .LBB0_320
